# all s_setprio flips removed from the GEMM K-loops
# speedup vs baseline: 1.0042x; 1.0042x over previous
; #define PG8_STAGE(bufoff, gbase, voff) do { _Pragma("unroll") for (int _i = 0; _i < 2; ++_i) \
;         __builtin_amdgcn_global_load_lds((const unsigned*)((const char*)(gbase) + (voff)[_i]), (PG8_LAS unsigned*)(lds + (bufoff) + ldsw + _i * 8192), 16, 0, 0); } while (0)
; #define PG8_LDA(dst, b, h) do { _Pragma("unroll") for (int m = 0; m < 4; ++m) _Pragma("unroll") for (int k = 0; k < 2; ++k) dst[m][k] = *(const PG8_LAS bf16x8*)(lds + PG8_SA(b, h) + aoff + m * 2048 + k * 1024); } while (0)
; #define PG8_LDB(dst, b, h) do { _Pragma("unroll") for (int n = 0; n < 2; ++n) _Pragma("unroll") for (int k = 0; k < 2; ++k) dst[n][k] = *(const PG8_LAS bf16x8*)(lds + PG8_SB(b, h) + boff + n * 2048 + k * 1024); } while (0)
; #define PG8_WAIT_V(n) asm volatile("s_waitcnt vmcnt(" #n ")" ::: "memory")
; #define PG8_WAIT_L(n) asm volatile("s_waitcnt lgkmcnt(" #n ")" ::: "memory")
; #define PG8_BAR __builtin_amdgcn_s_barrier()
; #define PG8_SCHED __builtin_amdgcn_sched_barrier(0)
; template <class Epi, class Sched, bool ALIGN_EPI = false, bool SP2 = false>
; __device__ __forceinline__ void gemm_phase(PG8_LAS unsigned char* lds, const Gemm g, const Sched& S, const Epi& E) {
;     ...
;         const bool has_next = S.next(ui + 1, nxt);
;         const char* nA = has_next ? (const char*)g.A + (size_t)nxt.pm * tstepA : cA; const char* nB = has_next ? (const char*)g.Bt + (size_t)nxt.pn * tstepB : cB;
;         for (int t = 0; t < nt; t += 2) {
;             const bool last = (t == nt - 2);
;             const char* a1 = cA + (size_t)(t + 1) * kstepA;
;             const char* a2 = last ? nA : cA + (size_t)(t + 2) * kstepA; const char* b2 = last ? nB : cB + (size_t)(t + 2) * kstep;
;             const char* a3 = a2 + kstepA; const char* b3 = b2 + kstep;
;             if (last && has_next) S.a_ready(nxt);
;             if constexpr (SP2) {
;             PG8_LDB(B0, 0, 0); PG8_LDB(B1, 0, 1); PG8_SCHED; PG8_LDA(At, 0, 0); PG8_STAGE(PG8_SA(1, 1), a1 + hstepA, voffA);
;             PG8_WAIT_V(8); PG8_WAIT_L(0); PG8_BAR; PG8_MMA(0, 0, At, B0); PG8_MMA(0, 1, At, B1); PG8_BAR; PG8_SCHED;
;             PG8_LDA(At, 0, 1); PG8_STAGE(PG8_SB(0, 0), b2, voffB); PG8_STAGE(PG8_SB(0, 1), b2 + hstepB, voffB); PG8_STAGE(PG8_SA(0, 0), a2, voffA);
;             PG8_WAIT_V(8); PG8_WAIT_L(0); PG8_BAR; PG8_MMA(1, 0, At, B0); PG8_MMA(1, 1, At, B1); PG8_BAR; PG8_SCHED;
.LBB0_140:
	s_ashr_i32 s59, s58, 31
	s_lshl_b64 s[60:61], s[58:59], 19
	s_add_u32 s60, s12, s60
	s_addc_u32 s61, s13, s61
	s_and_b64 s[62:63], s[2:3], exec
	s_cselect_b32 s59, s61, s71
	s_cselect_b32 s92, s60, s70
	s_ashr_i32 s57, s56, 31
	s_lshl_b64 s[62:63], s[56:57], 19
	s_add_u32 s62, s80, s62
	s_addc_u32 s63, s81, s63
	s_and_b64 s[94:95], s[2:3], exec
	s_cselect_b32 s57, s63, s73
	s_cselect_b32 s93, s62, s72
	s_add_u32 s70, s70, 0x10000
	s_addc_u32 s71, s71, 0
	s_add_u32 s72, s72, 0x10000
	s_addc_u32 s73, s73, 0
	s_mov_b32 s94, -2
	ds_read_b128 v[150:153], v143
	ds_read_b128 v[154:157], v143 offset:1024
	ds_read_b128 v[158:161], v143 offset:2048
	ds_read_b128 v[162:165], v143 offset:3072
	ds_read_b128 v[166:169], v144
	ds_read_b128 v[170:173], v144 offset:1024
	ds_read_b128 v[174:177], v144 offset:2048
	ds_read_b128 v[178:181], v144 offset:3072
	s_cmp_eq_u32 s94, 12
	s_cselect_b32 s97, s59, s71
	s_cselect_b32 s96, s92, s70
	s_cselect_b32 vcc_hi, s57, s73
	s_cselect_b32 vcc_lo, s93, s72
	s_movk_i32 s8, 0xc000
	v_lshl_add_u64 v[186:187], s[70:71], 0, v[128:129]
	s_mov_b32 s9, -1
	v_lshl_add_u64 v[220:221], v[186:187], 0, s[8:9]
	s_movk_i32 s8, 0xe000
	s_add_i32 m0, s18, 0xc000
	s_mov_b32 s9, -1
	ds_read_b128 v[182:185], v145
	ds_read_b128 v[190:193], v145 offset:1024
	ds_read_b128 v[194:197], v145 offset:2048
	ds_read_b128 v[198:201], v145 offset:3072
	ds_read_b128 v[202:205], v145 offset:4096
	ds_read_b128 v[206:209], v145 offset:5120
	ds_read_b128 v[210:213], v145 offset:6144
	ds_read_b128 v[214:217], v145 offset:7168
	global_load_lds_dwordx4 v[220:221], off
	v_lshl_add_u64 v[186:187], v[186:187], 0, s[8:9]
	s_add_i32 m0, s18, 0xe000
	s_nop 0
	global_load_lds_dwordx4 v[186:187], off
	s_waitcnt vmcnt(8)
	s_waitcnt lgkmcnt(0)
	s_barrier
	s_waitcnt lgkmcnt(0)
	v_mfma_f32_16x16x32_bf16 v[116:119], v[150:153], v[182:185], 0
	v_mfma_f32_16x16x32_bf16 v[112:115], v[158:161], v[182:185], 0
	v_mfma_f32_16x16x32_bf16 v[108:111], v[150:153], v[194:197], 0
	v_mfma_f32_16x16x32_bf16 v[100:103], v[158:161], v[194:197], 0
	v_mfma_f32_16x16x32_bf16 v[92:95], v[150:153], v[202:205], 0
	v_mfma_f32_16x16x32_bf16 v[84:87], v[158:161], v[202:205], 0
	v_mfma_f32_16x16x32_bf16 v[76:79], v[150:153], v[210:213], 0
	v_mfma_f32_16x16x32_bf16 v[68:71], v[158:161], v[210:213], 0
	v_mfma_f32_16x16x32_bf16 v[116:119], v[154:157], v[190:193], v[116:119]
	v_mfma_f32_16x16x32_bf16 v[112:115], v[162:165], v[190:193], v[112:115]
	v_mfma_f32_16x16x32_bf16 v[108:111], v[154:157], v[198:201], v[108:111]
	v_mfma_f32_16x16x32_bf16 v[100:103], v[162:165], v[198:201], v[100:103]
	v_mfma_f32_16x16x32_bf16 v[92:95], v[154:157], v[206:209], v[92:95]
	v_mfma_f32_16x16x32_bf16 v[84:87], v[162:165], v[206:209], v[84:87]
	v_mfma_f32_16x16x32_bf16 v[76:79], v[154:157], v[214:217], v[76:79]
	v_mfma_f32_16x16x32_bf16 v[68:71], v[162:165], v[214:217], v[68:71]
	v_mfma_f32_16x16x32_bf16 v[124:127], v[166:169], v[182:185], 0
	v_mfma_f32_16x16x32_bf16 v[120:123], v[174:177], v[182:185], 0
	v_mfma_f32_16x16x32_bf16 v[104:107], v[166:169], v[194:197], 0
	v_mfma_f32_16x16x32_bf16 v[96:99], v[174:177], v[194:197], 0
	v_mfma_f32_16x16x32_bf16 v[88:91], v[166:169], v[202:205], 0
	v_mfma_f32_16x16x32_bf16 v[80:83], v[174:177], v[202:205], 0
	v_mfma_f32_16x16x32_bf16 v[72:75], v[166:169], v[210:213], 0
	v_mfma_f32_16x16x32_bf16 v[64:67], v[174:177], v[210:213], 0
	v_mfma_f32_16x16x32_bf16 v[124:127], v[170:173], v[190:193], v[124:127]
	v_mfma_f32_16x16x32_bf16 v[120:123], v[178:181], v[190:193], v[120:123]
	v_mfma_f32_16x16x32_bf16 v[104:107], v[170:173], v[198:201], v[104:107]
	v_mfma_f32_16x16x32_bf16 v[96:99], v[178:181], v[198:201], v[96:99]
	v_mfma_f32_16x16x32_bf16 v[88:91], v[170:173], v[206:209], v[88:91]
	v_mfma_f32_16x16x32_bf16 v[80:83], v[178:181], v[206:209], v[80:83]
	v_mfma_f32_16x16x32_bf16 v[72:75], v[170:173], v[214:217], v[72:75]
	v_mfma_f32_16x16x32_bf16 v[64:67], v[178:181], v[214:217], v[64:67]
	s_barrier
	s_add_i32 s8, s86, s14
	v_lshl_add_u64 v[186:187], vcc, 0, v[128:129]
	s_mov_b32 m0, s8
	ds_read_b128 v[182:185], v145 offset:16384
	ds_read_b128 v[190:193], v145 offset:17408
	ds_read_b128 v[194:197], v145 offset:18432
	ds_read_b128 v[198:201], v145 offset:19456
	ds_read_b128 v[202:205], v145 offset:20480
	ds_read_b128 v[206:209], v145 offset:21504
	ds_read_b128 v[210:213], v145 offset:22528
	ds_read_b128 v[214:217], v145 offset:23552
	global_load_lds_dwordx4 v[186:187], off
	v_lshl_add_u64 v[220:221], v[186:187], 0, s[4:5]
	s_add_i32 m0, s8, 0x2000
	s_add_i32 s8, s89, s14
	global_load_lds_dwordx4 v[220:221], off
	v_lshl_add_u64 v[220:221], v[186:187], 0, s[6:7]
	s_mov_b32 m0, s8
	s_nop 0
	global_load_lds_dwordx4 v[220:221], off
	v_lshl_add_u64 v[220:221], v[186:187], 0, s[30:31]
	s_add_i32 m0, s8, 0x2000
	s_nop 0
	global_load_lds_dwordx4 v[220:221], off
	v_lshl_add_u64 v[220:221], s[96:97], 0, v[128:129]
	s_mov_b32 m0, s18
	v_lshl_add_u64 v[222:223], v[220:221], 0, s[4:5]
	global_load_lds_dwordx4 v[220:221], off
	s_mov_b32 m0, s19
	s_nop 0
	global_load_lds_dwordx4 v[222:223], off
	s_waitcnt vmcnt(8)
	s_waitcnt lgkmcnt(0)
	s_barrier
; #define PG8_STAGE(bufoff, gbase, voff) do { _Pragma("unroll") for (int _i = 0; _i < 2; ++_i) \
;         __builtin_amdgcn_global_load_lds((const unsigned*)((const char*)(gbase) + (voff)[_i]), (PG8_LAS unsigned*)(lds + (bufoff) + ldsw + _i * 8192), 16, 0, 0); } while (0)
; #define PG8_LDA(dst, b, h) do { _Pragma("unroll") for (int m = 0; m < 4; ++m) _Pragma("unroll") for (int k = 0; k < 2; ++k) dst[m][k] = *(const PG8_LAS bf16x8*)(lds + PG8_SA(b, h) + aoff + m * 2048 + k * 1024); } while (0)
; #define PG8_LDB(dst, b, h) do { _Pragma("unroll") for (int n = 0; n < 2; ++n) _Pragma("unroll") for (int k = 0; k < 2; ++k) dst[n][k] = *(const PG8_LAS bf16x8*)(lds + PG8_SB(b, h) + boff + n * 2048 + k * 1024); } while (0)
; #define PG8_MMA(ai, bj, At, Bt) do { __builtin_amdgcn_s_setprio(1); _Pragma("unroll") for (int m = 0; m < 4; ++m) _Pragma("unroll") for (int n = 0; n < 2; ++n) _Pragma("unroll") for (int k = 0; k < 2; ++k) \
;         acc[ai][bj][m][n] = __builtin_amdgcn_mfma_f32_16x16x32_bf16(Bt[n][k], At[m][k], acc[ai][bj][m][n], 0, 0, 0); __builtin_amdgcn_s_setprio(0); } while (0)
; #define PG8_WAIT_V(n) asm volatile("s_waitcnt vmcnt(" #n ")" ::: "memory")
; #define PG8_WAIT_L(n) asm volatile("s_waitcnt lgkmcnt(" #n ")" ::: "memory")
; #define PG8_BAR __builtin_amdgcn_s_barrier()
; #define PG8_SCHED __builtin_amdgcn_sched_barrier(0)
; template <class Epi, class Sched, bool ALIGN_EPI = false, bool SP2 = false>
; __device__ __forceinline__ void gemm_phase(PG8_LAS unsigned char* lds, const Gemm g, const Sched& S, const Epi& E) {
;     ...
;             PG8_WAIT_V(8); PG8_WAIT_L(0); PG8_BAR; PG8_MMA(1, 0, At, B0); PG8_MMA(1, 1, At, B1); PG8_BAR; PG8_SCHED;
;             PG8_LDB(B0, 1, 0); PG8_LDB(B1, 1, 1); PG8_SCHED; PG8_LDA(At, 1, 0); PG8_STAGE(PG8_SA(0, 1), a2 + hstepA, voffA);
;             PG8_WAIT_V(8); PG8_WAIT_L(0); PG8_BAR; PG8_MMA(0, 0, At, B0); PG8_MMA(0, 1, At, B1); PG8_BAR; PG8_SCHED;
	s_waitcnt lgkmcnt(0)
	v_mfma_f32_16x16x32_bf16 v[60:63], v[150:153], v[182:185], 0
	v_mfma_f32_16x16x32_bf16 v[52:55], v[158:161], v[182:185], 0
	v_mfma_f32_16x16x32_bf16 v[44:47], v[150:153], v[194:197], 0
	v_mfma_f32_16x16x32_bf16 v[36:39], v[158:161], v[194:197], 0
	v_mfma_f32_16x16x32_bf16 v[28:31], v[150:153], v[202:205], 0
	v_mfma_f32_16x16x32_bf16 v[20:23], v[158:161], v[202:205], 0
	v_mfma_f32_16x16x32_bf16 v[12:15], v[150:153], v[210:213], 0
	v_mfma_f32_16x16x32_bf16 v[4:7], v[158:161], v[210:213], 0
	v_mfma_f32_16x16x32_bf16 v[60:63], v[154:157], v[190:193], v[60:63]
	v_mfma_f32_16x16x32_bf16 v[52:55], v[162:165], v[190:193], v[52:55]
	v_mfma_f32_16x16x32_bf16 v[44:47], v[154:157], v[198:201], v[44:47]
	v_mfma_f32_16x16x32_bf16 v[36:39], v[162:165], v[198:201], v[36:39]
	v_mfma_f32_16x16x32_bf16 v[28:31], v[154:157], v[206:209], v[28:31]
	v_mfma_f32_16x16x32_bf16 v[20:23], v[162:165], v[206:209], v[20:23]
	v_mfma_f32_16x16x32_bf16 v[12:15], v[154:157], v[214:217], v[12:15]
	v_mfma_f32_16x16x32_bf16 v[4:7], v[162:165], v[214:217], v[4:7]
	v_mfma_f32_16x16x32_bf16 v[56:59], v[166:169], v[182:185], 0
	v_mfma_f32_16x16x32_bf16 v[48:51], v[174:177], v[182:185], 0
	v_mfma_f32_16x16x32_bf16 v[40:43], v[166:169], v[194:197], 0
	v_mfma_f32_16x16x32_bf16 v[32:35], v[174:177], v[194:197], 0
	v_mfma_f32_16x16x32_bf16 v[24:27], v[166:169], v[202:205], 0
	v_mfma_f32_16x16x32_bf16 v[16:19], v[174:177], v[202:205], 0
	v_mfma_f32_16x16x32_bf16 v[8:11], v[166:169], v[210:213], 0
	v_mfma_f32_16x16x32_bf16 v[0:3], v[174:177], v[210:213], 0
	v_mfma_f32_16x16x32_bf16 v[56:59], v[170:173], v[190:193], v[56:59]
	v_mfma_f32_16x16x32_bf16 v[48:51], v[178:181], v[190:193], v[48:51]
	v_mfma_f32_16x16x32_bf16 v[40:43], v[170:173], v[198:201], v[40:43]
	v_mfma_f32_16x16x32_bf16 v[32:35], v[178:181], v[198:201], v[32:35]
	v_mfma_f32_16x16x32_bf16 v[24:27], v[170:173], v[206:209], v[24:27]
	v_mfma_f32_16x16x32_bf16 v[16:19], v[178:181], v[206:209], v[16:19]
	v_mfma_f32_16x16x32_bf16 v[8:11], v[170:173], v[214:217], v[8:11]
	v_mfma_f32_16x16x32_bf16 v[0:3], v[178:181], v[214:217], v[0:3]
	s_barrier
	ds_read_b128 v[150:153], v146
	ds_read_b128 v[154:157], v146 offset:1024
	ds_read_b128 v[158:161], v146 offset:2048
	ds_read_b128 v[162:165], v146 offset:3072
	ds_read_b128 v[166:169], v147
	ds_read_b128 v[170:173], v147 offset:1024
	ds_read_b128 v[174:177], v147 offset:2048
	ds_read_b128 v[178:181], v147 offset:3072
	s_mov_b32 m0, s74
	v_lshl_add_u64 v[222:223], v[220:221], 0, s[6:7]
	ds_read_b128 v[182:185], v145 offset:32768
	ds_read_b128 v[190:193], v145 offset:33792
	ds_read_b128 v[194:197], v145 offset:34816
	ds_read_b128 v[198:201], v145 offset:35840
	ds_read_b128 v[202:205], v145 offset:36864
	ds_read_b128 v[206:209], v145 offset:37888
	ds_read_b128 v[210:213], v145 offset:38912
	ds_read_b128 v[214:217], v145 offset:39936
	global_load_lds_dwordx4 v[222:223], off
	v_lshl_add_u64 v[222:223], v[220:221], 0, s[30:31]
	s_mov_b32 m0, s75
	s_nop 0
	global_load_lds_dwordx4 v[222:223], off
	s_waitcnt vmcnt(8)
	s_waitcnt lgkmcnt(0)
	s_barrier
	s_waitcnt lgkmcnt(0)
	v_mfma_f32_16x16x32_bf16 v[116:119], v[150:153], v[182:185], v[116:119]
	v_mfma_f32_16x16x32_bf16 v[112:115], v[158:161], v[182:185], v[112:115]
	v_mfma_f32_16x16x32_bf16 v[108:111], v[150:153], v[194:197], v[108:111]
	v_mfma_f32_16x16x32_bf16 v[100:103], v[158:161], v[194:197], v[100:103]
	v_mfma_f32_16x16x32_bf16 v[92:95], v[150:153], v[202:205], v[92:95]
	v_mfma_f32_16x16x32_bf16 v[84:87], v[158:161], v[202:205], v[84:87]
	v_mfma_f32_16x16x32_bf16 v[76:79], v[150:153], v[210:213], v[76:79]
	v_mfma_f32_16x16x32_bf16 v[68:71], v[158:161], v[210:213], v[68:71]
	v_mfma_f32_16x16x32_bf16 v[116:119], v[154:157], v[190:193], v[116:119]
	v_mfma_f32_16x16x32_bf16 v[112:115], v[162:165], v[190:193], v[112:115]
	v_mfma_f32_16x16x32_bf16 v[108:111], v[154:157], v[198:201], v[108:111]
	v_mfma_f32_16x16x32_bf16 v[100:103], v[162:165], v[198:201], v[100:103]
	v_mfma_f32_16x16x32_bf16 v[92:95], v[154:157], v[206:209], v[92:95]
	v_mfma_f32_16x16x32_bf16 v[84:87], v[162:165], v[206:209], v[84:87]
	v_mfma_f32_16x16x32_bf16 v[76:79], v[154:157], v[214:217], v[76:79]
	v_mfma_f32_16x16x32_bf16 v[68:71], v[162:165], v[214:217], v[68:71]
	v_mfma_f32_16x16x32_bf16 v[124:127], v[166:169], v[182:185], v[124:127]
	v_mfma_f32_16x16x32_bf16 v[120:123], v[174:177], v[182:185], v[120:123]
	v_mfma_f32_16x16x32_bf16 v[104:107], v[166:169], v[194:197], v[104:107]
	v_mfma_f32_16x16x32_bf16 v[96:99], v[174:177], v[194:197], v[96:99]
	v_mfma_f32_16x16x32_bf16 v[88:91], v[166:169], v[202:205], v[88:91]
	v_mfma_f32_16x16x32_bf16 v[80:83], v[174:177], v[202:205], v[80:83]
	v_mfma_f32_16x16x32_bf16 v[72:75], v[166:169], v[210:213], v[72:75]
	v_mfma_f32_16x16x32_bf16 v[64:67], v[174:177], v[210:213], v[64:67]
	v_mfma_f32_16x16x32_bf16 v[124:127], v[170:173], v[190:193], v[124:127]
	v_mfma_f32_16x16x32_bf16 v[120:123], v[178:181], v[190:193], v[120:123]
	v_mfma_f32_16x16x32_bf16 v[104:107], v[170:173], v[198:201], v[104:107]
	v_mfma_f32_16x16x32_bf16 v[96:99], v[178:181], v[198:201], v[96:99]
	v_mfma_f32_16x16x32_bf16 v[88:91], v[170:173], v[206:209], v[88:91]
	v_mfma_f32_16x16x32_bf16 v[80:83], v[178:181], v[206:209], v[80:83]
	v_mfma_f32_16x16x32_bf16 v[72:75], v[170:173], v[214:217], v[72:75]
	v_mfma_f32_16x16x32_bf16 v[64:67], v[178:181], v[214:217], v[64:67]
	s_barrier
; #define PG8_STAGE(bufoff, gbase, voff) do { _Pragma("unroll") for (int _i = 0; _i < 2; ++_i) \
;         __builtin_amdgcn_global_load_lds((const unsigned*)((const char*)(gbase) + (voff)[_i]), (PG8_LAS unsigned*)(lds + (bufoff) + ldsw + _i * 8192), 16, 0, 0); } while (0)
; #define PG8_LDA(dst, b, h) do { _Pragma("unroll") for (int m = 0; m < 4; ++m) _Pragma("unroll") for (int k = 0; k < 2; ++k) dst[m][k] = *(const PG8_LAS bf16x8*)(lds + PG8_SA(b, h) + aoff + m * 2048 + k * 1024); } while (0)
; #define PG8_LDB(dst, b, h) do { _Pragma("unroll") for (int n = 0; n < 2; ++n) _Pragma("unroll") for (int k = 0; k < 2; ++k) dst[n][k] = *(const PG8_LAS bf16x8*)(lds + PG8_SB(b, h) + boff + n * 2048 + k * 1024); } while (0)
; #define PG8_MMA(ai, bj, At, Bt) do { __builtin_amdgcn_s_setprio(1); _Pragma("unroll") for (int m = 0; m < 4; ++m) _Pragma("unroll") for (int n = 0; n < 2; ++n) _Pragma("unroll") for (int k = 0; k < 2; ++k) \
;         acc[ai][bj][m][n] = __builtin_amdgcn_mfma_f32_16x16x32_bf16(Bt[n][k], At[m][k], acc[ai][bj][m][n], 0, 0, 0); __builtin_amdgcn_s_setprio(0); } while (0)
; #define PG8_WAIT_V(n) asm volatile("s_waitcnt vmcnt(" #n ")" ::: "memory")
; #define PG8_WAIT_L(n) asm volatile("s_waitcnt lgkmcnt(" #n ")" ::: "memory")
; #define PG8_BAR __builtin_amdgcn_s_barrier()
; #define PG8_SCHED __builtin_amdgcn_sched_barrier(0)
; template <class Epi, class Sched, bool ALIGN_EPI = false, bool SP2 = false>
; __device__ __forceinline__ void gemm_phase(PG8_LAS unsigned char* lds, const Gemm g, const Sched& S, const Epi& E) {
;     ...
;             PG8_LDB(B0, 0, 0); PG8_LDB(B1, 0, 1); PG8_SCHED; PG8_LDA(At, 0, 0); PG8_STAGE(PG8_SA(1, 1), a1 + hstepA, voffA);
;             PG8_WAIT_V(8); PG8_WAIT_L(0); PG8_BAR; PG8_MMA(0, 0, At, B0); PG8_MMA(0, 1, At, B1); PG8_BAR; PG8_SCHED;
;     ...
;             PG8_LDA(At, 1, 1); PG8_STAGE(PG8_SB(1, 0), b3, voffB); PG8_STAGE(PG8_SB(1, 1), b3 + hstepB, voffB); PG8_STAGE(PG8_SA(1, 0), a3, voffA);
;             PG8_WAIT_V(8); PG8_WAIT_L(0); PG8_BAR; PG8_MMA(1, 0, At, B0); PG8_MMA(1, 1, At, B1); PG8_BAR; PG8_SCHED;
	s_add_i32 s8, s90, s14
	v_lshl_add_u64 v[222:223], v[186:187], 0, s[34:35]
	s_mov_b32 m0, s8
	ds_read_b128 v[182:185], v145 offset:49152
	ds_read_b128 v[190:193], v145 offset:50176
	ds_read_b128 v[194:197], v145 offset:51200
	ds_read_b128 v[198:201], v145 offset:52224
	ds_read_b128 v[202:205], v145 offset:53248
	ds_read_b128 v[206:209], v145 offset:54272
	ds_read_b128 v[210:213], v145 offset:55296
	ds_read_b128 v[214:217], v145 offset:56320
	global_load_lds_dwordx4 v[222:223], off
	v_lshl_add_u64 v[222:223], v[186:187], 0, s[36:37]
	s_add_i32 m0, s8, 0x2000
	s_add_i32 s8, s91, s14
	global_load_lds_dwordx4 v[222:223], off
	v_lshl_add_u64 v[222:223], v[186:187], 0, s[38:39]
	s_mov_b32 m0, s8
	v_lshl_add_u64 v[186:187], v[186:187], 0, s[40:41]
	global_load_lds_dwordx4 v[222:223], off
	s_add_i32 m0, s8, 0x2000
	s_nop 0
	global_load_lds_dwordx4 v[186:187], off
	v_lshl_add_u64 v[186:187], v[220:221], 0, s[34:35]
	s_mov_b32 m0, s76
	s_nop 0
	global_load_lds_dwordx4 v[186:187], off
	v_lshl_add_u64 v[186:187], v[220:221], 0, s[36:37]
	s_mov_b32 m0, s77
	s_nop 0
	global_load_lds_dwordx4 v[186:187], off
	s_waitcnt vmcnt(8)
	s_waitcnt lgkmcnt(0)
	s_barrier
	s_waitcnt lgkmcnt(0)
	v_mfma_f32_16x16x32_bf16 v[60:63], v[150:153], v[182:185], v[60:63]
	v_mfma_f32_16x16x32_bf16 v[52:55], v[158:161], v[182:185], v[52:55]
	v_mfma_f32_16x16x32_bf16 v[44:47], v[150:153], v[194:197], v[44:47]
	v_mfma_f32_16x16x32_bf16 v[36:39], v[158:161], v[194:197], v[36:39]
	v_mfma_f32_16x16x32_bf16 v[28:31], v[150:153], v[202:205], v[28:31]
	v_mfma_f32_16x16x32_bf16 v[20:23], v[158:161], v[202:205], v[20:23]
	v_mfma_f32_16x16x32_bf16 v[12:15], v[150:153], v[210:213], v[12:15]
	v_mfma_f32_16x16x32_bf16 v[4:7], v[158:161], v[210:213], v[4:7]
	v_mfma_f32_16x16x32_bf16 v[60:63], v[154:157], v[190:193], v[60:63]
	v_mfma_f32_16x16x32_bf16 v[52:55], v[162:165], v[190:193], v[52:55]
	v_mfma_f32_16x16x32_bf16 v[44:47], v[154:157], v[198:201], v[44:47]
	v_mfma_f32_16x16x32_bf16 v[36:39], v[162:165], v[198:201], v[36:39]
	v_mfma_f32_16x16x32_bf16 v[28:31], v[154:157], v[206:209], v[28:31]
	v_mfma_f32_16x16x32_bf16 v[20:23], v[162:165], v[206:209], v[20:23]
	v_mfma_f32_16x16x32_bf16 v[12:15], v[154:157], v[214:217], v[12:15]
	v_mfma_f32_16x16x32_bf16 v[4:7], v[162:165], v[214:217], v[4:7]
	v_mfma_f32_16x16x32_bf16 v[56:59], v[166:169], v[182:185], v[56:59]
	v_mfma_f32_16x16x32_bf16 v[48:51], v[174:177], v[182:185], v[48:51]
	v_mfma_f32_16x16x32_bf16 v[40:43], v[166:169], v[194:197], v[40:43]
	v_mfma_f32_16x16x32_bf16 v[32:35], v[174:177], v[194:197], v[32:35]
	v_mfma_f32_16x16x32_bf16 v[24:27], v[166:169], v[202:205], v[24:27]
	v_mfma_f32_16x16x32_bf16 v[16:19], v[174:177], v[202:205], v[16:19]
	v_mfma_f32_16x16x32_bf16 v[8:11], v[166:169], v[210:213], v[8:11]
	v_mfma_f32_16x16x32_bf16 v[0:3], v[174:177], v[210:213], v[0:3]
	v_mfma_f32_16x16x32_bf16 v[56:59], v[170:173], v[190:193], v[56:59]
	v_mfma_f32_16x16x32_bf16 v[48:51], v[178:181], v[190:193], v[48:51]
	v_mfma_f32_16x16x32_bf16 v[40:43], v[170:173], v[198:201], v[40:43]
	v_mfma_f32_16x16x32_bf16 v[32:35], v[178:181], v[198:201], v[32:35]
	v_mfma_f32_16x16x32_bf16 v[24:27], v[170:173], v[206:209], v[24:27]
	v_mfma_f32_16x16x32_bf16 v[16:19], v[178:181], v[206:209], v[16:19]
	v_mfma_f32_16x16x32_bf16 v[8:11], v[170:173], v[214:217], v[8:11]
	v_mfma_f32_16x16x32_bf16 v[0:3], v[178:181], v[214:217], v[0:3]
	s_barrier
	s_add_i32 s94, s94, 2
	s_add_u32 s70, s70, 0x10000
	s_addc_u32 s71, s71, 0
	s_add_u32 s72, s72, 0x10000
	s_addc_u32 s73, s73, 0
	s_cmp_gt_u32 s94, 13
.LBB0_141:
	ds_read_b128 v[150:153], v143
	ds_read_b128 v[154:157], v143 offset:1024
	ds_read_b128 v[158:161], v143 offset:2048
	ds_read_b128 v[162:165], v143 offset:3072
	ds_read_b128 v[166:169], v144
	ds_read_b128 v[170:173], v144 offset:1024
	ds_read_b128 v[174:177], v144 offset:2048
	ds_read_b128 v[178:181], v144 offset:3072
	s_cmp_eq_u32 s94, 12
	s_cselect_b32 s97, s59, s71
	s_cselect_b32 s96, s92, s70
	s_cselect_b32 vcc_hi, s57, s73
	s_cselect_b32 vcc_lo, s93, s72
	s_movk_i32 s8, 0xc000
	v_lshl_add_u64 v[186:187], s[70:71], 0, v[128:129]
	s_mov_b32 s9, -1
	v_lshl_add_u64 v[220:221], v[186:187], 0, s[8:9]
	s_movk_i32 s8, 0xe000
	s_add_i32 m0, s18, 0xc000
	s_mov_b32 s9, -1
	ds_read_b128 v[182:185], v145
	ds_read_b128 v[190:193], v145 offset:1024
	ds_read_b128 v[194:197], v145 offset:2048
	ds_read_b128 v[198:201], v145 offset:3072
	ds_read_b128 v[202:205], v145 offset:4096
	ds_read_b128 v[206:209], v145 offset:5120
	ds_read_b128 v[210:213], v145 offset:6144
	ds_read_b128 v[214:217], v145 offset:7168
	global_load_lds_dwordx4 v[220:221], off
	v_lshl_add_u64 v[186:187], v[186:187], 0, s[8:9]
	s_add_i32 m0, s18, 0xe000
	s_nop 0
	global_load_lds_dwordx4 v[186:187], off
	s_waitcnt vmcnt(8)
	s_waitcnt lgkmcnt(0)
	s_barrier
; #define PG8_STAGE(bufoff, gbase, voff) do { _Pragma("unroll") for (int _i = 0; _i < 2; ++_i) \
;         __builtin_amdgcn_global_load_lds((const unsigned*)((const char*)(gbase) + (voff)[_i]), (PG8_LAS unsigned*)(lds + (bufoff) + ldsw + _i * 8192), 16, 0, 0); } while (0)
; #define PG8_LDA(dst, b, h) do { _Pragma("unroll") for (int m = 0; m < 4; ++m) _Pragma("unroll") for (int k = 0; k < 2; ++k) dst[m][k] = *(const PG8_LAS bf16x8*)(lds + PG8_SA(b, h) + aoff + m * 2048 + k * 1024); } while (0)
; #define PG8_MMA(ai, bj, At, Bt) do { __builtin_amdgcn_s_setprio(1); _Pragma("unroll") for (int m = 0; m < 4; ++m) _Pragma("unroll") for (int n = 0; n < 2; ++n) _Pragma("unroll") for (int k = 0; k < 2; ++k) \
;         acc[ai][bj][m][n] = __builtin_amdgcn_mfma_f32_16x16x32_bf16(Bt[n][k], At[m][k], acc[ai][bj][m][n], 0, 0, 0); __builtin_amdgcn_s_setprio(0); } while (0)
; #define PG8_WAIT_V(n) asm volatile("s_waitcnt vmcnt(" #n ")" ::: "memory")
; #define PG8_WAIT_L(n) asm volatile("s_waitcnt lgkmcnt(" #n ")" ::: "memory")
; #define PG8_BAR __builtin_amdgcn_s_barrier()
; #define PG8_SCHED __builtin_amdgcn_sched_barrier(0)
; template <class Epi, class Sched, bool ALIGN_EPI = false, bool SP2 = false>
; __device__ __forceinline__ void gemm_phase(PG8_LAS unsigned char* lds, const Gemm g, const Sched& S, const Epi& E) {
;     ...
;             PG8_WAIT_V(8); PG8_WAIT_L(0); PG8_BAR; PG8_MMA(0, 0, At, B0); PG8_MMA(0, 1, At, B1); PG8_BAR; PG8_SCHED;
;             PG8_LDA(At, 0, 1); PG8_STAGE(PG8_SB(0, 0), b2, voffB); PG8_STAGE(PG8_SB(0, 1), b2 + hstepB, voffB); PG8_STAGE(PG8_SA(0, 0), a2, voffA);
;             PG8_WAIT_V(8); PG8_WAIT_L(0); PG8_BAR; PG8_MMA(1, 0, At, B0); PG8_MMA(1, 1, At, B1); PG8_BAR; PG8_SCHED;
	s_waitcnt lgkmcnt(0)
	v_mfma_f32_16x16x32_bf16 v[116:119], v[150:153], v[182:185], v[116:119]
	v_mfma_f32_16x16x32_bf16 v[112:115], v[158:161], v[182:185], v[112:115]
	v_mfma_f32_16x16x32_bf16 v[108:111], v[150:153], v[194:197], v[108:111]
	v_mfma_f32_16x16x32_bf16 v[100:103], v[158:161], v[194:197], v[100:103]
	v_mfma_f32_16x16x32_bf16 v[92:95], v[150:153], v[202:205], v[92:95]
	v_mfma_f32_16x16x32_bf16 v[84:87], v[158:161], v[202:205], v[84:87]
	v_mfma_f32_16x16x32_bf16 v[76:79], v[150:153], v[210:213], v[76:79]
	v_mfma_f32_16x16x32_bf16 v[68:71], v[158:161], v[210:213], v[68:71]
	v_mfma_f32_16x16x32_bf16 v[116:119], v[154:157], v[190:193], v[116:119]
	v_mfma_f32_16x16x32_bf16 v[112:115], v[162:165], v[190:193], v[112:115]
	v_mfma_f32_16x16x32_bf16 v[108:111], v[154:157], v[198:201], v[108:111]
	v_mfma_f32_16x16x32_bf16 v[100:103], v[162:165], v[198:201], v[100:103]
	v_mfma_f32_16x16x32_bf16 v[92:95], v[154:157], v[206:209], v[92:95]
	v_mfma_f32_16x16x32_bf16 v[84:87], v[162:165], v[206:209], v[84:87]
	v_mfma_f32_16x16x32_bf16 v[76:79], v[154:157], v[214:217], v[76:79]
	v_mfma_f32_16x16x32_bf16 v[68:71], v[162:165], v[214:217], v[68:71]
	v_mfma_f32_16x16x32_bf16 v[124:127], v[166:169], v[182:185], v[124:127]
	v_mfma_f32_16x16x32_bf16 v[120:123], v[174:177], v[182:185], v[120:123]
	v_mfma_f32_16x16x32_bf16 v[104:107], v[166:169], v[194:197], v[104:107]
	v_mfma_f32_16x16x32_bf16 v[96:99], v[174:177], v[194:197], v[96:99]
	v_mfma_f32_16x16x32_bf16 v[88:91], v[166:169], v[202:205], v[88:91]
	v_mfma_f32_16x16x32_bf16 v[80:83], v[174:177], v[202:205], v[80:83]
	v_mfma_f32_16x16x32_bf16 v[72:75], v[166:169], v[210:213], v[72:75]
	v_mfma_f32_16x16x32_bf16 v[64:67], v[174:177], v[210:213], v[64:67]
	v_mfma_f32_16x16x32_bf16 v[124:127], v[170:173], v[190:193], v[124:127]
	v_mfma_f32_16x16x32_bf16 v[120:123], v[178:181], v[190:193], v[120:123]
	v_mfma_f32_16x16x32_bf16 v[104:107], v[170:173], v[198:201], v[104:107]
	v_mfma_f32_16x16x32_bf16 v[96:99], v[178:181], v[198:201], v[96:99]
	v_mfma_f32_16x16x32_bf16 v[88:91], v[170:173], v[206:209], v[88:91]
	v_mfma_f32_16x16x32_bf16 v[80:83], v[178:181], v[206:209], v[80:83]
	v_mfma_f32_16x16x32_bf16 v[72:75], v[170:173], v[214:217], v[72:75]
	v_mfma_f32_16x16x32_bf16 v[64:67], v[178:181], v[214:217], v[64:67]
	s_barrier
	s_add_i32 s8, s86, s14
	v_lshl_add_u64 v[186:187], vcc, 0, v[128:129]
	s_mov_b32 m0, s8
	ds_read_b128 v[182:185], v145 offset:16384
	ds_read_b128 v[190:193], v145 offset:17408
	ds_read_b128 v[194:197], v145 offset:18432
	ds_read_b128 v[198:201], v145 offset:19456
	ds_read_b128 v[202:205], v145 offset:20480
	ds_read_b128 v[206:209], v145 offset:21504
	ds_read_b128 v[210:213], v145 offset:22528
	ds_read_b128 v[214:217], v145 offset:23552
	global_load_lds_dwordx4 v[186:187], off
	v_lshl_add_u64 v[220:221], v[186:187], 0, s[4:5]
	s_add_i32 m0, s8, 0x2000
	s_add_i32 s8, s89, s14
	global_load_lds_dwordx4 v[220:221], off
	v_lshl_add_u64 v[220:221], v[186:187], 0, s[6:7]
	s_mov_b32 m0, s8
	s_nop 0
	global_load_lds_dwordx4 v[220:221], off
	v_lshl_add_u64 v[220:221], v[186:187], 0, s[30:31]
	s_add_i32 m0, s8, 0x2000
	s_nop 0
	global_load_lds_dwordx4 v[220:221], off
	v_lshl_add_u64 v[220:221], s[96:97], 0, v[128:129]
	s_mov_b32 m0, s18
	v_lshl_add_u64 v[222:223], v[220:221], 0, s[4:5]
	global_load_lds_dwordx4 v[220:221], off
	s_mov_b32 m0, s19
	s_nop 0
	global_load_lds_dwordx4 v[222:223], off
	s_waitcnt vmcnt(8)
	s_waitcnt lgkmcnt(0)
	s_barrier
	s_waitcnt lgkmcnt(0)
	v_mfma_f32_16x16x32_bf16 v[60:63], v[150:153], v[182:185], v[60:63]
	v_mfma_f32_16x16x32_bf16 v[52:55], v[158:161], v[182:185], v[52:55]
	v_mfma_f32_16x16x32_bf16 v[44:47], v[150:153], v[194:197], v[44:47]
	v_mfma_f32_16x16x32_bf16 v[36:39], v[158:161], v[194:197], v[36:39]
	v_mfma_f32_16x16x32_bf16 v[28:31], v[150:153], v[202:205], v[28:31]
	v_mfma_f32_16x16x32_bf16 v[20:23], v[158:161], v[202:205], v[20:23]
	v_mfma_f32_16x16x32_bf16 v[12:15], v[150:153], v[210:213], v[12:15]
	v_mfma_f32_16x16x32_bf16 v[4:7], v[158:161], v[210:213], v[4:7]
	v_mfma_f32_16x16x32_bf16 v[60:63], v[154:157], v[190:193], v[60:63]
	v_mfma_f32_16x16x32_bf16 v[52:55], v[162:165], v[190:193], v[52:55]
	v_mfma_f32_16x16x32_bf16 v[44:47], v[154:157], v[198:201], v[44:47]
	v_mfma_f32_16x16x32_bf16 v[36:39], v[162:165], v[198:201], v[36:39]
	v_mfma_f32_16x16x32_bf16 v[28:31], v[154:157], v[206:209], v[28:31]
	v_mfma_f32_16x16x32_bf16 v[20:23], v[162:165], v[206:209], v[20:23]
	v_mfma_f32_16x16x32_bf16 v[12:15], v[154:157], v[214:217], v[12:15]
	v_mfma_f32_16x16x32_bf16 v[4:7], v[162:165], v[214:217], v[4:7]
	v_mfma_f32_16x16x32_bf16 v[56:59], v[166:169], v[182:185], v[56:59]
	v_mfma_f32_16x16x32_bf16 v[48:51], v[174:177], v[182:185], v[48:51]
	v_mfma_f32_16x16x32_bf16 v[40:43], v[166:169], v[194:197], v[40:43]
	v_mfma_f32_16x16x32_bf16 v[32:35], v[174:177], v[194:197], v[32:35]
	v_mfma_f32_16x16x32_bf16 v[24:27], v[166:169], v[202:205], v[24:27]
	v_mfma_f32_16x16x32_bf16 v[16:19], v[174:177], v[202:205], v[16:19]
	v_mfma_f32_16x16x32_bf16 v[8:11], v[166:169], v[210:213], v[8:11]
	v_mfma_f32_16x16x32_bf16 v[0:3], v[174:177], v[210:213], v[0:3]
	v_mfma_f32_16x16x32_bf16 v[56:59], v[170:173], v[190:193], v[56:59]
	v_mfma_f32_16x16x32_bf16 v[48:51], v[178:181], v[190:193], v[48:51]
	v_mfma_f32_16x16x32_bf16 v[40:43], v[170:173], v[198:201], v[40:43]
	v_mfma_f32_16x16x32_bf16 v[32:35], v[178:181], v[198:201], v[32:35]
	v_mfma_f32_16x16x32_bf16 v[24:27], v[170:173], v[206:209], v[24:27]
	v_mfma_f32_16x16x32_bf16 v[16:19], v[178:181], v[206:209], v[16:19]
	v_mfma_f32_16x16x32_bf16 v[8:11], v[170:173], v[214:217], v[8:11]
	v_mfma_f32_16x16x32_bf16 v[0:3], v[178:181], v[214:217], v[0:3]
	s_barrier
; #define PG8_STAGE(bufoff, gbase, voff) do { _Pragma("unroll") for (int _i = 0; _i < 2; ++_i) \
;         __builtin_amdgcn_global_load_lds((const unsigned*)((const char*)(gbase) + (voff)[_i]), (PG8_LAS unsigned*)(lds + (bufoff) + ldsw + _i * 8192), 16, 0, 0); } while (0)
; #define PG8_LDA(dst, b, h) do { _Pragma("unroll") for (int m = 0; m < 4; ++m) _Pragma("unroll") for (int k = 0; k < 2; ++k) dst[m][k] = *(const PG8_LAS bf16x8*)(lds + PG8_SA(b, h) + aoff + m * 2048 + k * 1024); } while (0)
; #define PG8_LDB(dst, b, h) do { _Pragma("unroll") for (int n = 0; n < 2; ++n) _Pragma("unroll") for (int k = 0; k < 2; ++k) dst[n][k] = *(const PG8_LAS bf16x8*)(lds + PG8_SB(b, h) + boff + n * 2048 + k * 1024); } while (0)
; #define PG8_MMA(ai, bj, At, Bt) do { __builtin_amdgcn_s_setprio(1); _Pragma("unroll") for (int m = 0; m < 4; ++m) _Pragma("unroll") for (int n = 0; n < 2; ++n) _Pragma("unroll") for (int k = 0; k < 2; ++k) \
;         acc[ai][bj][m][n] = __builtin_amdgcn_mfma_f32_16x16x32_bf16(Bt[n][k], At[m][k], acc[ai][bj][m][n], 0, 0, 0); __builtin_amdgcn_s_setprio(0); } while (0)
; #define PG8_WAIT_V(n) asm volatile("s_waitcnt vmcnt(" #n ")" ::: "memory")
; #define PG8_WAIT_L(n) asm volatile("s_waitcnt lgkmcnt(" #n ")" ::: "memory")
; #define PG8_BAR __builtin_amdgcn_s_barrier()
; #define PG8_SCHED __builtin_amdgcn_sched_barrier(0)
; template <class Epi, class Sched, bool ALIGN_EPI = false, bool SP2 = false>
; __device__ __forceinline__ void gemm_phase(PG8_LAS unsigned char* lds, const Gemm g, const Sched& S, const Epi& E) {
;     ...
;             PG8_LDB(B0, 1, 0); PG8_LDB(B1, 1, 1); PG8_SCHED; PG8_LDA(At, 1, 0); PG8_STAGE(PG8_SA(0, 1), a2 + hstepA, voffA);
;             PG8_WAIT_V(8); PG8_WAIT_L(0); PG8_BAR; PG8_MMA(0, 0, At, B0); PG8_MMA(0, 1, At, B1); PG8_BAR; PG8_SCHED;
;             PG8_LDA(At, 1, 1); PG8_STAGE(PG8_SB(1, 0), b3, voffB); PG8_STAGE(PG8_SB(1, 1), b3 + hstepB, voffB); PG8_STAGE(PG8_SA(1, 0), a3, voffA);
;             PG8_WAIT_V(8); PG8_WAIT_L(0); PG8_BAR; PG8_MMA(1, 0, At, B0); PG8_MMA(1, 1, At, B1); PG8_BAR; PG8_SCHED;
	ds_read_b128 v[150:153], v146
	ds_read_b128 v[154:157], v146 offset:1024
	ds_read_b128 v[158:161], v146 offset:2048
	ds_read_b128 v[162:165], v146 offset:3072
	ds_read_b128 v[166:169], v147
	ds_read_b128 v[170:173], v147 offset:1024
	ds_read_b128 v[174:177], v147 offset:2048
	ds_read_b128 v[178:181], v147 offset:3072
	s_mov_b32 m0, s74
	v_lshl_add_u64 v[222:223], v[220:221], 0, s[6:7]
	ds_read_b128 v[182:185], v145 offset:32768
	ds_read_b128 v[190:193], v145 offset:33792
	ds_read_b128 v[194:197], v145 offset:34816
	ds_read_b128 v[198:201], v145 offset:35840
	ds_read_b128 v[202:205], v145 offset:36864
	ds_read_b128 v[206:209], v145 offset:37888
	ds_read_b128 v[210:213], v145 offset:38912
	ds_read_b128 v[214:217], v145 offset:39936
	global_load_lds_dwordx4 v[222:223], off
	v_lshl_add_u64 v[222:223], v[220:221], 0, s[30:31]
	s_mov_b32 m0, s75
	s_nop 0
	global_load_lds_dwordx4 v[222:223], off
	s_waitcnt vmcnt(8)
	s_waitcnt lgkmcnt(0)
	s_barrier
	s_waitcnt lgkmcnt(0)
	v_mfma_f32_16x16x32_bf16 v[116:119], v[150:153], v[182:185], v[116:119]
	v_mfma_f32_16x16x32_bf16 v[112:115], v[158:161], v[182:185], v[112:115]
	v_mfma_f32_16x16x32_bf16 v[108:111], v[150:153], v[194:197], v[108:111]
	v_mfma_f32_16x16x32_bf16 v[100:103], v[158:161], v[194:197], v[100:103]
	v_mfma_f32_16x16x32_bf16 v[92:95], v[150:153], v[202:205], v[92:95]
	v_mfma_f32_16x16x32_bf16 v[84:87], v[158:161], v[202:205], v[84:87]
	v_mfma_f32_16x16x32_bf16 v[76:79], v[150:153], v[210:213], v[76:79]
	v_mfma_f32_16x16x32_bf16 v[68:71], v[158:161], v[210:213], v[68:71]
	v_mfma_f32_16x16x32_bf16 v[116:119], v[154:157], v[190:193], v[116:119]
	v_mfma_f32_16x16x32_bf16 v[112:115], v[162:165], v[190:193], v[112:115]
	v_mfma_f32_16x16x32_bf16 v[108:111], v[154:157], v[198:201], v[108:111]
	v_mfma_f32_16x16x32_bf16 v[100:103], v[162:165], v[198:201], v[100:103]
	v_mfma_f32_16x16x32_bf16 v[92:95], v[154:157], v[206:209], v[92:95]
	v_mfma_f32_16x16x32_bf16 v[84:87], v[162:165], v[206:209], v[84:87]
	v_mfma_f32_16x16x32_bf16 v[76:79], v[154:157], v[214:217], v[76:79]
	v_mfma_f32_16x16x32_bf16 v[68:71], v[162:165], v[214:217], v[68:71]
	v_mfma_f32_16x16x32_bf16 v[124:127], v[166:169], v[182:185], v[124:127]
	v_mfma_f32_16x16x32_bf16 v[120:123], v[174:177], v[182:185], v[120:123]
	v_mfma_f32_16x16x32_bf16 v[104:107], v[166:169], v[194:197], v[104:107]
	v_mfma_f32_16x16x32_bf16 v[96:99], v[174:177], v[194:197], v[96:99]
	v_mfma_f32_16x16x32_bf16 v[88:91], v[166:169], v[202:205], v[88:91]
	v_mfma_f32_16x16x32_bf16 v[80:83], v[174:177], v[202:205], v[80:83]
	v_mfma_f32_16x16x32_bf16 v[72:75], v[166:169], v[210:213], v[72:75]
	v_mfma_f32_16x16x32_bf16 v[64:67], v[174:177], v[210:213], v[64:67]
	v_mfma_f32_16x16x32_bf16 v[124:127], v[170:173], v[190:193], v[124:127]
	v_mfma_f32_16x16x32_bf16 v[120:123], v[178:181], v[190:193], v[120:123]
	v_mfma_f32_16x16x32_bf16 v[104:107], v[170:173], v[198:201], v[104:107]
	v_mfma_f32_16x16x32_bf16 v[96:99], v[178:181], v[198:201], v[96:99]
	v_mfma_f32_16x16x32_bf16 v[88:91], v[170:173], v[206:209], v[88:91]
	v_mfma_f32_16x16x32_bf16 v[80:83], v[178:181], v[206:209], v[80:83]
	v_mfma_f32_16x16x32_bf16 v[72:75], v[170:173], v[214:217], v[72:75]
	v_mfma_f32_16x16x32_bf16 v[64:67], v[178:181], v[214:217], v[64:67]
	s_barrier
	s_add_i32 s8, s90, s14
	v_lshl_add_u64 v[222:223], v[186:187], 0, s[34:35]
	s_mov_b32 m0, s8
	ds_read_b128 v[182:185], v145 offset:49152
	ds_read_b128 v[190:193], v145 offset:50176
	ds_read_b128 v[194:197], v145 offset:51200
	ds_read_b128 v[198:201], v145 offset:52224
	ds_read_b128 v[202:205], v145 offset:53248
	ds_read_b128 v[206:209], v145 offset:54272
	ds_read_b128 v[210:213], v145 offset:55296
	ds_read_b128 v[214:217], v145 offset:56320
	global_load_lds_dwordx4 v[222:223], off
	v_lshl_add_u64 v[222:223], v[186:187], 0, s[36:37]
	s_add_i32 m0, s8, 0x2000
	s_add_i32 s8, s91, s14
	global_load_lds_dwordx4 v[222:223], off
	v_lshl_add_u64 v[222:223], v[186:187], 0, s[38:39]
	s_mov_b32 m0, s8
	v_lshl_add_u64 v[186:187], v[186:187], 0, s[40:41]
	global_load_lds_dwordx4 v[222:223], off
	s_add_i32 m0, s8, 0x2000
	s_nop 0
	global_load_lds_dwordx4 v[186:187], off
	v_lshl_add_u64 v[186:187], v[220:221], 0, s[34:35]
	s_mov_b32 m0, s76
	s_nop 0
	global_load_lds_dwordx4 v[186:187], off
	v_lshl_add_u64 v[186:187], v[220:221], 0, s[36:37]
	s_mov_b32 m0, s77
	s_nop 0
	global_load_lds_dwordx4 v[186:187], off
	s_waitcnt vmcnt(8)
	s_waitcnt lgkmcnt(0)
	s_barrier
	s_waitcnt lgkmcnt(0)
	v_mfma_f32_16x16x32_bf16 v[60:63], v[150:153], v[182:185], v[60:63]
	v_mfma_f32_16x16x32_bf16 v[52:55], v[158:161], v[182:185], v[52:55]
	v_mfma_f32_16x16x32_bf16 v[44:47], v[150:153], v[194:197], v[44:47]
	v_mfma_f32_16x16x32_bf16 v[36:39], v[158:161], v[194:197], v[36:39]
	v_mfma_f32_16x16x32_bf16 v[28:31], v[150:153], v[202:205], v[28:31]
	v_mfma_f32_16x16x32_bf16 v[20:23], v[158:161], v[202:205], v[20:23]
	v_mfma_f32_16x16x32_bf16 v[12:15], v[150:153], v[210:213], v[12:15]
	v_mfma_f32_16x16x32_bf16 v[4:7], v[158:161], v[210:213], v[4:7]
	v_mfma_f32_16x16x32_bf16 v[60:63], v[154:157], v[190:193], v[60:63]
	v_mfma_f32_16x16x32_bf16 v[52:55], v[162:165], v[190:193], v[52:55]
	v_mfma_f32_16x16x32_bf16 v[44:47], v[154:157], v[198:201], v[44:47]
	v_mfma_f32_16x16x32_bf16 v[36:39], v[162:165], v[198:201], v[36:39]
	v_mfma_f32_16x16x32_bf16 v[28:31], v[154:157], v[206:209], v[28:31]
	v_mfma_f32_16x16x32_bf16 v[20:23], v[162:165], v[206:209], v[20:23]
	v_mfma_f32_16x16x32_bf16 v[12:15], v[154:157], v[214:217], v[12:15]
	v_mfma_f32_16x16x32_bf16 v[4:7], v[162:165], v[214:217], v[4:7]
	v_mfma_f32_16x16x32_bf16 v[56:59], v[166:169], v[182:185], v[56:59]
	v_mfma_f32_16x16x32_bf16 v[48:51], v[174:177], v[182:185], v[48:51]
	v_mfma_f32_16x16x32_bf16 v[40:43], v[166:169], v[194:197], v[40:43]
	v_mfma_f32_16x16x32_bf16 v[32:35], v[174:177], v[194:197], v[32:35]
	v_mfma_f32_16x16x32_bf16 v[24:27], v[166:169], v[202:205], v[24:27]
	v_mfma_f32_16x16x32_bf16 v[16:19], v[174:177], v[202:205], v[16:19]
	v_mfma_f32_16x16x32_bf16 v[8:11], v[166:169], v[210:213], v[8:11]
	v_mfma_f32_16x16x32_bf16 v[0:3], v[174:177], v[210:213], v[0:3]
	v_mfma_f32_16x16x32_bf16 v[56:59], v[170:173], v[190:193], v[56:59]
	v_mfma_f32_16x16x32_bf16 v[48:51], v[178:181], v[190:193], v[48:51]
	v_mfma_f32_16x16x32_bf16 v[40:43], v[170:173], v[198:201], v[40:43]
	v_mfma_f32_16x16x32_bf16 v[32:35], v[178:181], v[198:201], v[32:35]
	v_mfma_f32_16x16x32_bf16 v[24:27], v[170:173], v[206:209], v[24:27]
	v_mfma_f32_16x16x32_bf16 v[16:19], v[178:181], v[206:209], v[16:19]
	v_mfma_f32_16x16x32_bf16 v[8:11], v[170:173], v[214:217], v[8:11]
	v_mfma_f32_16x16x32_bf16 v[0:3], v[178:181], v[214:217], v[0:3]
	s_barrier
	s_add_i32 s94, s94, 2
	s_add_u32 s70, s70, 0x10000
	s_addc_u32 s71, s71, 0
	s_add_u32 s72, s72, 0x10000
	s_addc_u32 s73, s73, 0
	s_cmp_gt_u32 s94, 13
	s_cbranch_scc0 .LBB0_141
	s_and_b64 vcc, exec, s[54:55]
	s_cbranch_vccz .LBB0_144
	s_barrier

; #define PG8_STAGE(bufoff, gbase, voff) do { _Pragma("unroll") for (int _i = 0; _i < 2; ++_i) \
;         __builtin_amdgcn_global_load_lds((const unsigned*)((const char*)(gbase) + (voff)[_i]), (PG8_LAS unsigned*)(lds + (bufoff) + ldsw + _i * 8192), 16, 0, 0); } while (0)
; #define PG8_LDA(dst, b, h) do { _Pragma("unroll") for (int m = 0; m < 4; ++m) _Pragma("unroll") for (int k = 0; k < 2; ++k) dst[m][k] = *(const PG8_LAS bf16x8*)(lds + PG8_SA(b, h) + aoff + m * 2048 + k * 1024); } while (0)
; #define PG8_LDB(dst, b, h) do { _Pragma("unroll") for (int n = 0; n < 2; ++n) _Pragma("unroll") for (int k = 0; k < 2; ++k) dst[n][k] = *(const PG8_LAS bf16x8*)(lds + PG8_SB(b, h) + boff + n * 2048 + k * 1024); } while (0)
; #define PG8_MMA(ai, bj, At, Bt) do { __builtin_amdgcn_s_setprio(1); _Pragma("unroll") for (int m = 0; m < 4; ++m) _Pragma("unroll") for (int n = 0; n < 2; ++n) _Pragma("unroll") for (int k = 0; k < 2; ++k) \
;         acc[ai][bj][m][n] = __builtin_amdgcn_mfma_f32_16x16x32_bf16(Bt[n][k], At[m][k], acc[ai][bj][m][n], 0, 0, 0); __builtin_amdgcn_s_setprio(0); } while (0)
; #define PG8_WAIT_V(n) asm volatile("s_waitcnt vmcnt(" #n ")" ::: "memory")
; #define PG8_WAIT_L(n) asm volatile("s_waitcnt lgkmcnt(" #n ")" ::: "memory")
; #define PG8_BAR __builtin_amdgcn_s_barrier()
; template <class Epi, class Sched, bool ALIGN_EPI = false, bool SP2 = false>
; __device__ __forceinline__ void gemm_phase(PG8_LAS unsigned char* lds, const Gemm g, const Sched& S, const Epi& E) {
;     ...
;             const char* a1 = cA + (size_t)(t + 1) * kstepA;
;             const char* a2 = last ? nA : cA + (size_t)(t + 2) * kstepA; const char* b2 = last ? nB : cB + (size_t)(t + 2) * kstep;
;             const char* a3 = a2 + kstepA; const char* b3 = b2 + kstep;
;             if (last && has_next) S.a_ready(nxt);
;             if constexpr (SP2) {
;             PG8_LDB(B0, 0, 0); PG8_LDB(B1, 0, 1); PG8_SCHED; PG8_LDA(At, 0, 0); PG8_STAGE(PG8_SA(1, 1), a1 + hstepA, voffA);
;             PG8_WAIT_V(8); PG8_WAIT_L(0); PG8_BAR; PG8_MMA(0, 0, At, B0); PG8_MMA(0, 1, At, B1); PG8_BAR; PG8_SCHED;
;             PG8_LDA(At, 0, 1); PG8_STAGE(PG8_SB(0, 0), b2, voffB); PG8_STAGE(PG8_SB(0, 1), b2 + hstepB, voffB); PG8_STAGE(PG8_SA(0, 0), a2, voffA);
;             PG8_WAIT_V(8); PG8_WAIT_L(0); PG8_BAR; PG8_MMA(1, 0, At, B0); PG8_MMA(1, 1, At, B1); PG8_BAR; PG8_SCHED;
.LBB0_225:
	s_add_u32 s68, s68, 0x10000
	s_addc_u32 s69, s69, 0
	s_add_u32 s70, s70, 0x10000
	s_addc_u32 s71, s71, 0
	s_mov_b32 s73, -2
	s_waitcnt lgkmcnt(0)
	ds_read_b128 v[112:115], v210
	ds_read_b128 v[124:127], v210 offset:1024
	ds_read_b128 v[136:139], v210 offset:2048
	ds_read_b128 v[140:143], v210 offset:3072
	ds_read_b128 v[144:147], v211
	ds_read_b128 v[148:151], v211 offset:1024
	ds_read_b128 v[152:155], v211 offset:2048
	ds_read_b128 v[156:159], v211 offset:3072
	s_cmp_eq_u32 s73, 40
	s_cselect_b32 s9, s1, s69
	s_cselect_b32 s8, s0, s68
	s_cselect_b32 s75, s63, s71
	s_cselect_b32 s74, s62, s70
	v_lshl_add_u64 v[208:209], s[68:69], 0, v[184:185]
	v_lshl_add_u64 v[216:217], v[208:209], 0, s[96:97]
	s_add_i32 m0, s15, 0xc000
	ds_read_b128 v[160:163], v212
	ds_read_b128 v[164:167], v212 offset:1024
	ds_read_b128 v[168:171], v212 offset:2048
	ds_read_b128 v[172:175], v212 offset:3072
	ds_read_b128 v[176:179], v212 offset:4096
	ds_read_b128 v[180:183], v212 offset:5120
	ds_read_b128 v[220:223], v212 offset:6144
	ds_read_b128 v[224:227], v212 offset:7168
	global_load_lds_dwordx4 v[216:217], off
	v_lshl_add_u64 v[208:209], v[208:209], 0, s[60:61]
	s_add_i32 m0, s15, 0xe000
	s_nop 0
	global_load_lds_dwordx4 v[208:209], off
	s_waitcnt vmcnt(8)
	s_waitcnt lgkmcnt(0)
	s_barrier
	s_waitcnt lgkmcnt(0)
	v_mfma_f32_16x16x32_bf16 v[132:135], v[112:115], v[160:163], 0
	v_mfma_f32_16x16x32_bf16 v[128:131], v[136:139], v[160:163], 0
	v_mfma_f32_16x16x32_bf16 v[108:111], v[112:115], v[168:171], 0
	v_mfma_f32_16x16x32_bf16 v[104:107], v[136:139], v[168:171], 0
	v_mfma_f32_16x16x32_bf16 v[92:95], v[112:115], v[176:179], 0
	v_mfma_f32_16x16x32_bf16 v[88:91], v[136:139], v[176:179], 0
	v_mfma_f32_16x16x32_bf16 v[76:79], v[112:115], v[220:223], 0
	v_mfma_f32_16x16x32_bf16 v[72:75], v[136:139], v[220:223], 0
	v_mfma_f32_16x16x32_bf16 v[132:135], v[124:127], v[164:167], v[132:135]
	v_mfma_f32_16x16x32_bf16 v[128:131], v[140:143], v[164:167], v[128:131]
	v_mfma_f32_16x16x32_bf16 v[108:111], v[124:127], v[172:175], v[108:111]
	v_mfma_f32_16x16x32_bf16 v[104:107], v[140:143], v[172:175], v[104:107]
	v_mfma_f32_16x16x32_bf16 v[92:95], v[124:127], v[180:183], v[92:95]
	v_mfma_f32_16x16x32_bf16 v[88:91], v[140:143], v[180:183], v[88:91]
	v_mfma_f32_16x16x32_bf16 v[76:79], v[124:127], v[224:227], v[76:79]
	v_mfma_f32_16x16x32_bf16 v[72:75], v[140:143], v[224:227], v[72:75]
	v_mfma_f32_16x16x32_bf16 v[120:123], v[144:147], v[160:163], 0
	v_mfma_f32_16x16x32_bf16 v[116:119], v[152:155], v[160:163], 0
	v_mfma_f32_16x16x32_bf16 v[100:103], v[144:147], v[168:171], 0
	v_mfma_f32_16x16x32_bf16 v[96:99], v[152:155], v[168:171], 0
	v_mfma_f32_16x16x32_bf16 v[84:87], v[144:147], v[176:179], 0
	v_mfma_f32_16x16x32_bf16 v[80:83], v[152:155], v[176:179], 0
	v_mfma_f32_16x16x32_bf16 v[68:71], v[144:147], v[220:223], 0
	v_mfma_f32_16x16x32_bf16 v[64:67], v[152:155], v[220:223], 0
	v_mfma_f32_16x16x32_bf16 v[120:123], v[148:151], v[164:167], v[120:123]
	v_mfma_f32_16x16x32_bf16 v[116:119], v[156:159], v[164:167], v[116:119]
	v_mfma_f32_16x16x32_bf16 v[100:103], v[148:151], v[172:175], v[100:103]
	v_mfma_f32_16x16x32_bf16 v[96:99], v[156:159], v[172:175], v[96:99]
	v_mfma_f32_16x16x32_bf16 v[84:87], v[148:151], v[180:183], v[84:87]
	v_mfma_f32_16x16x32_bf16 v[80:83], v[156:159], v[180:183], v[80:83]
	v_mfma_f32_16x16x32_bf16 v[68:71], v[148:151], v[224:227], v[68:71]
	v_mfma_f32_16x16x32_bf16 v[64:67], v[156:159], v[224:227], v[64:67]
	s_barrier
	s_add_i32 s33, s89, s14
	v_lshl_add_u64 v[208:209], s[74:75], 0, v[184:185]
	s_mov_b32 m0, s33
	ds_read_b128 v[160:163], v212 offset:16384
	ds_read_b128 v[164:167], v212 offset:17408
	ds_read_b128 v[168:171], v212 offset:18432
	ds_read_b128 v[172:175], v212 offset:19456
	ds_read_b128 v[176:179], v212 offset:20480
	ds_read_b128 v[180:183], v212 offset:21504
	ds_read_b128 v[220:223], v212 offset:22528
	ds_read_b128 v[224:227], v212 offset:23552
	global_load_lds_dwordx4 v[208:209], off
	v_lshl_add_u64 v[216:217], v[208:209], 0, s[30:31]
	s_add_i32 m0, s33, 0x2000
	s_add_i32 s33, s90, s14
	global_load_lds_dwordx4 v[216:217], off
	v_lshl_add_u64 v[216:217], v[208:209], 0, s[34:35]
	s_mov_b32 m0, s33
	s_nop 0
	global_load_lds_dwordx4 v[216:217], off
	v_lshl_add_u64 v[216:217], v[208:209], 0, s[36:37]
	s_add_i32 m0, s33, 0x2000
	s_nop 0
	global_load_lds_dwordx4 v[216:217], off
	v_lshl_add_u64 v[216:217], s[8:9], 0, v[184:185]
	s_mov_b32 m0, s15
	v_lshl_add_u64 v[228:229], v[216:217], 0, s[30:31]
	global_load_lds_dwordx4 v[216:217], off
	s_mov_b32 m0, s17
	s_nop 0
	global_load_lds_dwordx4 v[228:229], off
	s_waitcnt vmcnt(8)
	s_waitcnt lgkmcnt(0)
	s_barrier
; #define PG8_STAGE(bufoff, gbase, voff) do { _Pragma("unroll") for (int _i = 0; _i < 2; ++_i) \
;         __builtin_amdgcn_global_load_lds((const unsigned*)((const char*)(gbase) + (voff)[_i]), (PG8_LAS unsigned*)(lds + (bufoff) + ldsw + _i * 8192), 16, 0, 0); } while (0)
; #define PG8_LDA(dst, b, h) do { _Pragma("unroll") for (int m = 0; m < 4; ++m) _Pragma("unroll") for (int k = 0; k < 2; ++k) dst[m][k] = *(const PG8_LAS bf16x8*)(lds + PG8_SA(b, h) + aoff + m * 2048 + k * 1024); } while (0)
; #define PG8_LDB(dst, b, h) do { _Pragma("unroll") for (int n = 0; n < 2; ++n) _Pragma("unroll") for (int k = 0; k < 2; ++k) dst[n][k] = *(const PG8_LAS bf16x8*)(lds + PG8_SB(b, h) + boff + n * 2048 + k * 1024); } while (0)
; #define PG8_MMA(ai, bj, At, Bt) do { __builtin_amdgcn_s_setprio(1); _Pragma("unroll") for (int m = 0; m < 4; ++m) _Pragma("unroll") for (int n = 0; n < 2; ++n) _Pragma("unroll") for (int k = 0; k < 2; ++k) \
;         acc[ai][bj][m][n] = __builtin_amdgcn_mfma_f32_16x16x32_bf16(Bt[n][k], At[m][k], acc[ai][bj][m][n], 0, 0, 0); __builtin_amdgcn_s_setprio(0); } while (0)
; #define PG8_WAIT_V(n) asm volatile("s_waitcnt vmcnt(" #n ")" ::: "memory")
; #define PG8_WAIT_L(n) asm volatile("s_waitcnt lgkmcnt(" #n ")" ::: "memory")
; #define PG8_BAR __builtin_amdgcn_s_barrier()
; #define PG8_SCHED __builtin_amdgcn_sched_barrier(0)
; template <class Epi, class Sched, bool ALIGN_EPI = false, bool SP2 = false>
; __device__ __forceinline__ void gemm_phase(PG8_LAS unsigned char* lds, const Gemm g, const Sched& S, const Epi& E) {
;     ...
;             PG8_WAIT_V(8); PG8_WAIT_L(0); PG8_BAR; PG8_MMA(1, 0, At, B0); PG8_MMA(1, 1, At, B1); PG8_BAR; PG8_SCHED;
;             PG8_LDB(B0, 1, 0); PG8_LDB(B1, 1, 1); PG8_SCHED; PG8_LDA(At, 1, 0); PG8_STAGE(PG8_SA(0, 1), a2 + hstepA, voffA);
;             PG8_WAIT_V(8); PG8_WAIT_L(0); PG8_BAR; PG8_MMA(0, 0, At, B0); PG8_MMA(0, 1, At, B1); PG8_BAR; PG8_SCHED;
	s_waitcnt lgkmcnt(0)
	v_mfma_f32_16x16x32_bf16 v[60:63], v[112:115], v[160:163], 0
	v_mfma_f32_16x16x32_bf16 v[56:59], v[136:139], v[160:163], 0
	v_mfma_f32_16x16x32_bf16 v[44:47], v[112:115], v[168:171], 0
	v_mfma_f32_16x16x32_bf16 v[40:43], v[136:139], v[168:171], 0
	v_mfma_f32_16x16x32_bf16 v[28:31], v[112:115], v[176:179], 0
	v_mfma_f32_16x16x32_bf16 v[24:27], v[136:139], v[176:179], 0
	v_mfma_f32_16x16x32_bf16 v[12:15], v[112:115], v[220:223], 0
	v_mfma_f32_16x16x32_bf16 v[8:11], v[136:139], v[220:223], 0
	v_mfma_f32_16x16x32_bf16 v[60:63], v[124:127], v[164:167], v[60:63]
	v_mfma_f32_16x16x32_bf16 v[56:59], v[140:143], v[164:167], v[56:59]
	v_mfma_f32_16x16x32_bf16 v[44:47], v[124:127], v[172:175], v[44:47]
	v_mfma_f32_16x16x32_bf16 v[40:43], v[140:143], v[172:175], v[40:43]
	v_mfma_f32_16x16x32_bf16 v[28:31], v[124:127], v[180:183], v[28:31]
	v_mfma_f32_16x16x32_bf16 v[24:27], v[140:143], v[180:183], v[24:27]
	v_mfma_f32_16x16x32_bf16 v[12:15], v[124:127], v[224:227], v[12:15]
	v_mfma_f32_16x16x32_bf16 v[8:11], v[140:143], v[224:227], v[8:11]
	v_mfma_f32_16x16x32_bf16 v[52:55], v[144:147], v[160:163], 0
	v_mfma_f32_16x16x32_bf16 v[48:51], v[152:155], v[160:163], 0
	v_mfma_f32_16x16x32_bf16 v[36:39], v[144:147], v[168:171], 0
	v_mfma_f32_16x16x32_bf16 v[32:35], v[152:155], v[168:171], 0
	v_mfma_f32_16x16x32_bf16 v[20:23], v[144:147], v[176:179], 0
	v_mfma_f32_16x16x32_bf16 v[16:19], v[152:155], v[176:179], 0
	v_mfma_f32_16x16x32_bf16 v[4:7], v[144:147], v[220:223], 0
	v_mfma_f32_16x16x32_bf16 v[0:3], v[152:155], v[220:223], 0
	v_mfma_f32_16x16x32_bf16 v[52:55], v[148:151], v[164:167], v[52:55]
	v_mfma_f32_16x16x32_bf16 v[48:51], v[156:159], v[164:167], v[48:51]
	v_mfma_f32_16x16x32_bf16 v[36:39], v[148:151], v[172:175], v[36:39]
	v_mfma_f32_16x16x32_bf16 v[32:35], v[156:159], v[172:175], v[32:35]
	v_mfma_f32_16x16x32_bf16 v[20:23], v[148:151], v[180:183], v[20:23]
	v_mfma_f32_16x16x32_bf16 v[16:19], v[156:159], v[180:183], v[16:19]
	v_mfma_f32_16x16x32_bf16 v[4:7], v[148:151], v[224:227], v[4:7]
	v_mfma_f32_16x16x32_bf16 v[0:3], v[156:159], v[224:227], v[0:3]
	s_barrier
	ds_read_b128 v[112:115], v213
	ds_read_b128 v[124:127], v213 offset:1024
	ds_read_b128 v[136:139], v213 offset:2048
	ds_read_b128 v[140:143], v213 offset:3072
	ds_read_b128 v[144:147], v214
	ds_read_b128 v[148:151], v214 offset:1024
	ds_read_b128 v[152:155], v214 offset:2048
	ds_read_b128 v[156:159], v214 offset:3072
	s_mov_b32 m0, s18
	v_lshl_add_u64 v[228:229], v[216:217], 0, s[34:35]
	ds_read_b128 v[160:163], v212 offset:32768
	ds_read_b128 v[164:167], v212 offset:33792
	ds_read_b128 v[168:171], v212 offset:34816
	ds_read_b128 v[172:175], v212 offset:35840
	ds_read_b128 v[176:179], v212 offset:36864
	ds_read_b128 v[180:183], v212 offset:37888
	ds_read_b128 v[220:223], v212 offset:38912
	ds_read_b128 v[224:227], v212 offset:39936
	global_load_lds_dwordx4 v[228:229], off
	v_lshl_add_u64 v[228:229], v[216:217], 0, s[36:37]
	s_mov_b32 m0, s19
	s_nop 0
	global_load_lds_dwordx4 v[228:229], off
	s_waitcnt vmcnt(8)
	s_waitcnt lgkmcnt(0)
	s_barrier
	s_waitcnt lgkmcnt(0)
	v_mfma_f32_16x16x32_bf16 v[132:135], v[112:115], v[160:163], v[132:135]
	v_mfma_f32_16x16x32_bf16 v[128:131], v[136:139], v[160:163], v[128:131]
	v_mfma_f32_16x16x32_bf16 v[108:111], v[112:115], v[168:171], v[108:111]
	v_mfma_f32_16x16x32_bf16 v[104:107], v[136:139], v[168:171], v[104:107]
	v_mfma_f32_16x16x32_bf16 v[92:95], v[112:115], v[176:179], v[92:95]
	v_mfma_f32_16x16x32_bf16 v[88:91], v[136:139], v[176:179], v[88:91]
	v_mfma_f32_16x16x32_bf16 v[76:79], v[112:115], v[220:223], v[76:79]
	v_mfma_f32_16x16x32_bf16 v[72:75], v[136:139], v[220:223], v[72:75]
	v_mfma_f32_16x16x32_bf16 v[132:135], v[124:127], v[164:167], v[132:135]
	v_mfma_f32_16x16x32_bf16 v[128:131], v[140:143], v[164:167], v[128:131]
	v_mfma_f32_16x16x32_bf16 v[108:111], v[124:127], v[172:175], v[108:111]
	v_mfma_f32_16x16x32_bf16 v[104:107], v[140:143], v[172:175], v[104:107]
	v_mfma_f32_16x16x32_bf16 v[92:95], v[124:127], v[180:183], v[92:95]
	v_mfma_f32_16x16x32_bf16 v[88:91], v[140:143], v[180:183], v[88:91]
	v_mfma_f32_16x16x32_bf16 v[76:79], v[124:127], v[224:227], v[76:79]
	v_mfma_f32_16x16x32_bf16 v[72:75], v[140:143], v[224:227], v[72:75]
	v_mfma_f32_16x16x32_bf16 v[120:123], v[144:147], v[160:163], v[120:123]
	v_mfma_f32_16x16x32_bf16 v[116:119], v[152:155], v[160:163], v[116:119]
	v_mfma_f32_16x16x32_bf16 v[100:103], v[144:147], v[168:171], v[100:103]
	v_mfma_f32_16x16x32_bf16 v[96:99], v[152:155], v[168:171], v[96:99]
	v_mfma_f32_16x16x32_bf16 v[84:87], v[144:147], v[176:179], v[84:87]
	v_mfma_f32_16x16x32_bf16 v[80:83], v[152:155], v[176:179], v[80:83]
	v_mfma_f32_16x16x32_bf16 v[68:71], v[144:147], v[220:223], v[68:71]
	v_mfma_f32_16x16x32_bf16 v[64:67], v[152:155], v[220:223], v[64:67]
	v_mfma_f32_16x16x32_bf16 v[120:123], v[148:151], v[164:167], v[120:123]
	v_mfma_f32_16x16x32_bf16 v[116:119], v[156:159], v[164:167], v[116:119]
	v_mfma_f32_16x16x32_bf16 v[100:103], v[148:151], v[172:175], v[100:103]
	v_mfma_f32_16x16x32_bf16 v[96:99], v[156:159], v[172:175], v[96:99]
	v_mfma_f32_16x16x32_bf16 v[84:87], v[148:151], v[180:183], v[84:87]
	v_mfma_f32_16x16x32_bf16 v[80:83], v[156:159], v[180:183], v[80:83]
	v_mfma_f32_16x16x32_bf16 v[68:71], v[148:151], v[224:227], v[68:71]
	v_mfma_f32_16x16x32_bf16 v[64:67], v[156:159], v[224:227], v[64:67]
	s_barrier
; #define PG8_STAGE(bufoff, gbase, voff) do { _Pragma("unroll") for (int _i = 0; _i < 2; ++_i) \
;         __builtin_amdgcn_global_load_lds((const unsigned*)((const char*)(gbase) + (voff)[_i]), (PG8_LAS unsigned*)(lds + (bufoff) + ldsw + _i * 8192), 16, 0, 0); } while (0)
; #define PG8_LDA(dst, b, h) do { _Pragma("unroll") for (int m = 0; m < 4; ++m) _Pragma("unroll") for (int k = 0; k < 2; ++k) dst[m][k] = *(const PG8_LAS bf16x8*)(lds + PG8_SA(b, h) + aoff + m * 2048 + k * 1024); } while (0)
; #define PG8_LDB(dst, b, h) do { _Pragma("unroll") for (int n = 0; n < 2; ++n) _Pragma("unroll") for (int k = 0; k < 2; ++k) dst[n][k] = *(const PG8_LAS bf16x8*)(lds + PG8_SB(b, h) + boff + n * 2048 + k * 1024); } while (0)
; #define PG8_MMA(ai, bj, At, Bt) do { __builtin_amdgcn_s_setprio(1); _Pragma("unroll") for (int m = 0; m < 4; ++m) _Pragma("unroll") for (int n = 0; n < 2; ++n) _Pragma("unroll") for (int k = 0; k < 2; ++k) \
;         acc[ai][bj][m][n] = __builtin_amdgcn_mfma_f32_16x16x32_bf16(Bt[n][k], At[m][k], acc[ai][bj][m][n], 0, 0, 0); __builtin_amdgcn_s_setprio(0); } while (0)
; #define PG8_WAIT_V(n) asm volatile("s_waitcnt vmcnt(" #n ")" ::: "memory")
; #define PG8_WAIT_L(n) asm volatile("s_waitcnt lgkmcnt(" #n ")" ::: "memory")
; #define PG8_BAR __builtin_amdgcn_s_barrier()
; #define PG8_SCHED __builtin_amdgcn_sched_barrier(0)
; template <class Epi, class Sched, bool ALIGN_EPI = false, bool SP2 = false>
; __device__ __forceinline__ void gemm_phase(PG8_LAS unsigned char* lds, const Gemm g, const Sched& S, const Epi& E) {
;     ...
;             PG8_LDB(B0, 0, 0); PG8_LDB(B1, 0, 1); PG8_SCHED; PG8_LDA(At, 0, 0); PG8_STAGE(PG8_SA(1, 1), a1 + hstepA, voffA);
;             PG8_WAIT_V(8); PG8_WAIT_L(0); PG8_BAR; PG8_MMA(0, 0, At, B0); PG8_MMA(0, 1, At, B1); PG8_BAR; PG8_SCHED;
;     ...
;             PG8_LDA(At, 1, 1); PG8_STAGE(PG8_SB(1, 0), b3, voffB); PG8_STAGE(PG8_SB(1, 1), b3 + hstepB, voffB); PG8_STAGE(PG8_SA(1, 0), a3, voffA);
;             PG8_WAIT_V(8); PG8_WAIT_L(0); PG8_BAR; PG8_MMA(1, 0, At, B0); PG8_MMA(1, 1, At, B1); PG8_BAR; PG8_SCHED;
	s_add_i32 s8, s91, s14
	v_lshl_add_u64 v[228:229], v[208:209], 0, s[38:39]
	s_mov_b32 m0, s8
	ds_read_b128 v[160:163], v212 offset:49152
	ds_read_b128 v[164:167], v212 offset:50176
	ds_read_b128 v[168:171], v212 offset:51200
	ds_read_b128 v[172:175], v212 offset:52224
	ds_read_b128 v[176:179], v212 offset:53248
	ds_read_b128 v[180:183], v212 offset:54272
	ds_read_b128 v[220:223], v212 offset:55296
	ds_read_b128 v[224:227], v212 offset:56320
	global_load_lds_dwordx4 v[228:229], off
	v_lshl_add_u64 v[228:229], v[208:209], 0, s[40:41]
	s_add_i32 m0, s8, 0x2000
	s_add_i32 s8, s92, s14
	global_load_lds_dwordx4 v[228:229], off
	v_lshl_add_u64 v[228:229], v[208:209], 0, s[52:53]
	s_mov_b32 m0, s8
	v_lshl_add_u64 v[208:209], v[208:209], 0, s[54:55]
	global_load_lds_dwordx4 v[228:229], off
	s_add_i32 m0, s8, 0x2000
	s_nop 0
	global_load_lds_dwordx4 v[208:209], off
	v_lshl_add_u64 v[208:209], v[216:217], 0, s[38:39]
	s_mov_b32 m0, s78
	s_nop 0
	global_load_lds_dwordx4 v[208:209], off
	v_lshl_add_u64 v[208:209], v[216:217], 0, s[40:41]
	s_mov_b32 m0, s79
	s_nop 0
	global_load_lds_dwordx4 v[208:209], off
	s_waitcnt vmcnt(8)
	s_waitcnt lgkmcnt(0)
	s_barrier
	s_waitcnt lgkmcnt(0)
	v_mfma_f32_16x16x32_bf16 v[60:63], v[112:115], v[160:163], v[60:63]
	v_mfma_f32_16x16x32_bf16 v[56:59], v[136:139], v[160:163], v[56:59]
	v_mfma_f32_16x16x32_bf16 v[44:47], v[112:115], v[168:171], v[44:47]
	v_mfma_f32_16x16x32_bf16 v[40:43], v[136:139], v[168:171], v[40:43]
	v_mfma_f32_16x16x32_bf16 v[28:31], v[112:115], v[176:179], v[28:31]
	v_mfma_f32_16x16x32_bf16 v[24:27], v[136:139], v[176:179], v[24:27]
	v_mfma_f32_16x16x32_bf16 v[12:15], v[112:115], v[220:223], v[12:15]
	v_mfma_f32_16x16x32_bf16 v[8:11], v[136:139], v[220:223], v[8:11]
	v_mfma_f32_16x16x32_bf16 v[60:63], v[124:127], v[164:167], v[60:63]
	v_mfma_f32_16x16x32_bf16 v[56:59], v[140:143], v[164:167], v[56:59]
	v_mfma_f32_16x16x32_bf16 v[44:47], v[124:127], v[172:175], v[44:47]
	v_mfma_f32_16x16x32_bf16 v[40:43], v[140:143], v[172:175], v[40:43]
	v_mfma_f32_16x16x32_bf16 v[28:31], v[124:127], v[180:183], v[28:31]
	v_mfma_f32_16x16x32_bf16 v[24:27], v[140:143], v[180:183], v[24:27]
	v_mfma_f32_16x16x32_bf16 v[12:15], v[124:127], v[224:227], v[12:15]
	v_mfma_f32_16x16x32_bf16 v[8:11], v[140:143], v[224:227], v[8:11]
	v_mfma_f32_16x16x32_bf16 v[52:55], v[144:147], v[160:163], v[52:55]
	v_mfma_f32_16x16x32_bf16 v[48:51], v[152:155], v[160:163], v[48:51]
	v_mfma_f32_16x16x32_bf16 v[36:39], v[144:147], v[168:171], v[36:39]
	v_mfma_f32_16x16x32_bf16 v[32:35], v[152:155], v[168:171], v[32:35]
	v_mfma_f32_16x16x32_bf16 v[20:23], v[144:147], v[176:179], v[20:23]
	v_mfma_f32_16x16x32_bf16 v[16:19], v[152:155], v[176:179], v[16:19]
	v_mfma_f32_16x16x32_bf16 v[4:7], v[144:147], v[220:223], v[4:7]
	v_mfma_f32_16x16x32_bf16 v[0:3], v[152:155], v[220:223], v[0:3]
	v_mfma_f32_16x16x32_bf16 v[52:55], v[148:151], v[164:167], v[52:55]
	v_mfma_f32_16x16x32_bf16 v[48:51], v[156:159], v[164:167], v[48:51]
	v_mfma_f32_16x16x32_bf16 v[36:39], v[148:151], v[172:175], v[36:39]
	v_mfma_f32_16x16x32_bf16 v[32:35], v[156:159], v[172:175], v[32:35]
	v_mfma_f32_16x16x32_bf16 v[20:23], v[148:151], v[180:183], v[20:23]
	v_mfma_f32_16x16x32_bf16 v[16:19], v[156:159], v[180:183], v[16:19]
	v_mfma_f32_16x16x32_bf16 v[4:7], v[148:151], v[224:227], v[4:7]
	v_mfma_f32_16x16x32_bf16 v[0:3], v[156:159], v[224:227], v[0:3]
	s_barrier
	s_add_i32 s73, s73, 2
	s_add_u32 s68, s68, 0x10000
	s_addc_u32 s69, s69, 0
	s_add_u32 s70, s70, 0x10000
	s_addc_u32 s71, s71, 0
	s_cmp_gt_u32 s73, 41
.LBB0_226:
	ds_read_b128 v[112:115], v210
	ds_read_b128 v[124:127], v210 offset:1024
	ds_read_b128 v[136:139], v210 offset:2048
	ds_read_b128 v[140:143], v210 offset:3072
	ds_read_b128 v[144:147], v211
	ds_read_b128 v[148:151], v211 offset:1024
	ds_read_b128 v[152:155], v211 offset:2048
	ds_read_b128 v[156:159], v211 offset:3072
	s_cmp_eq_u32 s73, 40
	s_cselect_b32 s9, s1, s69
	s_cselect_b32 s8, s0, s68
	s_cselect_b32 s75, s63, s71
	s_cselect_b32 s74, s62, s70
	v_lshl_add_u64 v[208:209], s[68:69], 0, v[184:185]
	v_lshl_add_u64 v[216:217], v[208:209], 0, s[96:97]
	s_add_i32 m0, s15, 0xc000
	ds_read_b128 v[160:163], v212
	ds_read_b128 v[164:167], v212 offset:1024
	ds_read_b128 v[168:171], v212 offset:2048
	ds_read_b128 v[172:175], v212 offset:3072
	ds_read_b128 v[176:179], v212 offset:4096
	ds_read_b128 v[180:183], v212 offset:5120
	ds_read_b128 v[220:223], v212 offset:6144
	ds_read_b128 v[224:227], v212 offset:7168
	global_load_lds_dwordx4 v[216:217], off
	v_lshl_add_u64 v[208:209], v[208:209], 0, s[60:61]
	s_add_i32 m0, s15, 0xe000
	s_nop 0
	global_load_lds_dwordx4 v[208:209], off
	s_waitcnt vmcnt(8)
	s_waitcnt lgkmcnt(0)
	s_barrier
; #define PG8_STAGE(bufoff, gbase, voff) do { _Pragma("unroll") for (int _i = 0; _i < 2; ++_i) \
;         __builtin_amdgcn_global_load_lds((const unsigned*)((const char*)(gbase) + (voff)[_i]), (PG8_LAS unsigned*)(lds + (bufoff) + ldsw + _i * 8192), 16, 0, 0); } while (0)
; #define PG8_LDA(dst, b, h) do { _Pragma("unroll") for (int m = 0; m < 4; ++m) _Pragma("unroll") for (int k = 0; k < 2; ++k) dst[m][k] = *(const PG8_LAS bf16x8*)(lds + PG8_SA(b, h) + aoff + m * 2048 + k * 1024); } while (0)
; #define PG8_MMA(ai, bj, At, Bt) do { __builtin_amdgcn_s_setprio(1); _Pragma("unroll") for (int m = 0; m < 4; ++m) _Pragma("unroll") for (int n = 0; n < 2; ++n) _Pragma("unroll") for (int k = 0; k < 2; ++k) \
;         acc[ai][bj][m][n] = __builtin_amdgcn_mfma_f32_16x16x32_bf16(Bt[n][k], At[m][k], acc[ai][bj][m][n], 0, 0, 0); __builtin_amdgcn_s_setprio(0); } while (0)
; #define PG8_WAIT_V(n) asm volatile("s_waitcnt vmcnt(" #n ")" ::: "memory")
; #define PG8_WAIT_L(n) asm volatile("s_waitcnt lgkmcnt(" #n ")" ::: "memory")
; #define PG8_BAR __builtin_amdgcn_s_barrier()
; #define PG8_SCHED __builtin_amdgcn_sched_barrier(0)
; template <class Epi, class Sched, bool ALIGN_EPI = false, bool SP2 = false>
; __device__ __forceinline__ void gemm_phase(PG8_LAS unsigned char* lds, const Gemm g, const Sched& S, const Epi& E) {
;     ...
;             PG8_WAIT_V(8); PG8_WAIT_L(0); PG8_BAR; PG8_MMA(0, 0, At, B0); PG8_MMA(0, 1, At, B1); PG8_BAR; PG8_SCHED;
;             PG8_LDA(At, 0, 1); PG8_STAGE(PG8_SB(0, 0), b2, voffB); PG8_STAGE(PG8_SB(0, 1), b2 + hstepB, voffB); PG8_STAGE(PG8_SA(0, 0), a2, voffA);
;             PG8_WAIT_V(8); PG8_WAIT_L(0); PG8_BAR; PG8_MMA(1, 0, At, B0); PG8_MMA(1, 1, At, B1); PG8_BAR; PG8_SCHED;
	s_waitcnt lgkmcnt(0)
	v_mfma_f32_16x16x32_bf16 v[132:135], v[112:115], v[160:163], v[132:135]
	v_mfma_f32_16x16x32_bf16 v[128:131], v[136:139], v[160:163], v[128:131]
	v_mfma_f32_16x16x32_bf16 v[108:111], v[112:115], v[168:171], v[108:111]
	v_mfma_f32_16x16x32_bf16 v[104:107], v[136:139], v[168:171], v[104:107]
	v_mfma_f32_16x16x32_bf16 v[92:95], v[112:115], v[176:179], v[92:95]
	v_mfma_f32_16x16x32_bf16 v[88:91], v[136:139], v[176:179], v[88:91]
	v_mfma_f32_16x16x32_bf16 v[76:79], v[112:115], v[220:223], v[76:79]
	v_mfma_f32_16x16x32_bf16 v[72:75], v[136:139], v[220:223], v[72:75]
	v_mfma_f32_16x16x32_bf16 v[132:135], v[124:127], v[164:167], v[132:135]
	v_mfma_f32_16x16x32_bf16 v[128:131], v[140:143], v[164:167], v[128:131]
	v_mfma_f32_16x16x32_bf16 v[108:111], v[124:127], v[172:175], v[108:111]
	v_mfma_f32_16x16x32_bf16 v[104:107], v[140:143], v[172:175], v[104:107]
	v_mfma_f32_16x16x32_bf16 v[92:95], v[124:127], v[180:183], v[92:95]
	v_mfma_f32_16x16x32_bf16 v[88:91], v[140:143], v[180:183], v[88:91]
	v_mfma_f32_16x16x32_bf16 v[76:79], v[124:127], v[224:227], v[76:79]
	v_mfma_f32_16x16x32_bf16 v[72:75], v[140:143], v[224:227], v[72:75]
	v_mfma_f32_16x16x32_bf16 v[120:123], v[144:147], v[160:163], v[120:123]
	v_mfma_f32_16x16x32_bf16 v[116:119], v[152:155], v[160:163], v[116:119]
	v_mfma_f32_16x16x32_bf16 v[100:103], v[144:147], v[168:171], v[100:103]
	v_mfma_f32_16x16x32_bf16 v[96:99], v[152:155], v[168:171], v[96:99]
	v_mfma_f32_16x16x32_bf16 v[84:87], v[144:147], v[176:179], v[84:87]
	v_mfma_f32_16x16x32_bf16 v[80:83], v[152:155], v[176:179], v[80:83]
	v_mfma_f32_16x16x32_bf16 v[68:71], v[144:147], v[220:223], v[68:71]
	v_mfma_f32_16x16x32_bf16 v[64:67], v[152:155], v[220:223], v[64:67]
	v_mfma_f32_16x16x32_bf16 v[120:123], v[148:151], v[164:167], v[120:123]
	v_mfma_f32_16x16x32_bf16 v[116:119], v[156:159], v[164:167], v[116:119]
	v_mfma_f32_16x16x32_bf16 v[100:103], v[148:151], v[172:175], v[100:103]
	v_mfma_f32_16x16x32_bf16 v[96:99], v[156:159], v[172:175], v[96:99]
	v_mfma_f32_16x16x32_bf16 v[84:87], v[148:151], v[180:183], v[84:87]
	v_mfma_f32_16x16x32_bf16 v[80:83], v[156:159], v[180:183], v[80:83]
	v_mfma_f32_16x16x32_bf16 v[68:71], v[148:151], v[224:227], v[68:71]
	v_mfma_f32_16x16x32_bf16 v[64:67], v[156:159], v[224:227], v[64:67]
	s_barrier
	s_add_i32 s33, s89, s14
	v_lshl_add_u64 v[208:209], s[74:75], 0, v[184:185]
	s_mov_b32 m0, s33
	ds_read_b128 v[160:163], v212 offset:16384
	ds_read_b128 v[164:167], v212 offset:17408
	ds_read_b128 v[168:171], v212 offset:18432
	ds_read_b128 v[172:175], v212 offset:19456
	ds_read_b128 v[176:179], v212 offset:20480
	ds_read_b128 v[180:183], v212 offset:21504
	ds_read_b128 v[220:223], v212 offset:22528
	ds_read_b128 v[224:227], v212 offset:23552
	global_load_lds_dwordx4 v[208:209], off
	v_lshl_add_u64 v[216:217], v[208:209], 0, s[30:31]
	s_add_i32 m0, s33, 0x2000
	s_add_i32 s33, s90, s14
	global_load_lds_dwordx4 v[216:217], off
	v_lshl_add_u64 v[216:217], v[208:209], 0, s[34:35]
	s_mov_b32 m0, s33
	s_nop 0
	global_load_lds_dwordx4 v[216:217], off
	v_lshl_add_u64 v[216:217], v[208:209], 0, s[36:37]
	s_add_i32 m0, s33, 0x2000
	s_nop 0
	global_load_lds_dwordx4 v[216:217], off
	v_lshl_add_u64 v[216:217], s[8:9], 0, v[184:185]
	s_mov_b32 m0, s15
	v_lshl_add_u64 v[228:229], v[216:217], 0, s[30:31]
	global_load_lds_dwordx4 v[216:217], off
	s_mov_b32 m0, s17
	s_nop 0
	global_load_lds_dwordx4 v[228:229], off
	s_waitcnt vmcnt(8)
	s_waitcnt lgkmcnt(0)
	s_barrier
	s_waitcnt lgkmcnt(0)
	v_mfma_f32_16x16x32_bf16 v[60:63], v[112:115], v[160:163], v[60:63]
	v_mfma_f32_16x16x32_bf16 v[56:59], v[136:139], v[160:163], v[56:59]
	v_mfma_f32_16x16x32_bf16 v[44:47], v[112:115], v[168:171], v[44:47]
	v_mfma_f32_16x16x32_bf16 v[40:43], v[136:139], v[168:171], v[40:43]
	v_mfma_f32_16x16x32_bf16 v[28:31], v[112:115], v[176:179], v[28:31]
	v_mfma_f32_16x16x32_bf16 v[24:27], v[136:139], v[176:179], v[24:27]
	v_mfma_f32_16x16x32_bf16 v[12:15], v[112:115], v[220:223], v[12:15]
	v_mfma_f32_16x16x32_bf16 v[8:11], v[136:139], v[220:223], v[8:11]
	v_mfma_f32_16x16x32_bf16 v[60:63], v[124:127], v[164:167], v[60:63]
	v_mfma_f32_16x16x32_bf16 v[56:59], v[140:143], v[164:167], v[56:59]
	v_mfma_f32_16x16x32_bf16 v[44:47], v[124:127], v[172:175], v[44:47]
	v_mfma_f32_16x16x32_bf16 v[40:43], v[140:143], v[172:175], v[40:43]
	v_mfma_f32_16x16x32_bf16 v[28:31], v[124:127], v[180:183], v[28:31]
	v_mfma_f32_16x16x32_bf16 v[24:27], v[140:143], v[180:183], v[24:27]
	v_mfma_f32_16x16x32_bf16 v[12:15], v[124:127], v[224:227], v[12:15]
	v_mfma_f32_16x16x32_bf16 v[8:11], v[140:143], v[224:227], v[8:11]
	v_mfma_f32_16x16x32_bf16 v[52:55], v[144:147], v[160:163], v[52:55]
	v_mfma_f32_16x16x32_bf16 v[48:51], v[152:155], v[160:163], v[48:51]
	v_mfma_f32_16x16x32_bf16 v[36:39], v[144:147], v[168:171], v[36:39]
	v_mfma_f32_16x16x32_bf16 v[32:35], v[152:155], v[168:171], v[32:35]
	v_mfma_f32_16x16x32_bf16 v[20:23], v[144:147], v[176:179], v[20:23]
	v_mfma_f32_16x16x32_bf16 v[16:19], v[152:155], v[176:179], v[16:19]
	v_mfma_f32_16x16x32_bf16 v[4:7], v[144:147], v[220:223], v[4:7]
	v_mfma_f32_16x16x32_bf16 v[0:3], v[152:155], v[220:223], v[0:3]
	v_mfma_f32_16x16x32_bf16 v[52:55], v[148:151], v[164:167], v[52:55]
	v_mfma_f32_16x16x32_bf16 v[48:51], v[156:159], v[164:167], v[48:51]
	v_mfma_f32_16x16x32_bf16 v[36:39], v[148:151], v[172:175], v[36:39]
	v_mfma_f32_16x16x32_bf16 v[32:35], v[156:159], v[172:175], v[32:35]
	v_mfma_f32_16x16x32_bf16 v[20:23], v[148:151], v[180:183], v[20:23]
	v_mfma_f32_16x16x32_bf16 v[16:19], v[156:159], v[180:183], v[16:19]
	v_mfma_f32_16x16x32_bf16 v[4:7], v[148:151], v[224:227], v[4:7]
	v_mfma_f32_16x16x32_bf16 v[0:3], v[156:159], v[224:227], v[0:3]
	s_barrier
; #define PG8_STAGE(bufoff, gbase, voff) do { _Pragma("unroll") for (int _i = 0; _i < 2; ++_i) \
;         __builtin_amdgcn_global_load_lds((const unsigned*)((const char*)(gbase) + (voff)[_i]), (PG8_LAS unsigned*)(lds + (bufoff) + ldsw + _i * 8192), 16, 0, 0); } while (0)
; #define PG8_LDA(dst, b, h) do { _Pragma("unroll") for (int m = 0; m < 4; ++m) _Pragma("unroll") for (int k = 0; k < 2; ++k) dst[m][k] = *(const PG8_LAS bf16x8*)(lds + PG8_SA(b, h) + aoff + m * 2048 + k * 1024); } while (0)
; #define PG8_LDB(dst, b, h) do { _Pragma("unroll") for (int n = 0; n < 2; ++n) _Pragma("unroll") for (int k = 0; k < 2; ++k) dst[n][k] = *(const PG8_LAS bf16x8*)(lds + PG8_SB(b, h) + boff + n * 2048 + k * 1024); } while (0)
; #define PG8_MMA(ai, bj, At, Bt) do { __builtin_amdgcn_s_setprio(1); _Pragma("unroll") for (int m = 0; m < 4; ++m) _Pragma("unroll") for (int n = 0; n < 2; ++n) _Pragma("unroll") for (int k = 0; k < 2; ++k) \
;         acc[ai][bj][m][n] = __builtin_amdgcn_mfma_f32_16x16x32_bf16(Bt[n][k], At[m][k], acc[ai][bj][m][n], 0, 0, 0); __builtin_amdgcn_s_setprio(0); } while (0)
; #define PG8_WAIT_V(n) asm volatile("s_waitcnt vmcnt(" #n ")" ::: "memory")
; #define PG8_WAIT_L(n) asm volatile("s_waitcnt lgkmcnt(" #n ")" ::: "memory")
; #define PG8_BAR __builtin_amdgcn_s_barrier()
; #define PG8_SCHED __builtin_amdgcn_sched_barrier(0)
; template <class Epi, class Sched, bool ALIGN_EPI = false, bool SP2 = false>
; __device__ __forceinline__ void gemm_phase(PG8_LAS unsigned char* lds, const Gemm g, const Sched& S, const Epi& E) {
;     ...
;             PG8_LDB(B0, 1, 0); PG8_LDB(B1, 1, 1); PG8_SCHED; PG8_LDA(At, 1, 0); PG8_STAGE(PG8_SA(0, 1), a2 + hstepA, voffA);
;             PG8_WAIT_V(8); PG8_WAIT_L(0); PG8_BAR; PG8_MMA(0, 0, At, B0); PG8_MMA(0, 1, At, B1); PG8_BAR; PG8_SCHED;
;             PG8_LDA(At, 1, 1); PG8_STAGE(PG8_SB(1, 0), b3, voffB); PG8_STAGE(PG8_SB(1, 1), b3 + hstepB, voffB); PG8_STAGE(PG8_SA(1, 0), a3, voffA);
;             PG8_WAIT_V(8); PG8_WAIT_L(0); PG8_BAR; PG8_MMA(1, 0, At, B0); PG8_MMA(1, 1, At, B1); PG8_BAR; PG8_SCHED;
	ds_read_b128 v[112:115], v213
	ds_read_b128 v[124:127], v213 offset:1024
	ds_read_b128 v[136:139], v213 offset:2048
	ds_read_b128 v[140:143], v213 offset:3072
	ds_read_b128 v[144:147], v214
	ds_read_b128 v[148:151], v214 offset:1024
	ds_read_b128 v[152:155], v214 offset:2048
	ds_read_b128 v[156:159], v214 offset:3072
	s_mov_b32 m0, s18
	v_lshl_add_u64 v[228:229], v[216:217], 0, s[34:35]
	ds_read_b128 v[160:163], v212 offset:32768
	ds_read_b128 v[164:167], v212 offset:33792
	ds_read_b128 v[168:171], v212 offset:34816
	ds_read_b128 v[172:175], v212 offset:35840
	ds_read_b128 v[176:179], v212 offset:36864
	ds_read_b128 v[180:183], v212 offset:37888
	ds_read_b128 v[220:223], v212 offset:38912
	ds_read_b128 v[224:227], v212 offset:39936
	global_load_lds_dwordx4 v[228:229], off
	v_lshl_add_u64 v[228:229], v[216:217], 0, s[36:37]
	s_mov_b32 m0, s19
	s_nop 0
	global_load_lds_dwordx4 v[228:229], off
	s_waitcnt vmcnt(8)
	s_waitcnt lgkmcnt(0)
	s_barrier
	s_waitcnt lgkmcnt(0)
	v_mfma_f32_16x16x32_bf16 v[132:135], v[112:115], v[160:163], v[132:135]
	v_mfma_f32_16x16x32_bf16 v[128:131], v[136:139], v[160:163], v[128:131]
	v_mfma_f32_16x16x32_bf16 v[108:111], v[112:115], v[168:171], v[108:111]
	v_mfma_f32_16x16x32_bf16 v[104:107], v[136:139], v[168:171], v[104:107]
	v_mfma_f32_16x16x32_bf16 v[92:95], v[112:115], v[176:179], v[92:95]
	v_mfma_f32_16x16x32_bf16 v[88:91], v[136:139], v[176:179], v[88:91]
	v_mfma_f32_16x16x32_bf16 v[76:79], v[112:115], v[220:223], v[76:79]
	v_mfma_f32_16x16x32_bf16 v[72:75], v[136:139], v[220:223], v[72:75]
	v_mfma_f32_16x16x32_bf16 v[132:135], v[124:127], v[164:167], v[132:135]
	v_mfma_f32_16x16x32_bf16 v[128:131], v[140:143], v[164:167], v[128:131]
	v_mfma_f32_16x16x32_bf16 v[108:111], v[124:127], v[172:175], v[108:111]
	v_mfma_f32_16x16x32_bf16 v[104:107], v[140:143], v[172:175], v[104:107]
	v_mfma_f32_16x16x32_bf16 v[92:95], v[124:127], v[180:183], v[92:95]
	v_mfma_f32_16x16x32_bf16 v[88:91], v[140:143], v[180:183], v[88:91]
	v_mfma_f32_16x16x32_bf16 v[76:79], v[124:127], v[224:227], v[76:79]
	v_mfma_f32_16x16x32_bf16 v[72:75], v[140:143], v[224:227], v[72:75]
	v_mfma_f32_16x16x32_bf16 v[120:123], v[144:147], v[160:163], v[120:123]
	v_mfma_f32_16x16x32_bf16 v[116:119], v[152:155], v[160:163], v[116:119]
	v_mfma_f32_16x16x32_bf16 v[100:103], v[144:147], v[168:171], v[100:103]
	v_mfma_f32_16x16x32_bf16 v[96:99], v[152:155], v[168:171], v[96:99]
	v_mfma_f32_16x16x32_bf16 v[84:87], v[144:147], v[176:179], v[84:87]
	v_mfma_f32_16x16x32_bf16 v[80:83], v[152:155], v[176:179], v[80:83]
	v_mfma_f32_16x16x32_bf16 v[68:71], v[144:147], v[220:223], v[68:71]
	v_mfma_f32_16x16x32_bf16 v[64:67], v[152:155], v[220:223], v[64:67]
	v_mfma_f32_16x16x32_bf16 v[120:123], v[148:151], v[164:167], v[120:123]
	v_mfma_f32_16x16x32_bf16 v[116:119], v[156:159], v[164:167], v[116:119]
	v_mfma_f32_16x16x32_bf16 v[100:103], v[148:151], v[172:175], v[100:103]
	v_mfma_f32_16x16x32_bf16 v[96:99], v[156:159], v[172:175], v[96:99]
	v_mfma_f32_16x16x32_bf16 v[84:87], v[148:151], v[180:183], v[84:87]
	v_mfma_f32_16x16x32_bf16 v[80:83], v[156:159], v[180:183], v[80:83]
	v_mfma_f32_16x16x32_bf16 v[68:71], v[148:151], v[224:227], v[68:71]
	v_mfma_f32_16x16x32_bf16 v[64:67], v[156:159], v[224:227], v[64:67]
	s_barrier
	s_add_i32 s8, s91, s14
	v_lshl_add_u64 v[228:229], v[208:209], 0, s[38:39]
	s_mov_b32 m0, s8
	ds_read_b128 v[160:163], v212 offset:49152
	ds_read_b128 v[164:167], v212 offset:50176
	ds_read_b128 v[168:171], v212 offset:51200
	ds_read_b128 v[172:175], v212 offset:52224
	ds_read_b128 v[176:179], v212 offset:53248
	ds_read_b128 v[180:183], v212 offset:54272
	ds_read_b128 v[220:223], v212 offset:55296
	ds_read_b128 v[224:227], v212 offset:56320
	global_load_lds_dwordx4 v[228:229], off
	v_lshl_add_u64 v[228:229], v[208:209], 0, s[40:41]
	s_add_i32 m0, s8, 0x2000
	s_add_i32 s8, s92, s14
	global_load_lds_dwordx4 v[228:229], off
	v_lshl_add_u64 v[228:229], v[208:209], 0, s[52:53]
	s_mov_b32 m0, s8
	v_lshl_add_u64 v[208:209], v[208:209], 0, s[54:55]
	global_load_lds_dwordx4 v[228:229], off
	s_add_i32 m0, s8, 0x2000
	s_nop 0
	global_load_lds_dwordx4 v[208:209], off
	v_lshl_add_u64 v[208:209], v[216:217], 0, s[38:39]
	s_mov_b32 m0, s78
	s_nop 0
	global_load_lds_dwordx4 v[208:209], off
	v_lshl_add_u64 v[208:209], v[216:217], 0, s[40:41]
	s_mov_b32 m0, s79
	s_nop 0
	global_load_lds_dwordx4 v[208:209], off
	s_waitcnt vmcnt(8)
	s_waitcnt lgkmcnt(0)
	s_barrier
	s_waitcnt lgkmcnt(0)
	v_mfma_f32_16x16x32_bf16 v[60:63], v[112:115], v[160:163], v[60:63]
	v_mfma_f32_16x16x32_bf16 v[56:59], v[136:139], v[160:163], v[56:59]
	v_mfma_f32_16x16x32_bf16 v[44:47], v[112:115], v[168:171], v[44:47]
	v_mfma_f32_16x16x32_bf16 v[40:43], v[136:139], v[168:171], v[40:43]
	v_mfma_f32_16x16x32_bf16 v[28:31], v[112:115], v[176:179], v[28:31]
	v_mfma_f32_16x16x32_bf16 v[24:27], v[136:139], v[176:179], v[24:27]
	v_mfma_f32_16x16x32_bf16 v[12:15], v[112:115], v[220:223], v[12:15]
	v_mfma_f32_16x16x32_bf16 v[8:11], v[136:139], v[220:223], v[8:11]
	v_mfma_f32_16x16x32_bf16 v[60:63], v[124:127], v[164:167], v[60:63]
	v_mfma_f32_16x16x32_bf16 v[56:59], v[140:143], v[164:167], v[56:59]
	v_mfma_f32_16x16x32_bf16 v[44:47], v[124:127], v[172:175], v[44:47]
	v_mfma_f32_16x16x32_bf16 v[40:43], v[140:143], v[172:175], v[40:43]
	v_mfma_f32_16x16x32_bf16 v[28:31], v[124:127], v[180:183], v[28:31]
	v_mfma_f32_16x16x32_bf16 v[24:27], v[140:143], v[180:183], v[24:27]
	v_mfma_f32_16x16x32_bf16 v[12:15], v[124:127], v[224:227], v[12:15]
	v_mfma_f32_16x16x32_bf16 v[8:11], v[140:143], v[224:227], v[8:11]
	v_mfma_f32_16x16x32_bf16 v[52:55], v[144:147], v[160:163], v[52:55]
	v_mfma_f32_16x16x32_bf16 v[48:51], v[152:155], v[160:163], v[48:51]
	v_mfma_f32_16x16x32_bf16 v[36:39], v[144:147], v[168:171], v[36:39]
	v_mfma_f32_16x16x32_bf16 v[32:35], v[152:155], v[168:171], v[32:35]
	v_mfma_f32_16x16x32_bf16 v[20:23], v[144:147], v[176:179], v[20:23]
	v_mfma_f32_16x16x32_bf16 v[16:19], v[152:155], v[176:179], v[16:19]
	v_mfma_f32_16x16x32_bf16 v[4:7], v[144:147], v[220:223], v[4:7]
	v_mfma_f32_16x16x32_bf16 v[0:3], v[152:155], v[220:223], v[0:3]
	v_mfma_f32_16x16x32_bf16 v[52:55], v[148:151], v[164:167], v[52:55]
	v_mfma_f32_16x16x32_bf16 v[48:51], v[156:159], v[164:167], v[48:51]
	v_mfma_f32_16x16x32_bf16 v[36:39], v[148:151], v[172:175], v[36:39]
	v_mfma_f32_16x16x32_bf16 v[32:35], v[156:159], v[172:175], v[32:35]
	v_mfma_f32_16x16x32_bf16 v[20:23], v[148:151], v[180:183], v[20:23]
	v_mfma_f32_16x16x32_bf16 v[16:19], v[156:159], v[180:183], v[16:19]
	v_mfma_f32_16x16x32_bf16 v[4:7], v[148:151], v[224:227], v[4:7]
	v_mfma_f32_16x16x32_bf16 v[0:3], v[156:159], v[224:227], v[0:3]
	s_barrier
	s_add_i32 s73, s73, 2
	s_add_u32 s68, s68, 0x10000
	s_addc_u32 s69, s69, 0
	s_add_u32 s70, s70, 0x10000
	s_addc_u32 s71, s71, 0
	s_cmp_gt_u32 s73, 41
	s_cbranch_scc0 .LBB0_226
	s_and_b64 vcc, exec, s[58:59]
	s_cbranch_vccz .LBB0_229
	s_barrier

; #define PG8_STAGE(bufoff, gbase, voff) do { _Pragma("unroll") for (int _i = 0; _i < 2; ++_i) \
;         __builtin_amdgcn_global_load_lds((const unsigned*)((const char*)(gbase) + (voff)[_i]), (PG8_LAS unsigned*)(lds + (bufoff) + ldsw + _i * 8192), 16, 0, 0); } while (0)
; #define PG8_LDA(dst, b, h) do { _Pragma("unroll") for (int m = 0; m < 4; ++m) _Pragma("unroll") for (int k = 0; k < 2; ++k) dst[m][k] = *(const PG8_LAS bf16x8*)(lds + PG8_SA(b, h) + aoff + m * 2048 + k * 1024); } while (0)
; #define PG8_LDB(dst, b, h) do { _Pragma("unroll") for (int n = 0; n < 2; ++n) _Pragma("unroll") for (int k = 0; k < 2; ++k) dst[n][k] = *(const PG8_LAS bf16x8*)(lds + PG8_SB(b, h) + boff + n * 2048 + k * 1024); } while (0)
; #define PG8_MMA(ai, bj, At, Bt) do { __builtin_amdgcn_s_setprio(1); _Pragma("unroll") for (int m = 0; m < 4; ++m) _Pragma("unroll") for (int n = 0; n < 2; ++n) _Pragma("unroll") for (int k = 0; k < 2; ++k) \
;         acc[ai][bj][m][n] = __builtin_amdgcn_mfma_f32_16x16x32_bf16(Bt[n][k], At[m][k], acc[ai][bj][m][n], 0, 0, 0); __builtin_amdgcn_s_setprio(0); } while (0)
; #define PG8_BAR __builtin_amdgcn_s_barrier()
; template <class Epi, class Sched, bool ALIGN_EPI = false, bool SP2 = false>
; __device__ __forceinline__ void gemm_phase(PG8_LAS unsigned char* lds, const Gemm g, const Sched& S, const Epi& E) {
;     ...
;         const bool has_next = S.next(ui + 1, nxt);
;         const char* nA = has_next ? (const char*)g.A + (size_t)nxt.pm * tstepA : cA; const char* nB = has_next ? (const char*)g.Bt + (size_t)nxt.pn * tstepB : cB;
;         for (int t = 0; t < nt; t += 2) {
;             const bool last = (t == nt - 2);
;             const char* a1 = cA + (size_t)(t + 1) * kstepA;
;             const char* a2 = last ? nA : cA + (size_t)(t + 2) * kstepA; const char* b2 = last ? nB : cB + (size_t)(t + 2) * kstep;
;             const char* a3 = a2 + kstepA; const char* b3 = b2 + kstep;
;             if (last && has_next) S.a_ready(nxt);
;             if constexpr (SP2) {
;             PG8_LDB(B0, 0, 0); PG8_LDB(B1, 0, 1); PG8_SCHED; PG8_LDA(At, 0, 0); PG8_STAGE(PG8_SA(1, 1), a1 + hstepA, voffA);
;             PG8_WAIT_V(8); PG8_WAIT_L(0); PG8_BAR; PG8_MMA(0, 0, At, B0); PG8_MMA(0, 1, At, B1); PG8_BAR; PG8_SCHED;
;             PG8_LDA(At, 0, 1); PG8_STAGE(PG8_SB(0, 0), b2, voffB); PG8_STAGE(PG8_SB(0, 1), b2 + hstepB, voffB); PG8_STAGE(PG8_SA(0, 0), a2, voffA);
.LBB0_314:
	s_ashr_i32 s63, s62, 31
	s_lshl_b64 s[8:9], s[62:63], 19
	s_add_u32 s68, s12, s8
	s_addc_u32 s69, s13, s9
	s_and_b64 s[8:9], s[2:3], exec
	s_cselect_b32 s7, s69, s5
	s_cselect_b32 s63, s68, s4
	s_ashr_i32 s61, s60, 31
	s_lshl_b64 s[8:9], s[60:61], 19
	s_add_u32 s70, s87, s8
	s_addc_u32 s71, s88, s9
	s_and_b64 s[8:9], s[2:3], exec
	s_cselect_b32 s61, s71, s75
	s_cselect_b32 s73, s70, s74
	s_add_u32 s4, s4, 0x10000
	s_addc_u32 s5, s5, 0
	s_add_u32 s74, s74, 0x10000
	s_addc_u32 s75, s75, 0
	s_mov_b32 s76, -2
	ds_read_b128 v[140:143], v159
	ds_read_b128 v[144:147], v159 offset:1024
	ds_read_b128 v[148:151], v159 offset:2048
	ds_read_b128 v[166:169], v159 offset:3072
	ds_read_b128 v[170:173], v160
	ds_read_b128 v[174:177], v160 offset:1024
	ds_read_b128 v[178:181], v160 offset:2048
	ds_read_b128 v[182:185], v160 offset:3072
	s_cmp_eq_u32 s76, 12
	s_cselect_b32 s9, s7, s5
	s_cselect_b32 s8, s63, s4
	s_cselect_b32 vcc_hi, s61, s75
	s_cselect_b32 vcc_lo, s73, s74
	s_movk_i32 s78, 0xc000
	v_lshl_add_u64 v[2:3], s[4:5], 0, v[132:133]
	s_mov_b32 s79, -1
	v_lshl_add_u64 v[152:153], v[2:3], 0, s[78:79]
	s_movk_i32 s78, 0xe000
	s_add_i32 m0, s90, 0xc000
	s_mov_b32 s79, -1
	ds_read_b128 v[190:193], v161
	ds_read_b128 v[194:197], v161 offset:1024
	ds_read_b128 v[198:201], v161 offset:2048
	ds_read_b128 v[202:205], v161 offset:3072
	ds_read_b128 v[206:209], v161 offset:4096
	ds_read_b128 v[210:213], v161 offset:5120
	ds_read_b128 v[214:217], v161 offset:6144
	ds_read_b128 v[220:223], v161 offset:7168
	global_load_lds_dwordx4 v[152:153], off
	v_lshl_add_u64 v[2:3], v[2:3], 0, s[78:79]
	s_add_i32 m0, s90, 0xe000
	s_nop 0
	global_load_lds_dwordx4 v[2:3], off
	s_waitcnt vmcnt(8)
	s_waitcnt lgkmcnt(0)
	s_barrier
	s_waitcnt lgkmcnt(0)
	v_mfma_f32_16x16x32_bf16 v[128:131], v[140:143], v[190:193], 0
	v_mfma_f32_16x16x32_bf16 v[124:127], v[148:151], v[190:193], 0
	v_mfma_f32_16x16x32_bf16 v[112:115], v[140:143], v[198:201], 0
	v_mfma_f32_16x16x32_bf16 v[108:111], v[148:151], v[198:201], 0
	v_mfma_f32_16x16x32_bf16 v[96:99], v[140:143], v[206:209], 0
	v_mfma_f32_16x16x32_bf16 v[92:95], v[148:151], v[206:209], 0
	v_mfma_f32_16x16x32_bf16 v[80:83], v[140:143], v[214:217], 0
	v_mfma_f32_16x16x32_bf16 v[76:79], v[148:151], v[214:217], 0
	v_mfma_f32_16x16x32_bf16 v[128:131], v[144:147], v[194:197], v[128:131]
	v_mfma_f32_16x16x32_bf16 v[124:127], v[166:169], v[194:197], v[124:127]
	v_mfma_f32_16x16x32_bf16 v[112:115], v[144:147], v[202:205], v[112:115]
	v_mfma_f32_16x16x32_bf16 v[108:111], v[166:169], v[202:205], v[108:111]
	v_mfma_f32_16x16x32_bf16 v[96:99], v[144:147], v[210:213], v[96:99]
	v_mfma_f32_16x16x32_bf16 v[92:95], v[166:169], v[210:213], v[92:95]
	v_mfma_f32_16x16x32_bf16 v[80:83], v[144:147], v[220:223], v[80:83]
	v_mfma_f32_16x16x32_bf16 v[76:79], v[166:169], v[220:223], v[76:79]
	v_mfma_f32_16x16x32_bf16 v[120:123], v[170:173], v[190:193], 0
	v_mfma_f32_16x16x32_bf16 v[116:119], v[178:181], v[190:193], 0
	v_mfma_f32_16x16x32_bf16 v[104:107], v[170:173], v[198:201], 0
	v_mfma_f32_16x16x32_bf16 v[100:103], v[178:181], v[198:201], 0
	v_mfma_f32_16x16x32_bf16 v[88:91], v[170:173], v[206:209], 0
	v_mfma_f32_16x16x32_bf16 v[84:87], v[178:181], v[206:209], 0
	v_mfma_f32_16x16x32_bf16 v[72:75], v[170:173], v[214:217], 0
	v_mfma_f32_16x16x32_bf16 v[68:71], v[178:181], v[214:217], 0
	v_mfma_f32_16x16x32_bf16 v[120:123], v[174:177], v[194:197], v[120:123]
	v_mfma_f32_16x16x32_bf16 v[116:119], v[182:185], v[194:197], v[116:119]
	v_mfma_f32_16x16x32_bf16 v[104:107], v[174:177], v[202:205], v[104:107]
	v_mfma_f32_16x16x32_bf16 v[100:103], v[182:185], v[202:205], v[100:103]
	v_mfma_f32_16x16x32_bf16 v[88:91], v[174:177], v[210:213], v[88:91]
	v_mfma_f32_16x16x32_bf16 v[84:87], v[182:185], v[210:213], v[84:87]
	v_mfma_f32_16x16x32_bf16 v[72:75], v[174:177], v[220:223], v[72:75]
	v_mfma_f32_16x16x32_bf16 v[68:71], v[182:185], v[220:223], v[68:71]
	s_barrier
	s_add_i32 s77, s15, s89
	v_lshl_add_u64 v[152:153], vcc, 0, v[132:133]
	s_mov_b32 m0, s77
	ds_read_b128 v[190:193], v161 offset:16384
	ds_read_b128 v[194:197], v161 offset:17408
	ds_read_b128 v[198:201], v161 offset:18432
	ds_read_b128 v[202:205], v161 offset:19456
	ds_read_b128 v[206:209], v161 offset:20480
	ds_read_b128 v[210:213], v161 offset:21504
	ds_read_b128 v[214:217], v161 offset:22528
	ds_read_b128 v[220:223], v161 offset:23552
	global_load_lds_dwordx4 v[152:153], off
	v_lshl_add_u64 v[2:3], v[152:153], 0, s[30:31]
	s_add_i32 m0, s77, 0x2000
	s_add_i32 s77, s18, s89
	global_load_lds_dwordx4 v[2:3], off
	v_lshl_add_u64 v[2:3], v[152:153], 0, s[34:35]
	s_mov_b32 m0, s77
	v_lshl_add_u64 v[186:187], s[8:9], 0, v[132:133]
	global_load_lds_dwordx4 v[2:3], off
	v_lshl_add_u64 v[2:3], v[152:153], 0, s[36:37]
	s_add_i32 m0, s77, 0x2000
	s_nop 0
	global_load_lds_dwordx4 v[2:3], off
	s_mov_b32 m0, s90
	v_lshl_add_u64 v[2:3], v[186:187], 0, s[30:31]
	global_load_lds_dwordx4 v[186:187], off
	s_mov_b32 m0, s91
	s_nop 0
	global_load_lds_dwordx4 v[2:3], off
	s_waitcnt vmcnt(8)
	s_waitcnt lgkmcnt(0)
	s_barrier
; #define PG8_STAGE(bufoff, gbase, voff) do { _Pragma("unroll") for (int _i = 0; _i < 2; ++_i) \
;         __builtin_amdgcn_global_load_lds((const unsigned*)((const char*)(gbase) + (voff)[_i]), (PG8_LAS unsigned*)(lds + (bufoff) + ldsw + _i * 8192), 16, 0, 0); } while (0)
; #define PG8_LDA(dst, b, h) do { _Pragma("unroll") for (int m = 0; m < 4; ++m) _Pragma("unroll") for (int k = 0; k < 2; ++k) dst[m][k] = *(const PG8_LAS bf16x8*)(lds + PG8_SA(b, h) + aoff + m * 2048 + k * 1024); } while (0)
; #define PG8_LDB(dst, b, h) do { _Pragma("unroll") for (int n = 0; n < 2; ++n) _Pragma("unroll") for (int k = 0; k < 2; ++k) dst[n][k] = *(const PG8_LAS bf16x8*)(lds + PG8_SB(b, h) + boff + n * 2048 + k * 1024); } while (0)
; #define PG8_MMA(ai, bj, At, Bt) do { __builtin_amdgcn_s_setprio(1); _Pragma("unroll") for (int m = 0; m < 4; ++m) _Pragma("unroll") for (int n = 0; n < 2; ++n) _Pragma("unroll") for (int k = 0; k < 2; ++k) \
;         acc[ai][bj][m][n] = __builtin_amdgcn_mfma_f32_16x16x32_bf16(Bt[n][k], At[m][k], acc[ai][bj][m][n], 0, 0, 0); __builtin_amdgcn_s_setprio(0); } while (0)
; #define PG8_WAIT_V(n) asm volatile("s_waitcnt vmcnt(" #n ")" ::: "memory")
; #define PG8_WAIT_L(n) asm volatile("s_waitcnt lgkmcnt(" #n ")" ::: "memory")
; #define PG8_BAR __builtin_amdgcn_s_barrier()
; #define PG8_SCHED __builtin_amdgcn_sched_barrier(0)
; template <class Epi, class Sched, bool ALIGN_EPI = false, bool SP2 = false>
; __device__ __forceinline__ void gemm_phase(PG8_LAS unsigned char* lds, const Gemm g, const Sched& S, const Epi& E) {
;     ...
;             PG8_WAIT_V(8); PG8_WAIT_L(0); PG8_BAR; PG8_MMA(1, 0, At, B0); PG8_MMA(1, 1, At, B1); PG8_BAR; PG8_SCHED;
;             PG8_LDB(B0, 1, 0); PG8_LDB(B1, 1, 1); PG8_SCHED; PG8_LDA(At, 1, 0); PG8_STAGE(PG8_SA(0, 1), a2 + hstepA, voffA);
;             PG8_WAIT_V(8); PG8_WAIT_L(0); PG8_BAR; PG8_MMA(0, 0, At, B0); PG8_MMA(0, 1, At, B1); PG8_BAR; PG8_SCHED;
	s_waitcnt lgkmcnt(0)
	v_mfma_f32_16x16x32_bf16 v[64:67], v[140:143], v[190:193], 0
	v_mfma_f32_16x16x32_bf16 v[60:63], v[148:151], v[190:193], 0
	v_mfma_f32_16x16x32_bf16 v[48:51], v[140:143], v[198:201], 0
	v_mfma_f32_16x16x32_bf16 v[44:47], v[148:151], v[198:201], 0
	v_mfma_f32_16x16x32_bf16 v[32:35], v[140:143], v[206:209], 0
	v_mfma_f32_16x16x32_bf16 v[28:31], v[148:151], v[206:209], 0
	v_mfma_f32_16x16x32_bf16 v[16:19], v[140:143], v[214:217], 0
	v_mfma_f32_16x16x32_bf16 v[12:15], v[148:151], v[214:217], 0
	v_mfma_f32_16x16x32_bf16 v[64:67], v[144:147], v[194:197], v[64:67]
	v_mfma_f32_16x16x32_bf16 v[60:63], v[166:169], v[194:197], v[60:63]
	v_mfma_f32_16x16x32_bf16 v[48:51], v[144:147], v[202:205], v[48:51]
	v_mfma_f32_16x16x32_bf16 v[44:47], v[166:169], v[202:205], v[44:47]
	v_mfma_f32_16x16x32_bf16 v[32:35], v[144:147], v[210:213], v[32:35]
	v_mfma_f32_16x16x32_bf16 v[28:31], v[166:169], v[210:213], v[28:31]
	v_mfma_f32_16x16x32_bf16 v[16:19], v[144:147], v[220:223], v[16:19]
	v_mfma_f32_16x16x32_bf16 v[12:15], v[166:169], v[220:223], v[12:15]
	v_mfma_f32_16x16x32_bf16 v[56:59], v[170:173], v[190:193], 0
	v_mfma_f32_16x16x32_bf16 v[52:55], v[178:181], v[190:193], 0
	v_mfma_f32_16x16x32_bf16 v[40:43], v[170:173], v[198:201], 0
	v_mfma_f32_16x16x32_bf16 v[36:39], v[178:181], v[198:201], 0
	v_mfma_f32_16x16x32_bf16 v[24:27], v[170:173], v[206:209], 0
	v_mfma_f32_16x16x32_bf16 v[20:23], v[178:181], v[206:209], 0
	v_mfma_f32_16x16x32_bf16 v[8:11], v[170:173], v[214:217], 0
	v_mfma_f32_16x16x32_bf16 v[2:5], v[178:181], v[214:217], 0
	v_mfma_f32_16x16x32_bf16 v[56:59], v[174:177], v[194:197], v[56:59]
	v_mfma_f32_16x16x32_bf16 v[52:55], v[182:185], v[194:197], v[52:55]
	v_mfma_f32_16x16x32_bf16 v[40:43], v[174:177], v[202:205], v[40:43]
	v_mfma_f32_16x16x32_bf16 v[36:39], v[182:185], v[202:205], v[36:39]
	v_mfma_f32_16x16x32_bf16 v[24:27], v[174:177], v[210:213], v[24:27]
	v_mfma_f32_16x16x32_bf16 v[20:23], v[182:185], v[210:213], v[20:23]
	v_mfma_f32_16x16x32_bf16 v[8:11], v[174:177], v[220:223], v[8:11]
	v_mfma_f32_16x16x32_bf16 v[2:5], v[182:185], v[220:223], v[2:5]
	s_barrier
	ds_read_b128 v[140:143], v162
	ds_read_b128 v[144:147], v162 offset:1024
	ds_read_b128 v[148:151], v162 offset:2048
	ds_read_b128 v[166:169], v162 offset:3072
	ds_read_b128 v[170:173], v163
	ds_read_b128 v[174:177], v163 offset:1024
	ds_read_b128 v[178:181], v163 offset:2048
	ds_read_b128 v[182:185], v163 offset:3072
	s_mov_b32 m0, s92
	v_lshl_add_u64 v[6:7], v[186:187], 0, s[34:35]
	ds_read_b128 v[190:193], v161 offset:32768
	ds_read_b128 v[194:197], v161 offset:33792
	ds_read_b128 v[198:201], v161 offset:34816
	ds_read_b128 v[202:205], v161 offset:35840
	ds_read_b128 v[206:209], v161 offset:36864
	ds_read_b128 v[210:213], v161 offset:37888
	ds_read_b128 v[214:217], v161 offset:38912
	ds_read_b128 v[220:223], v161 offset:39936
	global_load_lds_dwordx4 v[6:7], off
	v_lshl_add_u64 v[6:7], v[186:187], 0, s[36:37]
	s_mov_b32 m0, s93
	s_nop 0
	global_load_lds_dwordx4 v[6:7], off
	s_waitcnt vmcnt(8)
	s_waitcnt lgkmcnt(0)
	s_barrier
	s_waitcnt lgkmcnt(0)
	v_mfma_f32_16x16x32_bf16 v[128:131], v[140:143], v[190:193], v[128:131]
	v_mfma_f32_16x16x32_bf16 v[124:127], v[148:151], v[190:193], v[124:127]
	v_mfma_f32_16x16x32_bf16 v[112:115], v[140:143], v[198:201], v[112:115]
	v_mfma_f32_16x16x32_bf16 v[108:111], v[148:151], v[198:201], v[108:111]
	v_mfma_f32_16x16x32_bf16 v[96:99], v[140:143], v[206:209], v[96:99]
	v_mfma_f32_16x16x32_bf16 v[92:95], v[148:151], v[206:209], v[92:95]
	v_mfma_f32_16x16x32_bf16 v[80:83], v[140:143], v[214:217], v[80:83]
	v_mfma_f32_16x16x32_bf16 v[76:79], v[148:151], v[214:217], v[76:79]
	v_mfma_f32_16x16x32_bf16 v[128:131], v[144:147], v[194:197], v[128:131]
	v_mfma_f32_16x16x32_bf16 v[124:127], v[166:169], v[194:197], v[124:127]
	v_mfma_f32_16x16x32_bf16 v[112:115], v[144:147], v[202:205], v[112:115]
	v_mfma_f32_16x16x32_bf16 v[108:111], v[166:169], v[202:205], v[108:111]
	v_mfma_f32_16x16x32_bf16 v[96:99], v[144:147], v[210:213], v[96:99]
	v_mfma_f32_16x16x32_bf16 v[92:95], v[166:169], v[210:213], v[92:95]
	v_mfma_f32_16x16x32_bf16 v[80:83], v[144:147], v[220:223], v[80:83]
	v_mfma_f32_16x16x32_bf16 v[76:79], v[166:169], v[220:223], v[76:79]
	v_mfma_f32_16x16x32_bf16 v[120:123], v[170:173], v[190:193], v[120:123]
	v_mfma_f32_16x16x32_bf16 v[116:119], v[178:181], v[190:193], v[116:119]
	v_mfma_f32_16x16x32_bf16 v[104:107], v[170:173], v[198:201], v[104:107]
	v_mfma_f32_16x16x32_bf16 v[100:103], v[178:181], v[198:201], v[100:103]
	v_mfma_f32_16x16x32_bf16 v[88:91], v[170:173], v[206:209], v[88:91]
	v_mfma_f32_16x16x32_bf16 v[84:87], v[178:181], v[206:209], v[84:87]
	v_mfma_f32_16x16x32_bf16 v[72:75], v[170:173], v[214:217], v[72:75]
	v_mfma_f32_16x16x32_bf16 v[68:71], v[178:181], v[214:217], v[68:71]
	v_mfma_f32_16x16x32_bf16 v[120:123], v[174:177], v[194:197], v[120:123]
	v_mfma_f32_16x16x32_bf16 v[116:119], v[182:185], v[194:197], v[116:119]
	v_mfma_f32_16x16x32_bf16 v[104:107], v[174:177], v[202:205], v[104:107]
	v_mfma_f32_16x16x32_bf16 v[100:103], v[182:185], v[202:205], v[100:103]
	v_mfma_f32_16x16x32_bf16 v[88:91], v[174:177], v[210:213], v[88:91]
	v_mfma_f32_16x16x32_bf16 v[84:87], v[182:185], v[210:213], v[84:87]
	v_mfma_f32_16x16x32_bf16 v[72:75], v[174:177], v[220:223], v[72:75]
	v_mfma_f32_16x16x32_bf16 v[68:71], v[182:185], v[220:223], v[68:71]
	s_barrier
; #define PG8_STAGE(bufoff, gbase, voff) do { _Pragma("unroll") for (int _i = 0; _i < 2; ++_i) \
;         __builtin_amdgcn_global_load_lds((const unsigned*)((const char*)(gbase) + (voff)[_i]), (PG8_LAS unsigned*)(lds + (bufoff) + ldsw + _i * 8192), 16, 0, 0); } while (0)
; #define PG8_LDA(dst, b, h) do { _Pragma("unroll") for (int m = 0; m < 4; ++m) _Pragma("unroll") for (int k = 0; k < 2; ++k) dst[m][k] = *(const PG8_LAS bf16x8*)(lds + PG8_SA(b, h) + aoff + m * 2048 + k * 1024); } while (0)
; #define PG8_LDB(dst, b, h) do { _Pragma("unroll") for (int n = 0; n < 2; ++n) _Pragma("unroll") for (int k = 0; k < 2; ++k) dst[n][k] = *(const PG8_LAS bf16x8*)(lds + PG8_SB(b, h) + boff + n * 2048 + k * 1024); } while (0)
; #define PG8_MMA(ai, bj, At, Bt) do { __builtin_amdgcn_s_setprio(1); _Pragma("unroll") for (int m = 0; m < 4; ++m) _Pragma("unroll") for (int n = 0; n < 2; ++n) _Pragma("unroll") for (int k = 0; k < 2; ++k) \
;         acc[ai][bj][m][n] = __builtin_amdgcn_mfma_f32_16x16x32_bf16(Bt[n][k], At[m][k], acc[ai][bj][m][n], 0, 0, 0); __builtin_amdgcn_s_setprio(0); } while (0)
; #define PG8_WAIT_V(n) asm volatile("s_waitcnt vmcnt(" #n ")" ::: "memory")
; #define PG8_WAIT_L(n) asm volatile("s_waitcnt lgkmcnt(" #n ")" ::: "memory")
; #define PG8_BAR __builtin_amdgcn_s_barrier()
; #define PG8_SCHED __builtin_amdgcn_sched_barrier(0)
; template <class Epi, class Sched, bool ALIGN_EPI = false, bool SP2 = false>
; __device__ __forceinline__ void gemm_phase(PG8_LAS unsigned char* lds, const Gemm g, const Sched& S, const Epi& E) {
;     ...
;             PG8_LDB(B0, 0, 0); PG8_LDB(B1, 0, 1); PG8_SCHED; PG8_LDA(At, 0, 0); PG8_STAGE(PG8_SA(1, 1), a1 + hstepA, voffA);
;     ...
;             PG8_LDA(At, 1, 1); PG8_STAGE(PG8_SB(1, 0), b3, voffB); PG8_STAGE(PG8_SB(1, 1), b3 + hstepB, voffB); PG8_STAGE(PG8_SA(1, 0), a3, voffA);
;             PG8_WAIT_V(8); PG8_WAIT_L(0); PG8_BAR; PG8_MMA(1, 0, At, B0); PG8_MMA(1, 1, At, B1); PG8_BAR; PG8_SCHED;
	s_add_i32 s8, s19, s89
	v_lshl_add_u64 v[6:7], v[152:153], 0, s[38:39]
	s_mov_b32 m0, s8
	ds_read_b128 v[190:193], v161 offset:49152
	ds_read_b128 v[194:197], v161 offset:50176
	ds_read_b128 v[198:201], v161 offset:51200
	ds_read_b128 v[202:205], v161 offset:52224
	ds_read_b128 v[206:209], v161 offset:53248
	ds_read_b128 v[210:213], v161 offset:54272
	ds_read_b128 v[214:217], v161 offset:55296
	ds_read_b128 v[220:223], v161 offset:56320
	global_load_lds_dwordx4 v[6:7], off
	v_lshl_add_u64 v[6:7], v[152:153], 0, s[40:41]
	s_add_i32 m0, s8, 0x2000
	s_add_i32 s8, s80, s89
	global_load_lds_dwordx4 v[6:7], off
	v_lshl_add_u64 v[6:7], v[152:153], 0, s[52:53]
	s_mov_b32 m0, s8
	s_nop 0
	global_load_lds_dwordx4 v[6:7], off
	v_lshl_add_u64 v[6:7], v[152:153], 0, s[54:55]
	s_add_i32 m0, s8, 0x2000
	s_nop 0
	global_load_lds_dwordx4 v[6:7], off
	v_lshl_add_u64 v[6:7], v[186:187], 0, s[38:39]
	s_mov_b32 m0, s94
	s_nop 0
	global_load_lds_dwordx4 v[6:7], off
	v_lshl_add_u64 v[6:7], v[186:187], 0, s[40:41]
	s_mov_b32 m0, s95
	s_nop 0
	global_load_lds_dwordx4 v[6:7], off
	s_waitcnt vmcnt(8)
	s_waitcnt lgkmcnt(0)
	s_barrier
	s_waitcnt lgkmcnt(0)
	v_mfma_f32_16x16x32_bf16 v[64:67], v[140:143], v[190:193], v[64:67]
	v_mfma_f32_16x16x32_bf16 v[60:63], v[148:151], v[190:193], v[60:63]
	v_mfma_f32_16x16x32_bf16 v[48:51], v[140:143], v[198:201], v[48:51]
	v_mfma_f32_16x16x32_bf16 v[44:47], v[148:151], v[198:201], v[44:47]
	v_mfma_f32_16x16x32_bf16 v[32:35], v[140:143], v[206:209], v[32:35]
	v_mfma_f32_16x16x32_bf16 v[28:31], v[148:151], v[206:209], v[28:31]
	v_mfma_f32_16x16x32_bf16 v[16:19], v[140:143], v[214:217], v[16:19]
	v_mfma_f32_16x16x32_bf16 v[12:15], v[148:151], v[214:217], v[12:15]
	v_mfma_f32_16x16x32_bf16 v[64:67], v[144:147], v[194:197], v[64:67]
	v_mfma_f32_16x16x32_bf16 v[60:63], v[166:169], v[194:197], v[60:63]
	v_mfma_f32_16x16x32_bf16 v[48:51], v[144:147], v[202:205], v[48:51]
	v_mfma_f32_16x16x32_bf16 v[44:47], v[166:169], v[202:205], v[44:47]
	v_mfma_f32_16x16x32_bf16 v[32:35], v[144:147], v[210:213], v[32:35]
	v_mfma_f32_16x16x32_bf16 v[28:31], v[166:169], v[210:213], v[28:31]
	v_mfma_f32_16x16x32_bf16 v[16:19], v[144:147], v[220:223], v[16:19]
	v_mfma_f32_16x16x32_bf16 v[12:15], v[166:169], v[220:223], v[12:15]
	v_mfma_f32_16x16x32_bf16 v[56:59], v[170:173], v[190:193], v[56:59]
	v_mfma_f32_16x16x32_bf16 v[52:55], v[178:181], v[190:193], v[52:55]
	v_mfma_f32_16x16x32_bf16 v[40:43], v[170:173], v[198:201], v[40:43]
	v_mfma_f32_16x16x32_bf16 v[36:39], v[178:181], v[198:201], v[36:39]
	v_mfma_f32_16x16x32_bf16 v[24:27], v[170:173], v[206:209], v[24:27]
	v_mfma_f32_16x16x32_bf16 v[20:23], v[178:181], v[206:209], v[20:23]
	v_mfma_f32_16x16x32_bf16 v[6:9], v[170:173], v[214:217], v[8:11]
	v_mfma_f32_16x16x32_bf16 v[2:5], v[178:181], v[214:217], v[2:5]
	v_mfma_f32_16x16x32_bf16 v[56:59], v[174:177], v[194:197], v[56:59]
	v_mfma_f32_16x16x32_bf16 v[52:55], v[182:185], v[194:197], v[52:55]
	v_mfma_f32_16x16x32_bf16 v[40:43], v[174:177], v[202:205], v[40:43]
	v_mfma_f32_16x16x32_bf16 v[36:39], v[182:185], v[202:205], v[36:39]
	v_mfma_f32_16x16x32_bf16 v[24:27], v[174:177], v[210:213], v[24:27]
	v_mfma_f32_16x16x32_bf16 v[20:23], v[182:185], v[210:213], v[20:23]
	v_mfma_f32_16x16x32_bf16 v[8:11], v[174:177], v[220:223], v[6:9]
	v_mfma_f32_16x16x32_bf16 v[4:7], v[182:185], v[220:223], v[2:5]
	s_barrier
	s_add_i32 s76, s76, 2
	s_add_u32 s4, s4, 0x10000
	s_addc_u32 s5, s5, 0
	s_add_u32 s74, s74, 0x10000
	s_addc_u32 s75, s75, 0
	s_cmp_gt_u32 s76, 13
.LBB0_315:
	ds_read_b128 v[140:143], v159
	ds_read_b128 v[144:147], v159 offset:1024
	ds_read_b128 v[148:151], v159 offset:2048
	ds_read_b128 v[166:169], v159 offset:3072
	ds_read_b128 v[170:173], v160
	ds_read_b128 v[174:177], v160 offset:1024
	ds_read_b128 v[178:181], v160 offset:2048
	ds_read_b128 v[182:185], v160 offset:3072
	s_cmp_eq_u32 s76, 12
	s_cselect_b32 s9, s7, s5
	s_cselect_b32 s8, s63, s4
	s_cselect_b32 vcc_hi, s61, s75
	s_cselect_b32 vcc_lo, s73, s74
	s_movk_i32 s78, 0xc000
	v_lshl_add_u64 v[2:3], s[4:5], 0, v[132:133]
	s_mov_b32 s79, -1
	v_lshl_add_u64 v[152:153], v[2:3], 0, s[78:79]
	s_movk_i32 s78, 0xe000
	s_add_i32 m0, s90, 0xc000
	s_mov_b32 s79, -1
	ds_read_b128 v[190:193], v161
	ds_read_b128 v[194:197], v161 offset:1024
	ds_read_b128 v[198:201], v161 offset:2048
	ds_read_b128 v[202:205], v161 offset:3072
	ds_read_b128 v[206:209], v161 offset:4096
	ds_read_b128 v[210:213], v161 offset:5120
	ds_read_b128 v[214:217], v161 offset:6144
	ds_read_b128 v[220:223], v161 offset:7168
	global_load_lds_dwordx4 v[152:153], off
	v_lshl_add_u64 v[2:3], v[2:3], 0, s[78:79]
	s_add_i32 m0, s90, 0xe000
	s_nop 0
	global_load_lds_dwordx4 v[2:3], off
	s_waitcnt vmcnt(8)
	s_waitcnt lgkmcnt(0)
	s_barrier
; #define PG8_STAGE(bufoff, gbase, voff) do { _Pragma("unroll") for (int _i = 0; _i < 2; ++_i) \
;         __builtin_amdgcn_global_load_lds((const unsigned*)((const char*)(gbase) + (voff)[_i]), (PG8_LAS unsigned*)(lds + (bufoff) + ldsw + _i * 8192), 16, 0, 0); } while (0)
; #define PG8_LDA(dst, b, h) do { _Pragma("unroll") for (int m = 0; m < 4; ++m) _Pragma("unroll") for (int k = 0; k < 2; ++k) dst[m][k] = *(const PG8_LAS bf16x8*)(lds + PG8_SA(b, h) + aoff + m * 2048 + k * 1024); } while (0)
; #define PG8_MMA(ai, bj, At, Bt) do { __builtin_amdgcn_s_setprio(1); _Pragma("unroll") for (int m = 0; m < 4; ++m) _Pragma("unroll") for (int n = 0; n < 2; ++n) _Pragma("unroll") for (int k = 0; k < 2; ++k) \
;         acc[ai][bj][m][n] = __builtin_amdgcn_mfma_f32_16x16x32_bf16(Bt[n][k], At[m][k], acc[ai][bj][m][n], 0, 0, 0); __builtin_amdgcn_s_setprio(0); } while (0)
; #define PG8_WAIT_V(n) asm volatile("s_waitcnt vmcnt(" #n ")" ::: "memory")
; #define PG8_WAIT_L(n) asm volatile("s_waitcnt lgkmcnt(" #n ")" ::: "memory")
; #define PG8_BAR __builtin_amdgcn_s_barrier()
; #define PG8_SCHED __builtin_amdgcn_sched_barrier(0)
; template <class Epi, class Sched, bool ALIGN_EPI = false, bool SP2 = false>
; __device__ __forceinline__ void gemm_phase(PG8_LAS unsigned char* lds, const Gemm g, const Sched& S, const Epi& E) {
;     ...
;             PG8_WAIT_V(8); PG8_WAIT_L(0); PG8_BAR; PG8_MMA(0, 0, At, B0); PG8_MMA(0, 1, At, B1); PG8_BAR; PG8_SCHED;
;             PG8_LDA(At, 0, 1); PG8_STAGE(PG8_SB(0, 0), b2, voffB); PG8_STAGE(PG8_SB(0, 1), b2 + hstepB, voffB); PG8_STAGE(PG8_SA(0, 0), a2, voffA);
;             PG8_WAIT_V(8); PG8_WAIT_L(0); PG8_BAR; PG8_MMA(1, 0, At, B0); PG8_MMA(1, 1, At, B1); PG8_BAR; PG8_SCHED;
	s_waitcnt lgkmcnt(0)
	v_mfma_f32_16x16x32_bf16 v[128:131], v[140:143], v[190:193], v[128:131]
	v_mfma_f32_16x16x32_bf16 v[124:127], v[148:151], v[190:193], v[124:127]
	v_mfma_f32_16x16x32_bf16 v[112:115], v[140:143], v[198:201], v[112:115]
	v_mfma_f32_16x16x32_bf16 v[108:111], v[148:151], v[198:201], v[108:111]
	v_mfma_f32_16x16x32_bf16 v[96:99], v[140:143], v[206:209], v[96:99]
	v_mfma_f32_16x16x32_bf16 v[92:95], v[148:151], v[206:209], v[92:95]
	v_mfma_f32_16x16x32_bf16 v[80:83], v[140:143], v[214:217], v[80:83]
	v_mfma_f32_16x16x32_bf16 v[76:79], v[148:151], v[214:217], v[76:79]
	v_mfma_f32_16x16x32_bf16 v[128:131], v[144:147], v[194:197], v[128:131]
	v_mfma_f32_16x16x32_bf16 v[124:127], v[166:169], v[194:197], v[124:127]
	v_mfma_f32_16x16x32_bf16 v[112:115], v[144:147], v[202:205], v[112:115]
	v_mfma_f32_16x16x32_bf16 v[108:111], v[166:169], v[202:205], v[108:111]
	v_mfma_f32_16x16x32_bf16 v[96:99], v[144:147], v[210:213], v[96:99]
	v_mfma_f32_16x16x32_bf16 v[92:95], v[166:169], v[210:213], v[92:95]
	v_mfma_f32_16x16x32_bf16 v[80:83], v[144:147], v[220:223], v[80:83]
	v_mfma_f32_16x16x32_bf16 v[76:79], v[166:169], v[220:223], v[76:79]
	v_mfma_f32_16x16x32_bf16 v[120:123], v[170:173], v[190:193], v[120:123]
	v_mfma_f32_16x16x32_bf16 v[116:119], v[178:181], v[190:193], v[116:119]
	v_mfma_f32_16x16x32_bf16 v[104:107], v[170:173], v[198:201], v[104:107]
	v_mfma_f32_16x16x32_bf16 v[100:103], v[178:181], v[198:201], v[100:103]
	v_mfma_f32_16x16x32_bf16 v[88:91], v[170:173], v[206:209], v[88:91]
	v_mfma_f32_16x16x32_bf16 v[84:87], v[178:181], v[206:209], v[84:87]
	v_mfma_f32_16x16x32_bf16 v[72:75], v[170:173], v[214:217], v[72:75]
	v_mfma_f32_16x16x32_bf16 v[68:71], v[178:181], v[214:217], v[68:71]
	v_mfma_f32_16x16x32_bf16 v[120:123], v[174:177], v[194:197], v[120:123]
	v_mfma_f32_16x16x32_bf16 v[116:119], v[182:185], v[194:197], v[116:119]
	v_mfma_f32_16x16x32_bf16 v[104:107], v[174:177], v[202:205], v[104:107]
	v_mfma_f32_16x16x32_bf16 v[100:103], v[182:185], v[202:205], v[100:103]
	v_mfma_f32_16x16x32_bf16 v[88:91], v[174:177], v[210:213], v[88:91]
	v_mfma_f32_16x16x32_bf16 v[84:87], v[182:185], v[210:213], v[84:87]
	v_mfma_f32_16x16x32_bf16 v[72:75], v[174:177], v[220:223], v[72:75]
	v_mfma_f32_16x16x32_bf16 v[68:71], v[182:185], v[220:223], v[68:71]
	s_barrier
	s_add_i32 s77, s15, s89
	v_lshl_add_u64 v[152:153], vcc, 0, v[132:133]
	s_mov_b32 m0, s77
	ds_read_b128 v[190:193], v161 offset:16384
	ds_read_b128 v[194:197], v161 offset:17408
	ds_read_b128 v[198:201], v161 offset:18432
	ds_read_b128 v[202:205], v161 offset:19456
	ds_read_b128 v[206:209], v161 offset:20480
	ds_read_b128 v[210:213], v161 offset:21504
	ds_read_b128 v[214:217], v161 offset:22528
	ds_read_b128 v[220:223], v161 offset:23552
	global_load_lds_dwordx4 v[152:153], off
	v_lshl_add_u64 v[2:3], v[152:153], 0, s[30:31]
	s_add_i32 m0, s77, 0x2000
	s_add_i32 s77, s18, s89
	global_load_lds_dwordx4 v[2:3], off
	v_lshl_add_u64 v[2:3], v[152:153], 0, s[34:35]
	s_mov_b32 m0, s77
	v_lshl_add_u64 v[186:187], s[8:9], 0, v[132:133]
	global_load_lds_dwordx4 v[2:3], off
	v_lshl_add_u64 v[2:3], v[152:153], 0, s[36:37]
	s_add_i32 m0, s77, 0x2000
	s_nop 0
	global_load_lds_dwordx4 v[2:3], off
	s_mov_b32 m0, s90
	v_lshl_add_u64 v[2:3], v[186:187], 0, s[30:31]
	global_load_lds_dwordx4 v[186:187], off
	s_mov_b32 m0, s91
	s_nop 0
	global_load_lds_dwordx4 v[2:3], off
	s_waitcnt vmcnt(8)
	s_waitcnt lgkmcnt(0)
	s_barrier
	s_waitcnt lgkmcnt(0)
	v_mfma_f32_16x16x32_bf16 v[64:67], v[140:143], v[190:193], v[64:67]
	v_mfma_f32_16x16x32_bf16 v[60:63], v[148:151], v[190:193], v[60:63]
	v_mfma_f32_16x16x32_bf16 v[48:51], v[140:143], v[198:201], v[48:51]
	v_mfma_f32_16x16x32_bf16 v[44:47], v[148:151], v[198:201], v[44:47]
	v_mfma_f32_16x16x32_bf16 v[32:35], v[140:143], v[206:209], v[32:35]
	v_mfma_f32_16x16x32_bf16 v[28:31], v[148:151], v[206:209], v[28:31]
	v_mfma_f32_16x16x32_bf16 v[16:19], v[140:143], v[214:217], v[16:19]
	v_mfma_f32_16x16x32_bf16 v[12:15], v[148:151], v[214:217], v[12:15]
	v_mfma_f32_16x16x32_bf16 v[64:67], v[144:147], v[194:197], v[64:67]
	v_mfma_f32_16x16x32_bf16 v[60:63], v[166:169], v[194:197], v[60:63]
	v_mfma_f32_16x16x32_bf16 v[48:51], v[144:147], v[202:205], v[48:51]
	v_mfma_f32_16x16x32_bf16 v[44:47], v[166:169], v[202:205], v[44:47]
	v_mfma_f32_16x16x32_bf16 v[32:35], v[144:147], v[210:213], v[32:35]
	v_mfma_f32_16x16x32_bf16 v[28:31], v[166:169], v[210:213], v[28:31]
	v_mfma_f32_16x16x32_bf16 v[16:19], v[144:147], v[220:223], v[16:19]
	v_mfma_f32_16x16x32_bf16 v[12:15], v[166:169], v[220:223], v[12:15]
	v_mfma_f32_16x16x32_bf16 v[56:59], v[170:173], v[190:193], v[56:59]
	v_mfma_f32_16x16x32_bf16 v[52:55], v[178:181], v[190:193], v[52:55]
	v_mfma_f32_16x16x32_bf16 v[40:43], v[170:173], v[198:201], v[40:43]
	v_mfma_f32_16x16x32_bf16 v[36:39], v[178:181], v[198:201], v[36:39]
	v_mfma_f32_16x16x32_bf16 v[24:27], v[170:173], v[206:209], v[24:27]
	v_mfma_f32_16x16x32_bf16 v[20:23], v[178:181], v[206:209], v[20:23]
	v_mfma_f32_16x16x32_bf16 v[8:11], v[170:173], v[214:217], v[8:11]
	v_mfma_f32_16x16x32_bf16 v[2:5], v[178:181], v[214:217], v[4:7]
	v_mfma_f32_16x16x32_bf16 v[56:59], v[174:177], v[194:197], v[56:59]
	v_mfma_f32_16x16x32_bf16 v[52:55], v[182:185], v[194:197], v[52:55]
	v_mfma_f32_16x16x32_bf16 v[40:43], v[174:177], v[202:205], v[40:43]
	v_mfma_f32_16x16x32_bf16 v[36:39], v[182:185], v[202:205], v[36:39]
	v_mfma_f32_16x16x32_bf16 v[24:27], v[174:177], v[210:213], v[24:27]
	v_mfma_f32_16x16x32_bf16 v[20:23], v[182:185], v[210:213], v[20:23]
	v_mfma_f32_16x16x32_bf16 v[8:11], v[174:177], v[220:223], v[8:11]
	v_mfma_f32_16x16x32_bf16 v[2:5], v[182:185], v[220:223], v[2:5]
	s_barrier
; #define PG8_STAGE(bufoff, gbase, voff) do { _Pragma("unroll") for (int _i = 0; _i < 2; ++_i) \
;         __builtin_amdgcn_global_load_lds((const unsigned*)((const char*)(gbase) + (voff)[_i]), (PG8_LAS unsigned*)(lds + (bufoff) + ldsw + _i * 8192), 16, 0, 0); } while (0)
; #define PG8_LDA(dst, b, h) do { _Pragma("unroll") for (int m = 0; m < 4; ++m) _Pragma("unroll") for (int k = 0; k < 2; ++k) dst[m][k] = *(const PG8_LAS bf16x8*)(lds + PG8_SA(b, h) + aoff + m * 2048 + k * 1024); } while (0)
; #define PG8_LDB(dst, b, h) do { _Pragma("unroll") for (int n = 0; n < 2; ++n) _Pragma("unroll") for (int k = 0; k < 2; ++k) dst[n][k] = *(const PG8_LAS bf16x8*)(lds + PG8_SB(b, h) + boff + n * 2048 + k * 1024); } while (0)
; #define PG8_MMA(ai, bj, At, Bt) do { __builtin_amdgcn_s_setprio(1); _Pragma("unroll") for (int m = 0; m < 4; ++m) _Pragma("unroll") for (int n = 0; n < 2; ++n) _Pragma("unroll") for (int k = 0; k < 2; ++k) \
;         acc[ai][bj][m][n] = __builtin_amdgcn_mfma_f32_16x16x32_bf16(Bt[n][k], At[m][k], acc[ai][bj][m][n], 0, 0, 0); __builtin_amdgcn_s_setprio(0); } while (0)
; #define PG8_WAIT_V(n) asm volatile("s_waitcnt vmcnt(" #n ")" ::: "memory")
; #define PG8_WAIT_L(n) asm volatile("s_waitcnt lgkmcnt(" #n ")" ::: "memory")
; #define PG8_BAR __builtin_amdgcn_s_barrier()
; #define PG8_SCHED __builtin_amdgcn_sched_barrier(0)
; template <class Epi, class Sched, bool ALIGN_EPI = false, bool SP2 = false>
; __device__ __forceinline__ void gemm_phase(PG8_LAS unsigned char* lds, const Gemm g, const Sched& S, const Epi& E) {
;     ...
;             PG8_LDB(B0, 1, 0); PG8_LDB(B1, 1, 1); PG8_SCHED; PG8_LDA(At, 1, 0); PG8_STAGE(PG8_SA(0, 1), a2 + hstepA, voffA);
;             PG8_WAIT_V(8); PG8_WAIT_L(0); PG8_BAR; PG8_MMA(0, 0, At, B0); PG8_MMA(0, 1, At, B1); PG8_BAR; PG8_SCHED;
;             PG8_LDA(At, 1, 1); PG8_STAGE(PG8_SB(1, 0), b3, voffB); PG8_STAGE(PG8_SB(1, 1), b3 + hstepB, voffB); PG8_STAGE(PG8_SA(1, 0), a3, voffA);
;             PG8_WAIT_V(8); PG8_WAIT_L(0); PG8_BAR; PG8_MMA(1, 0, At, B0); PG8_MMA(1, 1, At, B1); PG8_BAR; PG8_SCHED;
	ds_read_b128 v[140:143], v162
	ds_read_b128 v[144:147], v162 offset:1024
	ds_read_b128 v[148:151], v162 offset:2048
	ds_read_b128 v[166:169], v162 offset:3072
	ds_read_b128 v[170:173], v163
	ds_read_b128 v[174:177], v163 offset:1024
	ds_read_b128 v[178:181], v163 offset:2048
	ds_read_b128 v[182:185], v163 offset:3072
	s_mov_b32 m0, s92
	v_lshl_add_u64 v[6:7], v[186:187], 0, s[34:35]
	ds_read_b128 v[190:193], v161 offset:32768
	ds_read_b128 v[194:197], v161 offset:33792
	ds_read_b128 v[198:201], v161 offset:34816
	ds_read_b128 v[202:205], v161 offset:35840
	ds_read_b128 v[206:209], v161 offset:36864
	ds_read_b128 v[210:213], v161 offset:37888
	ds_read_b128 v[214:217], v161 offset:38912
	ds_read_b128 v[220:223], v161 offset:39936
	global_load_lds_dwordx4 v[6:7], off
	v_lshl_add_u64 v[6:7], v[186:187], 0, s[36:37]
	s_mov_b32 m0, s93
	s_nop 0
	global_load_lds_dwordx4 v[6:7], off
	s_waitcnt vmcnt(8)
	s_waitcnt lgkmcnt(0)
	s_barrier
	s_waitcnt lgkmcnt(0)
	v_mfma_f32_16x16x32_bf16 v[128:131], v[140:143], v[190:193], v[128:131]
	v_mfma_f32_16x16x32_bf16 v[124:127], v[148:151], v[190:193], v[124:127]
	v_mfma_f32_16x16x32_bf16 v[112:115], v[140:143], v[198:201], v[112:115]
	v_mfma_f32_16x16x32_bf16 v[108:111], v[148:151], v[198:201], v[108:111]
	v_mfma_f32_16x16x32_bf16 v[96:99], v[140:143], v[206:209], v[96:99]
	v_mfma_f32_16x16x32_bf16 v[92:95], v[148:151], v[206:209], v[92:95]
	v_mfma_f32_16x16x32_bf16 v[80:83], v[140:143], v[214:217], v[80:83]
	v_mfma_f32_16x16x32_bf16 v[76:79], v[148:151], v[214:217], v[76:79]
	v_mfma_f32_16x16x32_bf16 v[128:131], v[144:147], v[194:197], v[128:131]
	v_mfma_f32_16x16x32_bf16 v[124:127], v[166:169], v[194:197], v[124:127]
	v_mfma_f32_16x16x32_bf16 v[112:115], v[144:147], v[202:205], v[112:115]
	v_mfma_f32_16x16x32_bf16 v[108:111], v[166:169], v[202:205], v[108:111]
	v_mfma_f32_16x16x32_bf16 v[96:99], v[144:147], v[210:213], v[96:99]
	v_mfma_f32_16x16x32_bf16 v[92:95], v[166:169], v[210:213], v[92:95]
	v_mfma_f32_16x16x32_bf16 v[80:83], v[144:147], v[220:223], v[80:83]
	v_mfma_f32_16x16x32_bf16 v[76:79], v[166:169], v[220:223], v[76:79]
	v_mfma_f32_16x16x32_bf16 v[120:123], v[170:173], v[190:193], v[120:123]
	v_mfma_f32_16x16x32_bf16 v[116:119], v[178:181], v[190:193], v[116:119]
	v_mfma_f32_16x16x32_bf16 v[104:107], v[170:173], v[198:201], v[104:107]
	v_mfma_f32_16x16x32_bf16 v[100:103], v[178:181], v[198:201], v[100:103]
	v_mfma_f32_16x16x32_bf16 v[88:91], v[170:173], v[206:209], v[88:91]
	v_mfma_f32_16x16x32_bf16 v[84:87], v[178:181], v[206:209], v[84:87]
	v_mfma_f32_16x16x32_bf16 v[72:75], v[170:173], v[214:217], v[72:75]
	v_mfma_f32_16x16x32_bf16 v[68:71], v[178:181], v[214:217], v[68:71]
	v_mfma_f32_16x16x32_bf16 v[120:123], v[174:177], v[194:197], v[120:123]
	v_mfma_f32_16x16x32_bf16 v[116:119], v[182:185], v[194:197], v[116:119]
	v_mfma_f32_16x16x32_bf16 v[104:107], v[174:177], v[202:205], v[104:107]
	v_mfma_f32_16x16x32_bf16 v[100:103], v[182:185], v[202:205], v[100:103]
	v_mfma_f32_16x16x32_bf16 v[88:91], v[174:177], v[210:213], v[88:91]
	v_mfma_f32_16x16x32_bf16 v[84:87], v[182:185], v[210:213], v[84:87]
	v_mfma_f32_16x16x32_bf16 v[72:75], v[174:177], v[220:223], v[72:75]
	v_mfma_f32_16x16x32_bf16 v[68:71], v[182:185], v[220:223], v[68:71]
	s_barrier
	s_add_i32 s8, s19, s89
	v_lshl_add_u64 v[6:7], v[152:153], 0, s[38:39]
	s_mov_b32 m0, s8
	ds_read_b128 v[190:193], v161 offset:49152
	ds_read_b128 v[194:197], v161 offset:50176
	ds_read_b128 v[198:201], v161 offset:51200
	ds_read_b128 v[202:205], v161 offset:52224
	ds_read_b128 v[206:209], v161 offset:53248
	ds_read_b128 v[210:213], v161 offset:54272
	ds_read_b128 v[214:217], v161 offset:55296
	ds_read_b128 v[220:223], v161 offset:56320
	global_load_lds_dwordx4 v[6:7], off
	v_lshl_add_u64 v[6:7], v[152:153], 0, s[40:41]
	s_add_i32 m0, s8, 0x2000
	s_add_i32 s8, s80, s89
	global_load_lds_dwordx4 v[6:7], off
	v_lshl_add_u64 v[6:7], v[152:153], 0, s[52:53]
	s_mov_b32 m0, s8
	s_nop 0
	global_load_lds_dwordx4 v[6:7], off
	v_lshl_add_u64 v[6:7], v[152:153], 0, s[54:55]
	s_add_i32 m0, s8, 0x2000
	s_nop 0
	global_load_lds_dwordx4 v[6:7], off
	v_lshl_add_u64 v[6:7], v[186:187], 0, s[38:39]
	s_mov_b32 m0, s94
	s_nop 0
	global_load_lds_dwordx4 v[6:7], off
	v_lshl_add_u64 v[6:7], v[186:187], 0, s[40:41]
	s_mov_b32 m0, s95
	s_nop 0
	global_load_lds_dwordx4 v[6:7], off
	s_waitcnt vmcnt(8)
	s_waitcnt lgkmcnt(0)
	s_barrier
	s_waitcnt lgkmcnt(0)
	v_mfma_f32_16x16x32_bf16 v[64:67], v[140:143], v[190:193], v[64:67]
	v_mfma_f32_16x16x32_bf16 v[60:63], v[148:151], v[190:193], v[60:63]
	v_mfma_f32_16x16x32_bf16 v[48:51], v[140:143], v[198:201], v[48:51]
	v_mfma_f32_16x16x32_bf16 v[44:47], v[148:151], v[198:201], v[44:47]
	v_mfma_f32_16x16x32_bf16 v[32:35], v[140:143], v[206:209], v[32:35]
	v_mfma_f32_16x16x32_bf16 v[28:31], v[148:151], v[206:209], v[28:31]
	v_mfma_f32_16x16x32_bf16 v[16:19], v[140:143], v[214:217], v[16:19]
	v_mfma_f32_16x16x32_bf16 v[12:15], v[148:151], v[214:217], v[12:15]
	v_mfma_f32_16x16x32_bf16 v[64:67], v[144:147], v[194:197], v[64:67]
	v_mfma_f32_16x16x32_bf16 v[60:63], v[166:169], v[194:197], v[60:63]
	v_mfma_f32_16x16x32_bf16 v[48:51], v[144:147], v[202:205], v[48:51]
	v_mfma_f32_16x16x32_bf16 v[44:47], v[166:169], v[202:205], v[44:47]
	v_mfma_f32_16x16x32_bf16 v[32:35], v[144:147], v[210:213], v[32:35]
	v_mfma_f32_16x16x32_bf16 v[28:31], v[166:169], v[210:213], v[28:31]
	v_mfma_f32_16x16x32_bf16 v[16:19], v[144:147], v[220:223], v[16:19]
	v_mfma_f32_16x16x32_bf16 v[12:15], v[166:169], v[220:223], v[12:15]
	v_mfma_f32_16x16x32_bf16 v[56:59], v[170:173], v[190:193], v[56:59]
	v_mfma_f32_16x16x32_bf16 v[52:55], v[178:181], v[190:193], v[52:55]
	v_mfma_f32_16x16x32_bf16 v[40:43], v[170:173], v[198:201], v[40:43]
	v_mfma_f32_16x16x32_bf16 v[36:39], v[178:181], v[198:201], v[36:39]
	v_mfma_f32_16x16x32_bf16 v[24:27], v[170:173], v[206:209], v[24:27]
	v_mfma_f32_16x16x32_bf16 v[20:23], v[178:181], v[206:209], v[20:23]
	v_mfma_f32_16x16x32_bf16 v[6:9], v[170:173], v[214:217], v[8:11]
	v_mfma_f32_16x16x32_bf16 v[2:5], v[178:181], v[214:217], v[2:5]
	v_mfma_f32_16x16x32_bf16 v[56:59], v[174:177], v[194:197], v[56:59]
	v_mfma_f32_16x16x32_bf16 v[52:55], v[182:185], v[194:197], v[52:55]
	v_mfma_f32_16x16x32_bf16 v[40:43], v[174:177], v[202:205], v[40:43]
	v_mfma_f32_16x16x32_bf16 v[36:39], v[182:185], v[202:205], v[36:39]
	v_mfma_f32_16x16x32_bf16 v[24:27], v[174:177], v[210:213], v[24:27]
	v_mfma_f32_16x16x32_bf16 v[20:23], v[182:185], v[210:213], v[20:23]
	v_mfma_f32_16x16x32_bf16 v[8:11], v[174:177], v[220:223], v[6:9]
	v_mfma_f32_16x16x32_bf16 v[4:7], v[182:185], v[220:223], v[2:5]
	s_barrier
	s_add_i32 s76, s76, 2
	s_add_u32 s4, s4, 0x10000
	s_addc_u32 s5, s5, 0
	s_add_u32 s74, s74, 0x10000
	s_addc_u32 s75, s75, 0
	s_cmp_gt_u32 s76, 13
	s_cbranch_scc0 .LBB0_315
	s_and_b64 vcc, exec, s[58:59]
	s_cbranch_vccz .LBB0_318
	s_barrier

; #define PG8_STAGE(bufoff, gbase, voff) do { _Pragma("unroll") for (int _i = 0; _i < 2; ++_i) \
;         __builtin_amdgcn_global_load_lds((const unsigned*)((const char*)(gbase) + (voff)[_i]), (PG8_LAS unsigned*)(lds + (bufoff) + ldsw + _i * 8192), 16, 0, 0); } while (0)
; #define PG8_LDA(dst, b, h) do { _Pragma("unroll") for (int m = 0; m < 4; ++m) _Pragma("unroll") for (int k = 0; k < 2; ++k) dst[m][k] = *(const PG8_LAS bf16x8*)(lds + PG8_SA(b, h) + aoff + m * 2048 + k * 1024); } while (0)
; #define PG8_LDB(dst, b, h) do { _Pragma("unroll") for (int n = 0; n < 2; ++n) _Pragma("unroll") for (int k = 0; k < 2; ++k) dst[n][k] = *(const PG8_LAS bf16x8*)(lds + PG8_SB(b, h) + boff + n * 2048 + k * 1024); } while (0)
; #define PG8_MMA(ai, bj, At, Bt) do { __builtin_amdgcn_s_setprio(1); _Pragma("unroll") for (int m = 0; m < 4; ++m) _Pragma("unroll") for (int n = 0; n < 2; ++n) _Pragma("unroll") for (int k = 0; k < 2; ++k) \
;         acc[ai][bj][m][n] = __builtin_amdgcn_mfma_f32_16x16x32_bf16(Bt[n][k], At[m][k], acc[ai][bj][m][n], 0, 0, 0); __builtin_amdgcn_s_setprio(0); } while (0)
; #define PG8_BAR __builtin_amdgcn_s_barrier()
; template <class Epi, class Sched, bool ALIGN_EPI = false, bool SP2 = false>
; __device__ __forceinline__ void gemm_phase(PG8_LAS unsigned char* lds, const Gemm g, const Sched& S, const Epi& E) {
;     ...
;         const bool has_next = S.next(ui + 1, nxt);
;         const char* nA = has_next ? (const char*)g.A + (size_t)nxt.pm * tstepA : cA; const char* nB = has_next ? (const char*)g.Bt + (size_t)nxt.pn * tstepB : cB;
;         for (int t = 0; t < nt; t += 2) {
;             const bool last = (t == nt - 2);
;             const char* a1 = cA + (size_t)(t + 1) * kstepA;
;             const char* a2 = last ? nA : cA + (size_t)(t + 2) * kstepA; const char* b2 = last ? nB : cB + (size_t)(t + 2) * kstep;
;             const char* a3 = a2 + kstepA; const char* b3 = b2 + kstep;
;             if (last && has_next) S.a_ready(nxt);
;             if constexpr (SP2) {
;             PG8_LDB(B0, 0, 0); PG8_LDB(B1, 0, 1); PG8_SCHED; PG8_LDA(At, 0, 0); PG8_STAGE(PG8_SA(1, 1), a1 + hstepA, voffA);
;             PG8_WAIT_V(8); PG8_WAIT_L(0); PG8_BAR; PG8_MMA(0, 0, At, B0); PG8_MMA(0, 1, At, B1); PG8_BAR; PG8_SCHED;
;             PG8_LDA(At, 0, 1); PG8_STAGE(PG8_SB(0, 0), b2, voffB); PG8_STAGE(PG8_SB(0, 1), b2 + hstepB, voffB); PG8_STAGE(PG8_SA(0, 0), a2, voffA);
.LBB0_645:
	s_ashr_i32 s61, s60, 31
	s_lshl_b64 s[8:9], s[60:61], 19
	s_add_u32 s64, s85, s8
	s_addc_u32 s65, s86, s9
	s_and_b64 s[0:1], s[0:1], exec
	s_cselect_b32 s61, s65, s67
	s_cselect_b32 s90, s64, s66
	s_add_u32 s91, s66, 0x10000
	s_addc_u32 s92, s67, 0
	s_add_u32 s0, s68, 0xf0080
	s_addc_u32 s1, s69, 0
	s_mov_b32 s68, -2
	ds_read_b128 v[128:131], v197
	ds_read_b128 v[132:135], v197 offset:1024
	ds_read_b128 v[136:139], v197 offset:2048
	ds_read_b128 v[140:143], v197 offset:3072
	ds_read_b128 v[144:147], v198
	ds_read_b128 v[148:151], v198 offset:1024
	ds_read_b128 v[152:155], v198 offset:2048
	ds_read_b128 v[156:159], v198 offset:3072
	s_add_u32 s8, s0, 0xfff10080
	s_addc_u32 s9, s1, -1
	s_cmp_eq_u32 s68, 12
	s_cselect_b32 s67, s63, s9
	s_cselect_b32 s66, s62, s8
	s_cselect_b32 s9, s61, s92
	s_cselect_b32 s8, s90, s91
	v_lshl_add_u64 v[236:237], s[0:1], 0, v[174:175]
	s_add_i32 m0, s17, 0xc000
	ds_read_b128 v[202:205], v199
	ds_read_b128 v[206:209], v199 offset:1024
	ds_read_b128 v[210:213], v199 offset:2048
	ds_read_b128 v[214:217], v199 offset:3072
	ds_read_b128 v[220:223], v199 offset:4096
	ds_read_b128 v[224:227], v199 offset:5120
	ds_read_b128 v[228:231], v199 offset:6144
	ds_read_b128 v[232:235], v199 offset:7168
	global_load_lds_dwordx4 v[236:237], off
	v_lshl_add_u64 v[236:237], s[0:1], 0, v[176:177]
	s_add_i32 m0, s17, 0xe000
	s_nop 0
	global_load_lds_dwordx4 v[236:237], off
	s_waitcnt vmcnt(8)
	s_waitcnt lgkmcnt(0)
	s_barrier
	s_waitcnt lgkmcnt(0)
	v_mfma_f32_16x16x32_bf16 v[124:127], v[128:131], v[202:205], 0
	v_mfma_f32_16x16x32_bf16 v[120:123], v[136:139], v[202:205], 0
	v_mfma_f32_16x16x32_bf16 v[108:111], v[128:131], v[210:213], 0
	v_mfma_f32_16x16x32_bf16 v[104:107], v[136:139], v[210:213], 0
	v_mfma_f32_16x16x32_bf16 v[96:99], v[128:131], v[220:223], 0
	v_mfma_f32_16x16x32_bf16 v[88:91], v[136:139], v[220:223], 0
	v_mfma_f32_16x16x32_bf16 v[80:83], v[128:131], v[228:231], 0
	v_mfma_f32_16x16x32_bf16 v[72:75], v[136:139], v[228:231], 0
	v_mfma_f32_16x16x32_bf16 v[124:127], v[132:135], v[206:209], v[124:127]
	v_mfma_f32_16x16x32_bf16 v[120:123], v[140:143], v[206:209], v[120:123]
	v_mfma_f32_16x16x32_bf16 v[108:111], v[132:135], v[214:217], v[108:111]
	v_mfma_f32_16x16x32_bf16 v[104:107], v[140:143], v[214:217], v[104:107]
	v_mfma_f32_16x16x32_bf16 v[96:99], v[132:135], v[224:227], v[96:99]
	v_mfma_f32_16x16x32_bf16 v[88:91], v[140:143], v[224:227], v[88:91]
	v_mfma_f32_16x16x32_bf16 v[80:83], v[132:135], v[232:235], v[80:83]
	v_mfma_f32_16x16x32_bf16 v[72:75], v[140:143], v[232:235], v[72:75]
	v_mfma_f32_16x16x32_bf16 v[116:119], v[144:147], v[202:205], 0
	v_mfma_f32_16x16x32_bf16 v[112:115], v[152:155], v[202:205], 0
	v_mfma_f32_16x16x32_bf16 v[100:103], v[144:147], v[210:213], 0
	v_mfma_f32_16x16x32_bf16 v[92:95], v[152:155], v[210:213], 0
	v_mfma_f32_16x16x32_bf16 v[84:87], v[144:147], v[220:223], 0
	v_mfma_f32_16x16x32_bf16 v[76:79], v[152:155], v[220:223], 0
	v_mfma_f32_16x16x32_bf16 v[68:71], v[144:147], v[228:231], 0
	v_mfma_f32_16x16x32_bf16 v[64:67], v[152:155], v[228:231], 0
	v_mfma_f32_16x16x32_bf16 v[116:119], v[148:151], v[206:209], v[116:119]
	v_mfma_f32_16x16x32_bf16 v[112:115], v[156:159], v[206:209], v[112:115]
	v_mfma_f32_16x16x32_bf16 v[100:103], v[148:151], v[214:217], v[100:103]
	v_mfma_f32_16x16x32_bf16 v[92:95], v[156:159], v[214:217], v[92:95]
	v_mfma_f32_16x16x32_bf16 v[84:87], v[148:151], v[224:227], v[84:87]
	v_mfma_f32_16x16x32_bf16 v[76:79], v[156:159], v[224:227], v[76:79]
	v_mfma_f32_16x16x32_bf16 v[68:71], v[148:151], v[232:235], v[68:71]
	v_mfma_f32_16x16x32_bf16 v[64:67], v[156:159], v[232:235], v[64:67]
	s_barrier
	v_lshl_add_u64 v[236:237], s[8:9], 0, v[190:191]
	s_add_i32 s8, s77, s15
	s_mov_b32 m0, s8
	ds_read_b128 v[202:205], v199 offset:16384
	ds_read_b128 v[206:209], v199 offset:17408
	ds_read_b128 v[210:213], v199 offset:18432
	ds_read_b128 v[214:217], v199 offset:19456
	ds_read_b128 v[220:223], v199 offset:20480
	ds_read_b128 v[224:227], v199 offset:21504
	ds_read_b128 v[228:231], v199 offset:22528
	ds_read_b128 v[232:235], v199 offset:23552
	global_load_lds_dwordx4 v[236:237], off
	v_lshl_add_u64 v[238:239], v[236:237], 0, s[36:37]
	s_add_i32 m0, s8, 0x2000
	s_add_i32 s8, s80, s15
	global_load_lds_dwordx4 v[238:239], off
	v_lshl_add_u64 v[238:239], v[236:237], 0, s[38:39]
	s_mov_b32 m0, s8
	v_lshl_add_u64 v[240:241], s[66:67], 0, v[162:163]
	global_load_lds_dwordx4 v[238:239], off
	v_lshl_add_u64 v[238:239], v[236:237], 0, s[40:41]
	s_add_i32 m0, s8, 0x2000
	s_nop 0
	global_load_lds_dwordx4 v[238:239], off
	v_lshl_add_u64 v[238:239], s[66:67], 0, v[160:161]
	s_mov_b32 m0, s17
	s_nop 0
	global_load_lds_dwordx4 v[238:239], off
	s_mov_b32 m0, s18
	s_nop 0
	global_load_lds_dwordx4 v[240:241], off
	s_waitcnt vmcnt(8)
	s_waitcnt lgkmcnt(0)
	s_barrier
; #define PG8_STAGE(bufoff, gbase, voff) do { _Pragma("unroll") for (int _i = 0; _i < 2; ++_i) \
;         __builtin_amdgcn_global_load_lds((const unsigned*)((const char*)(gbase) + (voff)[_i]), (PG8_LAS unsigned*)(lds + (bufoff) + ldsw + _i * 8192), 16, 0, 0); } while (0)
; #define PG8_LDA(dst, b, h) do { _Pragma("unroll") for (int m = 0; m < 4; ++m) _Pragma("unroll") for (int k = 0; k < 2; ++k) dst[m][k] = *(const PG8_LAS bf16x8*)(lds + PG8_SA(b, h) + aoff + m * 2048 + k * 1024); } while (0)
; #define PG8_LDB(dst, b, h) do { _Pragma("unroll") for (int n = 0; n < 2; ++n) _Pragma("unroll") for (int k = 0; k < 2; ++k) dst[n][k] = *(const PG8_LAS bf16x8*)(lds + PG8_SB(b, h) + boff + n * 2048 + k * 1024); } while (0)
; #define PG8_MMA(ai, bj, At, Bt) do { __builtin_amdgcn_s_setprio(1); _Pragma("unroll") for (int m = 0; m < 4; ++m) _Pragma("unroll") for (int n = 0; n < 2; ++n) _Pragma("unroll") for (int k = 0; k < 2; ++k) \
;         acc[ai][bj][m][n] = __builtin_amdgcn_mfma_f32_16x16x32_bf16(Bt[n][k], At[m][k], acc[ai][bj][m][n], 0, 0, 0); __builtin_amdgcn_s_setprio(0); } while (0)
; #define PG8_WAIT_V(n) asm volatile("s_waitcnt vmcnt(" #n ")" ::: "memory")
; #define PG8_WAIT_L(n) asm volatile("s_waitcnt lgkmcnt(" #n ")" ::: "memory")
; #define PG8_BAR __builtin_amdgcn_s_barrier()
; #define PG8_SCHED __builtin_amdgcn_sched_barrier(0)
; template <class Epi, class Sched, bool ALIGN_EPI = false, bool SP2 = false>
; __device__ __forceinline__ void gemm_phase(PG8_LAS unsigned char* lds, const Gemm g, const Sched& S, const Epi& E) {
;     ...
;             PG8_WAIT_V(8); PG8_WAIT_L(0); PG8_BAR; PG8_MMA(1, 0, At, B0); PG8_MMA(1, 1, At, B1); PG8_BAR; PG8_SCHED;
;             PG8_LDB(B0, 1, 0); PG8_LDB(B1, 1, 1); PG8_SCHED; PG8_LDA(At, 1, 0); PG8_STAGE(PG8_SA(0, 1), a2 + hstepA, voffA);
;             PG8_WAIT_V(8); PG8_WAIT_L(0); PG8_BAR; PG8_MMA(0, 0, At, B0); PG8_MMA(0, 1, At, B1); PG8_BAR; PG8_SCHED;
	s_waitcnt lgkmcnt(0)
	v_mfma_f32_16x16x32_bf16 v[60:63], v[128:131], v[202:205], 0
	v_mfma_f32_16x16x32_bf16 v[56:59], v[136:139], v[202:205], 0
	v_mfma_f32_16x16x32_bf16 v[48:51], v[128:131], v[210:213], 0
	v_mfma_f32_16x16x32_bf16 v[40:43], v[136:139], v[210:213], 0
	v_mfma_f32_16x16x32_bf16 v[32:35], v[128:131], v[220:223], 0
	v_mfma_f32_16x16x32_bf16 v[24:27], v[136:139], v[220:223], 0
	v_mfma_f32_16x16x32_bf16 v[16:19], v[128:131], v[228:231], 0
	v_mfma_f32_16x16x32_bf16 v[8:11], v[136:139], v[228:231], 0
	v_mfma_f32_16x16x32_bf16 v[60:63], v[132:135], v[206:209], v[60:63]
	v_mfma_f32_16x16x32_bf16 v[56:59], v[140:143], v[206:209], v[56:59]
	v_mfma_f32_16x16x32_bf16 v[48:51], v[132:135], v[214:217], v[48:51]
	v_mfma_f32_16x16x32_bf16 v[40:43], v[140:143], v[214:217], v[40:43]
	v_mfma_f32_16x16x32_bf16 v[32:35], v[132:135], v[224:227], v[32:35]
	v_mfma_f32_16x16x32_bf16 v[24:27], v[140:143], v[224:227], v[24:27]
	v_mfma_f32_16x16x32_bf16 v[16:19], v[132:135], v[232:235], v[16:19]
	v_mfma_f32_16x16x32_bf16 v[8:11], v[140:143], v[232:235], v[8:11]
	v_mfma_f32_16x16x32_bf16 v[52:55], v[144:147], v[202:205], 0
	v_mfma_f32_16x16x32_bf16 v[44:47], v[152:155], v[202:205], 0
	v_mfma_f32_16x16x32_bf16 v[36:39], v[144:147], v[210:213], 0
	v_mfma_f32_16x16x32_bf16 v[28:31], v[152:155], v[210:213], 0
	v_mfma_f32_16x16x32_bf16 v[20:23], v[144:147], v[220:223], 0
	v_mfma_f32_16x16x32_bf16 v[12:15], v[152:155], v[220:223], 0
	v_mfma_f32_16x16x32_bf16 v[4:7], v[144:147], v[228:231], 0
	v_mfma_f32_16x16x32_bf16 v[0:3], v[152:155], v[228:231], 0
	v_mfma_f32_16x16x32_bf16 v[52:55], v[148:151], v[206:209], v[52:55]
	v_mfma_f32_16x16x32_bf16 v[44:47], v[156:159], v[206:209], v[44:47]
	v_mfma_f32_16x16x32_bf16 v[36:39], v[148:151], v[214:217], v[36:39]
	v_mfma_f32_16x16x32_bf16 v[28:31], v[156:159], v[214:217], v[28:31]
	v_mfma_f32_16x16x32_bf16 v[20:23], v[148:151], v[224:227], v[20:23]
	v_mfma_f32_16x16x32_bf16 v[12:15], v[156:159], v[224:227], v[12:15]
	v_mfma_f32_16x16x32_bf16 v[4:7], v[148:151], v[232:235], v[4:7]
	v_mfma_f32_16x16x32_bf16 v[0:3], v[156:159], v[232:235], v[0:3]
	s_barrier
	ds_read_b128 v[128:131], v200
	ds_read_b128 v[132:135], v200 offset:1024
	ds_read_b128 v[136:139], v200 offset:2048
	ds_read_b128 v[140:143], v200 offset:3072
	ds_read_b128 v[144:147], v201
	ds_read_b128 v[148:151], v201 offset:1024
	ds_read_b128 v[152:155], v201 offset:2048
	ds_read_b128 v[156:159], v201 offset:3072
	s_add_u32 s8, s66, 0xf0000
	s_addc_u32 s9, s67, 0
	s_mov_b32 m0, s19
	v_lshl_add_u64 v[242:243], s[8:9], 0, v[160:161]
	ds_read_b128 v[202:205], v199 offset:32768
	ds_read_b128 v[206:209], v199 offset:33792
	ds_read_b128 v[210:213], v199 offset:34816
	ds_read_b128 v[214:217], v199 offset:35840
	ds_read_b128 v[220:223], v199 offset:36864
	ds_read_b128 v[224:227], v199 offset:37888
	ds_read_b128 v[228:231], v199 offset:38912
	ds_read_b128 v[232:235], v199 offset:39936
	global_load_lds_dwordx4 v[242:243], off
	v_lshl_add_u64 v[242:243], s[8:9], 0, v[162:163]
	s_mov_b32 m0, s59
	s_nop 0
	global_load_lds_dwordx4 v[242:243], off
	s_waitcnt vmcnt(8)
	s_waitcnt lgkmcnt(0)
	s_barrier
	s_waitcnt lgkmcnt(0)
	v_mfma_f32_16x16x32_bf16 v[124:127], v[128:131], v[202:205], v[124:127]
	v_mfma_f32_16x16x32_bf16 v[120:123], v[136:139], v[202:205], v[120:123]
	v_mfma_f32_16x16x32_bf16 v[108:111], v[128:131], v[210:213], v[108:111]
	v_mfma_f32_16x16x32_bf16 v[104:107], v[136:139], v[210:213], v[104:107]
	v_mfma_f32_16x16x32_bf16 v[96:99], v[128:131], v[220:223], v[96:99]
	v_mfma_f32_16x16x32_bf16 v[88:91], v[136:139], v[220:223], v[88:91]
	v_mfma_f32_16x16x32_bf16 v[80:83], v[128:131], v[228:231], v[80:83]
	v_mfma_f32_16x16x32_bf16 v[72:75], v[136:139], v[228:231], v[72:75]
	v_mfma_f32_16x16x32_bf16 v[124:127], v[132:135], v[206:209], v[124:127]
	v_mfma_f32_16x16x32_bf16 v[120:123], v[140:143], v[206:209], v[120:123]
	v_mfma_f32_16x16x32_bf16 v[108:111], v[132:135], v[214:217], v[108:111]
	v_mfma_f32_16x16x32_bf16 v[104:107], v[140:143], v[214:217], v[104:107]
	v_mfma_f32_16x16x32_bf16 v[96:99], v[132:135], v[224:227], v[96:99]
	v_mfma_f32_16x16x32_bf16 v[88:91], v[140:143], v[224:227], v[88:91]
	v_mfma_f32_16x16x32_bf16 v[80:83], v[132:135], v[232:235], v[80:83]
	v_mfma_f32_16x16x32_bf16 v[72:75], v[140:143], v[232:235], v[72:75]
	v_mfma_f32_16x16x32_bf16 v[116:119], v[144:147], v[202:205], v[116:119]
	v_mfma_f32_16x16x32_bf16 v[112:115], v[152:155], v[202:205], v[112:115]
	v_mfma_f32_16x16x32_bf16 v[100:103], v[144:147], v[210:213], v[100:103]
	v_mfma_f32_16x16x32_bf16 v[92:95], v[152:155], v[210:213], v[92:95]
	v_mfma_f32_16x16x32_bf16 v[84:87], v[144:147], v[220:223], v[84:87]
	v_mfma_f32_16x16x32_bf16 v[76:79], v[152:155], v[220:223], v[76:79]
	v_mfma_f32_16x16x32_bf16 v[68:71], v[144:147], v[228:231], v[68:71]
	v_mfma_f32_16x16x32_bf16 v[64:67], v[152:155], v[228:231], v[64:67]
	v_mfma_f32_16x16x32_bf16 v[116:119], v[148:151], v[206:209], v[116:119]
	v_mfma_f32_16x16x32_bf16 v[112:115], v[156:159], v[206:209], v[112:115]
	v_mfma_f32_16x16x32_bf16 v[100:103], v[148:151], v[214:217], v[100:103]
	v_mfma_f32_16x16x32_bf16 v[92:95], v[156:159], v[214:217], v[92:95]
	v_mfma_f32_16x16x32_bf16 v[84:87], v[148:151], v[224:227], v[84:87]
	v_mfma_f32_16x16x32_bf16 v[76:79], v[156:159], v[224:227], v[76:79]
	v_mfma_f32_16x16x32_bf16 v[68:71], v[148:151], v[232:235], v[68:71]
	v_mfma_f32_16x16x32_bf16 v[64:67], v[156:159], v[232:235], v[64:67]
	s_barrier
; #define PG8_STAGE(bufoff, gbase, voff) do { _Pragma("unroll") for (int _i = 0; _i < 2; ++_i) \
;         __builtin_amdgcn_global_load_lds((const unsigned*)((const char*)(gbase) + (voff)[_i]), (PG8_LAS unsigned*)(lds + (bufoff) + ldsw + _i * 8192), 16, 0, 0); } while (0)
; #define PG8_LDA(dst, b, h) do { _Pragma("unroll") for (int m = 0; m < 4; ++m) _Pragma("unroll") for (int k = 0; k < 2; ++k) dst[m][k] = *(const PG8_LAS bf16x8*)(lds + PG8_SA(b, h) + aoff + m * 2048 + k * 1024); } while (0)
; #define PG8_LDB(dst, b, h) do { _Pragma("unroll") for (int n = 0; n < 2; ++n) _Pragma("unroll") for (int k = 0; k < 2; ++k) dst[n][k] = *(const PG8_LAS bf16x8*)(lds + PG8_SB(b, h) + boff + n * 2048 + k * 1024); } while (0)
; #define PG8_MMA(ai, bj, At, Bt) do { __builtin_amdgcn_s_setprio(1); _Pragma("unroll") for (int m = 0; m < 4; ++m) _Pragma("unroll") for (int n = 0; n < 2; ++n) _Pragma("unroll") for (int k = 0; k < 2; ++k) \
;         acc[ai][bj][m][n] = __builtin_amdgcn_mfma_f32_16x16x32_bf16(Bt[n][k], At[m][k], acc[ai][bj][m][n], 0, 0, 0); __builtin_amdgcn_s_setprio(0); } while (0)
; #define PG8_WAIT_V(n) asm volatile("s_waitcnt vmcnt(" #n ")" ::: "memory")
; #define PG8_WAIT_L(n) asm volatile("s_waitcnt lgkmcnt(" #n ")" ::: "memory")
; #define PG8_BAR __builtin_amdgcn_s_barrier()
; #define PG8_SCHED __builtin_amdgcn_sched_barrier(0)
; template <class Epi, class Sched, bool ALIGN_EPI = false, bool SP2 = false>
; __device__ __forceinline__ void gemm_phase(PG8_LAS unsigned char* lds, const Gemm g, const Sched& S, const Epi& E) {
;     ...
;             PG8_LDB(B0, 0, 0); PG8_LDB(B1, 0, 1); PG8_SCHED; PG8_LDA(At, 0, 0); PG8_STAGE(PG8_SA(1, 1), a1 + hstepA, voffA);
;     ...
;             PG8_LDA(At, 1, 1); PG8_STAGE(PG8_SB(1, 0), b3, voffB); PG8_STAGE(PG8_SB(1, 1), b3 + hstepB, voffB); PG8_STAGE(PG8_SA(1, 0), a3, voffA);
;             PG8_WAIT_V(8); PG8_WAIT_L(0); PG8_BAR; PG8_MMA(1, 0, At, B0); PG8_MMA(1, 1, At, B1); PG8_BAR; PG8_SCHED;
	s_add_i32 s8, s81, s15
	v_lshl_add_u64 v[242:243], v[236:237], 0, s[42:43]
	s_mov_b32 m0, s8
	ds_read_b128 v[202:205], v199 offset:49152
	ds_read_b128 v[206:209], v199 offset:50176
	ds_read_b128 v[210:213], v199 offset:51200
	ds_read_b128 v[214:217], v199 offset:52224
	ds_read_b128 v[220:223], v199 offset:53248
	ds_read_b128 v[224:227], v199 offset:54272
	ds_read_b128 v[228:231], v199 offset:55296
	ds_read_b128 v[232:235], v199 offset:56320
	global_load_lds_dwordx4 v[242:243], off
	v_lshl_add_u64 v[242:243], v[236:237], 0, s[44:45]
	s_add_i32 m0, s8, 0x2000
	s_add_i32 s8, s82, s15
	global_load_lds_dwordx4 v[242:243], off
	v_lshl_add_u64 v[242:243], v[236:237], 0, s[48:49]
	s_mov_b32 m0, s8
	v_lshl_add_u64 v[236:237], v[236:237], 0, s[52:53]
	global_load_lds_dwordx4 v[242:243], off
	s_add_i32 m0, s8, 0x2000
	s_nop 0
	global_load_lds_dwordx4 v[236:237], off
	v_lshl_add_u64 v[236:237], v[238:239], 0, s[46:47]
	s_mov_b32 m0, s70
	s_nop 0
	global_load_lds_dwordx4 v[236:237], off
	v_lshl_add_u64 v[236:237], v[240:241], 0, s[46:47]
	s_mov_b32 m0, s71
	s_nop 0
	global_load_lds_dwordx4 v[236:237], off
	s_waitcnt vmcnt(8)
	s_waitcnt lgkmcnt(0)
	s_barrier
	s_waitcnt lgkmcnt(0)
	v_mfma_f32_16x16x32_bf16 v[60:63], v[128:131], v[202:205], v[60:63]
	v_mfma_f32_16x16x32_bf16 v[56:59], v[136:139], v[202:205], v[56:59]
	v_mfma_f32_16x16x32_bf16 v[48:51], v[128:131], v[210:213], v[48:51]
	v_mfma_f32_16x16x32_bf16 v[40:43], v[136:139], v[210:213], v[40:43]
	v_mfma_f32_16x16x32_bf16 v[32:35], v[128:131], v[220:223], v[32:35]
	v_mfma_f32_16x16x32_bf16 v[24:27], v[136:139], v[220:223], v[24:27]
	v_mfma_f32_16x16x32_bf16 v[16:19], v[128:131], v[228:231], v[16:19]
	v_mfma_f32_16x16x32_bf16 v[8:11], v[136:139], v[228:231], v[8:11]
	v_mfma_f32_16x16x32_bf16 v[60:63], v[132:135], v[206:209], v[60:63]
	v_mfma_f32_16x16x32_bf16 v[56:59], v[140:143], v[206:209], v[56:59]
	v_mfma_f32_16x16x32_bf16 v[48:51], v[132:135], v[214:217], v[48:51]
	v_mfma_f32_16x16x32_bf16 v[40:43], v[140:143], v[214:217], v[40:43]
	v_mfma_f32_16x16x32_bf16 v[32:35], v[132:135], v[224:227], v[32:35]
	v_mfma_f32_16x16x32_bf16 v[24:27], v[140:143], v[224:227], v[24:27]
	v_mfma_f32_16x16x32_bf16 v[16:19], v[132:135], v[232:235], v[16:19]
	v_mfma_f32_16x16x32_bf16 v[8:11], v[140:143], v[232:235], v[8:11]
	v_mfma_f32_16x16x32_bf16 v[52:55], v[144:147], v[202:205], v[52:55]
	v_mfma_f32_16x16x32_bf16 v[44:47], v[152:155], v[202:205], v[44:47]
	v_mfma_f32_16x16x32_bf16 v[36:39], v[144:147], v[210:213], v[36:39]
	v_mfma_f32_16x16x32_bf16 v[28:31], v[152:155], v[210:213], v[28:31]
	v_mfma_f32_16x16x32_bf16 v[20:23], v[144:147], v[220:223], v[20:23]
	v_mfma_f32_16x16x32_bf16 v[12:15], v[152:155], v[220:223], v[12:15]
	v_mfma_f32_16x16x32_bf16 v[4:7], v[144:147], v[228:231], v[4:7]
	v_mfma_f32_16x16x32_bf16 v[0:3], v[152:155], v[228:231], v[0:3]
	v_mfma_f32_16x16x32_bf16 v[52:55], v[148:151], v[206:209], v[52:55]
	v_mfma_f32_16x16x32_bf16 v[44:47], v[156:159], v[206:209], v[44:47]
	v_mfma_f32_16x16x32_bf16 v[36:39], v[148:151], v[214:217], v[36:39]
	v_mfma_f32_16x16x32_bf16 v[28:31], v[156:159], v[214:217], v[28:31]
	v_mfma_f32_16x16x32_bf16 v[20:23], v[148:151], v[224:227], v[20:23]
	v_mfma_f32_16x16x32_bf16 v[12:15], v[156:159], v[224:227], v[12:15]
	v_mfma_f32_16x16x32_bf16 v[4:7], v[148:151], v[232:235], v[4:7]
	v_mfma_f32_16x16x32_bf16 v[0:3], v[156:159], v[232:235], v[0:3]
	s_barrier
	s_add_i32 s68, s68, 2
	s_add_u32 s91, s91, 0x10000
	s_addc_u32 s92, s92, 0
	s_add_u32 s0, s0, 0x100
	s_addc_u32 s1, s1, 0
	s_cmp_gt_u32 s68, 13
.LBB0_646:
	ds_read_b128 v[128:131], v197
	ds_read_b128 v[132:135], v197 offset:1024
	ds_read_b128 v[136:139], v197 offset:2048
	ds_read_b128 v[140:143], v197 offset:3072
	ds_read_b128 v[144:147], v198
	ds_read_b128 v[148:151], v198 offset:1024
	ds_read_b128 v[152:155], v198 offset:2048
	ds_read_b128 v[156:159], v198 offset:3072
	s_add_u32 s8, s0, 0xfff10080
	s_addc_u32 s9, s1, -1
	s_cmp_eq_u32 s68, 12
	s_cselect_b32 s67, s63, s9
	s_cselect_b32 s66, s62, s8
	s_cselect_b32 s9, s61, s92
	s_cselect_b32 s8, s90, s91
	v_lshl_add_u64 v[236:237], s[0:1], 0, v[174:175]
	s_add_i32 m0, s17, 0xc000
	ds_read_b128 v[202:205], v199
	ds_read_b128 v[206:209], v199 offset:1024
	ds_read_b128 v[210:213], v199 offset:2048
	ds_read_b128 v[214:217], v199 offset:3072
	ds_read_b128 v[220:223], v199 offset:4096
	ds_read_b128 v[224:227], v199 offset:5120
	ds_read_b128 v[228:231], v199 offset:6144
	ds_read_b128 v[232:235], v199 offset:7168
	global_load_lds_dwordx4 v[236:237], off
	v_lshl_add_u64 v[236:237], s[0:1], 0, v[176:177]
	s_add_i32 m0, s17, 0xe000
	s_nop 0
	global_load_lds_dwordx4 v[236:237], off
	s_waitcnt vmcnt(8)
	s_waitcnt lgkmcnt(0)
	s_barrier
; #define PG8_STAGE(bufoff, gbase, voff) do { _Pragma("unroll") for (int _i = 0; _i < 2; ++_i) \
;         __builtin_amdgcn_global_load_lds((const unsigned*)((const char*)(gbase) + (voff)[_i]), (PG8_LAS unsigned*)(lds + (bufoff) + ldsw + _i * 8192), 16, 0, 0); } while (0)
; #define PG8_LDA(dst, b, h) do { _Pragma("unroll") for (int m = 0; m < 4; ++m) _Pragma("unroll") for (int k = 0; k < 2; ++k) dst[m][k] = *(const PG8_LAS bf16x8*)(lds + PG8_SA(b, h) + aoff + m * 2048 + k * 1024); } while (0)
; #define PG8_MMA(ai, bj, At, Bt) do { __builtin_amdgcn_s_setprio(1); _Pragma("unroll") for (int m = 0; m < 4; ++m) _Pragma("unroll") for (int n = 0; n < 2; ++n) _Pragma("unroll") for (int k = 0; k < 2; ++k) \
;         acc[ai][bj][m][n] = __builtin_amdgcn_mfma_f32_16x16x32_bf16(Bt[n][k], At[m][k], acc[ai][bj][m][n], 0, 0, 0); __builtin_amdgcn_s_setprio(0); } while (0)
; #define PG8_WAIT_V(n) asm volatile("s_waitcnt vmcnt(" #n ")" ::: "memory")
; #define PG8_WAIT_L(n) asm volatile("s_waitcnt lgkmcnt(" #n ")" ::: "memory")
; #define PG8_BAR __builtin_amdgcn_s_barrier()
; #define PG8_SCHED __builtin_amdgcn_sched_barrier(0)
; template <class Epi, class Sched, bool ALIGN_EPI = false, bool SP2 = false>
; __device__ __forceinline__ void gemm_phase(PG8_LAS unsigned char* lds, const Gemm g, const Sched& S, const Epi& E) {
;     ...
;             PG8_WAIT_V(8); PG8_WAIT_L(0); PG8_BAR; PG8_MMA(0, 0, At, B0); PG8_MMA(0, 1, At, B1); PG8_BAR; PG8_SCHED;
;             PG8_LDA(At, 0, 1); PG8_STAGE(PG8_SB(0, 0), b2, voffB); PG8_STAGE(PG8_SB(0, 1), b2 + hstepB, voffB); PG8_STAGE(PG8_SA(0, 0), a2, voffA);
;             PG8_WAIT_V(8); PG8_WAIT_L(0); PG8_BAR; PG8_MMA(1, 0, At, B0); PG8_MMA(1, 1, At, B1); PG8_BAR; PG8_SCHED;
	s_waitcnt lgkmcnt(0)
	v_mfma_f32_16x16x32_bf16 v[124:127], v[128:131], v[202:205], v[124:127]
	v_mfma_f32_16x16x32_bf16 v[120:123], v[136:139], v[202:205], v[120:123]
	v_mfma_f32_16x16x32_bf16 v[108:111], v[128:131], v[210:213], v[108:111]
	v_mfma_f32_16x16x32_bf16 v[104:107], v[136:139], v[210:213], v[104:107]
	v_mfma_f32_16x16x32_bf16 v[96:99], v[128:131], v[220:223], v[96:99]
	v_mfma_f32_16x16x32_bf16 v[88:91], v[136:139], v[220:223], v[88:91]
	v_mfma_f32_16x16x32_bf16 v[80:83], v[128:131], v[228:231], v[80:83]
	v_mfma_f32_16x16x32_bf16 v[72:75], v[136:139], v[228:231], v[72:75]
	v_mfma_f32_16x16x32_bf16 v[124:127], v[132:135], v[206:209], v[124:127]
	v_mfma_f32_16x16x32_bf16 v[120:123], v[140:143], v[206:209], v[120:123]
	v_mfma_f32_16x16x32_bf16 v[108:111], v[132:135], v[214:217], v[108:111]
	v_mfma_f32_16x16x32_bf16 v[104:107], v[140:143], v[214:217], v[104:107]
	v_mfma_f32_16x16x32_bf16 v[96:99], v[132:135], v[224:227], v[96:99]
	v_mfma_f32_16x16x32_bf16 v[88:91], v[140:143], v[224:227], v[88:91]
	v_mfma_f32_16x16x32_bf16 v[80:83], v[132:135], v[232:235], v[80:83]
	v_mfma_f32_16x16x32_bf16 v[72:75], v[140:143], v[232:235], v[72:75]
	v_mfma_f32_16x16x32_bf16 v[116:119], v[144:147], v[202:205], v[116:119]
	v_mfma_f32_16x16x32_bf16 v[112:115], v[152:155], v[202:205], v[112:115]
	v_mfma_f32_16x16x32_bf16 v[100:103], v[144:147], v[210:213], v[100:103]
	v_mfma_f32_16x16x32_bf16 v[92:95], v[152:155], v[210:213], v[92:95]
	v_mfma_f32_16x16x32_bf16 v[84:87], v[144:147], v[220:223], v[84:87]
	v_mfma_f32_16x16x32_bf16 v[76:79], v[152:155], v[220:223], v[76:79]
	v_mfma_f32_16x16x32_bf16 v[68:71], v[144:147], v[228:231], v[68:71]
	v_mfma_f32_16x16x32_bf16 v[64:67], v[152:155], v[228:231], v[64:67]
	v_mfma_f32_16x16x32_bf16 v[116:119], v[148:151], v[206:209], v[116:119]
	v_mfma_f32_16x16x32_bf16 v[112:115], v[156:159], v[206:209], v[112:115]
	v_mfma_f32_16x16x32_bf16 v[100:103], v[148:151], v[214:217], v[100:103]
	v_mfma_f32_16x16x32_bf16 v[92:95], v[156:159], v[214:217], v[92:95]
	v_mfma_f32_16x16x32_bf16 v[84:87], v[148:151], v[224:227], v[84:87]
	v_mfma_f32_16x16x32_bf16 v[76:79], v[156:159], v[224:227], v[76:79]
	v_mfma_f32_16x16x32_bf16 v[68:71], v[148:151], v[232:235], v[68:71]
	v_mfma_f32_16x16x32_bf16 v[64:67], v[156:159], v[232:235], v[64:67]
	s_barrier
	v_lshl_add_u64 v[236:237], s[8:9], 0, v[190:191]
	s_add_i32 s8, s77, s15
	s_mov_b32 m0, s8
	ds_read_b128 v[202:205], v199 offset:16384
	ds_read_b128 v[206:209], v199 offset:17408
	ds_read_b128 v[210:213], v199 offset:18432
	ds_read_b128 v[214:217], v199 offset:19456
	ds_read_b128 v[220:223], v199 offset:20480
	ds_read_b128 v[224:227], v199 offset:21504
	ds_read_b128 v[228:231], v199 offset:22528
	ds_read_b128 v[232:235], v199 offset:23552
	global_load_lds_dwordx4 v[236:237], off
	v_lshl_add_u64 v[238:239], v[236:237], 0, s[36:37]
	s_add_i32 m0, s8, 0x2000
	s_add_i32 s8, s80, s15
	global_load_lds_dwordx4 v[238:239], off
	v_lshl_add_u64 v[238:239], v[236:237], 0, s[38:39]
	s_mov_b32 m0, s8
	v_lshl_add_u64 v[240:241], s[66:67], 0, v[162:163]
	global_load_lds_dwordx4 v[238:239], off
	v_lshl_add_u64 v[238:239], v[236:237], 0, s[40:41]
	s_add_i32 m0, s8, 0x2000
	s_nop 0
	global_load_lds_dwordx4 v[238:239], off
	v_lshl_add_u64 v[238:239], s[66:67], 0, v[160:161]
	s_mov_b32 m0, s17
	s_nop 0
	global_load_lds_dwordx4 v[238:239], off
	s_mov_b32 m0, s18
	s_nop 0
	global_load_lds_dwordx4 v[240:241], off
	s_waitcnt vmcnt(8)
	s_waitcnt lgkmcnt(0)
	s_barrier
	s_waitcnt lgkmcnt(0)
	v_mfma_f32_16x16x32_bf16 v[60:63], v[128:131], v[202:205], v[60:63]
	v_mfma_f32_16x16x32_bf16 v[56:59], v[136:139], v[202:205], v[56:59]
	v_mfma_f32_16x16x32_bf16 v[48:51], v[128:131], v[210:213], v[48:51]
	v_mfma_f32_16x16x32_bf16 v[40:43], v[136:139], v[210:213], v[40:43]
	v_mfma_f32_16x16x32_bf16 v[32:35], v[128:131], v[220:223], v[32:35]
	v_mfma_f32_16x16x32_bf16 v[24:27], v[136:139], v[220:223], v[24:27]
	v_mfma_f32_16x16x32_bf16 v[16:19], v[128:131], v[228:231], v[16:19]
	v_mfma_f32_16x16x32_bf16 v[8:11], v[136:139], v[228:231], v[8:11]
	v_mfma_f32_16x16x32_bf16 v[60:63], v[132:135], v[206:209], v[60:63]
	v_mfma_f32_16x16x32_bf16 v[56:59], v[140:143], v[206:209], v[56:59]
	v_mfma_f32_16x16x32_bf16 v[48:51], v[132:135], v[214:217], v[48:51]
	v_mfma_f32_16x16x32_bf16 v[40:43], v[140:143], v[214:217], v[40:43]
	v_mfma_f32_16x16x32_bf16 v[32:35], v[132:135], v[224:227], v[32:35]
	v_mfma_f32_16x16x32_bf16 v[24:27], v[140:143], v[224:227], v[24:27]
	v_mfma_f32_16x16x32_bf16 v[16:19], v[132:135], v[232:235], v[16:19]
	v_mfma_f32_16x16x32_bf16 v[8:11], v[140:143], v[232:235], v[8:11]
	v_mfma_f32_16x16x32_bf16 v[52:55], v[144:147], v[202:205], v[52:55]
	v_mfma_f32_16x16x32_bf16 v[44:47], v[152:155], v[202:205], v[44:47]
	v_mfma_f32_16x16x32_bf16 v[36:39], v[144:147], v[210:213], v[36:39]
	v_mfma_f32_16x16x32_bf16 v[28:31], v[152:155], v[210:213], v[28:31]
	v_mfma_f32_16x16x32_bf16 v[20:23], v[144:147], v[220:223], v[20:23]
	v_mfma_f32_16x16x32_bf16 v[12:15], v[152:155], v[220:223], v[12:15]
	v_mfma_f32_16x16x32_bf16 v[4:7], v[144:147], v[228:231], v[4:7]
	v_mfma_f32_16x16x32_bf16 v[0:3], v[152:155], v[228:231], v[0:3]
	v_mfma_f32_16x16x32_bf16 v[52:55], v[148:151], v[206:209], v[52:55]
	v_mfma_f32_16x16x32_bf16 v[44:47], v[156:159], v[206:209], v[44:47]
	v_mfma_f32_16x16x32_bf16 v[36:39], v[148:151], v[214:217], v[36:39]
	v_mfma_f32_16x16x32_bf16 v[28:31], v[156:159], v[214:217], v[28:31]
	v_mfma_f32_16x16x32_bf16 v[20:23], v[148:151], v[224:227], v[20:23]
	v_mfma_f32_16x16x32_bf16 v[12:15], v[156:159], v[224:227], v[12:15]
	v_mfma_f32_16x16x32_bf16 v[4:7], v[148:151], v[232:235], v[4:7]
	v_mfma_f32_16x16x32_bf16 v[0:3], v[156:159], v[232:235], v[0:3]
	s_barrier
; #define PG8_STAGE(bufoff, gbase, voff) do { _Pragma("unroll") for (int _i = 0; _i < 2; ++_i) \
;         __builtin_amdgcn_global_load_lds((const unsigned*)((const char*)(gbase) + (voff)[_i]), (PG8_LAS unsigned*)(lds + (bufoff) + ldsw + _i * 8192), 16, 0, 0); } while (0)
; #define PG8_LDA(dst, b, h) do { _Pragma("unroll") for (int m = 0; m < 4; ++m) _Pragma("unroll") for (int k = 0; k < 2; ++k) dst[m][k] = *(const PG8_LAS bf16x8*)(lds + PG8_SA(b, h) + aoff + m * 2048 + k * 1024); } while (0)
; #define PG8_LDB(dst, b, h) do { _Pragma("unroll") for (int n = 0; n < 2; ++n) _Pragma("unroll") for (int k = 0; k < 2; ++k) dst[n][k] = *(const PG8_LAS bf16x8*)(lds + PG8_SB(b, h) + boff + n * 2048 + k * 1024); } while (0)
; #define PG8_MMA(ai, bj, At, Bt) do { __builtin_amdgcn_s_setprio(1); _Pragma("unroll") for (int m = 0; m < 4; ++m) _Pragma("unroll") for (int n = 0; n < 2; ++n) _Pragma("unroll") for (int k = 0; k < 2; ++k) \
;         acc[ai][bj][m][n] = __builtin_amdgcn_mfma_f32_16x16x32_bf16(Bt[n][k], At[m][k], acc[ai][bj][m][n], 0, 0, 0); __builtin_amdgcn_s_setprio(0); } while (0)
; #define PG8_WAIT_V(n) asm volatile("s_waitcnt vmcnt(" #n ")" ::: "memory")
; #define PG8_WAIT_L(n) asm volatile("s_waitcnt lgkmcnt(" #n ")" ::: "memory")
; #define PG8_BAR __builtin_amdgcn_s_barrier()
; #define PG8_SCHED __builtin_amdgcn_sched_barrier(0)
; template <class Epi, class Sched, bool ALIGN_EPI = false, bool SP2 = false>
; __device__ __forceinline__ void gemm_phase(PG8_LAS unsigned char* lds, const Gemm g, const Sched& S, const Epi& E) {
;     ...
;             PG8_LDB(B0, 1, 0); PG8_LDB(B1, 1, 1); PG8_SCHED; PG8_LDA(At, 1, 0); PG8_STAGE(PG8_SA(0, 1), a2 + hstepA, voffA);
;             PG8_WAIT_V(8); PG8_WAIT_L(0); PG8_BAR; PG8_MMA(0, 0, At, B0); PG8_MMA(0, 1, At, B1); PG8_BAR; PG8_SCHED;
;             PG8_LDA(At, 1, 1); PG8_STAGE(PG8_SB(1, 0), b3, voffB); PG8_STAGE(PG8_SB(1, 1), b3 + hstepB, voffB); PG8_STAGE(PG8_SA(1, 0), a3, voffA);
;             PG8_WAIT_V(8); PG8_WAIT_L(0); PG8_BAR; PG8_MMA(1, 0, At, B0); PG8_MMA(1, 1, At, B1); PG8_BAR; PG8_SCHED;
	ds_read_b128 v[128:131], v200
	ds_read_b128 v[132:135], v200 offset:1024
	ds_read_b128 v[136:139], v200 offset:2048
	ds_read_b128 v[140:143], v200 offset:3072
	ds_read_b128 v[144:147], v201
	ds_read_b128 v[148:151], v201 offset:1024
	ds_read_b128 v[152:155], v201 offset:2048
	ds_read_b128 v[156:159], v201 offset:3072
	s_add_u32 s8, s66, 0xf0000
	s_addc_u32 s9, s67, 0
	s_mov_b32 m0, s19
	v_lshl_add_u64 v[242:243], s[8:9], 0, v[160:161]
	ds_read_b128 v[202:205], v199 offset:32768
	ds_read_b128 v[206:209], v199 offset:33792
	ds_read_b128 v[210:213], v199 offset:34816
	ds_read_b128 v[214:217], v199 offset:35840
	ds_read_b128 v[220:223], v199 offset:36864
	ds_read_b128 v[224:227], v199 offset:37888
	ds_read_b128 v[228:231], v199 offset:38912
	ds_read_b128 v[232:235], v199 offset:39936
	global_load_lds_dwordx4 v[242:243], off
	v_lshl_add_u64 v[242:243], s[8:9], 0, v[162:163]
	s_mov_b32 m0, s59
	s_nop 0
	global_load_lds_dwordx4 v[242:243], off
	s_waitcnt vmcnt(8)
	s_waitcnt lgkmcnt(0)
	s_barrier
	s_waitcnt lgkmcnt(0)
	v_mfma_f32_16x16x32_bf16 v[124:127], v[128:131], v[202:205], v[124:127]
	v_mfma_f32_16x16x32_bf16 v[120:123], v[136:139], v[202:205], v[120:123]
	v_mfma_f32_16x16x32_bf16 v[108:111], v[128:131], v[210:213], v[108:111]
	v_mfma_f32_16x16x32_bf16 v[104:107], v[136:139], v[210:213], v[104:107]
	v_mfma_f32_16x16x32_bf16 v[96:99], v[128:131], v[220:223], v[96:99]
	v_mfma_f32_16x16x32_bf16 v[88:91], v[136:139], v[220:223], v[88:91]
	v_mfma_f32_16x16x32_bf16 v[80:83], v[128:131], v[228:231], v[80:83]
	v_mfma_f32_16x16x32_bf16 v[72:75], v[136:139], v[228:231], v[72:75]
	v_mfma_f32_16x16x32_bf16 v[124:127], v[132:135], v[206:209], v[124:127]
	v_mfma_f32_16x16x32_bf16 v[120:123], v[140:143], v[206:209], v[120:123]
	v_mfma_f32_16x16x32_bf16 v[108:111], v[132:135], v[214:217], v[108:111]
	v_mfma_f32_16x16x32_bf16 v[104:107], v[140:143], v[214:217], v[104:107]
	v_mfma_f32_16x16x32_bf16 v[96:99], v[132:135], v[224:227], v[96:99]
	v_mfma_f32_16x16x32_bf16 v[88:91], v[140:143], v[224:227], v[88:91]
	v_mfma_f32_16x16x32_bf16 v[80:83], v[132:135], v[232:235], v[80:83]
	v_mfma_f32_16x16x32_bf16 v[72:75], v[140:143], v[232:235], v[72:75]
	v_mfma_f32_16x16x32_bf16 v[116:119], v[144:147], v[202:205], v[116:119]
	v_mfma_f32_16x16x32_bf16 v[112:115], v[152:155], v[202:205], v[112:115]
	v_mfma_f32_16x16x32_bf16 v[100:103], v[144:147], v[210:213], v[100:103]
	v_mfma_f32_16x16x32_bf16 v[92:95], v[152:155], v[210:213], v[92:95]
	v_mfma_f32_16x16x32_bf16 v[84:87], v[144:147], v[220:223], v[84:87]
	v_mfma_f32_16x16x32_bf16 v[76:79], v[152:155], v[220:223], v[76:79]
	v_mfma_f32_16x16x32_bf16 v[68:71], v[144:147], v[228:231], v[68:71]
	v_mfma_f32_16x16x32_bf16 v[64:67], v[152:155], v[228:231], v[64:67]
	v_mfma_f32_16x16x32_bf16 v[116:119], v[148:151], v[206:209], v[116:119]
	v_mfma_f32_16x16x32_bf16 v[112:115], v[156:159], v[206:209], v[112:115]
	v_mfma_f32_16x16x32_bf16 v[100:103], v[148:151], v[214:217], v[100:103]
	v_mfma_f32_16x16x32_bf16 v[92:95], v[156:159], v[214:217], v[92:95]
	v_mfma_f32_16x16x32_bf16 v[84:87], v[148:151], v[224:227], v[84:87]
	v_mfma_f32_16x16x32_bf16 v[76:79], v[156:159], v[224:227], v[76:79]
	v_mfma_f32_16x16x32_bf16 v[68:71], v[148:151], v[232:235], v[68:71]
	v_mfma_f32_16x16x32_bf16 v[64:67], v[156:159], v[232:235], v[64:67]
	s_barrier
	s_add_i32 s8, s81, s15
	v_lshl_add_u64 v[242:243], v[236:237], 0, s[42:43]
	s_mov_b32 m0, s8
	ds_read_b128 v[202:205], v199 offset:49152
	ds_read_b128 v[206:209], v199 offset:50176
	ds_read_b128 v[210:213], v199 offset:51200
	ds_read_b128 v[214:217], v199 offset:52224
	ds_read_b128 v[220:223], v199 offset:53248
	ds_read_b128 v[224:227], v199 offset:54272
	ds_read_b128 v[228:231], v199 offset:55296
	ds_read_b128 v[232:235], v199 offset:56320
	global_load_lds_dwordx4 v[242:243], off
	v_lshl_add_u64 v[242:243], v[236:237], 0, s[44:45]
	s_add_i32 m0, s8, 0x2000
	s_add_i32 s8, s82, s15
	global_load_lds_dwordx4 v[242:243], off
	v_lshl_add_u64 v[242:243], v[236:237], 0, s[48:49]
	s_mov_b32 m0, s8
	v_lshl_add_u64 v[236:237], v[236:237], 0, s[52:53]
	global_load_lds_dwordx4 v[242:243], off
	s_add_i32 m0, s8, 0x2000
	s_nop 0
	global_load_lds_dwordx4 v[236:237], off
	v_lshl_add_u64 v[236:237], v[238:239], 0, s[46:47]
	s_mov_b32 m0, s70
	s_nop 0
	global_load_lds_dwordx4 v[236:237], off
	v_lshl_add_u64 v[236:237], v[240:241], 0, s[46:47]
	s_mov_b32 m0, s71
	s_nop 0
	global_load_lds_dwordx4 v[236:237], off
	s_waitcnt vmcnt(8)
	s_waitcnt lgkmcnt(0)
	s_barrier
	s_waitcnt lgkmcnt(0)
	v_mfma_f32_16x16x32_bf16 v[60:63], v[128:131], v[202:205], v[60:63]
	v_mfma_f32_16x16x32_bf16 v[56:59], v[136:139], v[202:205], v[56:59]
	v_mfma_f32_16x16x32_bf16 v[48:51], v[128:131], v[210:213], v[48:51]
	v_mfma_f32_16x16x32_bf16 v[40:43], v[136:139], v[210:213], v[40:43]
	v_mfma_f32_16x16x32_bf16 v[32:35], v[128:131], v[220:223], v[32:35]
	v_mfma_f32_16x16x32_bf16 v[24:27], v[136:139], v[220:223], v[24:27]
	v_mfma_f32_16x16x32_bf16 v[16:19], v[128:131], v[228:231], v[16:19]
	v_mfma_f32_16x16x32_bf16 v[8:11], v[136:139], v[228:231], v[8:11]
	v_mfma_f32_16x16x32_bf16 v[60:63], v[132:135], v[206:209], v[60:63]
	v_mfma_f32_16x16x32_bf16 v[56:59], v[140:143], v[206:209], v[56:59]
	v_mfma_f32_16x16x32_bf16 v[48:51], v[132:135], v[214:217], v[48:51]
	v_mfma_f32_16x16x32_bf16 v[40:43], v[140:143], v[214:217], v[40:43]
	v_mfma_f32_16x16x32_bf16 v[32:35], v[132:135], v[224:227], v[32:35]
	v_mfma_f32_16x16x32_bf16 v[24:27], v[140:143], v[224:227], v[24:27]
	v_mfma_f32_16x16x32_bf16 v[16:19], v[132:135], v[232:235], v[16:19]
	v_mfma_f32_16x16x32_bf16 v[8:11], v[140:143], v[232:235], v[8:11]
	v_mfma_f32_16x16x32_bf16 v[52:55], v[144:147], v[202:205], v[52:55]
	v_mfma_f32_16x16x32_bf16 v[44:47], v[152:155], v[202:205], v[44:47]
	v_mfma_f32_16x16x32_bf16 v[36:39], v[144:147], v[210:213], v[36:39]
	v_mfma_f32_16x16x32_bf16 v[28:31], v[152:155], v[210:213], v[28:31]
	v_mfma_f32_16x16x32_bf16 v[20:23], v[144:147], v[220:223], v[20:23]
	v_mfma_f32_16x16x32_bf16 v[12:15], v[152:155], v[220:223], v[12:15]
	v_mfma_f32_16x16x32_bf16 v[4:7], v[144:147], v[228:231], v[4:7]
	v_mfma_f32_16x16x32_bf16 v[0:3], v[152:155], v[228:231], v[0:3]
	v_mfma_f32_16x16x32_bf16 v[52:55], v[148:151], v[206:209], v[52:55]
	v_mfma_f32_16x16x32_bf16 v[44:47], v[156:159], v[206:209], v[44:47]
	v_mfma_f32_16x16x32_bf16 v[36:39], v[148:151], v[214:217], v[36:39]
	v_mfma_f32_16x16x32_bf16 v[28:31], v[156:159], v[214:217], v[28:31]
	v_mfma_f32_16x16x32_bf16 v[20:23], v[148:151], v[224:227], v[20:23]
	v_mfma_f32_16x16x32_bf16 v[12:15], v[156:159], v[224:227], v[12:15]
	v_mfma_f32_16x16x32_bf16 v[4:7], v[148:151], v[232:235], v[4:7]
	v_mfma_f32_16x16x32_bf16 v[0:3], v[156:159], v[232:235], v[0:3]
	s_barrier
	s_add_i32 s68, s68, 2
	s_add_u32 s91, s91, 0x10000
	s_addc_u32 s92, s92, 0
	s_add_u32 s0, s0, 0x100
	s_addc_u32 s1, s1, 0
	s_cmp_gt_u32 s68, 13
	s_cbranch_scc0 .LBB0_646
	s_and_b64 vcc, exec, s[56:57]
	s_cbranch_vccz .LBB0_649
	s_barrier

; #define PG8_STAGE(bufoff, gbase, voff) do { _Pragma("unroll") for (int _i = 0; _i < 2; ++_i) \
;         __builtin_amdgcn_global_load_lds((const unsigned*)((const char*)(gbase) + (voff)[_i]), (PG8_LAS unsigned*)(lds + (bufoff) + ldsw + _i * 8192), 16, 0, 0); } while (0)
; #define PG8_LDA(dst, b, h) do { _Pragma("unroll") for (int m = 0; m < 4; ++m) _Pragma("unroll") for (int k = 0; k < 2; ++k) dst[m][k] = *(const PG8_LAS bf16x8*)(lds + PG8_SA(b, h) + aoff + m * 2048 + k * 1024); } while (0)
; #define PG8_LDB(dst, b, h) do { _Pragma("unroll") for (int n = 0; n < 2; ++n) _Pragma("unroll") for (int k = 0; k < 2; ++k) dst[n][k] = *(const PG8_LAS bf16x8*)(lds + PG8_SB(b, h) + boff + n * 2048 + k * 1024); } while (0)
; #define PG8_MMA(ai, bj, At, Bt) do { __builtin_amdgcn_s_setprio(1); _Pragma("unroll") for (int m = 0; m < 4; ++m) _Pragma("unroll") for (int n = 0; n < 2; ++n) _Pragma("unroll") for (int k = 0; k < 2; ++k) \
;         acc[ai][bj][m][n] = __builtin_amdgcn_mfma_f32_16x16x32_bf16(Bt[n][k], At[m][k], acc[ai][bj][m][n], 0, 0, 0); __builtin_amdgcn_s_setprio(0); } while (0)
; #define PG8_BAR __builtin_amdgcn_s_barrier()
; template <class Epi, class Sched, bool ALIGN_EPI = false, bool SP2 = false>
; __device__ __forceinline__ void gemm_phase(PG8_LAS unsigned char* lds, const Gemm g, const Sched& S, const Epi& E) {
;     ...
;         const bool has_next = S.next(ui + 1, nxt);
;         const char* nA = has_next ? (const char*)g.A + (size_t)nxt.pm * tstepA : cA; const char* nB = has_next ? (const char*)g.Bt + (size_t)nxt.pn * tstepB : cB;
;         for (int t = 0; t < nt; t += 2) {
;             const bool last = (t == nt - 2);
;             const char* a1 = cA + (size_t)(t + 1) * kstepA;
;             const char* a2 = last ? nA : cA + (size_t)(t + 2) * kstepA; const char* b2 = last ? nB : cB + (size_t)(t + 2) * kstep;
;             const char* a3 = a2 + kstepA; const char* b3 = b2 + kstep;
;             if (last && has_next) S.a_ready(nxt);
;             if constexpr (SP2) {
;             PG8_LDB(B0, 0, 0); PG8_LDB(B1, 0, 1); PG8_SCHED; PG8_LDA(At, 0, 0); PG8_STAGE(PG8_SA(1, 1), a1 + hstepA, voffA);
;             PG8_WAIT_V(8); PG8_WAIT_L(0); PG8_BAR; PG8_MMA(0, 0, At, B0); PG8_MMA(0, 1, At, B1); PG8_BAR; PG8_SCHED;
;             PG8_LDA(At, 0, 1); PG8_STAGE(PG8_SB(0, 0), b2, voffB); PG8_STAGE(PG8_SB(0, 1), b2 + hstepB, voffB); PG8_STAGE(PG8_SA(0, 0), a2, voffA);
.LBB0_669:
	s_ashr_i32 s57, s56, 31
	s_lshl_b64 s[8:9], s[56:57], 18
	s_add_u32 s58, s30, s8
	s_addc_u32 s59, s31, s9
	s_and_b64 s[8:9], s[2:3], exec
	s_cselect_b32 s57, s59, s67
	s_cselect_b32 s68, s58, s66
	s_ashr_i32 s55, s54, 31
	s_lshl_b64 s[8:9], s[54:55], 18
	v_readlane_b32 s60, v246, 7
	v_readlane_b32 s61, v246, 8
	s_add_u32 s60, s60, s8
	s_addc_u32 s61, s61, s9
	s_and_b64 s[8:9], s[2:3], exec
	s_cselect_b32 s55, s61, s65
	s_cselect_b32 s69, s60, s64
	s_add_u32 s82, s64, 0x10000
	s_addc_u32 s85, s65, 0
	s_add_u32 s64, s66, 0x20080
	s_addc_u32 s65, s67, 0
	s_mov_b32 s86, -2
	ds_read_b128 v[108:111], v200
	ds_read_b128 v[132:135], v200 offset:1024
	ds_read_b128 v[136:139], v200 offset:2048
	ds_read_b128 v[140:143], v200 offset:3072
	ds_read_b128 v[144:147], v201
	ds_read_b128 v[148:151], v201 offset:1024
	ds_read_b128 v[152:155], v201 offset:2048
	ds_read_b128 v[156:159], v201 offset:3072
	s_add_u32 s8, s64, 0xfffe0080
	s_addc_u32 s9, s65, -1
	s_cmp_eq_u32 s86, 4
	s_cselect_b32 s67, s57, s9
	s_cselect_b32 s66, s68, s8
	s_cselect_b32 s9, s55, s85
	s_cselect_b32 s8, s69, s82
	v_lshl_add_u64 v[216:217], s[64:65], 0, v[186:187]
	s_add_i32 m0, s17, 0xc000
	ds_read_b128 v[160:163], v202
	ds_read_b128 v[164:167], v202 offset:1024
	ds_read_b128 v[168:171], v202 offset:2048
	ds_read_b128 v[204:207], v202 offset:3072
	ds_read_b128 v[208:211], v202 offset:4096
	ds_read_b128 v[212:215], v202 offset:5120
	ds_read_b128 v[220:223], v202 offset:6144
	ds_read_b128 v[224:227], v202 offset:7168
	global_load_lds_dwordx4 v[216:217], off
	v_lshl_add_u64 v[216:217], s[64:65], 0, v[192:193]
	s_add_i32 m0, s17, 0xe000
	s_nop 0
	global_load_lds_dwordx4 v[216:217], off
	s_waitcnt vmcnt(8)
	s_waitcnt lgkmcnt(0)
	s_barrier
	s_waitcnt lgkmcnt(0)
	v_mfma_f32_16x16x32_bf16 v[128:131], v[108:111], v[160:163], 0
	v_mfma_f32_16x16x32_bf16 v[124:127], v[136:139], v[160:163], 0
	v_mfma_f32_16x16x32_bf16 v[112:115], v[108:111], v[168:171], 0
	v_mfma_f32_16x16x32_bf16 v[104:107], v[136:139], v[168:171], 0
	v_mfma_f32_16x16x32_bf16 v[92:95], v[108:111], v[208:211], 0
	v_mfma_f32_16x16x32_bf16 v[88:91], v[136:139], v[208:211], 0
	v_mfma_f32_16x16x32_bf16 v[76:79], v[108:111], v[220:223], 0
	v_mfma_f32_16x16x32_bf16 v[72:75], v[136:139], v[220:223], 0
	v_mfma_f32_16x16x32_bf16 v[128:131], v[132:135], v[164:167], v[128:131]
	v_mfma_f32_16x16x32_bf16 v[124:127], v[140:143], v[164:167], v[124:127]
	v_mfma_f32_16x16x32_bf16 v[112:115], v[132:135], v[204:207], v[112:115]
	v_mfma_f32_16x16x32_bf16 v[104:107], v[140:143], v[204:207], v[104:107]
	v_mfma_f32_16x16x32_bf16 v[92:95], v[132:135], v[212:215], v[92:95]
	v_mfma_f32_16x16x32_bf16 v[88:91], v[140:143], v[212:215], v[88:91]
	v_mfma_f32_16x16x32_bf16 v[76:79], v[132:135], v[224:227], v[76:79]
	v_mfma_f32_16x16x32_bf16 v[72:75], v[140:143], v[224:227], v[72:75]
	v_mfma_f32_16x16x32_bf16 v[120:123], v[144:147], v[160:163], 0
	v_mfma_f32_16x16x32_bf16 v[116:119], v[152:155], v[160:163], 0
	v_mfma_f32_16x16x32_bf16 v[100:103], v[144:147], v[168:171], 0
	v_mfma_f32_16x16x32_bf16 v[96:99], v[152:155], v[168:171], 0
	v_mfma_f32_16x16x32_bf16 v[84:87], v[144:147], v[208:211], 0
	v_mfma_f32_16x16x32_bf16 v[80:83], v[152:155], v[208:211], 0
	v_mfma_f32_16x16x32_bf16 v[68:71], v[144:147], v[220:223], 0
	v_mfma_f32_16x16x32_bf16 v[64:67], v[152:155], v[220:223], 0
	v_mfma_f32_16x16x32_bf16 v[120:123], v[148:151], v[164:167], v[120:123]
	v_mfma_f32_16x16x32_bf16 v[116:119], v[156:159], v[164:167], v[116:119]
	v_mfma_f32_16x16x32_bf16 v[100:103], v[148:151], v[204:207], v[100:103]
	v_mfma_f32_16x16x32_bf16 v[96:99], v[156:159], v[204:207], v[96:99]
	v_mfma_f32_16x16x32_bf16 v[84:87], v[148:151], v[212:215], v[84:87]
	v_mfma_f32_16x16x32_bf16 v[80:83], v[156:159], v[212:215], v[80:83]
	v_mfma_f32_16x16x32_bf16 v[68:71], v[148:151], v[224:227], v[68:71]
	v_mfma_f32_16x16x32_bf16 v[64:67], v[156:159], v[224:227], v[64:67]
	s_barrier
	v_lshl_add_u64 v[216:217], s[8:9], 0, v[190:191]
	s_add_i32 s8, s11, s15
	s_mov_b32 m0, s8
	ds_read_b128 v[160:163], v202 offset:16384
	ds_read_b128 v[164:167], v202 offset:17408
	ds_read_b128 v[168:171], v202 offset:18432
	ds_read_b128 v[204:207], v202 offset:19456
	ds_read_b128 v[208:211], v202 offset:20480
	ds_read_b128 v[212:215], v202 offset:21504
	ds_read_b128 v[220:223], v202 offset:22528
	ds_read_b128 v[224:227], v202 offset:23552
	global_load_lds_dwordx4 v[216:217], off
	v_lshl_add_u64 v[228:229], v[216:217], 0, s[0:1]
	s_add_i32 m0, s8, 0x2000
	s_add_i32 s8, s80, s15
	global_load_lds_dwordx4 v[228:229], off
	v_lshl_add_u64 v[228:229], v[216:217], 0, s[34:35]
	s_mov_b32 m0, s8
	v_lshl_add_u64 v[230:231], s[66:67], 0, v[174:175]
	global_load_lds_dwordx4 v[228:229], off
	v_lshl_add_u64 v[228:229], v[216:217], 0, s[36:37]
	s_add_i32 m0, s8, 0x2000
	s_nop 0
	global_load_lds_dwordx4 v[228:229], off
	v_lshl_add_u64 v[228:229], s[66:67], 0, v[172:173]
	s_mov_b32 m0, s17
	s_nop 0
	global_load_lds_dwordx4 v[228:229], off
	s_mov_b32 m0, s18
	s_nop 0
	global_load_lds_dwordx4 v[230:231], off
	s_waitcnt vmcnt(8)
	s_waitcnt lgkmcnt(0)
	s_barrier
; #define PG8_STAGE(bufoff, gbase, voff) do { _Pragma("unroll") for (int _i = 0; _i < 2; ++_i) \
;         __builtin_amdgcn_global_load_lds((const unsigned*)((const char*)(gbase) + (voff)[_i]), (PG8_LAS unsigned*)(lds + (bufoff) + ldsw + _i * 8192), 16, 0, 0); } while (0)
; #define PG8_LDA(dst, b, h) do { _Pragma("unroll") for (int m = 0; m < 4; ++m) _Pragma("unroll") for (int k = 0; k < 2; ++k) dst[m][k] = *(const PG8_LAS bf16x8*)(lds + PG8_SA(b, h) + aoff + m * 2048 + k * 1024); } while (0)
; #define PG8_LDB(dst, b, h) do { _Pragma("unroll") for (int n = 0; n < 2; ++n) _Pragma("unroll") for (int k = 0; k < 2; ++k) dst[n][k] = *(const PG8_LAS bf16x8*)(lds + PG8_SB(b, h) + boff + n * 2048 + k * 1024); } while (0)
; #define PG8_MMA(ai, bj, At, Bt) do { __builtin_amdgcn_s_setprio(1); _Pragma("unroll") for (int m = 0; m < 4; ++m) _Pragma("unroll") for (int n = 0; n < 2; ++n) _Pragma("unroll") for (int k = 0; k < 2; ++k) \
;         acc[ai][bj][m][n] = __builtin_amdgcn_mfma_f32_16x16x32_bf16(Bt[n][k], At[m][k], acc[ai][bj][m][n], 0, 0, 0); __builtin_amdgcn_s_setprio(0); } while (0)
; #define PG8_WAIT_V(n) asm volatile("s_waitcnt vmcnt(" #n ")" ::: "memory")
; #define PG8_WAIT_L(n) asm volatile("s_waitcnt lgkmcnt(" #n ")" ::: "memory")
; #define PG8_BAR __builtin_amdgcn_s_barrier()
; #define PG8_SCHED __builtin_amdgcn_sched_barrier(0)
; template <class Epi, class Sched, bool ALIGN_EPI = false, bool SP2 = false>
; __device__ __forceinline__ void gemm_phase(PG8_LAS unsigned char* lds, const Gemm g, const Sched& S, const Epi& E) {
;     ...
;             PG8_WAIT_V(8); PG8_WAIT_L(0); PG8_BAR; PG8_MMA(1, 0, At, B0); PG8_MMA(1, 1, At, B1); PG8_BAR; PG8_SCHED;
;             PG8_LDB(B0, 1, 0); PG8_LDB(B1, 1, 1); PG8_SCHED; PG8_LDA(At, 1, 0); PG8_STAGE(PG8_SA(0, 1), a2 + hstepA, voffA);
;             PG8_WAIT_V(8); PG8_WAIT_L(0); PG8_BAR; PG8_MMA(0, 0, At, B0); PG8_MMA(0, 1, At, B1); PG8_BAR; PG8_SCHED;
	s_waitcnt lgkmcnt(0)
	v_mfma_f32_16x16x32_bf16 v[60:63], v[108:111], v[160:163], 0
	v_mfma_f32_16x16x32_bf16 v[56:59], v[136:139], v[160:163], 0
	v_mfma_f32_16x16x32_bf16 v[44:47], v[108:111], v[168:171], 0
	v_mfma_f32_16x16x32_bf16 v[40:43], v[136:139], v[168:171], 0
	v_mfma_f32_16x16x32_bf16 v[28:31], v[108:111], v[208:211], 0
	v_mfma_f32_16x16x32_bf16 v[24:27], v[136:139], v[208:211], 0
	v_mfma_f32_16x16x32_bf16 v[12:15], v[108:111], v[220:223], 0
	v_mfma_f32_16x16x32_bf16 v[8:11], v[136:139], v[220:223], 0
	v_mfma_f32_16x16x32_bf16 v[60:63], v[132:135], v[164:167], v[60:63]
	v_mfma_f32_16x16x32_bf16 v[56:59], v[140:143], v[164:167], v[56:59]
	v_mfma_f32_16x16x32_bf16 v[44:47], v[132:135], v[204:207], v[44:47]
	v_mfma_f32_16x16x32_bf16 v[40:43], v[140:143], v[204:207], v[40:43]
	v_mfma_f32_16x16x32_bf16 v[28:31], v[132:135], v[212:215], v[28:31]
	v_mfma_f32_16x16x32_bf16 v[24:27], v[140:143], v[212:215], v[24:27]
	v_mfma_f32_16x16x32_bf16 v[12:15], v[132:135], v[224:227], v[12:15]
	v_mfma_f32_16x16x32_bf16 v[8:11], v[140:143], v[224:227], v[8:11]
	v_mfma_f32_16x16x32_bf16 v[52:55], v[144:147], v[160:163], 0
	v_mfma_f32_16x16x32_bf16 v[48:51], v[152:155], v[160:163], 0
	v_mfma_f32_16x16x32_bf16 v[36:39], v[144:147], v[168:171], 0
	v_mfma_f32_16x16x32_bf16 v[32:35], v[152:155], v[168:171], 0
	v_mfma_f32_16x16x32_bf16 v[20:23], v[144:147], v[208:211], 0
	v_mfma_f32_16x16x32_bf16 v[16:19], v[152:155], v[208:211], 0
	v_mfma_f32_16x16x32_bf16 v[4:7], v[144:147], v[220:223], 0
	v_mfma_f32_16x16x32_bf16 v[0:3], v[152:155], v[220:223], 0
	v_mfma_f32_16x16x32_bf16 v[52:55], v[148:151], v[164:167], v[52:55]
	v_mfma_f32_16x16x32_bf16 v[48:51], v[156:159], v[164:167], v[48:51]
	v_mfma_f32_16x16x32_bf16 v[36:39], v[148:151], v[204:207], v[36:39]
	v_mfma_f32_16x16x32_bf16 v[32:35], v[156:159], v[204:207], v[32:35]
	v_mfma_f32_16x16x32_bf16 v[20:23], v[148:151], v[212:215], v[20:23]
	v_mfma_f32_16x16x32_bf16 v[16:19], v[156:159], v[212:215], v[16:19]
	v_mfma_f32_16x16x32_bf16 v[4:7], v[148:151], v[224:227], v[4:7]
	v_mfma_f32_16x16x32_bf16 v[0:3], v[156:159], v[224:227], v[0:3]
	s_barrier
	s_add_i32 s78, 0, 0x1c000
	v_add_u32_e32 v156, s78, v199
	ds_read_b128 v[108:111], v203
	ds_read_b128 v[132:135], v203 offset:1024
	ds_read_b128 v[136:139], v203 offset:2048
	ds_read_b128 v[140:143], v203 offset:3072
	ds_read_b128 v[144:147], v156
	ds_read_b128 v[148:151], v156 offset:1024
	ds_read_b128 v[152:155], v156 offset:2048
	ds_read_b128 v[156:159], v156 offset:3072
	s_add_u32 s8, s66, 0x20000
	s_addc_u32 s9, s67, 0
	s_mov_b32 m0, s19
	v_lshl_add_u64 v[232:233], s[8:9], 0, v[172:173]
	ds_read_b128 v[160:163], v202 offset:32768
	ds_read_b128 v[164:167], v202 offset:33792
	ds_read_b128 v[168:171], v202 offset:34816
	ds_read_b128 v[204:207], v202 offset:35840
	ds_read_b128 v[208:211], v202 offset:36864
	ds_read_b128 v[212:215], v202 offset:37888
	ds_read_b128 v[220:223], v202 offset:38912
	ds_read_b128 v[224:227], v202 offset:39936
	global_load_lds_dwordx4 v[232:233], off
	v_lshl_add_u64 v[232:233], s[8:9], 0, v[174:175]
	s_mov_b32 m0, s70
	s_nop 0
	global_load_lds_dwordx4 v[232:233], off
	s_waitcnt vmcnt(8)
	s_waitcnt lgkmcnt(0)
	s_barrier
	s_waitcnt lgkmcnt(0)
	v_mfma_f32_16x16x32_bf16 v[128:131], v[108:111], v[160:163], v[128:131]
	v_mfma_f32_16x16x32_bf16 v[124:127], v[136:139], v[160:163], v[124:127]
	v_mfma_f32_16x16x32_bf16 v[112:115], v[108:111], v[168:171], v[112:115]
	v_mfma_f32_16x16x32_bf16 v[104:107], v[136:139], v[168:171], v[104:107]
	v_mfma_f32_16x16x32_bf16 v[92:95], v[108:111], v[208:211], v[92:95]
	v_mfma_f32_16x16x32_bf16 v[88:91], v[136:139], v[208:211], v[88:91]
	v_mfma_f32_16x16x32_bf16 v[76:79], v[108:111], v[220:223], v[76:79]
	v_mfma_f32_16x16x32_bf16 v[72:75], v[136:139], v[220:223], v[72:75]
	v_mfma_f32_16x16x32_bf16 v[128:131], v[132:135], v[164:167], v[128:131]
	v_mfma_f32_16x16x32_bf16 v[124:127], v[140:143], v[164:167], v[124:127]
	v_mfma_f32_16x16x32_bf16 v[112:115], v[132:135], v[204:207], v[112:115]
	v_mfma_f32_16x16x32_bf16 v[104:107], v[140:143], v[204:207], v[104:107]
	v_mfma_f32_16x16x32_bf16 v[92:95], v[132:135], v[212:215], v[92:95]
	v_mfma_f32_16x16x32_bf16 v[88:91], v[140:143], v[212:215], v[88:91]
	v_mfma_f32_16x16x32_bf16 v[76:79], v[132:135], v[224:227], v[76:79]
	v_mfma_f32_16x16x32_bf16 v[72:75], v[140:143], v[224:227], v[72:75]
	v_mfma_f32_16x16x32_bf16 v[120:123], v[144:147], v[160:163], v[120:123]
	v_mfma_f32_16x16x32_bf16 v[116:119], v[152:155], v[160:163], v[116:119]
	v_mfma_f32_16x16x32_bf16 v[100:103], v[144:147], v[168:171], v[100:103]
	v_mfma_f32_16x16x32_bf16 v[96:99], v[152:155], v[168:171], v[96:99]
	v_mfma_f32_16x16x32_bf16 v[84:87], v[144:147], v[208:211], v[84:87]
	v_mfma_f32_16x16x32_bf16 v[80:83], v[152:155], v[208:211], v[80:83]
	v_mfma_f32_16x16x32_bf16 v[68:71], v[144:147], v[220:223], v[68:71]
	v_mfma_f32_16x16x32_bf16 v[64:67], v[152:155], v[220:223], v[64:67]
	v_mfma_f32_16x16x32_bf16 v[120:123], v[148:151], v[164:167], v[120:123]
	v_mfma_f32_16x16x32_bf16 v[116:119], v[156:159], v[164:167], v[116:119]
	v_mfma_f32_16x16x32_bf16 v[100:103], v[148:151], v[204:207], v[100:103]
	v_mfma_f32_16x16x32_bf16 v[96:99], v[156:159], v[204:207], v[96:99]
	v_mfma_f32_16x16x32_bf16 v[84:87], v[148:151], v[212:215], v[84:87]
	v_mfma_f32_16x16x32_bf16 v[80:83], v[156:159], v[212:215], v[80:83]
	v_mfma_f32_16x16x32_bf16 v[68:71], v[148:151], v[224:227], v[68:71]
	v_mfma_f32_16x16x32_bf16 v[64:67], v[156:159], v[224:227], v[64:67]
	s_barrier
; #define PG8_STAGE(bufoff, gbase, voff) do { _Pragma("unroll") for (int _i = 0; _i < 2; ++_i) \
;         __builtin_amdgcn_global_load_lds((const unsigned*)((const char*)(gbase) + (voff)[_i]), (PG8_LAS unsigned*)(lds + (bufoff) + ldsw + _i * 8192), 16, 0, 0); } while (0)
; #define PG8_LDA(dst, b, h) do { _Pragma("unroll") for (int m = 0; m < 4; ++m) _Pragma("unroll") for (int k = 0; k < 2; ++k) dst[m][k] = *(const PG8_LAS bf16x8*)(lds + PG8_SA(b, h) + aoff + m * 2048 + k * 1024); } while (0)
; #define PG8_LDB(dst, b, h) do { _Pragma("unroll") for (int n = 0; n < 2; ++n) _Pragma("unroll") for (int k = 0; k < 2; ++k) dst[n][k] = *(const PG8_LAS bf16x8*)(lds + PG8_SB(b, h) + boff + n * 2048 + k * 1024); } while (0)
; #define PG8_MMA(ai, bj, At, Bt) do { __builtin_amdgcn_s_setprio(1); _Pragma("unroll") for (int m = 0; m < 4; ++m) _Pragma("unroll") for (int n = 0; n < 2; ++n) _Pragma("unroll") for (int k = 0; k < 2; ++k) \
;         acc[ai][bj][m][n] = __builtin_amdgcn_mfma_f32_16x16x32_bf16(Bt[n][k], At[m][k], acc[ai][bj][m][n], 0, 0, 0); __builtin_amdgcn_s_setprio(0); } while (0)
; #define PG8_WAIT_V(n) asm volatile("s_waitcnt vmcnt(" #n ")" ::: "memory")
; #define PG8_WAIT_L(n) asm volatile("s_waitcnt lgkmcnt(" #n ")" ::: "memory")
; #define PG8_BAR __builtin_amdgcn_s_barrier()
; #define PG8_SCHED __builtin_amdgcn_sched_barrier(0)
; template <class Epi, class Sched, bool ALIGN_EPI = false, bool SP2 = false>
; __device__ __forceinline__ void gemm_phase(PG8_LAS unsigned char* lds, const Gemm g, const Sched& S, const Epi& E) {
;     ...
;             PG8_LDB(B0, 0, 0); PG8_LDB(B1, 0, 1); PG8_SCHED; PG8_LDA(At, 0, 0); PG8_STAGE(PG8_SA(1, 1), a1 + hstepA, voffA);
;     ...
;             PG8_LDA(At, 1, 1); PG8_STAGE(PG8_SB(1, 0), b3, voffB); PG8_STAGE(PG8_SB(1, 1), b3 + hstepB, voffB); PG8_STAGE(PG8_SA(1, 0), a3, voffA);
;             PG8_WAIT_V(8); PG8_WAIT_L(0); PG8_BAR; PG8_MMA(1, 0, At, B0); PG8_MMA(1, 1, At, B1); PG8_BAR; PG8_SCHED;
	s_add_i32 s8, s81, s15
	v_lshl_add_u64 v[232:233], v[216:217], 0, s[38:39]
	s_mov_b32 m0, s8
	ds_read_b128 v[160:163], v202 offset:49152
	ds_read_b128 v[164:167], v202 offset:50176
	ds_read_b128 v[168:171], v202 offset:51200
	ds_read_b128 v[204:207], v202 offset:52224
	ds_read_b128 v[208:211], v202 offset:53248
	ds_read_b128 v[212:215], v202 offset:54272
	ds_read_b128 v[220:223], v202 offset:55296
	ds_read_b128 v[224:227], v202 offset:56320
	global_load_lds_dwordx4 v[232:233], off
	v_lshl_add_u64 v[232:233], v[216:217], 0, s[40:41]
	s_add_i32 m0, s8, 0x2000
	s_add_i32 s8, s78, s15
	global_load_lds_dwordx4 v[232:233], off
	v_lshl_add_u64 v[232:233], v[216:217], 0, s[44:45]
	s_mov_b32 m0, s8
	v_lshl_add_u64 v[216:217], v[216:217], 0, s[46:47]
	global_load_lds_dwordx4 v[232:233], off
	s_add_i32 m0, s8, 0x2000
	s_nop 0
	global_load_lds_dwordx4 v[216:217], off
	v_lshl_add_u64 v[216:217], v[228:229], 0, s[42:43]
	s_mov_b32 m0, s71
	s_nop 0
	global_load_lds_dwordx4 v[216:217], off
	v_lshl_add_u64 v[216:217], v[230:231], 0, s[42:43]
	s_mov_b32 m0, s72
	s_nop 0
	global_load_lds_dwordx4 v[216:217], off
	s_waitcnt vmcnt(8)
	s_waitcnt lgkmcnt(0)
	s_barrier
	s_waitcnt lgkmcnt(0)
	v_mfma_f32_16x16x32_bf16 v[60:63], v[108:111], v[160:163], v[60:63]
	v_mfma_f32_16x16x32_bf16 v[56:59], v[136:139], v[160:163], v[56:59]
	v_mfma_f32_16x16x32_bf16 v[44:47], v[108:111], v[168:171], v[44:47]
	v_mfma_f32_16x16x32_bf16 v[40:43], v[136:139], v[168:171], v[40:43]
	v_mfma_f32_16x16x32_bf16 v[28:31], v[108:111], v[208:211], v[28:31]
	v_mfma_f32_16x16x32_bf16 v[24:27], v[136:139], v[208:211], v[24:27]
	v_mfma_f32_16x16x32_bf16 v[12:15], v[108:111], v[220:223], v[12:15]
	v_mfma_f32_16x16x32_bf16 v[8:11], v[136:139], v[220:223], v[8:11]
	v_mfma_f32_16x16x32_bf16 v[60:63], v[132:135], v[164:167], v[60:63]
	v_mfma_f32_16x16x32_bf16 v[56:59], v[140:143], v[164:167], v[56:59]
	v_mfma_f32_16x16x32_bf16 v[44:47], v[132:135], v[204:207], v[44:47]
	v_mfma_f32_16x16x32_bf16 v[40:43], v[140:143], v[204:207], v[40:43]
	v_mfma_f32_16x16x32_bf16 v[28:31], v[132:135], v[212:215], v[28:31]
	v_mfma_f32_16x16x32_bf16 v[24:27], v[140:143], v[212:215], v[24:27]
	v_mfma_f32_16x16x32_bf16 v[12:15], v[132:135], v[224:227], v[12:15]
	v_mfma_f32_16x16x32_bf16 v[8:11], v[140:143], v[224:227], v[8:11]
	v_mfma_f32_16x16x32_bf16 v[52:55], v[144:147], v[160:163], v[52:55]
	v_mfma_f32_16x16x32_bf16 v[48:51], v[152:155], v[160:163], v[48:51]
	v_mfma_f32_16x16x32_bf16 v[36:39], v[144:147], v[168:171], v[36:39]
	v_mfma_f32_16x16x32_bf16 v[32:35], v[152:155], v[168:171], v[32:35]
	v_mfma_f32_16x16x32_bf16 v[20:23], v[144:147], v[208:211], v[20:23]
	v_mfma_f32_16x16x32_bf16 v[16:19], v[152:155], v[208:211], v[16:19]
	v_mfma_f32_16x16x32_bf16 v[4:7], v[144:147], v[220:223], v[4:7]
	v_mfma_f32_16x16x32_bf16 v[0:3], v[152:155], v[220:223], v[0:3]
	v_mfma_f32_16x16x32_bf16 v[52:55], v[148:151], v[164:167], v[52:55]
	v_mfma_f32_16x16x32_bf16 v[48:51], v[156:159], v[164:167], v[48:51]
	v_mfma_f32_16x16x32_bf16 v[36:39], v[148:151], v[204:207], v[36:39]
	v_mfma_f32_16x16x32_bf16 v[32:35], v[156:159], v[204:207], v[32:35]
	v_mfma_f32_16x16x32_bf16 v[20:23], v[148:151], v[212:215], v[20:23]
	v_mfma_f32_16x16x32_bf16 v[16:19], v[156:159], v[212:215], v[16:19]
	v_mfma_f32_16x16x32_bf16 v[4:7], v[148:151], v[224:227], v[4:7]
	v_mfma_f32_16x16x32_bf16 v[0:3], v[156:159], v[224:227], v[0:3]
	s_barrier
	s_add_i32 s86, s86, 2
	s_add_u32 s82, s82, 0x10000
	s_addc_u32 s85, s85, 0
	s_add_u32 s64, s64, 0x100
	s_addc_u32 s65, s65, 0
	s_cmp_gt_u32 s86, 5
.LBB0_670:
	ds_read_b128 v[108:111], v200
	ds_read_b128 v[132:135], v200 offset:1024
	ds_read_b128 v[136:139], v200 offset:2048
	ds_read_b128 v[140:143], v200 offset:3072
	ds_read_b128 v[144:147], v201
	ds_read_b128 v[148:151], v201 offset:1024
	ds_read_b128 v[152:155], v201 offset:2048
	ds_read_b128 v[156:159], v201 offset:3072
	s_add_u32 s8, s64, 0xfffe0080
	s_addc_u32 s9, s65, -1
	s_cmp_eq_u32 s86, 4
	s_cselect_b32 s67, s57, s9
	s_cselect_b32 s66, s68, s8
	s_cselect_b32 s9, s55, s85
	s_cselect_b32 s8, s69, s82
	v_lshl_add_u64 v[216:217], s[64:65], 0, v[186:187]
	s_add_i32 m0, s17, 0xc000
	ds_read_b128 v[160:163], v202
	ds_read_b128 v[164:167], v202 offset:1024
	ds_read_b128 v[168:171], v202 offset:2048
	ds_read_b128 v[204:207], v202 offset:3072
	ds_read_b128 v[208:211], v202 offset:4096
	ds_read_b128 v[212:215], v202 offset:5120
	ds_read_b128 v[220:223], v202 offset:6144
	ds_read_b128 v[224:227], v202 offset:7168
	global_load_lds_dwordx4 v[216:217], off
	v_lshl_add_u64 v[216:217], s[64:65], 0, v[192:193]
	s_add_i32 m0, s17, 0xe000
	s_nop 0
	global_load_lds_dwordx4 v[216:217], off
	s_waitcnt vmcnt(8)
	s_waitcnt lgkmcnt(0)
	s_barrier
; #define PG8_STAGE(bufoff, gbase, voff) do { _Pragma("unroll") for (int _i = 0; _i < 2; ++_i) \
;         __builtin_amdgcn_global_load_lds((const unsigned*)((const char*)(gbase) + (voff)[_i]), (PG8_LAS unsigned*)(lds + (bufoff) + ldsw + _i * 8192), 16, 0, 0); } while (0)
; #define PG8_LDA(dst, b, h) do { _Pragma("unroll") for (int m = 0; m < 4; ++m) _Pragma("unroll") for (int k = 0; k < 2; ++k) dst[m][k] = *(const PG8_LAS bf16x8*)(lds + PG8_SA(b, h) + aoff + m * 2048 + k * 1024); } while (0)
; #define PG8_MMA(ai, bj, At, Bt) do { __builtin_amdgcn_s_setprio(1); _Pragma("unroll") for (int m = 0; m < 4; ++m) _Pragma("unroll") for (int n = 0; n < 2; ++n) _Pragma("unroll") for (int k = 0; k < 2; ++k) \
;         acc[ai][bj][m][n] = __builtin_amdgcn_mfma_f32_16x16x32_bf16(Bt[n][k], At[m][k], acc[ai][bj][m][n], 0, 0, 0); __builtin_amdgcn_s_setprio(0); } while (0)
; #define PG8_WAIT_V(n) asm volatile("s_waitcnt vmcnt(" #n ")" ::: "memory")
; #define PG8_WAIT_L(n) asm volatile("s_waitcnt lgkmcnt(" #n ")" ::: "memory")
; #define PG8_BAR __builtin_amdgcn_s_barrier()
; #define PG8_SCHED __builtin_amdgcn_sched_barrier(0)
; template <class Epi, class Sched, bool ALIGN_EPI = false, bool SP2 = false>
; __device__ __forceinline__ void gemm_phase(PG8_LAS unsigned char* lds, const Gemm g, const Sched& S, const Epi& E) {
;     ...
;             PG8_WAIT_V(8); PG8_WAIT_L(0); PG8_BAR; PG8_MMA(0, 0, At, B0); PG8_MMA(0, 1, At, B1); PG8_BAR; PG8_SCHED;
;             PG8_LDA(At, 0, 1); PG8_STAGE(PG8_SB(0, 0), b2, voffB); PG8_STAGE(PG8_SB(0, 1), b2 + hstepB, voffB); PG8_STAGE(PG8_SA(0, 0), a2, voffA);
;             PG8_WAIT_V(8); PG8_WAIT_L(0); PG8_BAR; PG8_MMA(1, 0, At, B0); PG8_MMA(1, 1, At, B1); PG8_BAR; PG8_SCHED;
	s_waitcnt lgkmcnt(0)
	v_mfma_f32_16x16x32_bf16 v[128:131], v[108:111], v[160:163], v[128:131]
	v_mfma_f32_16x16x32_bf16 v[124:127], v[136:139], v[160:163], v[124:127]
	v_mfma_f32_16x16x32_bf16 v[112:115], v[108:111], v[168:171], v[112:115]
	v_mfma_f32_16x16x32_bf16 v[104:107], v[136:139], v[168:171], v[104:107]
	v_mfma_f32_16x16x32_bf16 v[92:95], v[108:111], v[208:211], v[92:95]
	v_mfma_f32_16x16x32_bf16 v[88:91], v[136:139], v[208:211], v[88:91]
	v_mfma_f32_16x16x32_bf16 v[76:79], v[108:111], v[220:223], v[76:79]
	v_mfma_f32_16x16x32_bf16 v[72:75], v[136:139], v[220:223], v[72:75]
	v_mfma_f32_16x16x32_bf16 v[128:131], v[132:135], v[164:167], v[128:131]
	v_mfma_f32_16x16x32_bf16 v[124:127], v[140:143], v[164:167], v[124:127]
	v_mfma_f32_16x16x32_bf16 v[112:115], v[132:135], v[204:207], v[112:115]
	v_mfma_f32_16x16x32_bf16 v[104:107], v[140:143], v[204:207], v[104:107]
	v_mfma_f32_16x16x32_bf16 v[92:95], v[132:135], v[212:215], v[92:95]
	v_mfma_f32_16x16x32_bf16 v[88:91], v[140:143], v[212:215], v[88:91]
	v_mfma_f32_16x16x32_bf16 v[76:79], v[132:135], v[224:227], v[76:79]
	v_mfma_f32_16x16x32_bf16 v[72:75], v[140:143], v[224:227], v[72:75]
	v_mfma_f32_16x16x32_bf16 v[120:123], v[144:147], v[160:163], v[120:123]
	v_mfma_f32_16x16x32_bf16 v[116:119], v[152:155], v[160:163], v[116:119]
	v_mfma_f32_16x16x32_bf16 v[100:103], v[144:147], v[168:171], v[100:103]
	v_mfma_f32_16x16x32_bf16 v[96:99], v[152:155], v[168:171], v[96:99]
	v_mfma_f32_16x16x32_bf16 v[84:87], v[144:147], v[208:211], v[84:87]
	v_mfma_f32_16x16x32_bf16 v[80:83], v[152:155], v[208:211], v[80:83]
	v_mfma_f32_16x16x32_bf16 v[68:71], v[144:147], v[220:223], v[68:71]
	v_mfma_f32_16x16x32_bf16 v[64:67], v[152:155], v[220:223], v[64:67]
	v_mfma_f32_16x16x32_bf16 v[120:123], v[148:151], v[164:167], v[120:123]
	v_mfma_f32_16x16x32_bf16 v[116:119], v[156:159], v[164:167], v[116:119]
	v_mfma_f32_16x16x32_bf16 v[100:103], v[148:151], v[204:207], v[100:103]
	v_mfma_f32_16x16x32_bf16 v[96:99], v[156:159], v[204:207], v[96:99]
	v_mfma_f32_16x16x32_bf16 v[84:87], v[148:151], v[212:215], v[84:87]
	v_mfma_f32_16x16x32_bf16 v[80:83], v[156:159], v[212:215], v[80:83]
	v_mfma_f32_16x16x32_bf16 v[68:71], v[148:151], v[224:227], v[68:71]
	v_mfma_f32_16x16x32_bf16 v[64:67], v[156:159], v[224:227], v[64:67]
	s_barrier
	v_lshl_add_u64 v[216:217], s[8:9], 0, v[190:191]
	s_add_i32 s8, s11, s15
	s_mov_b32 m0, s8
	ds_read_b128 v[160:163], v202 offset:16384
	ds_read_b128 v[164:167], v202 offset:17408
	ds_read_b128 v[168:171], v202 offset:18432
	ds_read_b128 v[204:207], v202 offset:19456
	ds_read_b128 v[208:211], v202 offset:20480
	ds_read_b128 v[212:215], v202 offset:21504
	ds_read_b128 v[220:223], v202 offset:22528
	ds_read_b128 v[224:227], v202 offset:23552
	global_load_lds_dwordx4 v[216:217], off
	v_lshl_add_u64 v[228:229], v[216:217], 0, s[0:1]
	s_add_i32 m0, s8, 0x2000
	s_add_i32 s8, s80, s15
	global_load_lds_dwordx4 v[228:229], off
	v_lshl_add_u64 v[228:229], v[216:217], 0, s[34:35]
	s_mov_b32 m0, s8
	v_lshl_add_u64 v[230:231], s[66:67], 0, v[174:175]
	global_load_lds_dwordx4 v[228:229], off
	v_lshl_add_u64 v[228:229], v[216:217], 0, s[36:37]
	s_add_i32 m0, s8, 0x2000
	s_nop 0
	global_load_lds_dwordx4 v[228:229], off
	v_lshl_add_u64 v[228:229], s[66:67], 0, v[172:173]
	s_mov_b32 m0, s17
	s_nop 0
	global_load_lds_dwordx4 v[228:229], off
	s_mov_b32 m0, s18
	s_nop 0
	global_load_lds_dwordx4 v[230:231], off
	s_waitcnt vmcnt(8)
	s_waitcnt lgkmcnt(0)
	s_barrier
	s_waitcnt lgkmcnt(0)
	v_mfma_f32_16x16x32_bf16 v[60:63], v[108:111], v[160:163], v[60:63]
	v_mfma_f32_16x16x32_bf16 v[56:59], v[136:139], v[160:163], v[56:59]
	v_mfma_f32_16x16x32_bf16 v[44:47], v[108:111], v[168:171], v[44:47]
	v_mfma_f32_16x16x32_bf16 v[40:43], v[136:139], v[168:171], v[40:43]
	v_mfma_f32_16x16x32_bf16 v[28:31], v[108:111], v[208:211], v[28:31]
	v_mfma_f32_16x16x32_bf16 v[24:27], v[136:139], v[208:211], v[24:27]
	v_mfma_f32_16x16x32_bf16 v[12:15], v[108:111], v[220:223], v[12:15]
	v_mfma_f32_16x16x32_bf16 v[8:11], v[136:139], v[220:223], v[8:11]
	v_mfma_f32_16x16x32_bf16 v[60:63], v[132:135], v[164:167], v[60:63]
	v_mfma_f32_16x16x32_bf16 v[56:59], v[140:143], v[164:167], v[56:59]
	v_mfma_f32_16x16x32_bf16 v[44:47], v[132:135], v[204:207], v[44:47]
	v_mfma_f32_16x16x32_bf16 v[40:43], v[140:143], v[204:207], v[40:43]
	v_mfma_f32_16x16x32_bf16 v[28:31], v[132:135], v[212:215], v[28:31]
	v_mfma_f32_16x16x32_bf16 v[24:27], v[140:143], v[212:215], v[24:27]
	v_mfma_f32_16x16x32_bf16 v[12:15], v[132:135], v[224:227], v[12:15]
	v_mfma_f32_16x16x32_bf16 v[8:11], v[140:143], v[224:227], v[8:11]
	v_mfma_f32_16x16x32_bf16 v[52:55], v[144:147], v[160:163], v[52:55]
	v_mfma_f32_16x16x32_bf16 v[48:51], v[152:155], v[160:163], v[48:51]
	v_mfma_f32_16x16x32_bf16 v[36:39], v[144:147], v[168:171], v[36:39]
	v_mfma_f32_16x16x32_bf16 v[32:35], v[152:155], v[168:171], v[32:35]
	v_mfma_f32_16x16x32_bf16 v[20:23], v[144:147], v[208:211], v[20:23]
	v_mfma_f32_16x16x32_bf16 v[16:19], v[152:155], v[208:211], v[16:19]
	v_mfma_f32_16x16x32_bf16 v[4:7], v[144:147], v[220:223], v[4:7]
	v_mfma_f32_16x16x32_bf16 v[0:3], v[152:155], v[220:223], v[0:3]
	v_mfma_f32_16x16x32_bf16 v[52:55], v[148:151], v[164:167], v[52:55]
	v_mfma_f32_16x16x32_bf16 v[48:51], v[156:159], v[164:167], v[48:51]
	v_mfma_f32_16x16x32_bf16 v[36:39], v[148:151], v[204:207], v[36:39]
	v_mfma_f32_16x16x32_bf16 v[32:35], v[156:159], v[204:207], v[32:35]
	v_mfma_f32_16x16x32_bf16 v[20:23], v[148:151], v[212:215], v[20:23]
	v_mfma_f32_16x16x32_bf16 v[16:19], v[156:159], v[212:215], v[16:19]
	v_mfma_f32_16x16x32_bf16 v[4:7], v[148:151], v[224:227], v[4:7]
	v_mfma_f32_16x16x32_bf16 v[0:3], v[156:159], v[224:227], v[0:3]
	s_barrier
; #define PG8_STAGE(bufoff, gbase, voff) do { _Pragma("unroll") for (int _i = 0; _i < 2; ++_i) \
;         __builtin_amdgcn_global_load_lds((const unsigned*)((const char*)(gbase) + (voff)[_i]), (PG8_LAS unsigned*)(lds + (bufoff) + ldsw + _i * 8192), 16, 0, 0); } while (0)
; #define PG8_LDA(dst, b, h) do { _Pragma("unroll") for (int m = 0; m < 4; ++m) _Pragma("unroll") for (int k = 0; k < 2; ++k) dst[m][k] = *(const PG8_LAS bf16x8*)(lds + PG8_SA(b, h) + aoff + m * 2048 + k * 1024); } while (0)
; #define PG8_LDB(dst, b, h) do { _Pragma("unroll") for (int n = 0; n < 2; ++n) _Pragma("unroll") for (int k = 0; k < 2; ++k) dst[n][k] = *(const PG8_LAS bf16x8*)(lds + PG8_SB(b, h) + boff + n * 2048 + k * 1024); } while (0)
; #define PG8_MMA(ai, bj, At, Bt) do { __builtin_amdgcn_s_setprio(1); _Pragma("unroll") for (int m = 0; m < 4; ++m) _Pragma("unroll") for (int n = 0; n < 2; ++n) _Pragma("unroll") for (int k = 0; k < 2; ++k) \
;         acc[ai][bj][m][n] = __builtin_amdgcn_mfma_f32_16x16x32_bf16(Bt[n][k], At[m][k], acc[ai][bj][m][n], 0, 0, 0); __builtin_amdgcn_s_setprio(0); } while (0)
; #define PG8_WAIT_V(n) asm volatile("s_waitcnt vmcnt(" #n ")" ::: "memory")
; #define PG8_WAIT_L(n) asm volatile("s_waitcnt lgkmcnt(" #n ")" ::: "memory")
; #define PG8_BAR __builtin_amdgcn_s_barrier()
; #define PG8_SCHED __builtin_amdgcn_sched_barrier(0)
; template <class Epi, class Sched, bool ALIGN_EPI = false, bool SP2 = false>
; __device__ __forceinline__ void gemm_phase(PG8_LAS unsigned char* lds, const Gemm g, const Sched& S, const Epi& E) {
;     ...
;             PG8_LDB(B0, 1, 0); PG8_LDB(B1, 1, 1); PG8_SCHED; PG8_LDA(At, 1, 0); PG8_STAGE(PG8_SA(0, 1), a2 + hstepA, voffA);
;             PG8_WAIT_V(8); PG8_WAIT_L(0); PG8_BAR; PG8_MMA(0, 0, At, B0); PG8_MMA(0, 1, At, B1); PG8_BAR; PG8_SCHED;
;             PG8_LDA(At, 1, 1); PG8_STAGE(PG8_SB(1, 0), b3, voffB); PG8_STAGE(PG8_SB(1, 1), b3 + hstepB, voffB); PG8_STAGE(PG8_SA(1, 0), a3, voffA);
;             PG8_WAIT_V(8); PG8_WAIT_L(0); PG8_BAR; PG8_MMA(1, 0, At, B0); PG8_MMA(1, 1, At, B1); PG8_BAR; PG8_SCHED;
	s_add_i32 s78, 0, 0x1c000
	v_add_u32_e32 v156, s78, v199
	ds_read_b128 v[108:111], v203
	ds_read_b128 v[132:135], v203 offset:1024
	ds_read_b128 v[136:139], v203 offset:2048
	ds_read_b128 v[140:143], v203 offset:3072
	ds_read_b128 v[144:147], v156
	ds_read_b128 v[148:151], v156 offset:1024
	ds_read_b128 v[152:155], v156 offset:2048
	ds_read_b128 v[156:159], v156 offset:3072
	s_add_u32 s8, s66, 0x20000
	s_addc_u32 s9, s67, 0
	s_mov_b32 m0, s19
	v_lshl_add_u64 v[232:233], s[8:9], 0, v[172:173]
	ds_read_b128 v[160:163], v202 offset:32768
	ds_read_b128 v[164:167], v202 offset:33792
	ds_read_b128 v[168:171], v202 offset:34816
	ds_read_b128 v[204:207], v202 offset:35840
	ds_read_b128 v[208:211], v202 offset:36864
	ds_read_b128 v[212:215], v202 offset:37888
	ds_read_b128 v[220:223], v202 offset:38912
	ds_read_b128 v[224:227], v202 offset:39936
	global_load_lds_dwordx4 v[232:233], off
	v_lshl_add_u64 v[232:233], s[8:9], 0, v[174:175]
	s_mov_b32 m0, s70
	s_nop 0
	global_load_lds_dwordx4 v[232:233], off
	s_waitcnt vmcnt(8)
	s_waitcnt lgkmcnt(0)
	s_barrier
	s_waitcnt lgkmcnt(0)
	v_mfma_f32_16x16x32_bf16 v[128:131], v[108:111], v[160:163], v[128:131]
	v_mfma_f32_16x16x32_bf16 v[124:127], v[136:139], v[160:163], v[124:127]
	v_mfma_f32_16x16x32_bf16 v[112:115], v[108:111], v[168:171], v[112:115]
	v_mfma_f32_16x16x32_bf16 v[104:107], v[136:139], v[168:171], v[104:107]
	v_mfma_f32_16x16x32_bf16 v[92:95], v[108:111], v[208:211], v[92:95]
	v_mfma_f32_16x16x32_bf16 v[88:91], v[136:139], v[208:211], v[88:91]
	v_mfma_f32_16x16x32_bf16 v[76:79], v[108:111], v[220:223], v[76:79]
	v_mfma_f32_16x16x32_bf16 v[72:75], v[136:139], v[220:223], v[72:75]
	v_mfma_f32_16x16x32_bf16 v[128:131], v[132:135], v[164:167], v[128:131]
	v_mfma_f32_16x16x32_bf16 v[124:127], v[140:143], v[164:167], v[124:127]
	v_mfma_f32_16x16x32_bf16 v[112:115], v[132:135], v[204:207], v[112:115]
	v_mfma_f32_16x16x32_bf16 v[104:107], v[140:143], v[204:207], v[104:107]
	v_mfma_f32_16x16x32_bf16 v[92:95], v[132:135], v[212:215], v[92:95]
	v_mfma_f32_16x16x32_bf16 v[88:91], v[140:143], v[212:215], v[88:91]
	v_mfma_f32_16x16x32_bf16 v[76:79], v[132:135], v[224:227], v[76:79]
	v_mfma_f32_16x16x32_bf16 v[72:75], v[140:143], v[224:227], v[72:75]
	v_mfma_f32_16x16x32_bf16 v[120:123], v[144:147], v[160:163], v[120:123]
	v_mfma_f32_16x16x32_bf16 v[116:119], v[152:155], v[160:163], v[116:119]
	v_mfma_f32_16x16x32_bf16 v[100:103], v[144:147], v[168:171], v[100:103]
	v_mfma_f32_16x16x32_bf16 v[96:99], v[152:155], v[168:171], v[96:99]
	v_mfma_f32_16x16x32_bf16 v[84:87], v[144:147], v[208:211], v[84:87]
	v_mfma_f32_16x16x32_bf16 v[80:83], v[152:155], v[208:211], v[80:83]
	v_mfma_f32_16x16x32_bf16 v[68:71], v[144:147], v[220:223], v[68:71]
	v_mfma_f32_16x16x32_bf16 v[64:67], v[152:155], v[220:223], v[64:67]
	v_mfma_f32_16x16x32_bf16 v[120:123], v[148:151], v[164:167], v[120:123]
	v_mfma_f32_16x16x32_bf16 v[116:119], v[156:159], v[164:167], v[116:119]
	v_mfma_f32_16x16x32_bf16 v[100:103], v[148:151], v[204:207], v[100:103]
	v_mfma_f32_16x16x32_bf16 v[96:99], v[156:159], v[204:207], v[96:99]
	v_mfma_f32_16x16x32_bf16 v[84:87], v[148:151], v[212:215], v[84:87]
	v_mfma_f32_16x16x32_bf16 v[80:83], v[156:159], v[212:215], v[80:83]
	v_mfma_f32_16x16x32_bf16 v[68:71], v[148:151], v[224:227], v[68:71]
	v_mfma_f32_16x16x32_bf16 v[64:67], v[156:159], v[224:227], v[64:67]
	s_barrier
	s_add_i32 s8, s81, s15
	v_lshl_add_u64 v[232:233], v[216:217], 0, s[38:39]
	s_mov_b32 m0, s8
	ds_read_b128 v[160:163], v202 offset:49152
	ds_read_b128 v[164:167], v202 offset:50176
	ds_read_b128 v[168:171], v202 offset:51200
	ds_read_b128 v[204:207], v202 offset:52224
	ds_read_b128 v[208:211], v202 offset:53248
	ds_read_b128 v[212:215], v202 offset:54272
	ds_read_b128 v[220:223], v202 offset:55296
	ds_read_b128 v[224:227], v202 offset:56320
	global_load_lds_dwordx4 v[232:233], off
	v_lshl_add_u64 v[232:233], v[216:217], 0, s[40:41]
	s_add_i32 m0, s8, 0x2000
	s_add_i32 s8, s78, s15
	global_load_lds_dwordx4 v[232:233], off
	v_lshl_add_u64 v[232:233], v[216:217], 0, s[44:45]
	s_mov_b32 m0, s8
	v_lshl_add_u64 v[216:217], v[216:217], 0, s[46:47]
	global_load_lds_dwordx4 v[232:233], off
	s_add_i32 m0, s8, 0x2000
	s_nop 0
	global_load_lds_dwordx4 v[216:217], off
	v_lshl_add_u64 v[216:217], v[228:229], 0, s[42:43]
	s_mov_b32 m0, s71
	s_nop 0
	global_load_lds_dwordx4 v[216:217], off
	v_lshl_add_u64 v[216:217], v[230:231], 0, s[42:43]
	s_mov_b32 m0, s72
	s_nop 0
	global_load_lds_dwordx4 v[216:217], off
	s_waitcnt vmcnt(8)
	s_waitcnt lgkmcnt(0)
	s_barrier
	s_waitcnt lgkmcnt(0)
	v_mfma_f32_16x16x32_bf16 v[60:63], v[108:111], v[160:163], v[60:63]
	v_mfma_f32_16x16x32_bf16 v[56:59], v[136:139], v[160:163], v[56:59]
	v_mfma_f32_16x16x32_bf16 v[44:47], v[108:111], v[168:171], v[44:47]
	v_mfma_f32_16x16x32_bf16 v[40:43], v[136:139], v[168:171], v[40:43]
	v_mfma_f32_16x16x32_bf16 v[28:31], v[108:111], v[208:211], v[28:31]
	v_mfma_f32_16x16x32_bf16 v[24:27], v[136:139], v[208:211], v[24:27]
	v_mfma_f32_16x16x32_bf16 v[12:15], v[108:111], v[220:223], v[12:15]
	v_mfma_f32_16x16x32_bf16 v[8:11], v[136:139], v[220:223], v[8:11]
	v_mfma_f32_16x16x32_bf16 v[60:63], v[132:135], v[164:167], v[60:63]
	v_mfma_f32_16x16x32_bf16 v[56:59], v[140:143], v[164:167], v[56:59]
	v_mfma_f32_16x16x32_bf16 v[44:47], v[132:135], v[204:207], v[44:47]
	v_mfma_f32_16x16x32_bf16 v[40:43], v[140:143], v[204:207], v[40:43]
	v_mfma_f32_16x16x32_bf16 v[28:31], v[132:135], v[212:215], v[28:31]
	v_mfma_f32_16x16x32_bf16 v[24:27], v[140:143], v[212:215], v[24:27]
	v_mfma_f32_16x16x32_bf16 v[12:15], v[132:135], v[224:227], v[12:15]
	v_mfma_f32_16x16x32_bf16 v[8:11], v[140:143], v[224:227], v[8:11]
	v_mfma_f32_16x16x32_bf16 v[52:55], v[144:147], v[160:163], v[52:55]
	v_mfma_f32_16x16x32_bf16 v[48:51], v[152:155], v[160:163], v[48:51]
	v_mfma_f32_16x16x32_bf16 v[36:39], v[144:147], v[168:171], v[36:39]
	v_mfma_f32_16x16x32_bf16 v[32:35], v[152:155], v[168:171], v[32:35]
	v_mfma_f32_16x16x32_bf16 v[20:23], v[144:147], v[208:211], v[20:23]
	v_mfma_f32_16x16x32_bf16 v[16:19], v[152:155], v[208:211], v[16:19]
	v_mfma_f32_16x16x32_bf16 v[4:7], v[144:147], v[220:223], v[4:7]
	v_mfma_f32_16x16x32_bf16 v[0:3], v[152:155], v[220:223], v[0:3]
	v_mfma_f32_16x16x32_bf16 v[52:55], v[148:151], v[164:167], v[52:55]
	v_mfma_f32_16x16x32_bf16 v[48:51], v[156:159], v[164:167], v[48:51]
	v_mfma_f32_16x16x32_bf16 v[36:39], v[148:151], v[204:207], v[36:39]
	v_mfma_f32_16x16x32_bf16 v[32:35], v[156:159], v[204:207], v[32:35]
	v_mfma_f32_16x16x32_bf16 v[20:23], v[148:151], v[212:215], v[20:23]
	v_mfma_f32_16x16x32_bf16 v[16:19], v[156:159], v[212:215], v[16:19]
	v_mfma_f32_16x16x32_bf16 v[4:7], v[148:151], v[224:227], v[4:7]
	v_mfma_f32_16x16x32_bf16 v[0:3], v[156:159], v[224:227], v[0:3]
	s_barrier
	s_add_i32 s86, s86, 2
	s_add_u32 s82, s82, 0x10000
	s_addc_u32 s85, s85, 0
	s_add_u32 s64, s64, 0x100
	s_addc_u32 s65, s65, 0
	s_cmp_gt_u32 s86, 5
	s_cbranch_scc0 .LBB0_670
	s_and_b64 vcc, exec, s[52:53]
	s_cbranch_vccz .LBB0_673
	s_barrier

; #define PG8_STAGE(bufoff, gbase, voff) do { _Pragma("unroll") for (int _i = 0; _i < 2; ++_i) \
;         __builtin_amdgcn_global_load_lds((const unsigned*)((const char*)(gbase) + (voff)[_i]), (PG8_LAS unsigned*)(lds + (bufoff) + ldsw + _i * 8192), 16, 0, 0); } while (0)
; #define PG8_LDA(dst, b, h) do { _Pragma("unroll") for (int m = 0; m < 4; ++m) _Pragma("unroll") for (int k = 0; k < 2; ++k) dst[m][k] = *(const PG8_LAS bf16x8*)(lds + PG8_SA(b, h) + aoff + m * 2048 + k * 1024); } while (0)
; #define PG8_LDB(dst, b, h) do { _Pragma("unroll") for (int n = 0; n < 2; ++n) _Pragma("unroll") for (int k = 0; k < 2; ++k) dst[n][k] = *(const PG8_LAS bf16x8*)(lds + PG8_SB(b, h) + boff + n * 2048 + k * 1024); } while (0)
; #define PG8_MMA(ai, bj, At, Bt) do { __builtin_amdgcn_s_setprio(1); _Pragma("unroll") for (int m = 0; m < 4; ++m) _Pragma("unroll") for (int n = 0; n < 2; ++n) _Pragma("unroll") for (int k = 0; k < 2; ++k) \
;         acc[ai][bj][m][n] = __builtin_amdgcn_mfma_f32_16x16x32_bf16(Bt[n][k], At[m][k], acc[ai][bj][m][n], 0, 0, 0); __builtin_amdgcn_s_setprio(0); } while (0)
; #define PG8_BAR __builtin_amdgcn_s_barrier()
; template <class Epi, class Sched, bool ALIGN_EPI = false, bool SP2 = false>
; __device__ __forceinline__ void gemm_phase(PG8_LAS unsigned char* lds, const Gemm g, const Sched& S, const Epi& E) {
;     ...
;         const bool has_next = S.next(ui + 1, nxt);
;         const char* nA = has_next ? (const char*)g.A + (size_t)nxt.pm * tstepA : cA; const char* nB = has_next ? (const char*)g.Bt + (size_t)nxt.pn * tstepB : cB;
;         for (int t = 0; t < nt; t += 2) {
;             const bool last = (t == nt - 2);
;             const char* a1 = cA + (size_t)(t + 1) * kstepA;
;             const char* a2 = last ? nA : cA + (size_t)(t + 2) * kstepA; const char* b2 = last ? nB : cB + (size_t)(t + 2) * kstep;
;             const char* a3 = a2 + kstepA; const char* b3 = b2 + kstep;
;             if (last && has_next) S.a_ready(nxt);
;             if constexpr (SP2) {
;             PG8_LDB(B0, 0, 0); PG8_LDB(B1, 0, 1); PG8_SCHED; PG8_LDA(At, 0, 0); PG8_STAGE(PG8_SA(1, 1), a1 + hstepA, voffA);
;             PG8_WAIT_V(8); PG8_WAIT_L(0); PG8_BAR; PG8_MMA(0, 0, At, B0); PG8_MMA(0, 1, At, B1); PG8_BAR; PG8_SCHED;
;             PG8_LDA(At, 0, 1); PG8_STAGE(PG8_SB(0, 0), b2, voffB); PG8_STAGE(PG8_SB(0, 1), b2 + hstepB, voffB); PG8_STAGE(PG8_SA(0, 0), a2, voffA);
.LBB0_750:
	s_ashr_i32 s59, s58, 31
	s_lshl_b64 s[60:61], s[58:59], 19
	s_add_u32 s60, s6, s60
	s_addc_u32 s61, s7, s61
	s_and_b64 s[62:63], s[4:5], exec
	s_cselect_b32 s59, s61, s69
	s_cselect_b32 s65, s60, s68
	s_ashr_i32 s57, s56, 31
	s_lshl_b64 s[62:63], s[56:57], 19
	s_add_u32 s62, s93, s62
	s_addc_u32 s63, s84, s63
	s_and_b64 s[72:73], s[4:5], exec
	s_cselect_b32 s57, s63, s71
	s_cselect_b32 s67, s62, s70
	s_add_u32 s68, s68, 0x10000
	s_addc_u32 s69, s69, 0
	s_add_u32 s70, s70, 0x10000
	s_addc_u32 s71, s71, 0
	s_mov_b32 s72, -2
	s_waitcnt lgkmcnt(0)
	ds_read_b128 v[128:131], v211
	ds_read_b128 v[132:135], v211 offset:1024
	ds_read_b128 v[136:139], v211 offset:2048
	ds_read_b128 v[140:143], v211 offset:3072
	ds_read_b128 v[144:147], v212
	ds_read_b128 v[148:151], v212 offset:1024
	ds_read_b128 v[152:155], v212 offset:2048
	ds_read_b128 v[156:159], v212 offset:3072
	s_cmp_eq_u32 s72, 12
	s_cselect_b32 s79, s59, s69
	s_cselect_b32 s78, s65, s68
	s_cselect_b32 s91, s57, s71
	s_cselect_b32 s90, s67, s70
	v_lshl_add_u64 v[208:209], s[68:69], 0, v[190:191]
	v_lshl_add_u64 v[228:229], v[208:209], 0, s[52:53]
	s_add_i32 m0, s15, 0xc000
	ds_read_b128 v[160:163], v213
	ds_read_b128 v[164:167], v213 offset:1024
	ds_read_b128 v[168:171], v213 offset:2048
	ds_read_b128 v[172:175], v213 offset:3072
	ds_read_b128 v[176:179], v213 offset:4096
	ds_read_b128 v[180:183], v213 offset:5120
	ds_read_b128 v[220:223], v213 offset:6144
	ds_read_b128 v[224:227], v213 offset:7168
	global_load_lds_dwordx4 v[228:229], off
	v_lshl_add_u64 v[208:209], v[208:209], 0, s[54:55]
	s_add_i32 m0, s15, 0xe000
	s_nop 0
	global_load_lds_dwordx4 v[208:209], off
	s_waitcnt vmcnt(8)
	s_waitcnt lgkmcnt(0)
	s_barrier
	s_waitcnt lgkmcnt(0)
	v_mfma_f32_16x16x32_bf16 v[124:127], v[128:131], v[160:163], 0
	v_mfma_f32_16x16x32_bf16 v[120:123], v[136:139], v[160:163], 0
	v_mfma_f32_16x16x32_bf16 v[108:111], v[128:131], v[168:171], 0
	v_mfma_f32_16x16x32_bf16 v[104:107], v[136:139], v[168:171], 0
	v_mfma_f32_16x16x32_bf16 v[92:95], v[128:131], v[176:179], 0
	v_mfma_f32_16x16x32_bf16 v[88:91], v[136:139], v[176:179], 0
	v_mfma_f32_16x16x32_bf16 v[76:79], v[128:131], v[220:223], 0
	v_mfma_f32_16x16x32_bf16 v[72:75], v[136:139], v[220:223], 0
	v_mfma_f32_16x16x32_bf16 v[124:127], v[132:135], v[164:167], v[124:127]
	v_mfma_f32_16x16x32_bf16 v[120:123], v[140:143], v[164:167], v[120:123]
	v_mfma_f32_16x16x32_bf16 v[108:111], v[132:135], v[172:175], v[108:111]
	v_mfma_f32_16x16x32_bf16 v[104:107], v[140:143], v[172:175], v[104:107]
	v_mfma_f32_16x16x32_bf16 v[92:95], v[132:135], v[180:183], v[92:95]
	v_mfma_f32_16x16x32_bf16 v[88:91], v[140:143], v[180:183], v[88:91]
	v_mfma_f32_16x16x32_bf16 v[76:79], v[132:135], v[224:227], v[76:79]
	v_mfma_f32_16x16x32_bf16 v[72:75], v[140:143], v[224:227], v[72:75]
	v_mfma_f32_16x16x32_bf16 v[116:119], v[144:147], v[160:163], 0
	v_mfma_f32_16x16x32_bf16 v[112:115], v[152:155], v[160:163], 0
	v_mfma_f32_16x16x32_bf16 v[100:103], v[144:147], v[168:171], 0
	v_mfma_f32_16x16x32_bf16 v[96:99], v[152:155], v[168:171], 0
	v_mfma_f32_16x16x32_bf16 v[84:87], v[144:147], v[176:179], 0
	v_mfma_f32_16x16x32_bf16 v[80:83], v[152:155], v[176:179], 0
	v_mfma_f32_16x16x32_bf16 v[68:71], v[144:147], v[220:223], 0
	v_mfma_f32_16x16x32_bf16 v[64:67], v[152:155], v[220:223], 0
	v_mfma_f32_16x16x32_bf16 v[116:119], v[148:151], v[164:167], v[116:119]
	v_mfma_f32_16x16x32_bf16 v[112:115], v[156:159], v[164:167], v[112:115]
	v_mfma_f32_16x16x32_bf16 v[100:103], v[148:151], v[172:175], v[100:103]
	v_mfma_f32_16x16x32_bf16 v[96:99], v[156:159], v[172:175], v[96:99]
	v_mfma_f32_16x16x32_bf16 v[84:87], v[148:151], v[180:183], v[84:87]
	v_mfma_f32_16x16x32_bf16 v[80:83], v[156:159], v[180:183], v[80:83]
	v_mfma_f32_16x16x32_bf16 v[68:71], v[148:151], v[224:227], v[68:71]
	v_mfma_f32_16x16x32_bf16 v[64:67], v[156:159], v[224:227], v[64:67]
	s_barrier
	s_add_i32 s73, s85, s14
	v_lshl_add_u64 v[208:209], s[90:91], 0, v[190:191]
	s_mov_b32 m0, s73
	ds_read_b128 v[160:163], v213 offset:16384
	ds_read_b128 v[164:167], v213 offset:17408
	ds_read_b128 v[168:171], v213 offset:18432
	ds_read_b128 v[172:175], v213 offset:19456
	ds_read_b128 v[176:179], v213 offset:20480
	ds_read_b128 v[180:183], v213 offset:21504
	ds_read_b128 v[220:223], v213 offset:22528
	ds_read_b128 v[224:227], v213 offset:23552
	global_load_lds_dwordx4 v[208:209], off
	v_lshl_add_u64 v[228:229], v[208:209], 0, s[10:11]
	s_add_i32 m0, s73, 0x2000
	s_add_i32 s73, s86, s14
	global_load_lds_dwordx4 v[228:229], off
	v_lshl_add_u64 v[228:229], v[208:209], 0, s[34:35]
	s_mov_b32 m0, s73
	s_nop 0
	global_load_lds_dwordx4 v[228:229], off
	v_lshl_add_u64 v[228:229], v[208:209], 0, s[36:37]
	s_add_i32 m0, s73, 0x2000
	s_nop 0
	global_load_lds_dwordx4 v[228:229], off
	v_lshl_add_u64 v[228:229], s[78:79], 0, v[190:191]
	s_mov_b32 m0, s15
	v_lshl_add_u64 v[230:231], v[228:229], 0, s[10:11]
	global_load_lds_dwordx4 v[228:229], off
	s_mov_b32 m0, s17
	s_nop 0
	global_load_lds_dwordx4 v[230:231], off
	s_waitcnt vmcnt(8)
	s_waitcnt lgkmcnt(0)
	s_barrier
; #define PG8_STAGE(bufoff, gbase, voff) do { _Pragma("unroll") for (int _i = 0; _i < 2; ++_i) \
;         __builtin_amdgcn_global_load_lds((const unsigned*)((const char*)(gbase) + (voff)[_i]), (PG8_LAS unsigned*)(lds + (bufoff) + ldsw + _i * 8192), 16, 0, 0); } while (0)
; #define PG8_LDA(dst, b, h) do { _Pragma("unroll") for (int m = 0; m < 4; ++m) _Pragma("unroll") for (int k = 0; k < 2; ++k) dst[m][k] = *(const PG8_LAS bf16x8*)(lds + PG8_SA(b, h) + aoff + m * 2048 + k * 1024); } while (0)
; #define PG8_LDB(dst, b, h) do { _Pragma("unroll") for (int n = 0; n < 2; ++n) _Pragma("unroll") for (int k = 0; k < 2; ++k) dst[n][k] = *(const PG8_LAS bf16x8*)(lds + PG8_SB(b, h) + boff + n * 2048 + k * 1024); } while (0)
; #define PG8_MMA(ai, bj, At, Bt) do { __builtin_amdgcn_s_setprio(1); _Pragma("unroll") for (int m = 0; m < 4; ++m) _Pragma("unroll") for (int n = 0; n < 2; ++n) _Pragma("unroll") for (int k = 0; k < 2; ++k) \
;         acc[ai][bj][m][n] = __builtin_amdgcn_mfma_f32_16x16x32_bf16(Bt[n][k], At[m][k], acc[ai][bj][m][n], 0, 0, 0); __builtin_amdgcn_s_setprio(0); } while (0)
; #define PG8_WAIT_V(n) asm volatile("s_waitcnt vmcnt(" #n ")" ::: "memory")
; #define PG8_WAIT_L(n) asm volatile("s_waitcnt lgkmcnt(" #n ")" ::: "memory")
; #define PG8_BAR __builtin_amdgcn_s_barrier()
; #define PG8_SCHED __builtin_amdgcn_sched_barrier(0)
; template <class Epi, class Sched, bool ALIGN_EPI = false, bool SP2 = false>
; __device__ __forceinline__ void gemm_phase(PG8_LAS unsigned char* lds, const Gemm g, const Sched& S, const Epi& E) {
;     ...
;             PG8_WAIT_V(8); PG8_WAIT_L(0); PG8_BAR; PG8_MMA(1, 0, At, B0); PG8_MMA(1, 1, At, B1); PG8_BAR; PG8_SCHED;
;             PG8_LDB(B0, 1, 0); PG8_LDB(B1, 1, 1); PG8_SCHED; PG8_LDA(At, 1, 0); PG8_STAGE(PG8_SA(0, 1), a2 + hstepA, voffA);
;             PG8_WAIT_V(8); PG8_WAIT_L(0); PG8_BAR; PG8_MMA(0, 0, At, B0); PG8_MMA(0, 1, At, B1); PG8_BAR; PG8_SCHED;
	s_waitcnt lgkmcnt(0)
	v_mfma_f32_16x16x32_bf16 v[60:63], v[128:131], v[160:163], 0
	v_mfma_f32_16x16x32_bf16 v[56:59], v[136:139], v[160:163], 0
	v_mfma_f32_16x16x32_bf16 v[44:47], v[128:131], v[168:171], 0
	v_mfma_f32_16x16x32_bf16 v[40:43], v[136:139], v[168:171], 0
	v_mfma_f32_16x16x32_bf16 v[28:31], v[128:131], v[176:179], 0
	v_mfma_f32_16x16x32_bf16 v[24:27], v[136:139], v[176:179], 0
	v_mfma_f32_16x16x32_bf16 v[12:15], v[128:131], v[220:223], 0
	v_mfma_f32_16x16x32_bf16 v[8:11], v[136:139], v[220:223], 0
	v_mfma_f32_16x16x32_bf16 v[60:63], v[132:135], v[164:167], v[60:63]
	v_mfma_f32_16x16x32_bf16 v[56:59], v[140:143], v[164:167], v[56:59]
	v_mfma_f32_16x16x32_bf16 v[44:47], v[132:135], v[172:175], v[44:47]
	v_mfma_f32_16x16x32_bf16 v[40:43], v[140:143], v[172:175], v[40:43]
	v_mfma_f32_16x16x32_bf16 v[28:31], v[132:135], v[180:183], v[28:31]
	v_mfma_f32_16x16x32_bf16 v[24:27], v[140:143], v[180:183], v[24:27]
	v_mfma_f32_16x16x32_bf16 v[12:15], v[132:135], v[224:227], v[12:15]
	v_mfma_f32_16x16x32_bf16 v[8:11], v[140:143], v[224:227], v[8:11]
	v_mfma_f32_16x16x32_bf16 v[52:55], v[144:147], v[160:163], 0
	v_mfma_f32_16x16x32_bf16 v[48:51], v[152:155], v[160:163], 0
	v_mfma_f32_16x16x32_bf16 v[36:39], v[144:147], v[168:171], 0
	v_mfma_f32_16x16x32_bf16 v[32:35], v[152:155], v[168:171], 0
	v_mfma_f32_16x16x32_bf16 v[20:23], v[144:147], v[176:179], 0
	v_mfma_f32_16x16x32_bf16 v[16:19], v[152:155], v[176:179], 0
	v_mfma_f32_16x16x32_bf16 v[4:7], v[144:147], v[220:223], 0
	v_mfma_f32_16x16x32_bf16 v[0:3], v[152:155], v[220:223], 0
	v_mfma_f32_16x16x32_bf16 v[52:55], v[148:151], v[164:167], v[52:55]
	v_mfma_f32_16x16x32_bf16 v[48:51], v[156:159], v[164:167], v[48:51]
	v_mfma_f32_16x16x32_bf16 v[36:39], v[148:151], v[172:175], v[36:39]
	v_mfma_f32_16x16x32_bf16 v[32:35], v[156:159], v[172:175], v[32:35]
	v_mfma_f32_16x16x32_bf16 v[20:23], v[148:151], v[180:183], v[20:23]
	v_mfma_f32_16x16x32_bf16 v[16:19], v[156:159], v[180:183], v[16:19]
	v_mfma_f32_16x16x32_bf16 v[4:7], v[148:151], v[224:227], v[4:7]
	v_mfma_f32_16x16x32_bf16 v[0:3], v[156:159], v[224:227], v[0:3]
	s_barrier
	ds_read_b128 v[128:131], v214
	ds_read_b128 v[132:135], v214 offset:1024
	ds_read_b128 v[136:139], v214 offset:2048
	ds_read_b128 v[140:143], v214 offset:3072
	ds_read_b128 v[144:147], v215
	ds_read_b128 v[148:151], v215 offset:1024
	ds_read_b128 v[152:155], v215 offset:2048
	ds_read_b128 v[156:159], v215 offset:3072
	s_mov_b32 m0, s18
	v_lshl_add_u64 v[230:231], v[228:229], 0, s[34:35]
	ds_read_b128 v[160:163], v213 offset:32768
	ds_read_b128 v[164:167], v213 offset:33792
	ds_read_b128 v[168:171], v213 offset:34816
	ds_read_b128 v[172:175], v213 offset:35840
	ds_read_b128 v[176:179], v213 offset:36864
	ds_read_b128 v[180:183], v213 offset:37888
	ds_read_b128 v[220:223], v213 offset:38912
	ds_read_b128 v[224:227], v213 offset:39936
	global_load_lds_dwordx4 v[230:231], off
	v_lshl_add_u64 v[230:231], v[228:229], 0, s[36:37]
	s_mov_b32 m0, s19
	s_nop 0
	global_load_lds_dwordx4 v[230:231], off
	s_waitcnt vmcnt(8)
	s_waitcnt lgkmcnt(0)
	s_barrier
	s_waitcnt lgkmcnt(0)
	v_mfma_f32_16x16x32_bf16 v[124:127], v[128:131], v[160:163], v[124:127]
	v_mfma_f32_16x16x32_bf16 v[120:123], v[136:139], v[160:163], v[120:123]
	v_mfma_f32_16x16x32_bf16 v[108:111], v[128:131], v[168:171], v[108:111]
	v_mfma_f32_16x16x32_bf16 v[104:107], v[136:139], v[168:171], v[104:107]
	v_mfma_f32_16x16x32_bf16 v[92:95], v[128:131], v[176:179], v[92:95]
	v_mfma_f32_16x16x32_bf16 v[88:91], v[136:139], v[176:179], v[88:91]
	v_mfma_f32_16x16x32_bf16 v[76:79], v[128:131], v[220:223], v[76:79]
	v_mfma_f32_16x16x32_bf16 v[72:75], v[136:139], v[220:223], v[72:75]
	v_mfma_f32_16x16x32_bf16 v[124:127], v[132:135], v[164:167], v[124:127]
	v_mfma_f32_16x16x32_bf16 v[120:123], v[140:143], v[164:167], v[120:123]
	v_mfma_f32_16x16x32_bf16 v[108:111], v[132:135], v[172:175], v[108:111]
	v_mfma_f32_16x16x32_bf16 v[104:107], v[140:143], v[172:175], v[104:107]
	v_mfma_f32_16x16x32_bf16 v[92:95], v[132:135], v[180:183], v[92:95]
	v_mfma_f32_16x16x32_bf16 v[88:91], v[140:143], v[180:183], v[88:91]
	v_mfma_f32_16x16x32_bf16 v[76:79], v[132:135], v[224:227], v[76:79]
	v_mfma_f32_16x16x32_bf16 v[72:75], v[140:143], v[224:227], v[72:75]
	v_mfma_f32_16x16x32_bf16 v[116:119], v[144:147], v[160:163], v[116:119]
	v_mfma_f32_16x16x32_bf16 v[112:115], v[152:155], v[160:163], v[112:115]
	v_mfma_f32_16x16x32_bf16 v[100:103], v[144:147], v[168:171], v[100:103]
	v_mfma_f32_16x16x32_bf16 v[96:99], v[152:155], v[168:171], v[96:99]
	v_mfma_f32_16x16x32_bf16 v[84:87], v[144:147], v[176:179], v[84:87]
	v_mfma_f32_16x16x32_bf16 v[80:83], v[152:155], v[176:179], v[80:83]
	v_mfma_f32_16x16x32_bf16 v[68:71], v[144:147], v[220:223], v[68:71]
	v_mfma_f32_16x16x32_bf16 v[64:67], v[152:155], v[220:223], v[64:67]
	v_mfma_f32_16x16x32_bf16 v[116:119], v[148:151], v[164:167], v[116:119]
	v_mfma_f32_16x16x32_bf16 v[112:115], v[156:159], v[164:167], v[112:115]
	v_mfma_f32_16x16x32_bf16 v[100:103], v[148:151], v[172:175], v[100:103]
	v_mfma_f32_16x16x32_bf16 v[96:99], v[156:159], v[172:175], v[96:99]
	v_mfma_f32_16x16x32_bf16 v[84:87], v[148:151], v[180:183], v[84:87]
	v_mfma_f32_16x16x32_bf16 v[80:83], v[156:159], v[180:183], v[80:83]
	v_mfma_f32_16x16x32_bf16 v[68:71], v[148:151], v[224:227], v[68:71]
	v_mfma_f32_16x16x32_bf16 v[64:67], v[156:159], v[224:227], v[64:67]
	s_barrier
; #define PG8_STAGE(bufoff, gbase, voff) do { _Pragma("unroll") for (int _i = 0; _i < 2; ++_i) \
;         __builtin_amdgcn_global_load_lds((const unsigned*)((const char*)(gbase) + (voff)[_i]), (PG8_LAS unsigned*)(lds + (bufoff) + ldsw + _i * 8192), 16, 0, 0); } while (0)
; #define PG8_LDA(dst, b, h) do { _Pragma("unroll") for (int m = 0; m < 4; ++m) _Pragma("unroll") for (int k = 0; k < 2; ++k) dst[m][k] = *(const PG8_LAS bf16x8*)(lds + PG8_SA(b, h) + aoff + m * 2048 + k * 1024); } while (0)
; #define PG8_LDB(dst, b, h) do { _Pragma("unroll") for (int n = 0; n < 2; ++n) _Pragma("unroll") for (int k = 0; k < 2; ++k) dst[n][k] = *(const PG8_LAS bf16x8*)(lds + PG8_SB(b, h) + boff + n * 2048 + k * 1024); } while (0)
; #define PG8_MMA(ai, bj, At, Bt) do { __builtin_amdgcn_s_setprio(1); _Pragma("unroll") for (int m = 0; m < 4; ++m) _Pragma("unroll") for (int n = 0; n < 2; ++n) _Pragma("unroll") for (int k = 0; k < 2; ++k) \
;         acc[ai][bj][m][n] = __builtin_amdgcn_mfma_f32_16x16x32_bf16(Bt[n][k], At[m][k], acc[ai][bj][m][n], 0, 0, 0); __builtin_amdgcn_s_setprio(0); } while (0)
; #define PG8_WAIT_V(n) asm volatile("s_waitcnt vmcnt(" #n ")" ::: "memory")
; #define PG8_WAIT_L(n) asm volatile("s_waitcnt lgkmcnt(" #n ")" ::: "memory")
; #define PG8_BAR __builtin_amdgcn_s_barrier()
; #define PG8_SCHED __builtin_amdgcn_sched_barrier(0)
; template <class Epi, class Sched, bool ALIGN_EPI = false, bool SP2 = false>
; __device__ __forceinline__ void gemm_phase(PG8_LAS unsigned char* lds, const Gemm g, const Sched& S, const Epi& E) {
;     ...
;             PG8_LDB(B0, 0, 0); PG8_LDB(B1, 0, 1); PG8_SCHED; PG8_LDA(At, 0, 0); PG8_STAGE(PG8_SA(1, 1), a1 + hstepA, voffA);
;     ...
;             PG8_LDA(At, 1, 1); PG8_STAGE(PG8_SB(1, 0), b3, voffB); PG8_STAGE(PG8_SB(1, 1), b3 + hstepB, voffB); PG8_STAGE(PG8_SA(1, 0), a3, voffA);
;             PG8_WAIT_V(8); PG8_WAIT_L(0); PG8_BAR; PG8_MMA(1, 0, At, B0); PG8_MMA(1, 1, At, B1); PG8_BAR; PG8_SCHED;
	s_add_i32 s73, s87, s14
	v_lshl_add_u64 v[230:231], v[208:209], 0, s[38:39]
	s_mov_b32 m0, s73
	ds_read_b128 v[160:163], v213 offset:49152
	ds_read_b128 v[164:167], v213 offset:50176
	ds_read_b128 v[168:171], v213 offset:51200
	ds_read_b128 v[172:175], v213 offset:52224
	ds_read_b128 v[176:179], v213 offset:53248
	ds_read_b128 v[180:183], v213 offset:54272
	ds_read_b128 v[220:223], v213 offset:55296
	ds_read_b128 v[224:227], v213 offset:56320
	global_load_lds_dwordx4 v[230:231], off
	v_lshl_add_u64 v[230:231], v[208:209], 0, s[40:41]
	s_add_i32 m0, s73, 0x2000
	s_add_i32 s73, s88, s14
	global_load_lds_dwordx4 v[230:231], off
	v_lshl_add_u64 v[230:231], v[208:209], 0, s[42:43]
	s_mov_b32 m0, s73
	v_lshl_add_u64 v[208:209], v[208:209], 0, s[44:45]
	global_load_lds_dwordx4 v[230:231], off
	s_add_i32 m0, s73, 0x2000
	s_nop 0
	global_load_lds_dwordx4 v[208:209], off
	v_lshl_add_u64 v[208:209], v[228:229], 0, s[38:39]
	s_mov_b32 m0, s74
	s_nop 0
	global_load_lds_dwordx4 v[208:209], off
	v_lshl_add_u64 v[208:209], v[228:229], 0, s[40:41]
	s_mov_b32 m0, s75
	s_nop 0
	global_load_lds_dwordx4 v[208:209], off
	s_waitcnt vmcnt(8)
	s_waitcnt lgkmcnt(0)
	s_barrier
	s_waitcnt lgkmcnt(0)
	v_mfma_f32_16x16x32_bf16 v[60:63], v[128:131], v[160:163], v[60:63]
	v_mfma_f32_16x16x32_bf16 v[56:59], v[136:139], v[160:163], v[56:59]
	v_mfma_f32_16x16x32_bf16 v[44:47], v[128:131], v[168:171], v[44:47]
	v_mfma_f32_16x16x32_bf16 v[40:43], v[136:139], v[168:171], v[40:43]
	v_mfma_f32_16x16x32_bf16 v[28:31], v[128:131], v[176:179], v[28:31]
	v_mfma_f32_16x16x32_bf16 v[24:27], v[136:139], v[176:179], v[24:27]
	v_mfma_f32_16x16x32_bf16 v[12:15], v[128:131], v[220:223], v[12:15]
	v_mfma_f32_16x16x32_bf16 v[8:11], v[136:139], v[220:223], v[8:11]
	v_mfma_f32_16x16x32_bf16 v[60:63], v[132:135], v[164:167], v[60:63]
	v_mfma_f32_16x16x32_bf16 v[56:59], v[140:143], v[164:167], v[56:59]
	v_mfma_f32_16x16x32_bf16 v[44:47], v[132:135], v[172:175], v[44:47]
	v_mfma_f32_16x16x32_bf16 v[40:43], v[140:143], v[172:175], v[40:43]
	v_mfma_f32_16x16x32_bf16 v[28:31], v[132:135], v[180:183], v[28:31]
	v_mfma_f32_16x16x32_bf16 v[24:27], v[140:143], v[180:183], v[24:27]
	v_mfma_f32_16x16x32_bf16 v[12:15], v[132:135], v[224:227], v[12:15]
	v_mfma_f32_16x16x32_bf16 v[8:11], v[140:143], v[224:227], v[8:11]
	v_mfma_f32_16x16x32_bf16 v[52:55], v[144:147], v[160:163], v[52:55]
	v_mfma_f32_16x16x32_bf16 v[48:51], v[152:155], v[160:163], v[48:51]
	v_mfma_f32_16x16x32_bf16 v[36:39], v[144:147], v[168:171], v[36:39]
	v_mfma_f32_16x16x32_bf16 v[32:35], v[152:155], v[168:171], v[32:35]
	v_mfma_f32_16x16x32_bf16 v[20:23], v[144:147], v[176:179], v[20:23]
	v_mfma_f32_16x16x32_bf16 v[16:19], v[152:155], v[176:179], v[16:19]
	v_mfma_f32_16x16x32_bf16 v[4:7], v[144:147], v[220:223], v[4:7]
	v_mfma_f32_16x16x32_bf16 v[0:3], v[152:155], v[220:223], v[0:3]
	v_mfma_f32_16x16x32_bf16 v[52:55], v[148:151], v[164:167], v[52:55]
	v_mfma_f32_16x16x32_bf16 v[48:51], v[156:159], v[164:167], v[48:51]
	v_mfma_f32_16x16x32_bf16 v[36:39], v[148:151], v[172:175], v[36:39]
	v_mfma_f32_16x16x32_bf16 v[32:35], v[156:159], v[172:175], v[32:35]
	v_mfma_f32_16x16x32_bf16 v[20:23], v[148:151], v[180:183], v[20:23]
	v_mfma_f32_16x16x32_bf16 v[16:19], v[156:159], v[180:183], v[16:19]
	v_mfma_f32_16x16x32_bf16 v[4:7], v[148:151], v[224:227], v[4:7]
	v_mfma_f32_16x16x32_bf16 v[0:3], v[156:159], v[224:227], v[0:3]
	s_barrier
	s_add_i32 s72, s72, 2
	s_add_u32 s68, s68, 0x10000
	s_addc_u32 s69, s69, 0
	s_add_u32 s70, s70, 0x10000
	s_addc_u32 s71, s71, 0
	s_cmp_gt_u32 s72, 13
.LBB0_751:
	ds_read_b128 v[128:131], v211
	ds_read_b128 v[132:135], v211 offset:1024
	ds_read_b128 v[136:139], v211 offset:2048
	ds_read_b128 v[140:143], v211 offset:3072
	ds_read_b128 v[144:147], v212
	ds_read_b128 v[148:151], v212 offset:1024
	ds_read_b128 v[152:155], v212 offset:2048
	ds_read_b128 v[156:159], v212 offset:3072
	s_cmp_eq_u32 s72, 12
	s_cselect_b32 s79, s59, s69
	s_cselect_b32 s78, s65, s68
	s_cselect_b32 s91, s57, s71
	s_cselect_b32 s90, s67, s70
	v_lshl_add_u64 v[208:209], s[68:69], 0, v[190:191]
	v_lshl_add_u64 v[228:229], v[208:209], 0, s[52:53]
	s_add_i32 m0, s15, 0xc000
	ds_read_b128 v[160:163], v213
	ds_read_b128 v[164:167], v213 offset:1024
	ds_read_b128 v[168:171], v213 offset:2048
	ds_read_b128 v[172:175], v213 offset:3072
	ds_read_b128 v[176:179], v213 offset:4096
	ds_read_b128 v[180:183], v213 offset:5120
	ds_read_b128 v[220:223], v213 offset:6144
	ds_read_b128 v[224:227], v213 offset:7168
	global_load_lds_dwordx4 v[228:229], off
	v_lshl_add_u64 v[208:209], v[208:209], 0, s[54:55]
	s_add_i32 m0, s15, 0xe000
	s_nop 0
	global_load_lds_dwordx4 v[208:209], off
	s_waitcnt vmcnt(8)
	s_waitcnt lgkmcnt(0)
	s_barrier
; #define PG8_STAGE(bufoff, gbase, voff) do { _Pragma("unroll") for (int _i = 0; _i < 2; ++_i) \
;         __builtin_amdgcn_global_load_lds((const unsigned*)((const char*)(gbase) + (voff)[_i]), (PG8_LAS unsigned*)(lds + (bufoff) + ldsw + _i * 8192), 16, 0, 0); } while (0)
; #define PG8_LDA(dst, b, h) do { _Pragma("unroll") for (int m = 0; m < 4; ++m) _Pragma("unroll") for (int k = 0; k < 2; ++k) dst[m][k] = *(const PG8_LAS bf16x8*)(lds + PG8_SA(b, h) + aoff + m * 2048 + k * 1024); } while (0)
; #define PG8_MMA(ai, bj, At, Bt) do { __builtin_amdgcn_s_setprio(1); _Pragma("unroll") for (int m = 0; m < 4; ++m) _Pragma("unroll") for (int n = 0; n < 2; ++n) _Pragma("unroll") for (int k = 0; k < 2; ++k) \
;         acc[ai][bj][m][n] = __builtin_amdgcn_mfma_f32_16x16x32_bf16(Bt[n][k], At[m][k], acc[ai][bj][m][n], 0, 0, 0); __builtin_amdgcn_s_setprio(0); } while (0)
; #define PG8_WAIT_V(n) asm volatile("s_waitcnt vmcnt(" #n ")" ::: "memory")
; #define PG8_WAIT_L(n) asm volatile("s_waitcnt lgkmcnt(" #n ")" ::: "memory")
; #define PG8_BAR __builtin_amdgcn_s_barrier()
; #define PG8_SCHED __builtin_amdgcn_sched_barrier(0)
; template <class Epi, class Sched, bool ALIGN_EPI = false, bool SP2 = false>
; __device__ __forceinline__ void gemm_phase(PG8_LAS unsigned char* lds, const Gemm g, const Sched& S, const Epi& E) {
;     ...
;             PG8_WAIT_V(8); PG8_WAIT_L(0); PG8_BAR; PG8_MMA(0, 0, At, B0); PG8_MMA(0, 1, At, B1); PG8_BAR; PG8_SCHED;
;             PG8_LDA(At, 0, 1); PG8_STAGE(PG8_SB(0, 0), b2, voffB); PG8_STAGE(PG8_SB(0, 1), b2 + hstepB, voffB); PG8_STAGE(PG8_SA(0, 0), a2, voffA);
;             PG8_WAIT_V(8); PG8_WAIT_L(0); PG8_BAR; PG8_MMA(1, 0, At, B0); PG8_MMA(1, 1, At, B1); PG8_BAR; PG8_SCHED;
	s_waitcnt lgkmcnt(0)
	v_mfma_f32_16x16x32_bf16 v[124:127], v[128:131], v[160:163], v[124:127]
	v_mfma_f32_16x16x32_bf16 v[120:123], v[136:139], v[160:163], v[120:123]
	v_mfma_f32_16x16x32_bf16 v[108:111], v[128:131], v[168:171], v[108:111]
	v_mfma_f32_16x16x32_bf16 v[104:107], v[136:139], v[168:171], v[104:107]
	v_mfma_f32_16x16x32_bf16 v[92:95], v[128:131], v[176:179], v[92:95]
	v_mfma_f32_16x16x32_bf16 v[88:91], v[136:139], v[176:179], v[88:91]
	v_mfma_f32_16x16x32_bf16 v[76:79], v[128:131], v[220:223], v[76:79]
	v_mfma_f32_16x16x32_bf16 v[72:75], v[136:139], v[220:223], v[72:75]
	v_mfma_f32_16x16x32_bf16 v[124:127], v[132:135], v[164:167], v[124:127]
	v_mfma_f32_16x16x32_bf16 v[120:123], v[140:143], v[164:167], v[120:123]
	v_mfma_f32_16x16x32_bf16 v[108:111], v[132:135], v[172:175], v[108:111]
	v_mfma_f32_16x16x32_bf16 v[104:107], v[140:143], v[172:175], v[104:107]
	v_mfma_f32_16x16x32_bf16 v[92:95], v[132:135], v[180:183], v[92:95]
	v_mfma_f32_16x16x32_bf16 v[88:91], v[140:143], v[180:183], v[88:91]
	v_mfma_f32_16x16x32_bf16 v[76:79], v[132:135], v[224:227], v[76:79]
	v_mfma_f32_16x16x32_bf16 v[72:75], v[140:143], v[224:227], v[72:75]
	v_mfma_f32_16x16x32_bf16 v[116:119], v[144:147], v[160:163], v[116:119]
	v_mfma_f32_16x16x32_bf16 v[112:115], v[152:155], v[160:163], v[112:115]
	v_mfma_f32_16x16x32_bf16 v[100:103], v[144:147], v[168:171], v[100:103]
	v_mfma_f32_16x16x32_bf16 v[96:99], v[152:155], v[168:171], v[96:99]
	v_mfma_f32_16x16x32_bf16 v[84:87], v[144:147], v[176:179], v[84:87]
	v_mfma_f32_16x16x32_bf16 v[80:83], v[152:155], v[176:179], v[80:83]
	v_mfma_f32_16x16x32_bf16 v[68:71], v[144:147], v[220:223], v[68:71]
	v_mfma_f32_16x16x32_bf16 v[64:67], v[152:155], v[220:223], v[64:67]
	v_mfma_f32_16x16x32_bf16 v[116:119], v[148:151], v[164:167], v[116:119]
	v_mfma_f32_16x16x32_bf16 v[112:115], v[156:159], v[164:167], v[112:115]
	v_mfma_f32_16x16x32_bf16 v[100:103], v[148:151], v[172:175], v[100:103]
	v_mfma_f32_16x16x32_bf16 v[96:99], v[156:159], v[172:175], v[96:99]
	v_mfma_f32_16x16x32_bf16 v[84:87], v[148:151], v[180:183], v[84:87]
	v_mfma_f32_16x16x32_bf16 v[80:83], v[156:159], v[180:183], v[80:83]
	v_mfma_f32_16x16x32_bf16 v[68:71], v[148:151], v[224:227], v[68:71]
	v_mfma_f32_16x16x32_bf16 v[64:67], v[156:159], v[224:227], v[64:67]
	s_barrier
	s_add_i32 s73, s85, s14
	v_lshl_add_u64 v[208:209], s[90:91], 0, v[190:191]
	s_mov_b32 m0, s73
	ds_read_b128 v[160:163], v213 offset:16384
	ds_read_b128 v[164:167], v213 offset:17408
	ds_read_b128 v[168:171], v213 offset:18432
	ds_read_b128 v[172:175], v213 offset:19456
	ds_read_b128 v[176:179], v213 offset:20480
	ds_read_b128 v[180:183], v213 offset:21504
	ds_read_b128 v[220:223], v213 offset:22528
	ds_read_b128 v[224:227], v213 offset:23552
	global_load_lds_dwordx4 v[208:209], off
	v_lshl_add_u64 v[228:229], v[208:209], 0, s[10:11]
	s_add_i32 m0, s73, 0x2000
	s_add_i32 s73, s86, s14
	global_load_lds_dwordx4 v[228:229], off
	v_lshl_add_u64 v[228:229], v[208:209], 0, s[34:35]
	s_mov_b32 m0, s73
	s_nop 0
	global_load_lds_dwordx4 v[228:229], off
	v_lshl_add_u64 v[228:229], v[208:209], 0, s[36:37]
	s_add_i32 m0, s73, 0x2000
	s_nop 0
	global_load_lds_dwordx4 v[228:229], off
	v_lshl_add_u64 v[228:229], s[78:79], 0, v[190:191]
	s_mov_b32 m0, s15
	v_lshl_add_u64 v[230:231], v[228:229], 0, s[10:11]
	global_load_lds_dwordx4 v[228:229], off
	s_mov_b32 m0, s17
	s_nop 0
	global_load_lds_dwordx4 v[230:231], off
	s_waitcnt vmcnt(8)
	s_waitcnt lgkmcnt(0)
	s_barrier
	s_waitcnt lgkmcnt(0)
	v_mfma_f32_16x16x32_bf16 v[60:63], v[128:131], v[160:163], v[60:63]
	v_mfma_f32_16x16x32_bf16 v[56:59], v[136:139], v[160:163], v[56:59]
	v_mfma_f32_16x16x32_bf16 v[44:47], v[128:131], v[168:171], v[44:47]
	v_mfma_f32_16x16x32_bf16 v[40:43], v[136:139], v[168:171], v[40:43]
	v_mfma_f32_16x16x32_bf16 v[28:31], v[128:131], v[176:179], v[28:31]
	v_mfma_f32_16x16x32_bf16 v[24:27], v[136:139], v[176:179], v[24:27]
	v_mfma_f32_16x16x32_bf16 v[12:15], v[128:131], v[220:223], v[12:15]
	v_mfma_f32_16x16x32_bf16 v[8:11], v[136:139], v[220:223], v[8:11]
	v_mfma_f32_16x16x32_bf16 v[60:63], v[132:135], v[164:167], v[60:63]
	v_mfma_f32_16x16x32_bf16 v[56:59], v[140:143], v[164:167], v[56:59]
	v_mfma_f32_16x16x32_bf16 v[44:47], v[132:135], v[172:175], v[44:47]
	v_mfma_f32_16x16x32_bf16 v[40:43], v[140:143], v[172:175], v[40:43]
	v_mfma_f32_16x16x32_bf16 v[28:31], v[132:135], v[180:183], v[28:31]
	v_mfma_f32_16x16x32_bf16 v[24:27], v[140:143], v[180:183], v[24:27]
	v_mfma_f32_16x16x32_bf16 v[12:15], v[132:135], v[224:227], v[12:15]
	v_mfma_f32_16x16x32_bf16 v[8:11], v[140:143], v[224:227], v[8:11]
	v_mfma_f32_16x16x32_bf16 v[52:55], v[144:147], v[160:163], v[52:55]
	v_mfma_f32_16x16x32_bf16 v[48:51], v[152:155], v[160:163], v[48:51]
	v_mfma_f32_16x16x32_bf16 v[36:39], v[144:147], v[168:171], v[36:39]
	v_mfma_f32_16x16x32_bf16 v[32:35], v[152:155], v[168:171], v[32:35]
	v_mfma_f32_16x16x32_bf16 v[20:23], v[144:147], v[176:179], v[20:23]
	v_mfma_f32_16x16x32_bf16 v[16:19], v[152:155], v[176:179], v[16:19]
	v_mfma_f32_16x16x32_bf16 v[4:7], v[144:147], v[220:223], v[4:7]
	v_mfma_f32_16x16x32_bf16 v[0:3], v[152:155], v[220:223], v[0:3]
	v_mfma_f32_16x16x32_bf16 v[52:55], v[148:151], v[164:167], v[52:55]
	v_mfma_f32_16x16x32_bf16 v[48:51], v[156:159], v[164:167], v[48:51]
	v_mfma_f32_16x16x32_bf16 v[36:39], v[148:151], v[172:175], v[36:39]
	v_mfma_f32_16x16x32_bf16 v[32:35], v[156:159], v[172:175], v[32:35]
	v_mfma_f32_16x16x32_bf16 v[20:23], v[148:151], v[180:183], v[20:23]
	v_mfma_f32_16x16x32_bf16 v[16:19], v[156:159], v[180:183], v[16:19]
	v_mfma_f32_16x16x32_bf16 v[4:7], v[148:151], v[224:227], v[4:7]
	v_mfma_f32_16x16x32_bf16 v[0:3], v[156:159], v[224:227], v[0:3]
	s_barrier
; #define PG8_STAGE(bufoff, gbase, voff) do { _Pragma("unroll") for (int _i = 0; _i < 2; ++_i) \
;         __builtin_amdgcn_global_load_lds((const unsigned*)((const char*)(gbase) + (voff)[_i]), (PG8_LAS unsigned*)(lds + (bufoff) + ldsw + _i * 8192), 16, 0, 0); } while (0)
; #define PG8_LDA(dst, b, h) do { _Pragma("unroll") for (int m = 0; m < 4; ++m) _Pragma("unroll") for (int k = 0; k < 2; ++k) dst[m][k] = *(const PG8_LAS bf16x8*)(lds + PG8_SA(b, h) + aoff + m * 2048 + k * 1024); } while (0)
; #define PG8_LDB(dst, b, h) do { _Pragma("unroll") for (int n = 0; n < 2; ++n) _Pragma("unroll") for (int k = 0; k < 2; ++k) dst[n][k] = *(const PG8_LAS bf16x8*)(lds + PG8_SB(b, h) + boff + n * 2048 + k * 1024); } while (0)
; #define PG8_MMA(ai, bj, At, Bt) do { __builtin_amdgcn_s_setprio(1); _Pragma("unroll") for (int m = 0; m < 4; ++m) _Pragma("unroll") for (int n = 0; n < 2; ++n) _Pragma("unroll") for (int k = 0; k < 2; ++k) \
;         acc[ai][bj][m][n] = __builtin_amdgcn_mfma_f32_16x16x32_bf16(Bt[n][k], At[m][k], acc[ai][bj][m][n], 0, 0, 0); __builtin_amdgcn_s_setprio(0); } while (0)
; #define PG8_WAIT_V(n) asm volatile("s_waitcnt vmcnt(" #n ")" ::: "memory")
; #define PG8_WAIT_L(n) asm volatile("s_waitcnt lgkmcnt(" #n ")" ::: "memory")
; #define PG8_BAR __builtin_amdgcn_s_barrier()
; #define PG8_SCHED __builtin_amdgcn_sched_barrier(0)
; template <class Epi, class Sched, bool ALIGN_EPI = false, bool SP2 = false>
; __device__ __forceinline__ void gemm_phase(PG8_LAS unsigned char* lds, const Gemm g, const Sched& S, const Epi& E) {
;     ...
;             PG8_LDB(B0, 1, 0); PG8_LDB(B1, 1, 1); PG8_SCHED; PG8_LDA(At, 1, 0); PG8_STAGE(PG8_SA(0, 1), a2 + hstepA, voffA);
;             PG8_WAIT_V(8); PG8_WAIT_L(0); PG8_BAR; PG8_MMA(0, 0, At, B0); PG8_MMA(0, 1, At, B1); PG8_BAR; PG8_SCHED;
;             PG8_LDA(At, 1, 1); PG8_STAGE(PG8_SB(1, 0), b3, voffB); PG8_STAGE(PG8_SB(1, 1), b3 + hstepB, voffB); PG8_STAGE(PG8_SA(1, 0), a3, voffA);
;             PG8_WAIT_V(8); PG8_WAIT_L(0); PG8_BAR; PG8_MMA(1, 0, At, B0); PG8_MMA(1, 1, At, B1); PG8_BAR; PG8_SCHED;
;     ...
;         if constexpr (ALIGN_EPI) { if (wr == 0) PG8_BAR; }
	ds_read_b128 v[128:131], v214
	ds_read_b128 v[132:135], v214 offset:1024
	ds_read_b128 v[136:139], v214 offset:2048
	ds_read_b128 v[140:143], v214 offset:3072
	ds_read_b128 v[144:147], v215
	ds_read_b128 v[148:151], v215 offset:1024
	ds_read_b128 v[152:155], v215 offset:2048
	ds_read_b128 v[156:159], v215 offset:3072
	s_mov_b32 m0, s18
	v_lshl_add_u64 v[230:231], v[228:229], 0, s[34:35]
	ds_read_b128 v[160:163], v213 offset:32768
	ds_read_b128 v[164:167], v213 offset:33792
	ds_read_b128 v[168:171], v213 offset:34816
	ds_read_b128 v[172:175], v213 offset:35840
	ds_read_b128 v[176:179], v213 offset:36864
	ds_read_b128 v[180:183], v213 offset:37888
	ds_read_b128 v[220:223], v213 offset:38912
	ds_read_b128 v[224:227], v213 offset:39936
	global_load_lds_dwordx4 v[230:231], off
	v_lshl_add_u64 v[230:231], v[228:229], 0, s[36:37]
	s_mov_b32 m0, s19
	s_nop 0
	global_load_lds_dwordx4 v[230:231], off
	s_waitcnt vmcnt(8)
	s_waitcnt lgkmcnt(0)
	s_barrier
	s_waitcnt lgkmcnt(0)
	v_mfma_f32_16x16x32_bf16 v[124:127], v[128:131], v[160:163], v[124:127]
	v_mfma_f32_16x16x32_bf16 v[120:123], v[136:139], v[160:163], v[120:123]
	v_mfma_f32_16x16x32_bf16 v[108:111], v[128:131], v[168:171], v[108:111]
	v_mfma_f32_16x16x32_bf16 v[104:107], v[136:139], v[168:171], v[104:107]
	v_mfma_f32_16x16x32_bf16 v[92:95], v[128:131], v[176:179], v[92:95]
	v_mfma_f32_16x16x32_bf16 v[88:91], v[136:139], v[176:179], v[88:91]
	v_mfma_f32_16x16x32_bf16 v[76:79], v[128:131], v[220:223], v[76:79]
	v_mfma_f32_16x16x32_bf16 v[72:75], v[136:139], v[220:223], v[72:75]
	v_mfma_f32_16x16x32_bf16 v[124:127], v[132:135], v[164:167], v[124:127]
	v_mfma_f32_16x16x32_bf16 v[120:123], v[140:143], v[164:167], v[120:123]
	v_mfma_f32_16x16x32_bf16 v[108:111], v[132:135], v[172:175], v[108:111]
	v_mfma_f32_16x16x32_bf16 v[104:107], v[140:143], v[172:175], v[104:107]
	v_mfma_f32_16x16x32_bf16 v[92:95], v[132:135], v[180:183], v[92:95]
	v_mfma_f32_16x16x32_bf16 v[88:91], v[140:143], v[180:183], v[88:91]
	v_mfma_f32_16x16x32_bf16 v[76:79], v[132:135], v[224:227], v[76:79]
	v_mfma_f32_16x16x32_bf16 v[72:75], v[140:143], v[224:227], v[72:75]
	v_mfma_f32_16x16x32_bf16 v[116:119], v[144:147], v[160:163], v[116:119]
	v_mfma_f32_16x16x32_bf16 v[112:115], v[152:155], v[160:163], v[112:115]
	v_mfma_f32_16x16x32_bf16 v[100:103], v[144:147], v[168:171], v[100:103]
	v_mfma_f32_16x16x32_bf16 v[96:99], v[152:155], v[168:171], v[96:99]
	v_mfma_f32_16x16x32_bf16 v[84:87], v[144:147], v[176:179], v[84:87]
	v_mfma_f32_16x16x32_bf16 v[80:83], v[152:155], v[176:179], v[80:83]
	v_mfma_f32_16x16x32_bf16 v[68:71], v[144:147], v[220:223], v[68:71]
	v_mfma_f32_16x16x32_bf16 v[64:67], v[152:155], v[220:223], v[64:67]
	v_mfma_f32_16x16x32_bf16 v[116:119], v[148:151], v[164:167], v[116:119]
	v_mfma_f32_16x16x32_bf16 v[112:115], v[156:159], v[164:167], v[112:115]
	v_mfma_f32_16x16x32_bf16 v[100:103], v[148:151], v[172:175], v[100:103]
	v_mfma_f32_16x16x32_bf16 v[96:99], v[156:159], v[172:175], v[96:99]
	v_mfma_f32_16x16x32_bf16 v[84:87], v[148:151], v[180:183], v[84:87]
	v_mfma_f32_16x16x32_bf16 v[80:83], v[156:159], v[180:183], v[80:83]
	v_mfma_f32_16x16x32_bf16 v[68:71], v[148:151], v[224:227], v[68:71]
	v_mfma_f32_16x16x32_bf16 v[64:67], v[156:159], v[224:227], v[64:67]
	s_barrier
	s_add_i32 s73, s87, s14
	v_lshl_add_u64 v[230:231], v[208:209], 0, s[38:39]
	s_mov_b32 m0, s73
	ds_read_b128 v[160:163], v213 offset:49152
	ds_read_b128 v[164:167], v213 offset:50176
	ds_read_b128 v[168:171], v213 offset:51200
	ds_read_b128 v[172:175], v213 offset:52224
	ds_read_b128 v[176:179], v213 offset:53248
	ds_read_b128 v[180:183], v213 offset:54272
	ds_read_b128 v[220:223], v213 offset:55296
	ds_read_b128 v[224:227], v213 offset:56320
	global_load_lds_dwordx4 v[230:231], off
	v_lshl_add_u64 v[230:231], v[208:209], 0, s[40:41]
	s_add_i32 m0, s73, 0x2000
	s_add_i32 s73, s88, s14
	global_load_lds_dwordx4 v[230:231], off
	v_lshl_add_u64 v[230:231], v[208:209], 0, s[42:43]
	s_mov_b32 m0, s73
	v_lshl_add_u64 v[208:209], v[208:209], 0, s[44:45]
	global_load_lds_dwordx4 v[230:231], off
	s_add_i32 m0, s73, 0x2000
	s_nop 0
	global_load_lds_dwordx4 v[208:209], off
	v_lshl_add_u64 v[208:209], v[228:229], 0, s[38:39]
	s_mov_b32 m0, s74
	s_nop 0
	global_load_lds_dwordx4 v[208:209], off
	v_lshl_add_u64 v[208:209], v[228:229], 0, s[40:41]
	s_mov_b32 m0, s75
	s_nop 0
	global_load_lds_dwordx4 v[208:209], off
	s_waitcnt vmcnt(8)
	s_waitcnt lgkmcnt(0)
	s_barrier
	s_waitcnt lgkmcnt(0)
	v_mfma_f32_16x16x32_bf16 v[60:63], v[128:131], v[160:163], v[60:63]
	v_mfma_f32_16x16x32_bf16 v[56:59], v[136:139], v[160:163], v[56:59]
	v_mfma_f32_16x16x32_bf16 v[44:47], v[128:131], v[168:171], v[44:47]
	v_mfma_f32_16x16x32_bf16 v[40:43], v[136:139], v[168:171], v[40:43]
	v_mfma_f32_16x16x32_bf16 v[28:31], v[128:131], v[176:179], v[28:31]
	v_mfma_f32_16x16x32_bf16 v[24:27], v[136:139], v[176:179], v[24:27]
	v_mfma_f32_16x16x32_bf16 v[12:15], v[128:131], v[220:223], v[12:15]
	v_mfma_f32_16x16x32_bf16 v[8:11], v[136:139], v[220:223], v[8:11]
	v_mfma_f32_16x16x32_bf16 v[60:63], v[132:135], v[164:167], v[60:63]
	v_mfma_f32_16x16x32_bf16 v[56:59], v[140:143], v[164:167], v[56:59]
	v_mfma_f32_16x16x32_bf16 v[44:47], v[132:135], v[172:175], v[44:47]
	v_mfma_f32_16x16x32_bf16 v[40:43], v[140:143], v[172:175], v[40:43]
	v_mfma_f32_16x16x32_bf16 v[28:31], v[132:135], v[180:183], v[28:31]
	v_mfma_f32_16x16x32_bf16 v[24:27], v[140:143], v[180:183], v[24:27]
	v_mfma_f32_16x16x32_bf16 v[12:15], v[132:135], v[224:227], v[12:15]
	v_mfma_f32_16x16x32_bf16 v[8:11], v[140:143], v[224:227], v[8:11]
	v_mfma_f32_16x16x32_bf16 v[52:55], v[144:147], v[160:163], v[52:55]
	v_mfma_f32_16x16x32_bf16 v[48:51], v[152:155], v[160:163], v[48:51]
	v_mfma_f32_16x16x32_bf16 v[36:39], v[144:147], v[168:171], v[36:39]
	v_mfma_f32_16x16x32_bf16 v[32:35], v[152:155], v[168:171], v[32:35]
	v_mfma_f32_16x16x32_bf16 v[20:23], v[144:147], v[176:179], v[20:23]
	v_mfma_f32_16x16x32_bf16 v[16:19], v[152:155], v[176:179], v[16:19]
	v_mfma_f32_16x16x32_bf16 v[4:7], v[144:147], v[220:223], v[4:7]
	v_mfma_f32_16x16x32_bf16 v[0:3], v[152:155], v[220:223], v[0:3]
	v_mfma_f32_16x16x32_bf16 v[52:55], v[148:151], v[164:167], v[52:55]
	v_mfma_f32_16x16x32_bf16 v[48:51], v[156:159], v[164:167], v[48:51]
	v_mfma_f32_16x16x32_bf16 v[36:39], v[148:151], v[172:175], v[36:39]
	v_mfma_f32_16x16x32_bf16 v[32:35], v[156:159], v[172:175], v[32:35]
	v_mfma_f32_16x16x32_bf16 v[20:23], v[148:151], v[180:183], v[20:23]
	v_mfma_f32_16x16x32_bf16 v[16:19], v[156:159], v[180:183], v[16:19]
	v_mfma_f32_16x16x32_bf16 v[4:7], v[148:151], v[224:227], v[4:7]
	v_mfma_f32_16x16x32_bf16 v[0:3], v[156:159], v[224:227], v[0:3]
	s_barrier
	s_add_i32 s72, s72, 2
	s_add_u32 s68, s68, 0x10000
	s_addc_u32 s69, s69, 0
	s_add_u32 s70, s70, 0x10000
	s_addc_u32 s71, s71, 0
	s_cmp_gt_u32 s72, 13
	s_cbranch_scc0 .LBB0_751
	s_and_b64 vcc, exec, s[48:49]
	s_cbranch_vccz .LBB0_754
	s_barrier

; #define PG8_STAGE(bufoff, gbase, voff) do { _Pragma("unroll") for (int _i = 0; _i < 2; ++_i) \
;         __builtin_amdgcn_global_load_lds((const unsigned*)((const char*)(gbase) + (voff)[_i]), (PG8_LAS unsigned*)(lds + (bufoff) + ldsw + _i * 8192), 16, 0, 0); } while (0)
; #define PG8_LDA(dst, b, h) do { _Pragma("unroll") for (int m = 0; m < 4; ++m) _Pragma("unroll") for (int k = 0; k < 2; ++k) dst[m][k] = *(const PG8_LAS bf16x8*)(lds + PG8_SA(b, h) + aoff + m * 2048 + k * 1024); } while (0)
; #define PG8_LDB(dst, b, h) do { _Pragma("unroll") for (int n = 0; n < 2; ++n) _Pragma("unroll") for (int k = 0; k < 2; ++k) dst[n][k] = *(const PG8_LAS bf16x8*)(lds + PG8_SB(b, h) + boff + n * 2048 + k * 1024); } while (0)
; #define PG8_WAIT_V(n) asm volatile("s_waitcnt vmcnt(" #n ")" ::: "memory")
; #define PG8_WAIT_L(n) asm volatile("s_waitcnt lgkmcnt(" #n ")" ::: "memory")
; #define PG8_BAR __builtin_amdgcn_s_barrier()
; #define PG8_SCHED __builtin_amdgcn_sched_barrier(0)
; template <class Epi, class Sched, bool ALIGN_EPI = false, bool SP2 = false>
; __device__ __forceinline__ void gemm_phase(PG8_LAS unsigned char* lds, const Gemm g, const Sched& S, const Epi& E) {
;     ...
;         const char* nA = has_next ? (const char*)g.A + (size_t)nxt.pm * tstepA : cA; const char* nB = has_next ? (const char*)g.Bt + (size_t)nxt.pn * tstepB : cB;
;         for (int t = 0; t < nt; t += 2) {
;             const bool last = (t == nt - 2);
;             const char* a1 = cA + (size_t)(t + 1) * kstepA;
;             const char* a2 = last ? nA : cA + (size_t)(t + 2) * kstepA; const char* b2 = last ? nB : cB + (size_t)(t + 2) * kstep;
;             const char* a3 = a2 + kstepA; const char* b3 = b2 + kstep;
;             if (last && has_next) S.a_ready(nxt);
;             if constexpr (SP2) {
;             PG8_LDB(B0, 0, 0); PG8_LDB(B1, 0, 1); PG8_SCHED; PG8_LDA(At, 0, 0); PG8_STAGE(PG8_SA(1, 1), a1 + hstepA, voffA);
;             PG8_WAIT_V(8); PG8_WAIT_L(0); PG8_BAR; PG8_MMA(0, 0, At, B0); PG8_MMA(0, 1, At, B1); PG8_BAR; PG8_SCHED;
;             PG8_LDA(At, 0, 1); PG8_STAGE(PG8_SB(0, 0), b2, voffB); PG8_STAGE(PG8_SB(0, 1), b2 + hstepB, voffB); PG8_STAGE(PG8_SA(0, 0), a2, voffA);
;             PG8_WAIT_V(8); PG8_WAIT_L(0); PG8_BAR; PG8_MMA(1, 0, At, B0); PG8_MMA(1, 1, At, B1); PG8_BAR; PG8_SCHED;
.LBB0_837:
	s_ashr_i32 s55, s54, 31
	s_lshl_b64 s[56:57], s[54:55], 19
	s_add_u32 s56, s12, s56
	s_addc_u32 s57, s13, s57
	s_and_b64 s[58:59], s[2:3], exec
	s_cselect_b32 s55, s57, s63
	s_cselect_b32 s80, s56, s62
	s_ashr_i32 s53, s52, 31
	s_lshl_b64 s[58:59], s[52:53], 19
	s_add_u32 s58, s33, s58
	s_addc_u32 s59, s83, s59
	s_and_b64 s[78:79], s[2:3], exec
	s_cselect_b32 s53, s59, s65
	s_cselect_b32 s81, s58, s64
	s_add_u32 s62, s62, 0x10000
	s_addc_u32 s63, s63, 0
	s_add_u32 s64, s64, 0x10000
	s_addc_u32 s65, s65, 0
	s_mov_b32 s82, -2
	ds_read_b128 v[148:151], v141
	ds_read_b128 v[152:155], v141 offset:1024
	ds_read_b128 v[156:159], v141 offset:2048
	ds_read_b128 v[160:163], v141 offset:3072
	ds_read_b128 v[164:167], v142
	ds_read_b128 v[168:171], v142 offset:1024
	ds_read_b128 v[172:175], v142 offset:2048
	ds_read_b128 v[176:179], v142 offset:3072
	s_cmp_eq_u32 s82, 12
	s_cselect_b32 s79, s55, s63
	s_cselect_b32 s78, s80, s62
	s_cselect_b32 s85, s53, s65
	s_cselect_b32 s84, s81, s64
	v_lshl_add_u64 v[216:217], s[62:63], 0, v[190:191]
	v_lshl_add_u64 v[220:221], v[216:217], 0, s[46:47]
	s_add_i32 m0, s18, 0xc000
	ds_read_b128 v[180:183], v143
	ds_read_b128 v[184:187], v143 offset:1024
	ds_read_b128 v[192:195], v143 offset:2048
	ds_read_b128 v[196:199], v143 offset:3072
	ds_read_b128 v[200:203], v143 offset:4096
	ds_read_b128 v[204:207], v143 offset:5120
	ds_read_b128 v[208:211], v143 offset:6144
	ds_read_b128 v[212:215], v143 offset:7168
	global_load_lds_dwordx4 v[220:221], off
	v_lshl_add_u64 v[216:217], v[216:217], 0, s[48:49]
	s_add_i32 m0, s18, 0xe000
	s_nop 0
	global_load_lds_dwordx4 v[216:217], off
	s_waitcnt vmcnt(8)
	s_waitcnt lgkmcnt(0)
	s_barrier
	s_waitcnt lgkmcnt(0)
	v_mfma_f32_16x16x32_bf16 v[116:119], v[148:151], v[180:183], 0
	v_mfma_f32_16x16x32_bf16 v[112:115], v[156:159], v[180:183], 0
	v_mfma_f32_16x16x32_bf16 v[108:111], v[148:151], v[192:195], 0
	v_mfma_f32_16x16x32_bf16 v[100:103], v[156:159], v[192:195], 0
	v_mfma_f32_16x16x32_bf16 v[92:95], v[148:151], v[200:203], 0
	v_mfma_f32_16x16x32_bf16 v[84:87], v[156:159], v[200:203], 0
	v_mfma_f32_16x16x32_bf16 v[76:79], v[148:151], v[208:211], 0
	v_mfma_f32_16x16x32_bf16 v[68:71], v[156:159], v[208:211], 0
	v_mfma_f32_16x16x32_bf16 v[116:119], v[152:155], v[184:187], v[116:119]
	v_mfma_f32_16x16x32_bf16 v[112:115], v[160:163], v[184:187], v[112:115]
	v_mfma_f32_16x16x32_bf16 v[108:111], v[152:155], v[196:199], v[108:111]
	v_mfma_f32_16x16x32_bf16 v[100:103], v[160:163], v[196:199], v[100:103]
	v_mfma_f32_16x16x32_bf16 v[92:95], v[152:155], v[204:207], v[92:95]
	v_mfma_f32_16x16x32_bf16 v[84:87], v[160:163], v[204:207], v[84:87]
	v_mfma_f32_16x16x32_bf16 v[76:79], v[152:155], v[212:215], v[76:79]
	v_mfma_f32_16x16x32_bf16 v[68:71], v[160:163], v[212:215], v[68:71]
	v_mfma_f32_16x16x32_bf16 v[124:127], v[164:167], v[180:183], 0
	v_mfma_f32_16x16x32_bf16 v[120:123], v[172:175], v[180:183], 0
	v_mfma_f32_16x16x32_bf16 v[104:107], v[164:167], v[192:195], 0
	v_mfma_f32_16x16x32_bf16 v[96:99], v[172:175], v[192:195], 0
	v_mfma_f32_16x16x32_bf16 v[88:91], v[164:167], v[200:203], 0
	v_mfma_f32_16x16x32_bf16 v[80:83], v[172:175], v[200:203], 0
	v_mfma_f32_16x16x32_bf16 v[72:75], v[164:167], v[208:211], 0
	v_mfma_f32_16x16x32_bf16 v[64:67], v[172:175], v[208:211], 0
	v_mfma_f32_16x16x32_bf16 v[124:127], v[168:171], v[184:187], v[124:127]
	v_mfma_f32_16x16x32_bf16 v[120:123], v[176:179], v[184:187], v[120:123]
	v_mfma_f32_16x16x32_bf16 v[104:107], v[168:171], v[196:199], v[104:107]
	v_mfma_f32_16x16x32_bf16 v[96:99], v[176:179], v[196:199], v[96:99]
	v_mfma_f32_16x16x32_bf16 v[88:91], v[168:171], v[204:207], v[88:91]
	v_mfma_f32_16x16x32_bf16 v[80:83], v[176:179], v[204:207], v[80:83]
	v_mfma_f32_16x16x32_bf16 v[72:75], v[168:171], v[212:215], v[72:75]
	v_mfma_f32_16x16x32_bf16 v[64:67], v[176:179], v[212:215], v[64:67]
	s_barrier
	v_lshl_add_u64 v[216:217], s[84:85], 0, v[190:191]
	s_add_i32 s84, s74, s14
	s_mov_b32 m0, s84
	ds_read_b128 v[180:183], v143 offset:16384
	ds_read_b128 v[184:187], v143 offset:17408
	ds_read_b128 v[192:195], v143 offset:18432
	ds_read_b128 v[196:199], v143 offset:19456
	ds_read_b128 v[200:203], v143 offset:20480
	ds_read_b128 v[204:207], v143 offset:21504
	ds_read_b128 v[208:211], v143 offset:22528
	ds_read_b128 v[212:215], v143 offset:23552
	global_load_lds_dwordx4 v[216:217], off
	v_lshl_add_u64 v[220:221], v[216:217], 0, s[6:7]
	s_add_i32 m0, s84, 0x2000
	s_add_i32 s84, s75, s14
	global_load_lds_dwordx4 v[220:221], off
	v_lshl_add_u64 v[220:221], v[216:217], 0, s[8:9]
	s_mov_b32 m0, s84
	s_nop 0
	global_load_lds_dwordx4 v[220:221], off
	v_lshl_add_u64 v[220:221], v[216:217], 0, s[10:11]
	s_add_i32 m0, s84, 0x2000
	s_nop 0
	global_load_lds_dwordx4 v[220:221], off
	v_lshl_add_u64 v[220:221], s[78:79], 0, v[190:191]
	s_mov_b32 m0, s18
	v_lshl_add_u64 v[222:223], v[220:221], 0, s[6:7]
	global_load_lds_dwordx4 v[220:221], off
	s_mov_b32 m0, s19
	s_nop 0
	global_load_lds_dwordx4 v[222:223], off
	s_waitcnt vmcnt(8)
	s_waitcnt lgkmcnt(0)
	s_barrier
; #define PG8_STAGE(bufoff, gbase, voff) do { _Pragma("unroll") for (int _i = 0; _i < 2; ++_i) \
;         __builtin_amdgcn_global_load_lds((const unsigned*)((const char*)(gbase) + (voff)[_i]), (PG8_LAS unsigned*)(lds + (bufoff) + ldsw + _i * 8192), 16, 0, 0); } while (0)
; #define PG8_LDA(dst, b, h) do { _Pragma("unroll") for (int m = 0; m < 4; ++m) _Pragma("unroll") for (int k = 0; k < 2; ++k) dst[m][k] = *(const PG8_LAS bf16x8*)(lds + PG8_SA(b, h) + aoff + m * 2048 + k * 1024); } while (0)
; #define PG8_LDB(dst, b, h) do { _Pragma("unroll") for (int n = 0; n < 2; ++n) _Pragma("unroll") for (int k = 0; k < 2; ++k) dst[n][k] = *(const PG8_LAS bf16x8*)(lds + PG8_SB(b, h) + boff + n * 2048 + k * 1024); } while (0)
; #define PG8_MMA(ai, bj, At, Bt) do { __builtin_amdgcn_s_setprio(1); _Pragma("unroll") for (int m = 0; m < 4; ++m) _Pragma("unroll") for (int n = 0; n < 2; ++n) _Pragma("unroll") for (int k = 0; k < 2; ++k) \
;         acc[ai][bj][m][n] = __builtin_amdgcn_mfma_f32_16x16x32_bf16(Bt[n][k], At[m][k], acc[ai][bj][m][n], 0, 0, 0); __builtin_amdgcn_s_setprio(0); } while (0)
; #define PG8_WAIT_V(n) asm volatile("s_waitcnt vmcnt(" #n ")" ::: "memory")
; #define PG8_WAIT_L(n) asm volatile("s_waitcnt lgkmcnt(" #n ")" ::: "memory")
; #define PG8_BAR __builtin_amdgcn_s_barrier()
; #define PG8_SCHED __builtin_amdgcn_sched_barrier(0)
; template <class Epi, class Sched, bool ALIGN_EPI = false, bool SP2 = false>
; __device__ __forceinline__ void gemm_phase(PG8_LAS unsigned char* lds, const Gemm g, const Sched& S, const Epi& E) {
;     ...
;             PG8_WAIT_V(8); PG8_WAIT_L(0); PG8_BAR; PG8_MMA(1, 0, At, B0); PG8_MMA(1, 1, At, B1); PG8_BAR; PG8_SCHED;
;             PG8_LDB(B0, 1, 0); PG8_LDB(B1, 1, 1); PG8_SCHED; PG8_LDA(At, 1, 0); PG8_STAGE(PG8_SA(0, 1), a2 + hstepA, voffA);
;             PG8_WAIT_V(8); PG8_WAIT_L(0); PG8_BAR; PG8_MMA(0, 0, At, B0); PG8_MMA(0, 1, At, B1); PG8_BAR; PG8_SCHED;
	s_waitcnt lgkmcnt(0)
	v_mfma_f32_16x16x32_bf16 v[60:63], v[148:151], v[180:183], 0
	v_mfma_f32_16x16x32_bf16 v[52:55], v[156:159], v[180:183], 0
	v_mfma_f32_16x16x32_bf16 v[44:47], v[148:151], v[192:195], 0
	v_mfma_f32_16x16x32_bf16 v[36:39], v[156:159], v[192:195], 0
	v_mfma_f32_16x16x32_bf16 v[28:31], v[148:151], v[200:203], 0
	v_mfma_f32_16x16x32_bf16 v[20:23], v[156:159], v[200:203], 0
	v_mfma_f32_16x16x32_bf16 v[12:15], v[148:151], v[208:211], 0
	v_mfma_f32_16x16x32_bf16 v[4:7], v[156:159], v[208:211], 0
	v_mfma_f32_16x16x32_bf16 v[60:63], v[152:155], v[184:187], v[60:63]
	v_mfma_f32_16x16x32_bf16 v[52:55], v[160:163], v[184:187], v[52:55]
	v_mfma_f32_16x16x32_bf16 v[44:47], v[152:155], v[196:199], v[44:47]
	v_mfma_f32_16x16x32_bf16 v[36:39], v[160:163], v[196:199], v[36:39]
	v_mfma_f32_16x16x32_bf16 v[28:31], v[152:155], v[204:207], v[28:31]
	v_mfma_f32_16x16x32_bf16 v[20:23], v[160:163], v[204:207], v[20:23]
	v_mfma_f32_16x16x32_bf16 v[12:15], v[152:155], v[212:215], v[12:15]
	v_mfma_f32_16x16x32_bf16 v[4:7], v[160:163], v[212:215], v[4:7]
	v_mfma_f32_16x16x32_bf16 v[56:59], v[164:167], v[180:183], 0
	v_mfma_f32_16x16x32_bf16 v[48:51], v[172:175], v[180:183], 0
	v_mfma_f32_16x16x32_bf16 v[40:43], v[164:167], v[192:195], 0
	v_mfma_f32_16x16x32_bf16 v[32:35], v[172:175], v[192:195], 0
	v_mfma_f32_16x16x32_bf16 v[24:27], v[164:167], v[200:203], 0
	v_mfma_f32_16x16x32_bf16 v[16:19], v[172:175], v[200:203], 0
	v_mfma_f32_16x16x32_bf16 v[8:11], v[164:167], v[208:211], 0
	v_mfma_f32_16x16x32_bf16 v[0:3], v[172:175], v[208:211], 0
	v_mfma_f32_16x16x32_bf16 v[56:59], v[168:171], v[184:187], v[56:59]
	v_mfma_f32_16x16x32_bf16 v[48:51], v[176:179], v[184:187], v[48:51]
	v_mfma_f32_16x16x32_bf16 v[40:43], v[168:171], v[196:199], v[40:43]
	v_mfma_f32_16x16x32_bf16 v[32:35], v[176:179], v[196:199], v[32:35]
	v_mfma_f32_16x16x32_bf16 v[24:27], v[168:171], v[204:207], v[24:27]
	v_mfma_f32_16x16x32_bf16 v[16:19], v[176:179], v[204:207], v[16:19]
	v_mfma_f32_16x16x32_bf16 v[8:11], v[168:171], v[212:215], v[8:11]
	v_mfma_f32_16x16x32_bf16 v[0:3], v[176:179], v[212:215], v[0:3]
	s_barrier
	ds_read_b128 v[148:151], v144
	ds_read_b128 v[152:155], v144 offset:1024
	ds_read_b128 v[156:159], v144 offset:2048
	ds_read_b128 v[160:163], v144 offset:3072
	ds_read_b128 v[164:167], v145
	ds_read_b128 v[168:171], v145 offset:1024
	ds_read_b128 v[172:175], v145 offset:2048
	ds_read_b128 v[176:179], v145 offset:3072
	s_mov_b32 m0, s66
	v_lshl_add_u64 v[222:223], v[220:221], 0, s[8:9]
	ds_read_b128 v[180:183], v143 offset:32768
	ds_read_b128 v[184:187], v143 offset:33792
	ds_read_b128 v[192:195], v143 offset:34816
	ds_read_b128 v[196:199], v143 offset:35840
	ds_read_b128 v[200:203], v143 offset:36864
	ds_read_b128 v[204:207], v143 offset:37888
	ds_read_b128 v[208:211], v143 offset:38912
	ds_read_b128 v[212:215], v143 offset:39936
	global_load_lds_dwordx4 v[222:223], off
	v_lshl_add_u64 v[222:223], v[220:221], 0, s[10:11]
	s_mov_b32 m0, s67
	s_nop 0
	global_load_lds_dwordx4 v[222:223], off
	s_waitcnt vmcnt(8)
	s_waitcnt lgkmcnt(0)
	s_barrier
	s_waitcnt lgkmcnt(0)
	v_mfma_f32_16x16x32_bf16 v[116:119], v[148:151], v[180:183], v[116:119]
	v_mfma_f32_16x16x32_bf16 v[112:115], v[156:159], v[180:183], v[112:115]
	v_mfma_f32_16x16x32_bf16 v[108:111], v[148:151], v[192:195], v[108:111]
	v_mfma_f32_16x16x32_bf16 v[100:103], v[156:159], v[192:195], v[100:103]
	v_mfma_f32_16x16x32_bf16 v[92:95], v[148:151], v[200:203], v[92:95]
	v_mfma_f32_16x16x32_bf16 v[84:87], v[156:159], v[200:203], v[84:87]
	v_mfma_f32_16x16x32_bf16 v[76:79], v[148:151], v[208:211], v[76:79]
	v_mfma_f32_16x16x32_bf16 v[68:71], v[156:159], v[208:211], v[68:71]
	v_mfma_f32_16x16x32_bf16 v[116:119], v[152:155], v[184:187], v[116:119]
	v_mfma_f32_16x16x32_bf16 v[112:115], v[160:163], v[184:187], v[112:115]
	v_mfma_f32_16x16x32_bf16 v[108:111], v[152:155], v[196:199], v[108:111]
	v_mfma_f32_16x16x32_bf16 v[100:103], v[160:163], v[196:199], v[100:103]
	v_mfma_f32_16x16x32_bf16 v[92:95], v[152:155], v[204:207], v[92:95]
	v_mfma_f32_16x16x32_bf16 v[84:87], v[160:163], v[204:207], v[84:87]
	v_mfma_f32_16x16x32_bf16 v[76:79], v[152:155], v[212:215], v[76:79]
	v_mfma_f32_16x16x32_bf16 v[68:71], v[160:163], v[212:215], v[68:71]
	v_mfma_f32_16x16x32_bf16 v[124:127], v[164:167], v[180:183], v[124:127]
	v_mfma_f32_16x16x32_bf16 v[120:123], v[172:175], v[180:183], v[120:123]
	v_mfma_f32_16x16x32_bf16 v[104:107], v[164:167], v[192:195], v[104:107]
	v_mfma_f32_16x16x32_bf16 v[96:99], v[172:175], v[192:195], v[96:99]
	v_mfma_f32_16x16x32_bf16 v[88:91], v[164:167], v[200:203], v[88:91]
	v_mfma_f32_16x16x32_bf16 v[80:83], v[172:175], v[200:203], v[80:83]
	v_mfma_f32_16x16x32_bf16 v[72:75], v[164:167], v[208:211], v[72:75]
	v_mfma_f32_16x16x32_bf16 v[64:67], v[172:175], v[208:211], v[64:67]
	v_mfma_f32_16x16x32_bf16 v[124:127], v[168:171], v[184:187], v[124:127]
	v_mfma_f32_16x16x32_bf16 v[120:123], v[176:179], v[184:187], v[120:123]
	v_mfma_f32_16x16x32_bf16 v[104:107], v[168:171], v[196:199], v[104:107]
	v_mfma_f32_16x16x32_bf16 v[96:99], v[176:179], v[196:199], v[96:99]
	v_mfma_f32_16x16x32_bf16 v[88:91], v[168:171], v[204:207], v[88:91]
	v_mfma_f32_16x16x32_bf16 v[80:83], v[176:179], v[204:207], v[80:83]
	v_mfma_f32_16x16x32_bf16 v[72:75], v[168:171], v[212:215], v[72:75]
	v_mfma_f32_16x16x32_bf16 v[64:67], v[176:179], v[212:215], v[64:67]
	s_barrier
; #define PG8_STAGE(bufoff, gbase, voff) do { _Pragma("unroll") for (int _i = 0; _i < 2; ++_i) \
;         __builtin_amdgcn_global_load_lds((const unsigned*)((const char*)(gbase) + (voff)[_i]), (PG8_LAS unsigned*)(lds + (bufoff) + ldsw + _i * 8192), 16, 0, 0); } while (0)
; #define PG8_LDA(dst, b, h) do { _Pragma("unroll") for (int m = 0; m < 4; ++m) _Pragma("unroll") for (int k = 0; k < 2; ++k) dst[m][k] = *(const PG8_LAS bf16x8*)(lds + PG8_SA(b, h) + aoff + m * 2048 + k * 1024); } while (0)
; #define PG8_LDB(dst, b, h) do { _Pragma("unroll") for (int n = 0; n < 2; ++n) _Pragma("unroll") for (int k = 0; k < 2; ++k) dst[n][k] = *(const PG8_LAS bf16x8*)(lds + PG8_SB(b, h) + boff + n * 2048 + k * 1024); } while (0)
; #define PG8_MMA(ai, bj, At, Bt) do { __builtin_amdgcn_s_setprio(1); _Pragma("unroll") for (int m = 0; m < 4; ++m) _Pragma("unroll") for (int n = 0; n < 2; ++n) _Pragma("unroll") for (int k = 0; k < 2; ++k) \
;         acc[ai][bj][m][n] = __builtin_amdgcn_mfma_f32_16x16x32_bf16(Bt[n][k], At[m][k], acc[ai][bj][m][n], 0, 0, 0); __builtin_amdgcn_s_setprio(0); } while (0)
; #define PG8_WAIT_V(n) asm volatile("s_waitcnt vmcnt(" #n ")" ::: "memory")
; template <class Epi, class Sched, bool ALIGN_EPI = false, bool SP2 = false>
; __device__ __forceinline__ void gemm_phase(PG8_LAS unsigned char* lds, const Gemm g, const Sched& S, const Epi& E) {
;     ...
;             PG8_LDB(B0, 0, 0); PG8_LDB(B1, 0, 1); PG8_SCHED; PG8_LDA(At, 0, 0); PG8_STAGE(PG8_SA(1, 1), a1 + hstepA, voffA);
;             PG8_WAIT_V(8); PG8_WAIT_L(0); PG8_BAR; PG8_MMA(0, 0, At, B0); PG8_MMA(0, 1, At, B1); PG8_BAR; PG8_SCHED;
;             PG8_LDA(At, 0, 1); PG8_STAGE(PG8_SB(0, 0), b2, voffB); PG8_STAGE(PG8_SB(0, 1), b2 + hstepB, voffB); PG8_STAGE(PG8_SA(0, 0), a2, voffA);
;             PG8_WAIT_V(8); PG8_WAIT_L(0); PG8_BAR; PG8_MMA(1, 0, At, B0); PG8_MMA(1, 1, At, B1); PG8_BAR; PG8_SCHED;
;             PG8_LDB(B0, 1, 0); PG8_LDB(B1, 1, 1); PG8_SCHED; PG8_LDA(At, 1, 0); PG8_STAGE(PG8_SA(0, 1), a2 + hstepA, voffA);
;             PG8_WAIT_V(8); PG8_WAIT_L(0); PG8_BAR; PG8_MMA(0, 0, At, B0); PG8_MMA(0, 1, At, B1); PG8_BAR; PG8_SCHED;
;             PG8_LDA(At, 1, 1); PG8_STAGE(PG8_SB(1, 0), b3, voffB); PG8_STAGE(PG8_SB(1, 1), b3 + hstepB, voffB); PG8_STAGE(PG8_SA(1, 0), a3, voffA);
;             PG8_WAIT_V(8); PG8_WAIT_L(0); PG8_BAR; PG8_MMA(1, 0, At, B0); PG8_MMA(1, 1, At, B1); PG8_BAR; PG8_SCHED;
	s_add_i32 s78, s76, s14
	v_lshl_add_u64 v[222:223], v[216:217], 0, s[34:35]
	s_mov_b32 m0, s78
	ds_read_b128 v[180:183], v143 offset:49152
	ds_read_b128 v[184:187], v143 offset:50176
	ds_read_b128 v[192:195], v143 offset:51200
	ds_read_b128 v[196:199], v143 offset:52224
	ds_read_b128 v[200:203], v143 offset:53248
	ds_read_b128 v[204:207], v143 offset:54272
	ds_read_b128 v[208:211], v143 offset:55296
	ds_read_b128 v[212:215], v143 offset:56320
	global_load_lds_dwordx4 v[222:223], off
	v_lshl_add_u64 v[222:223], v[216:217], 0, s[36:37]
	s_add_i32 m0, s78, 0x2000
	s_add_i32 s78, s77, s14
	global_load_lds_dwordx4 v[222:223], off
	v_lshl_add_u64 v[222:223], v[216:217], 0, s[38:39]
	s_mov_b32 m0, s78
	v_lshl_add_u64 v[216:217], v[216:217], 0, s[40:41]
	global_load_lds_dwordx4 v[222:223], off
	s_add_i32 m0, s78, 0x2000
	s_nop 0
	global_load_lds_dwordx4 v[216:217], off
	v_lshl_add_u64 v[216:217], v[220:221], 0, s[34:35]
	s_mov_b32 m0, s68
	s_nop 0
	global_load_lds_dwordx4 v[216:217], off
	v_lshl_add_u64 v[216:217], v[220:221], 0, s[36:37]
	s_mov_b32 m0, s69
	s_nop 0
	global_load_lds_dwordx4 v[216:217], off
	s_waitcnt vmcnt(8)
	s_waitcnt lgkmcnt(0)
	s_barrier
	s_waitcnt lgkmcnt(0)
	v_mfma_f32_16x16x32_bf16 v[60:63], v[148:151], v[180:183], v[60:63]
	v_mfma_f32_16x16x32_bf16 v[52:55], v[156:159], v[180:183], v[52:55]
	v_mfma_f32_16x16x32_bf16 v[44:47], v[148:151], v[192:195], v[44:47]
	v_mfma_f32_16x16x32_bf16 v[36:39], v[156:159], v[192:195], v[36:39]
	v_mfma_f32_16x16x32_bf16 v[28:31], v[148:151], v[200:203], v[28:31]
	v_mfma_f32_16x16x32_bf16 v[20:23], v[156:159], v[200:203], v[20:23]
	v_mfma_f32_16x16x32_bf16 v[12:15], v[148:151], v[208:211], v[12:15]
	v_mfma_f32_16x16x32_bf16 v[4:7], v[156:159], v[208:211], v[4:7]
	v_mfma_f32_16x16x32_bf16 v[60:63], v[152:155], v[184:187], v[60:63]
	v_mfma_f32_16x16x32_bf16 v[52:55], v[160:163], v[184:187], v[52:55]
	v_mfma_f32_16x16x32_bf16 v[44:47], v[152:155], v[196:199], v[44:47]
	v_mfma_f32_16x16x32_bf16 v[36:39], v[160:163], v[196:199], v[36:39]
	v_mfma_f32_16x16x32_bf16 v[28:31], v[152:155], v[204:207], v[28:31]
	v_mfma_f32_16x16x32_bf16 v[20:23], v[160:163], v[204:207], v[20:23]
	v_mfma_f32_16x16x32_bf16 v[12:15], v[152:155], v[212:215], v[12:15]
	v_mfma_f32_16x16x32_bf16 v[4:7], v[160:163], v[212:215], v[4:7]
	v_mfma_f32_16x16x32_bf16 v[56:59], v[164:167], v[180:183], v[56:59]
	v_mfma_f32_16x16x32_bf16 v[48:51], v[172:175], v[180:183], v[48:51]
	v_mfma_f32_16x16x32_bf16 v[40:43], v[164:167], v[192:195], v[40:43]
	v_mfma_f32_16x16x32_bf16 v[32:35], v[172:175], v[192:195], v[32:35]
	v_mfma_f32_16x16x32_bf16 v[24:27], v[164:167], v[200:203], v[24:27]
	v_mfma_f32_16x16x32_bf16 v[16:19], v[172:175], v[200:203], v[16:19]
	v_mfma_f32_16x16x32_bf16 v[8:11], v[164:167], v[208:211], v[8:11]
	v_mfma_f32_16x16x32_bf16 v[0:3], v[172:175], v[208:211], v[0:3]
	v_mfma_f32_16x16x32_bf16 v[56:59], v[168:171], v[184:187], v[56:59]
	v_mfma_f32_16x16x32_bf16 v[48:51], v[176:179], v[184:187], v[48:51]
	v_mfma_f32_16x16x32_bf16 v[40:43], v[168:171], v[196:199], v[40:43]
	v_mfma_f32_16x16x32_bf16 v[32:35], v[176:179], v[196:199], v[32:35]
	v_mfma_f32_16x16x32_bf16 v[24:27], v[168:171], v[204:207], v[24:27]
	v_mfma_f32_16x16x32_bf16 v[16:19], v[176:179], v[204:207], v[16:19]
	v_mfma_f32_16x16x32_bf16 v[8:11], v[168:171], v[212:215], v[8:11]
	v_mfma_f32_16x16x32_bf16 v[0:3], v[176:179], v[212:215], v[0:3]
	s_barrier
	s_add_i32 s82, s82, 2
	s_add_u32 s62, s62, 0x10000
	s_addc_u32 s63, s63, 0
	s_add_u32 s64, s64, 0x10000
	s_addc_u32 s65, s65, 0
	s_cmp_gt_u32 s82, 13
.LBB0_838:
	ds_read_b128 v[148:151], v141
	ds_read_b128 v[152:155], v141 offset:1024
	ds_read_b128 v[156:159], v141 offset:2048
	ds_read_b128 v[160:163], v141 offset:3072
	ds_read_b128 v[164:167], v142
	ds_read_b128 v[168:171], v142 offset:1024
	ds_read_b128 v[172:175], v142 offset:2048
	ds_read_b128 v[176:179], v142 offset:3072
	s_cmp_eq_u32 s82, 12
	s_cselect_b32 s79, s55, s63
	s_cselect_b32 s78, s80, s62
	s_cselect_b32 s85, s53, s65
	s_cselect_b32 s84, s81, s64
	v_lshl_add_u64 v[216:217], s[62:63], 0, v[190:191]
	v_lshl_add_u64 v[220:221], v[216:217], 0, s[46:47]
	s_add_i32 m0, s18, 0xc000
	ds_read_b128 v[180:183], v143
	ds_read_b128 v[184:187], v143 offset:1024
	ds_read_b128 v[192:195], v143 offset:2048
	ds_read_b128 v[196:199], v143 offset:3072
	ds_read_b128 v[200:203], v143 offset:4096
	ds_read_b128 v[204:207], v143 offset:5120
	ds_read_b128 v[208:211], v143 offset:6144
	ds_read_b128 v[212:215], v143 offset:7168
	global_load_lds_dwordx4 v[220:221], off
	v_lshl_add_u64 v[216:217], v[216:217], 0, s[48:49]
	s_add_i32 m0, s18, 0xe000
	s_nop 0
	global_load_lds_dwordx4 v[216:217], off
	s_waitcnt vmcnt(8)
	s_waitcnt lgkmcnt(0)
	s_barrier
; #define PG8_STAGE(bufoff, gbase, voff) do { _Pragma("unroll") for (int _i = 0; _i < 2; ++_i) \
;         __builtin_amdgcn_global_load_lds((const unsigned*)((const char*)(gbase) + (voff)[_i]), (PG8_LAS unsigned*)(lds + (bufoff) + ldsw + _i * 8192), 16, 0, 0); } while (0)
; #define PG8_LDA(dst, b, h) do { _Pragma("unroll") for (int m = 0; m < 4; ++m) _Pragma("unroll") for (int k = 0; k < 2; ++k) dst[m][k] = *(const PG8_LAS bf16x8*)(lds + PG8_SA(b, h) + aoff + m * 2048 + k * 1024); } while (0)
; #define PG8_MMA(ai, bj, At, Bt) do { __builtin_amdgcn_s_setprio(1); _Pragma("unroll") for (int m = 0; m < 4; ++m) _Pragma("unroll") for (int n = 0; n < 2; ++n) _Pragma("unroll") for (int k = 0; k < 2; ++k) \
;         acc[ai][bj][m][n] = __builtin_amdgcn_mfma_f32_16x16x32_bf16(Bt[n][k], At[m][k], acc[ai][bj][m][n], 0, 0, 0); __builtin_amdgcn_s_setprio(0); } while (0)
; #define PG8_WAIT_V(n) asm volatile("s_waitcnt vmcnt(" #n ")" ::: "memory")
; #define PG8_WAIT_L(n) asm volatile("s_waitcnt lgkmcnt(" #n ")" ::: "memory")
; #define PG8_BAR __builtin_amdgcn_s_barrier()
; #define PG8_SCHED __builtin_amdgcn_sched_barrier(0)
; template <class Epi, class Sched, bool ALIGN_EPI = false, bool SP2 = false>
; __device__ __forceinline__ void gemm_phase(PG8_LAS unsigned char* lds, const Gemm g, const Sched& S, const Epi& E) {
;     ...
;             PG8_WAIT_V(8); PG8_WAIT_L(0); PG8_BAR; PG8_MMA(0, 0, At, B0); PG8_MMA(0, 1, At, B1); PG8_BAR; PG8_SCHED;
;             PG8_LDA(At, 0, 1); PG8_STAGE(PG8_SB(0, 0), b2, voffB); PG8_STAGE(PG8_SB(0, 1), b2 + hstepB, voffB); PG8_STAGE(PG8_SA(0, 0), a2, voffA);
;             PG8_WAIT_V(8); PG8_WAIT_L(0); PG8_BAR; PG8_MMA(1, 0, At, B0); PG8_MMA(1, 1, At, B1); PG8_BAR; PG8_SCHED;
	s_waitcnt lgkmcnt(0)
	v_mfma_f32_16x16x32_bf16 v[116:119], v[148:151], v[180:183], v[116:119]
	v_mfma_f32_16x16x32_bf16 v[112:115], v[156:159], v[180:183], v[112:115]
	v_mfma_f32_16x16x32_bf16 v[108:111], v[148:151], v[192:195], v[108:111]
	v_mfma_f32_16x16x32_bf16 v[100:103], v[156:159], v[192:195], v[100:103]
	v_mfma_f32_16x16x32_bf16 v[92:95], v[148:151], v[200:203], v[92:95]
	v_mfma_f32_16x16x32_bf16 v[84:87], v[156:159], v[200:203], v[84:87]
	v_mfma_f32_16x16x32_bf16 v[76:79], v[148:151], v[208:211], v[76:79]
	v_mfma_f32_16x16x32_bf16 v[68:71], v[156:159], v[208:211], v[68:71]
	v_mfma_f32_16x16x32_bf16 v[116:119], v[152:155], v[184:187], v[116:119]
	v_mfma_f32_16x16x32_bf16 v[112:115], v[160:163], v[184:187], v[112:115]
	v_mfma_f32_16x16x32_bf16 v[108:111], v[152:155], v[196:199], v[108:111]
	v_mfma_f32_16x16x32_bf16 v[100:103], v[160:163], v[196:199], v[100:103]
	v_mfma_f32_16x16x32_bf16 v[92:95], v[152:155], v[204:207], v[92:95]
	v_mfma_f32_16x16x32_bf16 v[84:87], v[160:163], v[204:207], v[84:87]
	v_mfma_f32_16x16x32_bf16 v[76:79], v[152:155], v[212:215], v[76:79]
	v_mfma_f32_16x16x32_bf16 v[68:71], v[160:163], v[212:215], v[68:71]
	v_mfma_f32_16x16x32_bf16 v[124:127], v[164:167], v[180:183], v[124:127]
	v_mfma_f32_16x16x32_bf16 v[120:123], v[172:175], v[180:183], v[120:123]
	v_mfma_f32_16x16x32_bf16 v[104:107], v[164:167], v[192:195], v[104:107]
	v_mfma_f32_16x16x32_bf16 v[96:99], v[172:175], v[192:195], v[96:99]
	v_mfma_f32_16x16x32_bf16 v[88:91], v[164:167], v[200:203], v[88:91]
	v_mfma_f32_16x16x32_bf16 v[80:83], v[172:175], v[200:203], v[80:83]
	v_mfma_f32_16x16x32_bf16 v[72:75], v[164:167], v[208:211], v[72:75]
	v_mfma_f32_16x16x32_bf16 v[64:67], v[172:175], v[208:211], v[64:67]
	v_mfma_f32_16x16x32_bf16 v[124:127], v[168:171], v[184:187], v[124:127]
	v_mfma_f32_16x16x32_bf16 v[120:123], v[176:179], v[184:187], v[120:123]
	v_mfma_f32_16x16x32_bf16 v[104:107], v[168:171], v[196:199], v[104:107]
	v_mfma_f32_16x16x32_bf16 v[96:99], v[176:179], v[196:199], v[96:99]
	v_mfma_f32_16x16x32_bf16 v[88:91], v[168:171], v[204:207], v[88:91]
	v_mfma_f32_16x16x32_bf16 v[80:83], v[176:179], v[204:207], v[80:83]
	v_mfma_f32_16x16x32_bf16 v[72:75], v[168:171], v[212:215], v[72:75]
	v_mfma_f32_16x16x32_bf16 v[64:67], v[176:179], v[212:215], v[64:67]
	s_barrier
	v_lshl_add_u64 v[216:217], s[84:85], 0, v[190:191]
	s_add_i32 s84, s74, s14
	s_mov_b32 m0, s84
	ds_read_b128 v[180:183], v143 offset:16384
	ds_read_b128 v[184:187], v143 offset:17408
	ds_read_b128 v[192:195], v143 offset:18432
	ds_read_b128 v[196:199], v143 offset:19456
	ds_read_b128 v[200:203], v143 offset:20480
	ds_read_b128 v[204:207], v143 offset:21504
	ds_read_b128 v[208:211], v143 offset:22528
	ds_read_b128 v[212:215], v143 offset:23552
	global_load_lds_dwordx4 v[216:217], off
	v_lshl_add_u64 v[220:221], v[216:217], 0, s[6:7]
	s_add_i32 m0, s84, 0x2000
	s_add_i32 s84, s75, s14
	global_load_lds_dwordx4 v[220:221], off
	v_lshl_add_u64 v[220:221], v[216:217], 0, s[8:9]
	s_mov_b32 m0, s84
	s_nop 0
	global_load_lds_dwordx4 v[220:221], off
	v_lshl_add_u64 v[220:221], v[216:217], 0, s[10:11]
	s_add_i32 m0, s84, 0x2000
	s_nop 0
	global_load_lds_dwordx4 v[220:221], off
	v_lshl_add_u64 v[220:221], s[78:79], 0, v[190:191]
	s_mov_b32 m0, s18
	v_lshl_add_u64 v[222:223], v[220:221], 0, s[6:7]
	global_load_lds_dwordx4 v[220:221], off
	s_mov_b32 m0, s19
	s_nop 0
	global_load_lds_dwordx4 v[222:223], off
	s_waitcnt vmcnt(8)
	s_waitcnt lgkmcnt(0)
	s_barrier
	s_waitcnt lgkmcnt(0)
	v_mfma_f32_16x16x32_bf16 v[60:63], v[148:151], v[180:183], v[60:63]
	v_mfma_f32_16x16x32_bf16 v[52:55], v[156:159], v[180:183], v[52:55]
	v_mfma_f32_16x16x32_bf16 v[44:47], v[148:151], v[192:195], v[44:47]
	v_mfma_f32_16x16x32_bf16 v[36:39], v[156:159], v[192:195], v[36:39]
	v_mfma_f32_16x16x32_bf16 v[28:31], v[148:151], v[200:203], v[28:31]
	v_mfma_f32_16x16x32_bf16 v[20:23], v[156:159], v[200:203], v[20:23]
	v_mfma_f32_16x16x32_bf16 v[12:15], v[148:151], v[208:211], v[12:15]
	v_mfma_f32_16x16x32_bf16 v[4:7], v[156:159], v[208:211], v[4:7]
	v_mfma_f32_16x16x32_bf16 v[60:63], v[152:155], v[184:187], v[60:63]
	v_mfma_f32_16x16x32_bf16 v[52:55], v[160:163], v[184:187], v[52:55]
	v_mfma_f32_16x16x32_bf16 v[44:47], v[152:155], v[196:199], v[44:47]
	v_mfma_f32_16x16x32_bf16 v[36:39], v[160:163], v[196:199], v[36:39]
	v_mfma_f32_16x16x32_bf16 v[28:31], v[152:155], v[204:207], v[28:31]
	v_mfma_f32_16x16x32_bf16 v[20:23], v[160:163], v[204:207], v[20:23]
	v_mfma_f32_16x16x32_bf16 v[12:15], v[152:155], v[212:215], v[12:15]
	v_mfma_f32_16x16x32_bf16 v[4:7], v[160:163], v[212:215], v[4:7]
	v_mfma_f32_16x16x32_bf16 v[56:59], v[164:167], v[180:183], v[56:59]
	v_mfma_f32_16x16x32_bf16 v[48:51], v[172:175], v[180:183], v[48:51]
	v_mfma_f32_16x16x32_bf16 v[40:43], v[164:167], v[192:195], v[40:43]
	v_mfma_f32_16x16x32_bf16 v[32:35], v[172:175], v[192:195], v[32:35]
	v_mfma_f32_16x16x32_bf16 v[24:27], v[164:167], v[200:203], v[24:27]
	v_mfma_f32_16x16x32_bf16 v[16:19], v[172:175], v[200:203], v[16:19]
	v_mfma_f32_16x16x32_bf16 v[8:11], v[164:167], v[208:211], v[8:11]
	v_mfma_f32_16x16x32_bf16 v[0:3], v[172:175], v[208:211], v[0:3]
	v_mfma_f32_16x16x32_bf16 v[56:59], v[168:171], v[184:187], v[56:59]
	v_mfma_f32_16x16x32_bf16 v[48:51], v[176:179], v[184:187], v[48:51]
	v_mfma_f32_16x16x32_bf16 v[40:43], v[168:171], v[196:199], v[40:43]
	v_mfma_f32_16x16x32_bf16 v[32:35], v[176:179], v[196:199], v[32:35]
	v_mfma_f32_16x16x32_bf16 v[24:27], v[168:171], v[204:207], v[24:27]
	v_mfma_f32_16x16x32_bf16 v[16:19], v[176:179], v[204:207], v[16:19]
	v_mfma_f32_16x16x32_bf16 v[8:11], v[168:171], v[212:215], v[8:11]
	v_mfma_f32_16x16x32_bf16 v[0:3], v[176:179], v[212:215], v[0:3]
	s_barrier
; #define PG8_STAGE(bufoff, gbase, voff) do { _Pragma("unroll") for (int _i = 0; _i < 2; ++_i) \
;         __builtin_amdgcn_global_load_lds((const unsigned*)((const char*)(gbase) + (voff)[_i]), (PG8_LAS unsigned*)(lds + (bufoff) + ldsw + _i * 8192), 16, 0, 0); } while (0)
; #define PG8_LDA(dst, b, h) do { _Pragma("unroll") for (int m = 0; m < 4; ++m) _Pragma("unroll") for (int k = 0; k < 2; ++k) dst[m][k] = *(const PG8_LAS bf16x8*)(lds + PG8_SA(b, h) + aoff + m * 2048 + k * 1024); } while (0)
; #define PG8_LDB(dst, b, h) do { _Pragma("unroll") for (int n = 0; n < 2; ++n) _Pragma("unroll") for (int k = 0; k < 2; ++k) dst[n][k] = *(const PG8_LAS bf16x8*)(lds + PG8_SB(b, h) + boff + n * 2048 + k * 1024); } while (0)
; #define PG8_MMA(ai, bj, At, Bt) do { __builtin_amdgcn_s_setprio(1); _Pragma("unroll") for (int m = 0; m < 4; ++m) _Pragma("unroll") for (int n = 0; n < 2; ++n) _Pragma("unroll") for (int k = 0; k < 2; ++k) \
;         acc[ai][bj][m][n] = __builtin_amdgcn_mfma_f32_16x16x32_bf16(Bt[n][k], At[m][k], acc[ai][bj][m][n], 0, 0, 0); __builtin_amdgcn_s_setprio(0); } while (0)
; #define PG8_WAIT_V(n) asm volatile("s_waitcnt vmcnt(" #n ")" ::: "memory")
; #define PG8_WAIT_L(n) asm volatile("s_waitcnt lgkmcnt(" #n ")" ::: "memory")
; #define PG8_BAR __builtin_amdgcn_s_barrier()
; #define PG8_SCHED __builtin_amdgcn_sched_barrier(0)
; template <class Epi, class Sched, bool ALIGN_EPI = false, bool SP2 = false>
; __device__ __forceinline__ void gemm_phase(PG8_LAS unsigned char* lds, const Gemm g, const Sched& S, const Epi& E) {
;     ...
;             PG8_LDB(B0, 1, 0); PG8_LDB(B1, 1, 1); PG8_SCHED; PG8_LDA(At, 1, 0); PG8_STAGE(PG8_SA(0, 1), a2 + hstepA, voffA);
;             PG8_WAIT_V(8); PG8_WAIT_L(0); PG8_BAR; PG8_MMA(0, 0, At, B0); PG8_MMA(0, 1, At, B1); PG8_BAR; PG8_SCHED;
;             PG8_LDA(At, 1, 1); PG8_STAGE(PG8_SB(1, 0), b3, voffB); PG8_STAGE(PG8_SB(1, 1), b3 + hstepB, voffB); PG8_STAGE(PG8_SA(1, 0), a3, voffA);
;             PG8_WAIT_V(8); PG8_WAIT_L(0); PG8_BAR; PG8_MMA(1, 0, At, B0); PG8_MMA(1, 1, At, B1); PG8_BAR; PG8_SCHED;
;     ...
;         if constexpr (ALIGN_EPI) { if (wr == 0) PG8_BAR; }
	ds_read_b128 v[148:151], v144
	ds_read_b128 v[152:155], v144 offset:1024
	ds_read_b128 v[156:159], v144 offset:2048
	ds_read_b128 v[160:163], v144 offset:3072
	ds_read_b128 v[164:167], v145
	ds_read_b128 v[168:171], v145 offset:1024
	ds_read_b128 v[172:175], v145 offset:2048
	ds_read_b128 v[176:179], v145 offset:3072
	s_mov_b32 m0, s66
	v_lshl_add_u64 v[222:223], v[220:221], 0, s[8:9]
	ds_read_b128 v[180:183], v143 offset:32768
	ds_read_b128 v[184:187], v143 offset:33792
	ds_read_b128 v[192:195], v143 offset:34816
	ds_read_b128 v[196:199], v143 offset:35840
	ds_read_b128 v[200:203], v143 offset:36864
	ds_read_b128 v[204:207], v143 offset:37888
	ds_read_b128 v[208:211], v143 offset:38912
	ds_read_b128 v[212:215], v143 offset:39936
	global_load_lds_dwordx4 v[222:223], off
	v_lshl_add_u64 v[222:223], v[220:221], 0, s[10:11]
	s_mov_b32 m0, s67
	s_nop 0
	global_load_lds_dwordx4 v[222:223], off
	s_waitcnt vmcnt(8)
	s_waitcnt lgkmcnt(0)
	s_barrier
	s_waitcnt lgkmcnt(0)
	v_mfma_f32_16x16x32_bf16 v[116:119], v[148:151], v[180:183], v[116:119]
	v_mfma_f32_16x16x32_bf16 v[112:115], v[156:159], v[180:183], v[112:115]
	v_mfma_f32_16x16x32_bf16 v[108:111], v[148:151], v[192:195], v[108:111]
	v_mfma_f32_16x16x32_bf16 v[100:103], v[156:159], v[192:195], v[100:103]
	v_mfma_f32_16x16x32_bf16 v[92:95], v[148:151], v[200:203], v[92:95]
	v_mfma_f32_16x16x32_bf16 v[84:87], v[156:159], v[200:203], v[84:87]
	v_mfma_f32_16x16x32_bf16 v[76:79], v[148:151], v[208:211], v[76:79]
	v_mfma_f32_16x16x32_bf16 v[68:71], v[156:159], v[208:211], v[68:71]
	v_mfma_f32_16x16x32_bf16 v[116:119], v[152:155], v[184:187], v[116:119]
	v_mfma_f32_16x16x32_bf16 v[112:115], v[160:163], v[184:187], v[112:115]
	v_mfma_f32_16x16x32_bf16 v[108:111], v[152:155], v[196:199], v[108:111]
	v_mfma_f32_16x16x32_bf16 v[100:103], v[160:163], v[196:199], v[100:103]
	v_mfma_f32_16x16x32_bf16 v[92:95], v[152:155], v[204:207], v[92:95]
	v_mfma_f32_16x16x32_bf16 v[84:87], v[160:163], v[204:207], v[84:87]
	v_mfma_f32_16x16x32_bf16 v[76:79], v[152:155], v[212:215], v[76:79]
	v_mfma_f32_16x16x32_bf16 v[68:71], v[160:163], v[212:215], v[68:71]
	v_mfma_f32_16x16x32_bf16 v[124:127], v[164:167], v[180:183], v[124:127]
	v_mfma_f32_16x16x32_bf16 v[120:123], v[172:175], v[180:183], v[120:123]
	v_mfma_f32_16x16x32_bf16 v[104:107], v[164:167], v[192:195], v[104:107]
	v_mfma_f32_16x16x32_bf16 v[96:99], v[172:175], v[192:195], v[96:99]
	v_mfma_f32_16x16x32_bf16 v[88:91], v[164:167], v[200:203], v[88:91]
	v_mfma_f32_16x16x32_bf16 v[80:83], v[172:175], v[200:203], v[80:83]
	v_mfma_f32_16x16x32_bf16 v[72:75], v[164:167], v[208:211], v[72:75]
	v_mfma_f32_16x16x32_bf16 v[64:67], v[172:175], v[208:211], v[64:67]
	v_mfma_f32_16x16x32_bf16 v[124:127], v[168:171], v[184:187], v[124:127]
	v_mfma_f32_16x16x32_bf16 v[120:123], v[176:179], v[184:187], v[120:123]
	v_mfma_f32_16x16x32_bf16 v[104:107], v[168:171], v[196:199], v[104:107]
	v_mfma_f32_16x16x32_bf16 v[96:99], v[176:179], v[196:199], v[96:99]
	v_mfma_f32_16x16x32_bf16 v[88:91], v[168:171], v[204:207], v[88:91]
	v_mfma_f32_16x16x32_bf16 v[80:83], v[176:179], v[204:207], v[80:83]
	v_mfma_f32_16x16x32_bf16 v[72:75], v[168:171], v[212:215], v[72:75]
	v_mfma_f32_16x16x32_bf16 v[64:67], v[176:179], v[212:215], v[64:67]
	s_barrier
	s_add_i32 s78, s76, s14
	v_lshl_add_u64 v[222:223], v[216:217], 0, s[34:35]
	s_mov_b32 m0, s78
	ds_read_b128 v[180:183], v143 offset:49152
	ds_read_b128 v[184:187], v143 offset:50176
	ds_read_b128 v[192:195], v143 offset:51200
	ds_read_b128 v[196:199], v143 offset:52224
	ds_read_b128 v[200:203], v143 offset:53248
	ds_read_b128 v[204:207], v143 offset:54272
	ds_read_b128 v[208:211], v143 offset:55296
	ds_read_b128 v[212:215], v143 offset:56320
	global_load_lds_dwordx4 v[222:223], off
	v_lshl_add_u64 v[222:223], v[216:217], 0, s[36:37]
	s_add_i32 m0, s78, 0x2000
	s_add_i32 s78, s77, s14
	global_load_lds_dwordx4 v[222:223], off
	v_lshl_add_u64 v[222:223], v[216:217], 0, s[38:39]
	s_mov_b32 m0, s78
	v_lshl_add_u64 v[216:217], v[216:217], 0, s[40:41]
	global_load_lds_dwordx4 v[222:223], off
	s_add_i32 m0, s78, 0x2000
	s_nop 0
	global_load_lds_dwordx4 v[216:217], off
	v_lshl_add_u64 v[216:217], v[220:221], 0, s[34:35]
	s_mov_b32 m0, s68
	s_nop 0
	global_load_lds_dwordx4 v[216:217], off
	v_lshl_add_u64 v[216:217], v[220:221], 0, s[36:37]
	s_mov_b32 m0, s69
	s_nop 0
	global_load_lds_dwordx4 v[216:217], off
	s_waitcnt vmcnt(8)
	s_waitcnt lgkmcnt(0)
	s_barrier
	s_waitcnt lgkmcnt(0)
	v_mfma_f32_16x16x32_bf16 v[60:63], v[148:151], v[180:183], v[60:63]
	v_mfma_f32_16x16x32_bf16 v[52:55], v[156:159], v[180:183], v[52:55]
	v_mfma_f32_16x16x32_bf16 v[44:47], v[148:151], v[192:195], v[44:47]
	v_mfma_f32_16x16x32_bf16 v[36:39], v[156:159], v[192:195], v[36:39]
	v_mfma_f32_16x16x32_bf16 v[28:31], v[148:151], v[200:203], v[28:31]
	v_mfma_f32_16x16x32_bf16 v[20:23], v[156:159], v[200:203], v[20:23]
	v_mfma_f32_16x16x32_bf16 v[12:15], v[148:151], v[208:211], v[12:15]
	v_mfma_f32_16x16x32_bf16 v[4:7], v[156:159], v[208:211], v[4:7]
	v_mfma_f32_16x16x32_bf16 v[60:63], v[152:155], v[184:187], v[60:63]
	v_mfma_f32_16x16x32_bf16 v[52:55], v[160:163], v[184:187], v[52:55]
	v_mfma_f32_16x16x32_bf16 v[44:47], v[152:155], v[196:199], v[44:47]
	v_mfma_f32_16x16x32_bf16 v[36:39], v[160:163], v[196:199], v[36:39]
	v_mfma_f32_16x16x32_bf16 v[28:31], v[152:155], v[204:207], v[28:31]
	v_mfma_f32_16x16x32_bf16 v[20:23], v[160:163], v[204:207], v[20:23]
	v_mfma_f32_16x16x32_bf16 v[12:15], v[152:155], v[212:215], v[12:15]
	v_mfma_f32_16x16x32_bf16 v[4:7], v[160:163], v[212:215], v[4:7]
	v_mfma_f32_16x16x32_bf16 v[56:59], v[164:167], v[180:183], v[56:59]
	v_mfma_f32_16x16x32_bf16 v[48:51], v[172:175], v[180:183], v[48:51]
	v_mfma_f32_16x16x32_bf16 v[40:43], v[164:167], v[192:195], v[40:43]
	v_mfma_f32_16x16x32_bf16 v[32:35], v[172:175], v[192:195], v[32:35]
	v_mfma_f32_16x16x32_bf16 v[24:27], v[164:167], v[200:203], v[24:27]
	v_mfma_f32_16x16x32_bf16 v[16:19], v[172:175], v[200:203], v[16:19]
	v_mfma_f32_16x16x32_bf16 v[8:11], v[164:167], v[208:211], v[8:11]
	v_mfma_f32_16x16x32_bf16 v[0:3], v[172:175], v[208:211], v[0:3]
	v_mfma_f32_16x16x32_bf16 v[56:59], v[168:171], v[184:187], v[56:59]
	v_mfma_f32_16x16x32_bf16 v[48:51], v[176:179], v[184:187], v[48:51]
	v_mfma_f32_16x16x32_bf16 v[40:43], v[168:171], v[196:199], v[40:43]
	v_mfma_f32_16x16x32_bf16 v[32:35], v[176:179], v[196:199], v[32:35]
	v_mfma_f32_16x16x32_bf16 v[24:27], v[168:171], v[204:207], v[24:27]
	v_mfma_f32_16x16x32_bf16 v[16:19], v[176:179], v[204:207], v[16:19]
	v_mfma_f32_16x16x32_bf16 v[8:11], v[168:171], v[212:215], v[8:11]
	v_mfma_f32_16x16x32_bf16 v[0:3], v[176:179], v[212:215], v[0:3]
	s_barrier
	s_add_i32 s82, s82, 2
	s_add_u32 s62, s62, 0x10000
	s_addc_u32 s63, s63, 0
	s_add_u32 s64, s64, 0x10000
	s_addc_u32 s65, s65, 0
	s_cmp_gt_u32 s82, 13
	s_cbranch_scc0 .LBB0_838
	s_and_b64 vcc, exec, s[44:45]
	s_cbranch_vccz .LBB0_841
	s_barrier

; #define PG8_STAGE(bufoff, gbase, voff) do { _Pragma("unroll") for (int _i = 0; _i < 2; ++_i) \
;         __builtin_amdgcn_global_load_lds((const unsigned*)((const char*)(gbase) + (voff)[_i]), (PG8_LAS unsigned*)(lds + (bufoff) + ldsw + _i * 8192), 16, 0, 0); } while (0)
; #define PG8_LDA(dst, b, h) do { _Pragma("unroll") for (int m = 0; m < 4; ++m) _Pragma("unroll") for (int k = 0; k < 2; ++k) dst[m][k] = *(const PG8_LAS bf16x8*)(lds + PG8_SA(b, h) + aoff + m * 2048 + k * 1024); } while (0)
; #define PG8_LDB(dst, b, h) do { _Pragma("unroll") for (int n = 0; n < 2; ++n) _Pragma("unroll") for (int k = 0; k < 2; ++k) dst[n][k] = *(const PG8_LAS bf16x8*)(lds + PG8_SB(b, h) + boff + n * 2048 + k * 1024); } while (0)
; #define PG8_WAIT_V(n) asm volatile("s_waitcnt vmcnt(" #n ")" ::: "memory")
; #define PG8_WAIT_L(n) asm volatile("s_waitcnt lgkmcnt(" #n ")" ::: "memory")
; #define PG8_BAR __builtin_amdgcn_s_barrier()
; #define PG8_SCHED __builtin_amdgcn_sched_barrier(0)
; template <class Epi, class Sched, bool ALIGN_EPI = false, bool SP2 = false>
; __device__ __forceinline__ void gemm_phase(PG8_LAS unsigned char* lds, const Gemm g, const Sched& S, const Epi& E) {
;     ...
;         const char* nA = has_next ? (const char*)g.A + (size_t)nxt.pm * tstepA : cA; const char* nB = has_next ? (const char*)g.Bt + (size_t)nxt.pn * tstepB : cB;
;         for (int t = 0; t < nt; t += 2) {
;             const bool last = (t == nt - 2);
;             const char* a1 = cA + (size_t)(t + 1) * kstepA;
;             const char* a2 = last ? nA : cA + (size_t)(t + 2) * kstepA; const char* b2 = last ? nB : cB + (size_t)(t + 2) * kstep;
;             const char* a3 = a2 + kstepA; const char* b3 = b2 + kstep;
;             if (last && has_next) S.a_ready(nxt);
;             if constexpr (SP2) {
;             PG8_LDB(B0, 0, 0); PG8_LDB(B1, 0, 1); PG8_SCHED; PG8_LDA(At, 0, 0); PG8_STAGE(PG8_SA(1, 1), a1 + hstepA, voffA);
;             PG8_WAIT_V(8); PG8_WAIT_L(0); PG8_BAR; PG8_MMA(0, 0, At, B0); PG8_MMA(0, 1, At, B1); PG8_BAR; PG8_SCHED;
;             PG8_LDA(At, 0, 1); PG8_STAGE(PG8_SB(0, 0), b2, voffB); PG8_STAGE(PG8_SB(0, 1), b2 + hstepB, voffB); PG8_STAGE(PG8_SA(0, 0), a2, voffA);
;             PG8_WAIT_V(8); PG8_WAIT_L(0); PG8_BAR; PG8_MMA(1, 0, At, B0); PG8_MMA(1, 1, At, B1); PG8_BAR; PG8_SCHED;
.LBB0_923:
	s_add_u32 s6, s6, 0x10000
	s_addc_u32 s7, s7, 0
	s_add_u32 s64, s64, 0x10000
	s_addc_u32 s65, s65, 0
	s_mov_b32 s66, -2
	s_waitcnt lgkmcnt(0)
	ds_read_b128 v[84:87], v221
	ds_read_b128 v[92:95], v221 offset:1024
	ds_read_b128 v[104:107], v221 offset:2048
	ds_read_b128 v[116:119], v221 offset:3072
	ds_read_b128 v[128:131], v222
	ds_read_b128 v[140:143], v222 offset:1024
	ds_read_b128 v[152:155], v222 offset:2048
	ds_read_b128 v[156:159], v222 offset:3072
	s_cmp_eq_u32 s66, 40
	s_cselect_b32 s69, s1, s7
	s_cselect_b32 s68, s0, s6
	s_cselect_b32 s71, s63, s65
	s_cselect_b32 s70, s62, s64
	v_lshl_add_u64 v[216:217], s[6:7], 0, v[190:191]
	v_lshl_add_u64 v[228:229], v[216:217], 0, s[58:59]
	s_add_i32 m0, s15, 0xc000
	ds_read_b128 v[160:163], v223
	ds_read_b128 v[164:167], v223 offset:1024
	ds_read_b128 v[168:171], v223 offset:2048
	ds_read_b128 v[172:175], v223 offset:3072
	ds_read_b128 v[176:179], v223 offset:4096
	ds_read_b128 v[180:183], v223 offset:5120
	ds_read_b128 v[184:187], v223 offset:6144
	ds_read_b128 v[212:215], v223 offset:7168
	global_load_lds_dwordx4 v[228:229], off
	v_lshl_add_u64 v[216:217], v[216:217], 0, s[60:61]
	s_add_i32 m0, s15, 0xe000
	s_nop 0
	global_load_lds_dwordx4 v[216:217], off
	s_waitcnt vmcnt(8)
	s_waitcnt lgkmcnt(0)
	s_barrier
	s_waitcnt lgkmcnt(0)
	v_mfma_f32_16x16x32_bf16 v[148:151], v[84:87], v[160:163], 0
	v_mfma_f32_16x16x32_bf16 v[144:147], v[104:107], v[160:163], 0
	v_mfma_f32_16x16x32_bf16 v[124:127], v[84:87], v[168:171], 0
	v_mfma_f32_16x16x32_bf16 v[120:123], v[104:107], v[168:171], 0
	v_mfma_f32_16x16x32_bf16 v[100:103], v[84:87], v[176:179], 0
	v_mfma_f32_16x16x32_bf16 v[96:99], v[104:107], v[176:179], 0
	v_mfma_f32_16x16x32_bf16 v[76:79], v[84:87], v[184:187], 0
	v_mfma_f32_16x16x32_bf16 v[72:75], v[104:107], v[184:187], 0
	v_mfma_f32_16x16x32_bf16 v[148:151], v[92:95], v[164:167], v[148:151]
	v_mfma_f32_16x16x32_bf16 v[144:147], v[116:119], v[164:167], v[144:147]
	v_mfma_f32_16x16x32_bf16 v[124:127], v[92:95], v[172:175], v[124:127]
	v_mfma_f32_16x16x32_bf16 v[120:123], v[116:119], v[172:175], v[120:123]
	v_mfma_f32_16x16x32_bf16 v[100:103], v[92:95], v[180:183], v[100:103]
	v_mfma_f32_16x16x32_bf16 v[96:99], v[116:119], v[180:183], v[96:99]
	v_mfma_f32_16x16x32_bf16 v[76:79], v[92:95], v[212:215], v[76:79]
	v_mfma_f32_16x16x32_bf16 v[72:75], v[116:119], v[212:215], v[72:75]
	v_mfma_f32_16x16x32_bf16 v[136:139], v[128:131], v[160:163], 0
	v_mfma_f32_16x16x32_bf16 v[132:135], v[152:155], v[160:163], 0
	v_mfma_f32_16x16x32_bf16 v[112:115], v[128:131], v[168:171], 0
	v_mfma_f32_16x16x32_bf16 v[108:111], v[152:155], v[168:171], 0
	v_mfma_f32_16x16x32_bf16 v[88:91], v[128:131], v[176:179], 0
	v_mfma_f32_16x16x32_bf16 v[80:83], v[152:155], v[176:179], 0
	v_mfma_f32_16x16x32_bf16 v[68:71], v[128:131], v[184:187], 0
	v_mfma_f32_16x16x32_bf16 v[64:67], v[152:155], v[184:187], 0
	v_mfma_f32_16x16x32_bf16 v[136:139], v[140:143], v[164:167], v[136:139]
	v_mfma_f32_16x16x32_bf16 v[132:135], v[156:159], v[164:167], v[132:135]
	v_mfma_f32_16x16x32_bf16 v[112:115], v[140:143], v[172:175], v[112:115]
	v_mfma_f32_16x16x32_bf16 v[108:111], v[156:159], v[172:175], v[108:111]
	v_mfma_f32_16x16x32_bf16 v[88:91], v[140:143], v[180:183], v[88:91]
	v_mfma_f32_16x16x32_bf16 v[80:83], v[156:159], v[180:183], v[80:83]
	v_mfma_f32_16x16x32_bf16 v[68:71], v[140:143], v[212:215], v[68:71]
	v_mfma_f32_16x16x32_bf16 v[64:67], v[156:159], v[212:215], v[64:67]
	s_barrier
	s_add_i32 s33, s81, s14
	v_lshl_add_u64 v[216:217], s[70:71], 0, v[190:191]
	s_mov_b32 m0, s33
	ds_read_b128 v[160:163], v223 offset:16384
	ds_read_b128 v[164:167], v223 offset:17408
	ds_read_b128 v[168:171], v223 offset:18432
	ds_read_b128 v[172:175], v223 offset:19456
	ds_read_b128 v[176:179], v223 offset:20480
	ds_read_b128 v[180:183], v223 offset:21504
	ds_read_b128 v[184:187], v223 offset:22528
	ds_read_b128 v[212:215], v223 offset:23552
	global_load_lds_dwordx4 v[216:217], off
	v_lshl_add_u64 v[228:229], v[216:217], 0, s[8:9]
	s_add_i32 m0, s33, 0x2000
	s_add_i32 s33, s82, s14
	global_load_lds_dwordx4 v[228:229], off
	v_lshl_add_u64 v[228:229], v[216:217], 0, s[10:11]
	s_mov_b32 m0, s33
	s_nop 0
	global_load_lds_dwordx4 v[228:229], off
	v_lshl_add_u64 v[228:229], v[216:217], 0, s[40:41]
	s_add_i32 m0, s33, 0x2000
	s_nop 0
	global_load_lds_dwordx4 v[228:229], off
	v_lshl_add_u64 v[228:229], s[68:69], 0, v[190:191]
	s_mov_b32 m0, s15
	v_lshl_add_u64 v[230:231], v[228:229], 0, s[8:9]
	global_load_lds_dwordx4 v[228:229], off
	s_mov_b32 m0, s17
	s_nop 0
	global_load_lds_dwordx4 v[230:231], off
	s_waitcnt vmcnt(8)
	s_waitcnt lgkmcnt(0)
	s_barrier
; #define PG8_STAGE(bufoff, gbase, voff) do { _Pragma("unroll") for (int _i = 0; _i < 2; ++_i) \
;         __builtin_amdgcn_global_load_lds((const unsigned*)((const char*)(gbase) + (voff)[_i]), (PG8_LAS unsigned*)(lds + (bufoff) + ldsw + _i * 8192), 16, 0, 0); } while (0)
; #define PG8_LDA(dst, b, h) do { _Pragma("unroll") for (int m = 0; m < 4; ++m) _Pragma("unroll") for (int k = 0; k < 2; ++k) dst[m][k] = *(const PG8_LAS bf16x8*)(lds + PG8_SA(b, h) + aoff + m * 2048 + k * 1024); } while (0)
; #define PG8_LDB(dst, b, h) do { _Pragma("unroll") for (int n = 0; n < 2; ++n) _Pragma("unroll") for (int k = 0; k < 2; ++k) dst[n][k] = *(const PG8_LAS bf16x8*)(lds + PG8_SB(b, h) + boff + n * 2048 + k * 1024); } while (0)
; #define PG8_MMA(ai, bj, At, Bt) do { __builtin_amdgcn_s_setprio(1); _Pragma("unroll") for (int m = 0; m < 4; ++m) _Pragma("unroll") for (int n = 0; n < 2; ++n) _Pragma("unroll") for (int k = 0; k < 2; ++k) \
;         acc[ai][bj][m][n] = __builtin_amdgcn_mfma_f32_16x16x32_bf16(Bt[n][k], At[m][k], acc[ai][bj][m][n], 0, 0, 0); __builtin_amdgcn_s_setprio(0); } while (0)
; #define PG8_WAIT_V(n) asm volatile("s_waitcnt vmcnt(" #n ")" ::: "memory")
; #define PG8_WAIT_L(n) asm volatile("s_waitcnt lgkmcnt(" #n ")" ::: "memory")
; #define PG8_BAR __builtin_amdgcn_s_barrier()
; #define PG8_SCHED __builtin_amdgcn_sched_barrier(0)
; template <class Epi, class Sched, bool ALIGN_EPI = false, bool SP2 = false>
; __device__ __forceinline__ void gemm_phase(PG8_LAS unsigned char* lds, const Gemm g, const Sched& S, const Epi& E) {
;     ...
;             PG8_WAIT_V(8); PG8_WAIT_L(0); PG8_BAR; PG8_MMA(1, 0, At, B0); PG8_MMA(1, 1, At, B1); PG8_BAR; PG8_SCHED;
;             PG8_LDB(B0, 1, 0); PG8_LDB(B1, 1, 1); PG8_SCHED; PG8_LDA(At, 1, 0); PG8_STAGE(PG8_SA(0, 1), a2 + hstepA, voffA);
;             PG8_WAIT_V(8); PG8_WAIT_L(0); PG8_BAR; PG8_MMA(0, 0, At, B0); PG8_MMA(0, 1, At, B1); PG8_BAR; PG8_SCHED;
	s_waitcnt lgkmcnt(0)
	v_mfma_f32_16x16x32_bf16 v[60:63], v[84:87], v[160:163], 0
	v_mfma_f32_16x16x32_bf16 v[56:59], v[104:107], v[160:163], 0
	v_mfma_f32_16x16x32_bf16 v[44:47], v[84:87], v[168:171], 0
	v_mfma_f32_16x16x32_bf16 v[40:43], v[104:107], v[168:171], 0
	v_mfma_f32_16x16x32_bf16 v[28:31], v[84:87], v[176:179], 0
	v_mfma_f32_16x16x32_bf16 v[24:27], v[104:107], v[176:179], 0
	v_mfma_f32_16x16x32_bf16 v[12:15], v[84:87], v[184:187], 0
	v_mfma_f32_16x16x32_bf16 v[8:11], v[104:107], v[184:187], 0
	v_mfma_f32_16x16x32_bf16 v[60:63], v[92:95], v[164:167], v[60:63]
	v_mfma_f32_16x16x32_bf16 v[56:59], v[116:119], v[164:167], v[56:59]
	v_mfma_f32_16x16x32_bf16 v[44:47], v[92:95], v[172:175], v[44:47]
	v_mfma_f32_16x16x32_bf16 v[40:43], v[116:119], v[172:175], v[40:43]
	v_mfma_f32_16x16x32_bf16 v[28:31], v[92:95], v[180:183], v[28:31]
	v_mfma_f32_16x16x32_bf16 v[24:27], v[116:119], v[180:183], v[24:27]
	v_mfma_f32_16x16x32_bf16 v[12:15], v[92:95], v[212:215], v[12:15]
	v_mfma_f32_16x16x32_bf16 v[8:11], v[116:119], v[212:215], v[8:11]
	v_mfma_f32_16x16x32_bf16 v[52:55], v[128:131], v[160:163], 0
	v_mfma_f32_16x16x32_bf16 v[48:51], v[152:155], v[160:163], 0
	v_mfma_f32_16x16x32_bf16 v[36:39], v[128:131], v[168:171], 0
	v_mfma_f32_16x16x32_bf16 v[32:35], v[152:155], v[168:171], 0
	v_mfma_f32_16x16x32_bf16 v[20:23], v[128:131], v[176:179], 0
	v_mfma_f32_16x16x32_bf16 v[16:19], v[152:155], v[176:179], 0
	v_mfma_f32_16x16x32_bf16 v[4:7], v[128:131], v[184:187], 0
	v_mfma_f32_16x16x32_bf16 v[0:3], v[152:155], v[184:187], 0
	v_mfma_f32_16x16x32_bf16 v[52:55], v[140:143], v[164:167], v[52:55]
	v_mfma_f32_16x16x32_bf16 v[48:51], v[156:159], v[164:167], v[48:51]
	v_mfma_f32_16x16x32_bf16 v[36:39], v[140:143], v[172:175], v[36:39]
	v_mfma_f32_16x16x32_bf16 v[32:35], v[156:159], v[172:175], v[32:35]
	v_mfma_f32_16x16x32_bf16 v[20:23], v[140:143], v[180:183], v[20:23]
	v_mfma_f32_16x16x32_bf16 v[16:19], v[156:159], v[180:183], v[16:19]
	v_mfma_f32_16x16x32_bf16 v[4:7], v[140:143], v[212:215], v[4:7]
	v_mfma_f32_16x16x32_bf16 v[0:3], v[156:159], v[212:215], v[0:3]
	s_barrier
	ds_read_b128 v[84:87], v224
	ds_read_b128 v[92:95], v224 offset:1024
	ds_read_b128 v[104:107], v224 offset:2048
	ds_read_b128 v[116:119], v224 offset:3072
	ds_read_b128 v[128:131], v225
	ds_read_b128 v[140:143], v225 offset:1024
	ds_read_b128 v[152:155], v225 offset:2048
	ds_read_b128 v[156:159], v225 offset:3072
	s_mov_b32 m0, s18
	v_lshl_add_u64 v[230:231], v[228:229], 0, s[10:11]
	ds_read_b128 v[160:163], v223 offset:32768
	ds_read_b128 v[164:167], v223 offset:33792
	ds_read_b128 v[168:171], v223 offset:34816
	ds_read_b128 v[172:175], v223 offset:35840
	ds_read_b128 v[176:179], v223 offset:36864
	ds_read_b128 v[180:183], v223 offset:37888
	ds_read_b128 v[184:187], v223 offset:38912
	ds_read_b128 v[212:215], v223 offset:39936
	global_load_lds_dwordx4 v[230:231], off
	v_lshl_add_u64 v[230:231], v[228:229], 0, s[40:41]
	s_mov_b32 m0, s19
	s_nop 0
	global_load_lds_dwordx4 v[230:231], off
	s_waitcnt vmcnt(8)
	s_waitcnt lgkmcnt(0)
	s_barrier
	s_waitcnt lgkmcnt(0)
	v_mfma_f32_16x16x32_bf16 v[148:151], v[84:87], v[160:163], v[148:151]
	v_mfma_f32_16x16x32_bf16 v[144:147], v[104:107], v[160:163], v[144:147]
	v_mfma_f32_16x16x32_bf16 v[124:127], v[84:87], v[168:171], v[124:127]
	v_mfma_f32_16x16x32_bf16 v[120:123], v[104:107], v[168:171], v[120:123]
	v_mfma_f32_16x16x32_bf16 v[100:103], v[84:87], v[176:179], v[100:103]
	v_mfma_f32_16x16x32_bf16 v[96:99], v[104:107], v[176:179], v[96:99]
	v_mfma_f32_16x16x32_bf16 v[76:79], v[84:87], v[184:187], v[76:79]
	v_mfma_f32_16x16x32_bf16 v[72:75], v[104:107], v[184:187], v[72:75]
	v_mfma_f32_16x16x32_bf16 v[148:151], v[92:95], v[164:167], v[148:151]
	v_mfma_f32_16x16x32_bf16 v[144:147], v[116:119], v[164:167], v[144:147]
	v_mfma_f32_16x16x32_bf16 v[124:127], v[92:95], v[172:175], v[124:127]
	v_mfma_f32_16x16x32_bf16 v[120:123], v[116:119], v[172:175], v[120:123]
	v_mfma_f32_16x16x32_bf16 v[100:103], v[92:95], v[180:183], v[100:103]
	v_mfma_f32_16x16x32_bf16 v[96:99], v[116:119], v[180:183], v[96:99]
	v_mfma_f32_16x16x32_bf16 v[76:79], v[92:95], v[212:215], v[76:79]
	v_mfma_f32_16x16x32_bf16 v[72:75], v[116:119], v[212:215], v[72:75]
	v_mfma_f32_16x16x32_bf16 v[136:139], v[128:131], v[160:163], v[136:139]
	v_mfma_f32_16x16x32_bf16 v[132:135], v[152:155], v[160:163], v[132:135]
	v_mfma_f32_16x16x32_bf16 v[112:115], v[128:131], v[168:171], v[112:115]
	v_mfma_f32_16x16x32_bf16 v[108:111], v[152:155], v[168:171], v[108:111]
	v_mfma_f32_16x16x32_bf16 v[88:91], v[128:131], v[176:179], v[88:91]
	v_mfma_f32_16x16x32_bf16 v[80:83], v[152:155], v[176:179], v[80:83]
	v_mfma_f32_16x16x32_bf16 v[68:71], v[128:131], v[184:187], v[68:71]
	v_mfma_f32_16x16x32_bf16 v[64:67], v[152:155], v[184:187], v[64:67]
	v_mfma_f32_16x16x32_bf16 v[136:139], v[140:143], v[164:167], v[136:139]
	v_mfma_f32_16x16x32_bf16 v[132:135], v[156:159], v[164:167], v[132:135]
	v_mfma_f32_16x16x32_bf16 v[112:115], v[140:143], v[172:175], v[112:115]
	v_mfma_f32_16x16x32_bf16 v[108:111], v[156:159], v[172:175], v[108:111]
	v_mfma_f32_16x16x32_bf16 v[88:91], v[140:143], v[180:183], v[88:91]
	v_mfma_f32_16x16x32_bf16 v[80:83], v[156:159], v[180:183], v[80:83]
	v_mfma_f32_16x16x32_bf16 v[68:71], v[140:143], v[212:215], v[68:71]
	v_mfma_f32_16x16x32_bf16 v[64:67], v[156:159], v[212:215], v[64:67]
	s_barrier
; #define PG8_STAGE(bufoff, gbase, voff) do { _Pragma("unroll") for (int _i = 0; _i < 2; ++_i) \
;         __builtin_amdgcn_global_load_lds((const unsigned*)((const char*)(gbase) + (voff)[_i]), (PG8_LAS unsigned*)(lds + (bufoff) + ldsw + _i * 8192), 16, 0, 0); } while (0)
; #define PG8_LDA(dst, b, h) do { _Pragma("unroll") for (int m = 0; m < 4; ++m) _Pragma("unroll") for (int k = 0; k < 2; ++k) dst[m][k] = *(const PG8_LAS bf16x8*)(lds + PG8_SA(b, h) + aoff + m * 2048 + k * 1024); } while (0)
; #define PG8_LDB(dst, b, h) do { _Pragma("unroll") for (int n = 0; n < 2; ++n) _Pragma("unroll") for (int k = 0; k < 2; ++k) dst[n][k] = *(const PG8_LAS bf16x8*)(lds + PG8_SB(b, h) + boff + n * 2048 + k * 1024); } while (0)
; #define PG8_MMA(ai, bj, At, Bt) do { __builtin_amdgcn_s_setprio(1); _Pragma("unroll") for (int m = 0; m < 4; ++m) _Pragma("unroll") for (int n = 0; n < 2; ++n) _Pragma("unroll") for (int k = 0; k < 2; ++k) \
;         acc[ai][bj][m][n] = __builtin_amdgcn_mfma_f32_16x16x32_bf16(Bt[n][k], At[m][k], acc[ai][bj][m][n], 0, 0, 0); __builtin_amdgcn_s_setprio(0); } while (0)
; #define PG8_WAIT_V(n) asm volatile("s_waitcnt vmcnt(" #n ")" ::: "memory")
; template <class Epi, class Sched, bool ALIGN_EPI = false, bool SP2 = false>
; __device__ __forceinline__ void gemm_phase(PG8_LAS unsigned char* lds, const Gemm g, const Sched& S, const Epi& E) {
;     ...
;             PG8_LDB(B0, 0, 0); PG8_LDB(B1, 0, 1); PG8_SCHED; PG8_LDA(At, 0, 0); PG8_STAGE(PG8_SA(1, 1), a1 + hstepA, voffA);
;             PG8_WAIT_V(8); PG8_WAIT_L(0); PG8_BAR; PG8_MMA(0, 0, At, B0); PG8_MMA(0, 1, At, B1); PG8_BAR; PG8_SCHED;
;             PG8_LDA(At, 0, 1); PG8_STAGE(PG8_SB(0, 0), b2, voffB); PG8_STAGE(PG8_SB(0, 1), b2 + hstepB, voffB); PG8_STAGE(PG8_SA(0, 0), a2, voffA);
;             PG8_WAIT_V(8); PG8_WAIT_L(0); PG8_BAR; PG8_MMA(1, 0, At, B0); PG8_MMA(1, 1, At, B1); PG8_BAR; PG8_SCHED;
;             PG8_LDB(B0, 1, 0); PG8_LDB(B1, 1, 1); PG8_SCHED; PG8_LDA(At, 1, 0); PG8_STAGE(PG8_SA(0, 1), a2 + hstepA, voffA);
;             PG8_WAIT_V(8); PG8_WAIT_L(0); PG8_BAR; PG8_MMA(0, 0, At, B0); PG8_MMA(0, 1, At, B1); PG8_BAR; PG8_SCHED;
;             PG8_LDA(At, 1, 1); PG8_STAGE(PG8_SB(1, 0), b3, voffB); PG8_STAGE(PG8_SB(1, 1), b3 + hstepB, voffB); PG8_STAGE(PG8_SA(1, 0), a3, voffA);
;             PG8_WAIT_V(8); PG8_WAIT_L(0); PG8_BAR; PG8_MMA(1, 0, At, B0); PG8_MMA(1, 1, At, B1); PG8_BAR; PG8_SCHED;
	s_add_i32 s33, s83, s14
	v_lshl_add_u64 v[230:231], v[216:217], 0, s[42:43]
	s_mov_b32 m0, s33
	ds_read_b128 v[160:163], v223 offset:49152
	ds_read_b128 v[164:167], v223 offset:50176
	ds_read_b128 v[168:171], v223 offset:51200
	ds_read_b128 v[172:175], v223 offset:52224
	ds_read_b128 v[176:179], v223 offset:53248
	ds_read_b128 v[180:183], v223 offset:54272
	ds_read_b128 v[184:187], v223 offset:55296
	ds_read_b128 v[212:215], v223 offset:56320
	global_load_lds_dwordx4 v[230:231], off
	v_lshl_add_u64 v[230:231], v[216:217], 0, s[44:45]
	s_add_i32 m0, s33, 0x2000
	s_add_i32 s33, s84, s14
	global_load_lds_dwordx4 v[230:231], off
	v_lshl_add_u64 v[230:231], v[216:217], 0, s[46:47]
	s_mov_b32 m0, s33
	v_lshl_add_u64 v[216:217], v[216:217], 0, s[48:49]
	global_load_lds_dwordx4 v[230:231], off
	s_add_i32 m0, s33, 0x2000
	s_nop 0
	global_load_lds_dwordx4 v[216:217], off
	v_lshl_add_u64 v[216:217], v[228:229], 0, s[42:43]
	s_mov_b32 m0, s74
	s_nop 0
	global_load_lds_dwordx4 v[216:217], off
	v_lshl_add_u64 v[216:217], v[228:229], 0, s[44:45]
	s_mov_b32 m0, s75
	s_nop 0
	global_load_lds_dwordx4 v[216:217], off
	s_waitcnt vmcnt(8)
	s_waitcnt lgkmcnt(0)
	s_barrier
	s_waitcnt lgkmcnt(0)
	v_mfma_f32_16x16x32_bf16 v[60:63], v[84:87], v[160:163], v[60:63]
	v_mfma_f32_16x16x32_bf16 v[56:59], v[104:107], v[160:163], v[56:59]
	v_mfma_f32_16x16x32_bf16 v[44:47], v[84:87], v[168:171], v[44:47]
	v_mfma_f32_16x16x32_bf16 v[40:43], v[104:107], v[168:171], v[40:43]
	v_mfma_f32_16x16x32_bf16 v[28:31], v[84:87], v[176:179], v[28:31]
	v_mfma_f32_16x16x32_bf16 v[24:27], v[104:107], v[176:179], v[24:27]
	v_mfma_f32_16x16x32_bf16 v[12:15], v[84:87], v[184:187], v[12:15]
	v_mfma_f32_16x16x32_bf16 v[8:11], v[104:107], v[184:187], v[8:11]
	v_mfma_f32_16x16x32_bf16 v[60:63], v[92:95], v[164:167], v[60:63]
	v_mfma_f32_16x16x32_bf16 v[56:59], v[116:119], v[164:167], v[56:59]
	v_mfma_f32_16x16x32_bf16 v[44:47], v[92:95], v[172:175], v[44:47]
	v_mfma_f32_16x16x32_bf16 v[40:43], v[116:119], v[172:175], v[40:43]
	v_mfma_f32_16x16x32_bf16 v[28:31], v[92:95], v[180:183], v[28:31]
	v_mfma_f32_16x16x32_bf16 v[24:27], v[116:119], v[180:183], v[24:27]
	v_mfma_f32_16x16x32_bf16 v[12:15], v[92:95], v[212:215], v[12:15]
	v_mfma_f32_16x16x32_bf16 v[8:11], v[116:119], v[212:215], v[8:11]
	v_mfma_f32_16x16x32_bf16 v[52:55], v[128:131], v[160:163], v[52:55]
	v_mfma_f32_16x16x32_bf16 v[48:51], v[152:155], v[160:163], v[48:51]
	v_mfma_f32_16x16x32_bf16 v[36:39], v[128:131], v[168:171], v[36:39]
	v_mfma_f32_16x16x32_bf16 v[32:35], v[152:155], v[168:171], v[32:35]
	v_mfma_f32_16x16x32_bf16 v[20:23], v[128:131], v[176:179], v[20:23]
	v_mfma_f32_16x16x32_bf16 v[16:19], v[152:155], v[176:179], v[16:19]
	v_mfma_f32_16x16x32_bf16 v[4:7], v[128:131], v[184:187], v[4:7]
	v_mfma_f32_16x16x32_bf16 v[0:3], v[152:155], v[184:187], v[0:3]
	v_mfma_f32_16x16x32_bf16 v[52:55], v[140:143], v[164:167], v[52:55]
	v_mfma_f32_16x16x32_bf16 v[48:51], v[156:159], v[164:167], v[48:51]
	v_mfma_f32_16x16x32_bf16 v[36:39], v[140:143], v[172:175], v[36:39]
	v_mfma_f32_16x16x32_bf16 v[32:35], v[156:159], v[172:175], v[32:35]
	v_mfma_f32_16x16x32_bf16 v[20:23], v[140:143], v[180:183], v[20:23]
	v_mfma_f32_16x16x32_bf16 v[16:19], v[156:159], v[180:183], v[16:19]
	v_mfma_f32_16x16x32_bf16 v[4:7], v[140:143], v[212:215], v[4:7]
	v_mfma_f32_16x16x32_bf16 v[0:3], v[156:159], v[212:215], v[0:3]
	s_barrier
	s_add_i32 s66, s66, 2
	s_add_u32 s6, s6, 0x10000
	s_addc_u32 s7, s7, 0
	s_add_u32 s64, s64, 0x10000
	s_addc_u32 s65, s65, 0
	s_cmp_gt_u32 s66, 41
.LBB0_924:
	ds_read_b128 v[84:87], v221
	ds_read_b128 v[92:95], v221 offset:1024
	ds_read_b128 v[104:107], v221 offset:2048
	ds_read_b128 v[116:119], v221 offset:3072
	ds_read_b128 v[128:131], v222
	ds_read_b128 v[140:143], v222 offset:1024
	ds_read_b128 v[152:155], v222 offset:2048
	ds_read_b128 v[156:159], v222 offset:3072
	s_cmp_eq_u32 s66, 40
	s_cselect_b32 s69, s1, s7
	s_cselect_b32 s68, s0, s6
	s_cselect_b32 s71, s63, s65
	s_cselect_b32 s70, s62, s64
	v_lshl_add_u64 v[216:217], s[6:7], 0, v[190:191]
	v_lshl_add_u64 v[228:229], v[216:217], 0, s[58:59]
	s_add_i32 m0, s15, 0xc000
	ds_read_b128 v[160:163], v223
	ds_read_b128 v[164:167], v223 offset:1024
	ds_read_b128 v[168:171], v223 offset:2048
	ds_read_b128 v[172:175], v223 offset:3072
	ds_read_b128 v[176:179], v223 offset:4096
	ds_read_b128 v[180:183], v223 offset:5120
	ds_read_b128 v[184:187], v223 offset:6144
	ds_read_b128 v[212:215], v223 offset:7168
	global_load_lds_dwordx4 v[228:229], off
	v_lshl_add_u64 v[216:217], v[216:217], 0, s[60:61]
	s_add_i32 m0, s15, 0xe000
	s_nop 0
	global_load_lds_dwordx4 v[216:217], off
	s_waitcnt vmcnt(8)
	s_waitcnt lgkmcnt(0)
	s_barrier
; #define PG8_STAGE(bufoff, gbase, voff) do { _Pragma("unroll") for (int _i = 0; _i < 2; ++_i) \
;         __builtin_amdgcn_global_load_lds((const unsigned*)((const char*)(gbase) + (voff)[_i]), (PG8_LAS unsigned*)(lds + (bufoff) + ldsw + _i * 8192), 16, 0, 0); } while (0)
; #define PG8_LDA(dst, b, h) do { _Pragma("unroll") for (int m = 0; m < 4; ++m) _Pragma("unroll") for (int k = 0; k < 2; ++k) dst[m][k] = *(const PG8_LAS bf16x8*)(lds + PG8_SA(b, h) + aoff + m * 2048 + k * 1024); } while (0)
; #define PG8_MMA(ai, bj, At, Bt) do { __builtin_amdgcn_s_setprio(1); _Pragma("unroll") for (int m = 0; m < 4; ++m) _Pragma("unroll") for (int n = 0; n < 2; ++n) _Pragma("unroll") for (int k = 0; k < 2; ++k) \
;         acc[ai][bj][m][n] = __builtin_amdgcn_mfma_f32_16x16x32_bf16(Bt[n][k], At[m][k], acc[ai][bj][m][n], 0, 0, 0); __builtin_amdgcn_s_setprio(0); } while (0)
; #define PG8_WAIT_V(n) asm volatile("s_waitcnt vmcnt(" #n ")" ::: "memory")
; #define PG8_WAIT_L(n) asm volatile("s_waitcnt lgkmcnt(" #n ")" ::: "memory")
; #define PG8_BAR __builtin_amdgcn_s_barrier()
; #define PG8_SCHED __builtin_amdgcn_sched_barrier(0)
; template <class Epi, class Sched, bool ALIGN_EPI = false, bool SP2 = false>
; __device__ __forceinline__ void gemm_phase(PG8_LAS unsigned char* lds, const Gemm g, const Sched& S, const Epi& E) {
;     ...
;             PG8_WAIT_V(8); PG8_WAIT_L(0); PG8_BAR; PG8_MMA(0, 0, At, B0); PG8_MMA(0, 1, At, B1); PG8_BAR; PG8_SCHED;
;             PG8_LDA(At, 0, 1); PG8_STAGE(PG8_SB(0, 0), b2, voffB); PG8_STAGE(PG8_SB(0, 1), b2 + hstepB, voffB); PG8_STAGE(PG8_SA(0, 0), a2, voffA);
;             PG8_WAIT_V(8); PG8_WAIT_L(0); PG8_BAR; PG8_MMA(1, 0, At, B0); PG8_MMA(1, 1, At, B1); PG8_BAR; PG8_SCHED;
	s_waitcnt lgkmcnt(0)
	v_mfma_f32_16x16x32_bf16 v[148:151], v[84:87], v[160:163], v[148:151]
	v_mfma_f32_16x16x32_bf16 v[144:147], v[104:107], v[160:163], v[144:147]
	v_mfma_f32_16x16x32_bf16 v[124:127], v[84:87], v[168:171], v[124:127]
	v_mfma_f32_16x16x32_bf16 v[120:123], v[104:107], v[168:171], v[120:123]
	v_mfma_f32_16x16x32_bf16 v[100:103], v[84:87], v[176:179], v[100:103]
	v_mfma_f32_16x16x32_bf16 v[96:99], v[104:107], v[176:179], v[96:99]
	v_mfma_f32_16x16x32_bf16 v[76:79], v[84:87], v[184:187], v[76:79]
	v_mfma_f32_16x16x32_bf16 v[72:75], v[104:107], v[184:187], v[72:75]
	v_mfma_f32_16x16x32_bf16 v[148:151], v[92:95], v[164:167], v[148:151]
	v_mfma_f32_16x16x32_bf16 v[144:147], v[116:119], v[164:167], v[144:147]
	v_mfma_f32_16x16x32_bf16 v[124:127], v[92:95], v[172:175], v[124:127]
	v_mfma_f32_16x16x32_bf16 v[120:123], v[116:119], v[172:175], v[120:123]
	v_mfma_f32_16x16x32_bf16 v[100:103], v[92:95], v[180:183], v[100:103]
	v_mfma_f32_16x16x32_bf16 v[96:99], v[116:119], v[180:183], v[96:99]
	v_mfma_f32_16x16x32_bf16 v[76:79], v[92:95], v[212:215], v[76:79]
	v_mfma_f32_16x16x32_bf16 v[72:75], v[116:119], v[212:215], v[72:75]
	v_mfma_f32_16x16x32_bf16 v[136:139], v[128:131], v[160:163], v[136:139]
	v_mfma_f32_16x16x32_bf16 v[132:135], v[152:155], v[160:163], v[132:135]
	v_mfma_f32_16x16x32_bf16 v[112:115], v[128:131], v[168:171], v[112:115]
	v_mfma_f32_16x16x32_bf16 v[108:111], v[152:155], v[168:171], v[108:111]
	v_mfma_f32_16x16x32_bf16 v[88:91], v[128:131], v[176:179], v[88:91]
	v_mfma_f32_16x16x32_bf16 v[80:83], v[152:155], v[176:179], v[80:83]
	v_mfma_f32_16x16x32_bf16 v[68:71], v[128:131], v[184:187], v[68:71]
	v_mfma_f32_16x16x32_bf16 v[64:67], v[152:155], v[184:187], v[64:67]
	v_mfma_f32_16x16x32_bf16 v[136:139], v[140:143], v[164:167], v[136:139]
	v_mfma_f32_16x16x32_bf16 v[132:135], v[156:159], v[164:167], v[132:135]
	v_mfma_f32_16x16x32_bf16 v[112:115], v[140:143], v[172:175], v[112:115]
	v_mfma_f32_16x16x32_bf16 v[108:111], v[156:159], v[172:175], v[108:111]
	v_mfma_f32_16x16x32_bf16 v[88:91], v[140:143], v[180:183], v[88:91]
	v_mfma_f32_16x16x32_bf16 v[80:83], v[156:159], v[180:183], v[80:83]
	v_mfma_f32_16x16x32_bf16 v[68:71], v[140:143], v[212:215], v[68:71]
	v_mfma_f32_16x16x32_bf16 v[64:67], v[156:159], v[212:215], v[64:67]
	s_barrier
	s_add_i32 s33, s81, s14
	v_lshl_add_u64 v[216:217], s[70:71], 0, v[190:191]
	s_mov_b32 m0, s33
	ds_read_b128 v[160:163], v223 offset:16384
	ds_read_b128 v[164:167], v223 offset:17408
	ds_read_b128 v[168:171], v223 offset:18432
	ds_read_b128 v[172:175], v223 offset:19456
	ds_read_b128 v[176:179], v223 offset:20480
	ds_read_b128 v[180:183], v223 offset:21504
	ds_read_b128 v[184:187], v223 offset:22528
	ds_read_b128 v[212:215], v223 offset:23552
	global_load_lds_dwordx4 v[216:217], off
	v_lshl_add_u64 v[228:229], v[216:217], 0, s[8:9]
	s_add_i32 m0, s33, 0x2000
	s_add_i32 s33, s82, s14
	global_load_lds_dwordx4 v[228:229], off
	v_lshl_add_u64 v[228:229], v[216:217], 0, s[10:11]
	s_mov_b32 m0, s33
	s_nop 0
	global_load_lds_dwordx4 v[228:229], off
	v_lshl_add_u64 v[228:229], v[216:217], 0, s[40:41]
	s_add_i32 m0, s33, 0x2000
	s_nop 0
	global_load_lds_dwordx4 v[228:229], off
	v_lshl_add_u64 v[228:229], s[68:69], 0, v[190:191]
	s_mov_b32 m0, s15
	v_lshl_add_u64 v[230:231], v[228:229], 0, s[8:9]
	global_load_lds_dwordx4 v[228:229], off
	s_mov_b32 m0, s17
	s_nop 0
	global_load_lds_dwordx4 v[230:231], off
	s_waitcnt vmcnt(8)
	s_waitcnt lgkmcnt(0)
	s_barrier
	s_waitcnt lgkmcnt(0)
	v_mfma_f32_16x16x32_bf16 v[60:63], v[84:87], v[160:163], v[60:63]
	v_mfma_f32_16x16x32_bf16 v[56:59], v[104:107], v[160:163], v[56:59]
	v_mfma_f32_16x16x32_bf16 v[44:47], v[84:87], v[168:171], v[44:47]
	v_mfma_f32_16x16x32_bf16 v[40:43], v[104:107], v[168:171], v[40:43]
	v_mfma_f32_16x16x32_bf16 v[28:31], v[84:87], v[176:179], v[28:31]
	v_mfma_f32_16x16x32_bf16 v[24:27], v[104:107], v[176:179], v[24:27]
	v_mfma_f32_16x16x32_bf16 v[12:15], v[84:87], v[184:187], v[12:15]
	v_mfma_f32_16x16x32_bf16 v[8:11], v[104:107], v[184:187], v[8:11]
	v_mfma_f32_16x16x32_bf16 v[60:63], v[92:95], v[164:167], v[60:63]
	v_mfma_f32_16x16x32_bf16 v[56:59], v[116:119], v[164:167], v[56:59]
	v_mfma_f32_16x16x32_bf16 v[44:47], v[92:95], v[172:175], v[44:47]
	v_mfma_f32_16x16x32_bf16 v[40:43], v[116:119], v[172:175], v[40:43]
	v_mfma_f32_16x16x32_bf16 v[28:31], v[92:95], v[180:183], v[28:31]
	v_mfma_f32_16x16x32_bf16 v[24:27], v[116:119], v[180:183], v[24:27]
	v_mfma_f32_16x16x32_bf16 v[12:15], v[92:95], v[212:215], v[12:15]
	v_mfma_f32_16x16x32_bf16 v[8:11], v[116:119], v[212:215], v[8:11]
	v_mfma_f32_16x16x32_bf16 v[52:55], v[128:131], v[160:163], v[52:55]
	v_mfma_f32_16x16x32_bf16 v[48:51], v[152:155], v[160:163], v[48:51]
	v_mfma_f32_16x16x32_bf16 v[36:39], v[128:131], v[168:171], v[36:39]
	v_mfma_f32_16x16x32_bf16 v[32:35], v[152:155], v[168:171], v[32:35]
	v_mfma_f32_16x16x32_bf16 v[20:23], v[128:131], v[176:179], v[20:23]
	v_mfma_f32_16x16x32_bf16 v[16:19], v[152:155], v[176:179], v[16:19]
	v_mfma_f32_16x16x32_bf16 v[4:7], v[128:131], v[184:187], v[4:7]
	v_mfma_f32_16x16x32_bf16 v[0:3], v[152:155], v[184:187], v[0:3]
	v_mfma_f32_16x16x32_bf16 v[52:55], v[140:143], v[164:167], v[52:55]
	v_mfma_f32_16x16x32_bf16 v[48:51], v[156:159], v[164:167], v[48:51]
	v_mfma_f32_16x16x32_bf16 v[36:39], v[140:143], v[172:175], v[36:39]
	v_mfma_f32_16x16x32_bf16 v[32:35], v[156:159], v[172:175], v[32:35]
	v_mfma_f32_16x16x32_bf16 v[20:23], v[140:143], v[180:183], v[20:23]
	v_mfma_f32_16x16x32_bf16 v[16:19], v[156:159], v[180:183], v[16:19]
	v_mfma_f32_16x16x32_bf16 v[4:7], v[140:143], v[212:215], v[4:7]
	v_mfma_f32_16x16x32_bf16 v[0:3], v[156:159], v[212:215], v[0:3]
	s_barrier
; #define PG8_STAGE(bufoff, gbase, voff) do { _Pragma("unroll") for (int _i = 0; _i < 2; ++_i) \
;         __builtin_amdgcn_global_load_lds((const unsigned*)((const char*)(gbase) + (voff)[_i]), (PG8_LAS unsigned*)(lds + (bufoff) + ldsw + _i * 8192), 16, 0, 0); } while (0)
; #define PG8_LDA(dst, b, h) do { _Pragma("unroll") for (int m = 0; m < 4; ++m) _Pragma("unroll") for (int k = 0; k < 2; ++k) dst[m][k] = *(const PG8_LAS bf16x8*)(lds + PG8_SA(b, h) + aoff + m * 2048 + k * 1024); } while (0)
; #define PG8_LDB(dst, b, h) do { _Pragma("unroll") for (int n = 0; n < 2; ++n) _Pragma("unroll") for (int k = 0; k < 2; ++k) dst[n][k] = *(const PG8_LAS bf16x8*)(lds + PG8_SB(b, h) + boff + n * 2048 + k * 1024); } while (0)
; #define PG8_MMA(ai, bj, At, Bt) do { __builtin_amdgcn_s_setprio(1); _Pragma("unroll") for (int m = 0; m < 4; ++m) _Pragma("unroll") for (int n = 0; n < 2; ++n) _Pragma("unroll") for (int k = 0; k < 2; ++k) \
;         acc[ai][bj][m][n] = __builtin_amdgcn_mfma_f32_16x16x32_bf16(Bt[n][k], At[m][k], acc[ai][bj][m][n], 0, 0, 0); __builtin_amdgcn_s_setprio(0); } while (0)
; #define PG8_WAIT_V(n) asm volatile("s_waitcnt vmcnt(" #n ")" ::: "memory")
; #define PG8_WAIT_L(n) asm volatile("s_waitcnt lgkmcnt(" #n ")" ::: "memory")
; #define PG8_BAR __builtin_amdgcn_s_barrier()
; #define PG8_SCHED __builtin_amdgcn_sched_barrier(0)
; template <class Epi, class Sched, bool ALIGN_EPI = false, bool SP2 = false>
; __device__ __forceinline__ void gemm_phase(PG8_LAS unsigned char* lds, const Gemm g, const Sched& S, const Epi& E) {
;     ...
;             PG8_LDB(B0, 1, 0); PG8_LDB(B1, 1, 1); PG8_SCHED; PG8_LDA(At, 1, 0); PG8_STAGE(PG8_SA(0, 1), a2 + hstepA, voffA);
;             PG8_WAIT_V(8); PG8_WAIT_L(0); PG8_BAR; PG8_MMA(0, 0, At, B0); PG8_MMA(0, 1, At, B1); PG8_BAR; PG8_SCHED;
;             PG8_LDA(At, 1, 1); PG8_STAGE(PG8_SB(1, 0), b3, voffB); PG8_STAGE(PG8_SB(1, 1), b3 + hstepB, voffB); PG8_STAGE(PG8_SA(1, 0), a3, voffA);
;             PG8_WAIT_V(8); PG8_WAIT_L(0); PG8_BAR; PG8_MMA(1, 0, At, B0); PG8_MMA(1, 1, At, B1); PG8_BAR; PG8_SCHED;
;     ...
;         if constexpr (ALIGN_EPI) { if (wr == 0) PG8_BAR; }
	ds_read_b128 v[84:87], v224
	ds_read_b128 v[92:95], v224 offset:1024
	ds_read_b128 v[104:107], v224 offset:2048
	ds_read_b128 v[116:119], v224 offset:3072
	ds_read_b128 v[128:131], v225
	ds_read_b128 v[140:143], v225 offset:1024
	ds_read_b128 v[152:155], v225 offset:2048
	ds_read_b128 v[156:159], v225 offset:3072
	s_mov_b32 m0, s18
	v_lshl_add_u64 v[230:231], v[228:229], 0, s[10:11]
	ds_read_b128 v[160:163], v223 offset:32768
	ds_read_b128 v[164:167], v223 offset:33792
	ds_read_b128 v[168:171], v223 offset:34816
	ds_read_b128 v[172:175], v223 offset:35840
	ds_read_b128 v[176:179], v223 offset:36864
	ds_read_b128 v[180:183], v223 offset:37888
	ds_read_b128 v[184:187], v223 offset:38912
	ds_read_b128 v[212:215], v223 offset:39936
	global_load_lds_dwordx4 v[230:231], off
	v_lshl_add_u64 v[230:231], v[228:229], 0, s[40:41]
	s_mov_b32 m0, s19
	s_nop 0
	global_load_lds_dwordx4 v[230:231], off
	s_waitcnt vmcnt(8)
	s_waitcnt lgkmcnt(0)
	s_barrier
	s_waitcnt lgkmcnt(0)
	v_mfma_f32_16x16x32_bf16 v[148:151], v[84:87], v[160:163], v[148:151]
	v_mfma_f32_16x16x32_bf16 v[144:147], v[104:107], v[160:163], v[144:147]
	v_mfma_f32_16x16x32_bf16 v[124:127], v[84:87], v[168:171], v[124:127]
	v_mfma_f32_16x16x32_bf16 v[120:123], v[104:107], v[168:171], v[120:123]
	v_mfma_f32_16x16x32_bf16 v[100:103], v[84:87], v[176:179], v[100:103]
	v_mfma_f32_16x16x32_bf16 v[96:99], v[104:107], v[176:179], v[96:99]
	v_mfma_f32_16x16x32_bf16 v[76:79], v[84:87], v[184:187], v[76:79]
	v_mfma_f32_16x16x32_bf16 v[72:75], v[104:107], v[184:187], v[72:75]
	v_mfma_f32_16x16x32_bf16 v[148:151], v[92:95], v[164:167], v[148:151]
	v_mfma_f32_16x16x32_bf16 v[144:147], v[116:119], v[164:167], v[144:147]
	v_mfma_f32_16x16x32_bf16 v[124:127], v[92:95], v[172:175], v[124:127]
	v_mfma_f32_16x16x32_bf16 v[120:123], v[116:119], v[172:175], v[120:123]
	v_mfma_f32_16x16x32_bf16 v[100:103], v[92:95], v[180:183], v[100:103]
	v_mfma_f32_16x16x32_bf16 v[96:99], v[116:119], v[180:183], v[96:99]
	v_mfma_f32_16x16x32_bf16 v[76:79], v[92:95], v[212:215], v[76:79]
	v_mfma_f32_16x16x32_bf16 v[72:75], v[116:119], v[212:215], v[72:75]
	v_mfma_f32_16x16x32_bf16 v[136:139], v[128:131], v[160:163], v[136:139]
	v_mfma_f32_16x16x32_bf16 v[132:135], v[152:155], v[160:163], v[132:135]
	v_mfma_f32_16x16x32_bf16 v[112:115], v[128:131], v[168:171], v[112:115]
	v_mfma_f32_16x16x32_bf16 v[108:111], v[152:155], v[168:171], v[108:111]
	v_mfma_f32_16x16x32_bf16 v[88:91], v[128:131], v[176:179], v[88:91]
	v_mfma_f32_16x16x32_bf16 v[80:83], v[152:155], v[176:179], v[80:83]
	v_mfma_f32_16x16x32_bf16 v[68:71], v[128:131], v[184:187], v[68:71]
	v_mfma_f32_16x16x32_bf16 v[64:67], v[152:155], v[184:187], v[64:67]
	v_mfma_f32_16x16x32_bf16 v[136:139], v[140:143], v[164:167], v[136:139]
	v_mfma_f32_16x16x32_bf16 v[132:135], v[156:159], v[164:167], v[132:135]
	v_mfma_f32_16x16x32_bf16 v[112:115], v[140:143], v[172:175], v[112:115]
	v_mfma_f32_16x16x32_bf16 v[108:111], v[156:159], v[172:175], v[108:111]
	v_mfma_f32_16x16x32_bf16 v[88:91], v[140:143], v[180:183], v[88:91]
	v_mfma_f32_16x16x32_bf16 v[80:83], v[156:159], v[180:183], v[80:83]
	v_mfma_f32_16x16x32_bf16 v[68:71], v[140:143], v[212:215], v[68:71]
	v_mfma_f32_16x16x32_bf16 v[64:67], v[156:159], v[212:215], v[64:67]
	s_barrier
	s_add_i32 s33, s83, s14
	v_lshl_add_u64 v[230:231], v[216:217], 0, s[42:43]
	s_mov_b32 m0, s33
	ds_read_b128 v[160:163], v223 offset:49152
	ds_read_b128 v[164:167], v223 offset:50176
	ds_read_b128 v[168:171], v223 offset:51200
	ds_read_b128 v[172:175], v223 offset:52224
	ds_read_b128 v[176:179], v223 offset:53248
	ds_read_b128 v[180:183], v223 offset:54272
	ds_read_b128 v[184:187], v223 offset:55296
	ds_read_b128 v[212:215], v223 offset:56320
	global_load_lds_dwordx4 v[230:231], off
	v_lshl_add_u64 v[230:231], v[216:217], 0, s[44:45]
	s_add_i32 m0, s33, 0x2000
	s_add_i32 s33, s84, s14
	global_load_lds_dwordx4 v[230:231], off
	v_lshl_add_u64 v[230:231], v[216:217], 0, s[46:47]
	s_mov_b32 m0, s33
	v_lshl_add_u64 v[216:217], v[216:217], 0, s[48:49]
	global_load_lds_dwordx4 v[230:231], off
	s_add_i32 m0, s33, 0x2000
	s_nop 0
	global_load_lds_dwordx4 v[216:217], off
	v_lshl_add_u64 v[216:217], v[228:229], 0, s[42:43]
	s_mov_b32 m0, s74
	s_nop 0
	global_load_lds_dwordx4 v[216:217], off
	v_lshl_add_u64 v[216:217], v[228:229], 0, s[44:45]
	s_mov_b32 m0, s75
	s_nop 0
	global_load_lds_dwordx4 v[216:217], off
	s_waitcnt vmcnt(8)
	s_waitcnt lgkmcnt(0)
	s_barrier
	s_waitcnt lgkmcnt(0)
	v_mfma_f32_16x16x32_bf16 v[60:63], v[84:87], v[160:163], v[60:63]
	v_mfma_f32_16x16x32_bf16 v[56:59], v[104:107], v[160:163], v[56:59]
	v_mfma_f32_16x16x32_bf16 v[44:47], v[84:87], v[168:171], v[44:47]
	v_mfma_f32_16x16x32_bf16 v[40:43], v[104:107], v[168:171], v[40:43]
	v_mfma_f32_16x16x32_bf16 v[28:31], v[84:87], v[176:179], v[28:31]
	v_mfma_f32_16x16x32_bf16 v[24:27], v[104:107], v[176:179], v[24:27]
	v_mfma_f32_16x16x32_bf16 v[12:15], v[84:87], v[184:187], v[12:15]
	v_mfma_f32_16x16x32_bf16 v[8:11], v[104:107], v[184:187], v[8:11]
	v_mfma_f32_16x16x32_bf16 v[60:63], v[92:95], v[164:167], v[60:63]
	v_mfma_f32_16x16x32_bf16 v[56:59], v[116:119], v[164:167], v[56:59]
	v_mfma_f32_16x16x32_bf16 v[44:47], v[92:95], v[172:175], v[44:47]
	v_mfma_f32_16x16x32_bf16 v[40:43], v[116:119], v[172:175], v[40:43]
	v_mfma_f32_16x16x32_bf16 v[28:31], v[92:95], v[180:183], v[28:31]
	v_mfma_f32_16x16x32_bf16 v[24:27], v[116:119], v[180:183], v[24:27]
	v_mfma_f32_16x16x32_bf16 v[12:15], v[92:95], v[212:215], v[12:15]
	v_mfma_f32_16x16x32_bf16 v[8:11], v[116:119], v[212:215], v[8:11]
	v_mfma_f32_16x16x32_bf16 v[52:55], v[128:131], v[160:163], v[52:55]
	v_mfma_f32_16x16x32_bf16 v[48:51], v[152:155], v[160:163], v[48:51]
	v_mfma_f32_16x16x32_bf16 v[36:39], v[128:131], v[168:171], v[36:39]
	v_mfma_f32_16x16x32_bf16 v[32:35], v[152:155], v[168:171], v[32:35]
	v_mfma_f32_16x16x32_bf16 v[20:23], v[128:131], v[176:179], v[20:23]
	v_mfma_f32_16x16x32_bf16 v[16:19], v[152:155], v[176:179], v[16:19]
	v_mfma_f32_16x16x32_bf16 v[4:7], v[128:131], v[184:187], v[4:7]
	v_mfma_f32_16x16x32_bf16 v[0:3], v[152:155], v[184:187], v[0:3]
	v_mfma_f32_16x16x32_bf16 v[52:55], v[140:143], v[164:167], v[52:55]
	v_mfma_f32_16x16x32_bf16 v[48:51], v[156:159], v[164:167], v[48:51]
	v_mfma_f32_16x16x32_bf16 v[36:39], v[140:143], v[172:175], v[36:39]
	v_mfma_f32_16x16x32_bf16 v[32:35], v[156:159], v[172:175], v[32:35]
	v_mfma_f32_16x16x32_bf16 v[20:23], v[140:143], v[180:183], v[20:23]
	v_mfma_f32_16x16x32_bf16 v[16:19], v[156:159], v[180:183], v[16:19]
	v_mfma_f32_16x16x32_bf16 v[4:7], v[140:143], v[212:215], v[4:7]
	v_mfma_f32_16x16x32_bf16 v[0:3], v[156:159], v[212:215], v[0:3]
	s_barrier
	s_add_i32 s66, s66, 2
	s_add_u32 s6, s6, 0x10000
	s_addc_u32 s7, s7, 0
	s_add_u32 s64, s64, 0x10000
	s_addc_u32 s65, s65, 0
	s_cmp_gt_u32 s66, 41
	s_cbranch_scc0 .LBB0_924
	s_and_b64 vcc, exec, s[54:55]
	s_cbranch_vccz .LBB0_927
	s_barrier

; #define PG8_STAGE(bufoff, gbase, voff) do { _Pragma("unroll") for (int _i = 0; _i < 2; ++_i) \
;         __builtin_amdgcn_global_load_lds((const unsigned*)((const char*)(gbase) + (voff)[_i]), (PG8_LAS unsigned*)(lds + (bufoff) + ldsw + _i * 8192), 16, 0, 0); } while (0)
; #define PG8_LDA(dst, b, h) do { _Pragma("unroll") for (int m = 0; m < 4; ++m) _Pragma("unroll") for (int k = 0; k < 2; ++k) dst[m][k] = *(const PG8_LAS bf16x8*)(lds + PG8_SA(b, h) + aoff + m * 2048 + k * 1024); } while (0)
; #define PG8_LDB(dst, b, h) do { _Pragma("unroll") for (int n = 0; n < 2; ++n) _Pragma("unroll") for (int k = 0; k < 2; ++k) dst[n][k] = *(const PG8_LAS bf16x8*)(lds + PG8_SB(b, h) + boff + n * 2048 + k * 1024); } while (0)
; #define PG8_WAIT_V(n) asm volatile("s_waitcnt vmcnt(" #n ")" ::: "memory")
; #define PG8_WAIT_L(n) asm volatile("s_waitcnt lgkmcnt(" #n ")" ::: "memory")
; #define PG8_BAR __builtin_amdgcn_s_barrier()
; #define PG8_SCHED __builtin_amdgcn_sched_barrier(0)
; template <class Epi, class Sched, bool ALIGN_EPI = false, bool SP2 = false>
; __device__ __forceinline__ void gemm_phase(PG8_LAS unsigned char* lds, const Gemm g, const Sched& S, const Epi& E) {
;     ...
;         const char* nA = has_next ? (const char*)g.A + (size_t)nxt.pm * tstepA : cA; const char* nB = has_next ? (const char*)g.Bt + (size_t)nxt.pn * tstepB : cB;
;         for (int t = 0; t < nt; t += 2) {
;             const bool last = (t == nt - 2);
;             const char* a1 = cA + (size_t)(t + 1) * kstepA;
;             const char* a2 = last ? nA : cA + (size_t)(t + 2) * kstepA; const char* b2 = last ? nB : cB + (size_t)(t + 2) * kstep;
;             const char* a3 = a2 + kstepA; const char* b3 = b2 + kstep;
;             if (last && has_next) S.a_ready(nxt);
;             if constexpr (SP2) {
;             PG8_LDB(B0, 0, 0); PG8_LDB(B1, 0, 1); PG8_SCHED; PG8_LDA(At, 0, 0); PG8_STAGE(PG8_SA(1, 1), a1 + hstepA, voffA);
;             PG8_WAIT_V(8); PG8_WAIT_L(0); PG8_BAR; PG8_MMA(0, 0, At, B0); PG8_MMA(0, 1, At, B1); PG8_BAR; PG8_SCHED;
;             PG8_LDA(At, 0, 1); PG8_STAGE(PG8_SB(0, 0), b2, voffB); PG8_STAGE(PG8_SB(0, 1), b2 + hstepB, voffB); PG8_STAGE(PG8_SA(0, 0), a2, voffA);
;             PG8_WAIT_V(8); PG8_WAIT_L(0); PG8_BAR; PG8_MMA(1, 0, At, B0); PG8_MMA(1, 1, At, B1); PG8_BAR; PG8_SCHED;
.LBB0_1003:
	s_add_u32 s70, s70, 0x10000
	s_addc_u32 s71, s71, 0
	s_add_u32 s69, s72, 0x10000
	s_addc_u32 s72, s73, 0
	s_mov_b32 s73, -2
	ds_read_b128 v[128:131], v220
	ds_read_b128 v[132:135], v220 offset:1024
	ds_read_b128 v[136:139], v220 offset:2048
	ds_read_b128 v[140:143], v220 offset:3072
	ds_read_b128 v[144:147], v221
	ds_read_b128 v[148:151], v221 offset:1024
	ds_read_b128 v[152:155], v221 offset:2048
	ds_read_b128 v[156:159], v221 offset:3072
	s_cmp_eq_u32 s73, 40
	s_cselect_b32 s75, s1, s71
	s_cselect_b32 s74, s0, s70
	s_cselect_b32 s77, s67, s72
	s_cselect_b32 s76, s66, s69
	v_lshl_add_u64 v[238:239], s[70:71], 0, v[190:191]
	v_lshl_add_u64 v[240:241], v[238:239], 0, s[62:63]
	s_add_i32 m0, s15, 0xc000
	ds_read_b128 v[160:163], v222
	ds_read_b128 v[164:167], v222 offset:1024
	ds_read_b128 v[168:171], v222 offset:2048
	ds_read_b128 v[172:175], v222 offset:3072
	ds_read_b128 v[176:179], v222 offset:4096
	ds_read_b128 v[180:183], v222 offset:5120
	ds_read_b128 v[230:233], v222 offset:6144
	ds_read_b128 v[234:237], v222 offset:7168
	global_load_lds_dwordx4 v[240:241], off
	v_lshl_add_u64 v[238:239], v[238:239], 0, s[64:65]
	s_add_i32 m0, s15, 0xe000
	s_nop 0
	global_load_lds_dwordx4 v[238:239], off
	s_waitcnt vmcnt(8)
	s_waitcnt lgkmcnt(0)
	s_barrier
	s_waitcnt lgkmcnt(0)
	v_mfma_f32_16x16x32_bf16 v[124:127], v[128:131], v[160:163], 0
	v_mfma_f32_16x16x32_bf16 v[120:123], v[136:139], v[160:163], 0
	v_mfma_f32_16x16x32_bf16 v[108:111], v[128:131], v[168:171], 0
	v_mfma_f32_16x16x32_bf16 v[104:107], v[136:139], v[168:171], 0
	v_mfma_f32_16x16x32_bf16 v[92:95], v[128:131], v[176:179], 0
	v_mfma_f32_16x16x32_bf16 v[88:91], v[136:139], v[176:179], 0
	v_mfma_f32_16x16x32_bf16 v[76:79], v[128:131], v[230:233], 0
	v_mfma_f32_16x16x32_bf16 v[72:75], v[136:139], v[230:233], 0
	v_mfma_f32_16x16x32_bf16 v[124:127], v[132:135], v[164:167], v[124:127]
	v_mfma_f32_16x16x32_bf16 v[120:123], v[140:143], v[164:167], v[120:123]
	v_mfma_f32_16x16x32_bf16 v[108:111], v[132:135], v[172:175], v[108:111]
	v_mfma_f32_16x16x32_bf16 v[104:107], v[140:143], v[172:175], v[104:107]
	v_mfma_f32_16x16x32_bf16 v[92:95], v[132:135], v[180:183], v[92:95]
	v_mfma_f32_16x16x32_bf16 v[88:91], v[140:143], v[180:183], v[88:91]
	v_mfma_f32_16x16x32_bf16 v[76:79], v[132:135], v[234:237], v[76:79]
	v_mfma_f32_16x16x32_bf16 v[72:75], v[140:143], v[234:237], v[72:75]
	v_mfma_f32_16x16x32_bf16 v[116:119], v[144:147], v[160:163], 0
	v_mfma_f32_16x16x32_bf16 v[112:115], v[152:155], v[160:163], 0
	v_mfma_f32_16x16x32_bf16 v[100:103], v[144:147], v[168:171], 0
	v_mfma_f32_16x16x32_bf16 v[96:99], v[152:155], v[168:171], 0
	v_mfma_f32_16x16x32_bf16 v[84:87], v[144:147], v[176:179], 0
	v_mfma_f32_16x16x32_bf16 v[80:83], v[152:155], v[176:179], 0
	v_mfma_f32_16x16x32_bf16 v[68:71], v[144:147], v[230:233], 0
	v_mfma_f32_16x16x32_bf16 v[64:67], v[152:155], v[230:233], 0
	v_mfma_f32_16x16x32_bf16 v[116:119], v[148:151], v[164:167], v[116:119]
	v_mfma_f32_16x16x32_bf16 v[112:115], v[156:159], v[164:167], v[112:115]
	v_mfma_f32_16x16x32_bf16 v[100:103], v[148:151], v[172:175], v[100:103]
	v_mfma_f32_16x16x32_bf16 v[96:99], v[156:159], v[172:175], v[96:99]
	v_mfma_f32_16x16x32_bf16 v[84:87], v[148:151], v[180:183], v[84:87]
	v_mfma_f32_16x16x32_bf16 v[80:83], v[156:159], v[180:183], v[80:83]
	v_mfma_f32_16x16x32_bf16 v[68:71], v[148:151], v[234:237], v[68:71]
	v_mfma_f32_16x16x32_bf16 v[64:67], v[156:159], v[234:237], v[64:67]
	s_barrier
	s_add_i32 s33, s86, s14
	v_lshl_add_u64 v[238:239], s[76:77], 0, v[190:191]
	s_mov_b32 m0, s33
	ds_read_b128 v[160:163], v222 offset:16384
	ds_read_b128 v[164:167], v222 offset:17408
	ds_read_b128 v[168:171], v222 offset:18432
	ds_read_b128 v[172:175], v222 offset:19456
	ds_read_b128 v[176:179], v222 offset:20480
	ds_read_b128 v[180:183], v222 offset:21504
	ds_read_b128 v[230:233], v222 offset:22528
	ds_read_b128 v[234:237], v222 offset:23552
	global_load_lds_dwordx4 v[238:239], off
	v_lshl_add_u64 v[240:241], v[238:239], 0, s[40:41]
	s_add_i32 m0, s33, 0x2000
	s_add_i32 s33, s87, s14
	global_load_lds_dwordx4 v[240:241], off
	v_lshl_add_u64 v[240:241], v[238:239], 0, s[42:43]
	s_mov_b32 m0, s33
	s_nop 0
	global_load_lds_dwordx4 v[240:241], off
	v_lshl_add_u64 v[240:241], v[238:239], 0, s[44:45]
	s_add_i32 m0, s33, 0x2000
	s_nop 0
	global_load_lds_dwordx4 v[240:241], off
	v_lshl_add_u64 v[240:241], s[74:75], 0, v[190:191]
	s_mov_b32 m0, s15
	v_lshl_add_u64 v[242:243], v[240:241], 0, s[40:41]
	global_load_lds_dwordx4 v[240:241], off
	s_mov_b32 m0, s17
	s_nop 0
	global_load_lds_dwordx4 v[242:243], off
	s_waitcnt vmcnt(8)
	s_waitcnt lgkmcnt(0)
	s_barrier
; #define PG8_STAGE(bufoff, gbase, voff) do { _Pragma("unroll") for (int _i = 0; _i < 2; ++_i) \
;         __builtin_amdgcn_global_load_lds((const unsigned*)((const char*)(gbase) + (voff)[_i]), (PG8_LAS unsigned*)(lds + (bufoff) + ldsw + _i * 8192), 16, 0, 0); } while (0)
; #define PG8_LDA(dst, b, h) do { _Pragma("unroll") for (int m = 0; m < 4; ++m) _Pragma("unroll") for (int k = 0; k < 2; ++k) dst[m][k] = *(const PG8_LAS bf16x8*)(lds + PG8_SA(b, h) + aoff + m * 2048 + k * 1024); } while (0)
; #define PG8_LDB(dst, b, h) do { _Pragma("unroll") for (int n = 0; n < 2; ++n) _Pragma("unroll") for (int k = 0; k < 2; ++k) dst[n][k] = *(const PG8_LAS bf16x8*)(lds + PG8_SB(b, h) + boff + n * 2048 + k * 1024); } while (0)
; #define PG8_MMA(ai, bj, At, Bt) do { __builtin_amdgcn_s_setprio(1); _Pragma("unroll") for (int m = 0; m < 4; ++m) _Pragma("unroll") for (int n = 0; n < 2; ++n) _Pragma("unroll") for (int k = 0; k < 2; ++k) \
;         acc[ai][bj][m][n] = __builtin_amdgcn_mfma_f32_16x16x32_bf16(Bt[n][k], At[m][k], acc[ai][bj][m][n], 0, 0, 0); __builtin_amdgcn_s_setprio(0); } while (0)
; #define PG8_WAIT_V(n) asm volatile("s_waitcnt vmcnt(" #n ")" ::: "memory")
; #define PG8_WAIT_L(n) asm volatile("s_waitcnt lgkmcnt(" #n ")" ::: "memory")
; #define PG8_BAR __builtin_amdgcn_s_barrier()
; #define PG8_SCHED __builtin_amdgcn_sched_barrier(0)
; template <class Epi, class Sched, bool ALIGN_EPI = false, bool SP2 = false>
; __device__ __forceinline__ void gemm_phase(PG8_LAS unsigned char* lds, const Gemm g, const Sched& S, const Epi& E) {
;     ...
;             PG8_WAIT_V(8); PG8_WAIT_L(0); PG8_BAR; PG8_MMA(1, 0, At, B0); PG8_MMA(1, 1, At, B1); PG8_BAR; PG8_SCHED;
;             PG8_LDB(B0, 1, 0); PG8_LDB(B1, 1, 1); PG8_SCHED; PG8_LDA(At, 1, 0); PG8_STAGE(PG8_SA(0, 1), a2 + hstepA, voffA);
;             PG8_WAIT_V(8); PG8_WAIT_L(0); PG8_BAR; PG8_MMA(0, 0, At, B0); PG8_MMA(0, 1, At, B1); PG8_BAR; PG8_SCHED;
	s_waitcnt lgkmcnt(0)
	v_mfma_f32_16x16x32_bf16 v[60:63], v[128:131], v[160:163], 0
	v_mfma_f32_16x16x32_bf16 v[56:59], v[136:139], v[160:163], 0
	v_mfma_f32_16x16x32_bf16 v[44:47], v[128:131], v[168:171], 0
	v_mfma_f32_16x16x32_bf16 v[40:43], v[136:139], v[168:171], 0
	v_mfma_f32_16x16x32_bf16 v[28:31], v[128:131], v[176:179], 0
	v_mfma_f32_16x16x32_bf16 v[24:27], v[136:139], v[176:179], 0
	v_mfma_f32_16x16x32_bf16 v[12:15], v[128:131], v[230:233], 0
	v_mfma_f32_16x16x32_bf16 v[8:11], v[136:139], v[230:233], 0
	v_mfma_f32_16x16x32_bf16 v[60:63], v[132:135], v[164:167], v[60:63]
	v_mfma_f32_16x16x32_bf16 v[56:59], v[140:143], v[164:167], v[56:59]
	v_mfma_f32_16x16x32_bf16 v[44:47], v[132:135], v[172:175], v[44:47]
	v_mfma_f32_16x16x32_bf16 v[40:43], v[140:143], v[172:175], v[40:43]
	v_mfma_f32_16x16x32_bf16 v[28:31], v[132:135], v[180:183], v[28:31]
	v_mfma_f32_16x16x32_bf16 v[24:27], v[140:143], v[180:183], v[24:27]
	v_mfma_f32_16x16x32_bf16 v[12:15], v[132:135], v[234:237], v[12:15]
	v_mfma_f32_16x16x32_bf16 v[8:11], v[140:143], v[234:237], v[8:11]
	v_mfma_f32_16x16x32_bf16 v[52:55], v[144:147], v[160:163], 0
	v_mfma_f32_16x16x32_bf16 v[48:51], v[152:155], v[160:163], 0
	v_mfma_f32_16x16x32_bf16 v[36:39], v[144:147], v[168:171], 0
	v_mfma_f32_16x16x32_bf16 v[32:35], v[152:155], v[168:171], 0
	v_mfma_f32_16x16x32_bf16 v[20:23], v[144:147], v[176:179], 0
	v_mfma_f32_16x16x32_bf16 v[16:19], v[152:155], v[176:179], 0
	v_mfma_f32_16x16x32_bf16 v[4:7], v[144:147], v[230:233], 0
	v_mfma_f32_16x16x32_bf16 v[0:3], v[152:155], v[230:233], 0
	v_mfma_f32_16x16x32_bf16 v[52:55], v[148:151], v[164:167], v[52:55]
	v_mfma_f32_16x16x32_bf16 v[48:51], v[156:159], v[164:167], v[48:51]
	v_mfma_f32_16x16x32_bf16 v[36:39], v[148:151], v[172:175], v[36:39]
	v_mfma_f32_16x16x32_bf16 v[32:35], v[156:159], v[172:175], v[32:35]
	v_mfma_f32_16x16x32_bf16 v[20:23], v[148:151], v[180:183], v[20:23]
	v_mfma_f32_16x16x32_bf16 v[16:19], v[156:159], v[180:183], v[16:19]
	v_mfma_f32_16x16x32_bf16 v[4:7], v[148:151], v[234:237], v[4:7]
	v_mfma_f32_16x16x32_bf16 v[0:3], v[156:159], v[234:237], v[0:3]
	s_barrier
	ds_read_b128 v[128:131], v223
	ds_read_b128 v[132:135], v223 offset:1024
	ds_read_b128 v[136:139], v223 offset:2048
	ds_read_b128 v[140:143], v223 offset:3072
	ds_read_b128 v[144:147], v224
	ds_read_b128 v[148:151], v224 offset:1024
	ds_read_b128 v[152:155], v224 offset:2048
	ds_read_b128 v[156:159], v224 offset:3072
	s_mov_b32 m0, s18
	v_lshl_add_u64 v[242:243], v[240:241], 0, s[42:43]
	ds_read_b128 v[160:163], v222 offset:32768
	ds_read_b128 v[164:167], v222 offset:33792
	ds_read_b128 v[168:171], v222 offset:34816
	ds_read_b128 v[172:175], v222 offset:35840
	ds_read_b128 v[176:179], v222 offset:36864
	ds_read_b128 v[180:183], v222 offset:37888
	ds_read_b128 v[230:233], v222 offset:38912
	ds_read_b128 v[234:237], v222 offset:39936
	global_load_lds_dwordx4 v[242:243], off
	v_lshl_add_u64 v[242:243], v[240:241], 0, s[44:45]
	s_mov_b32 m0, s19
	s_nop 0
	global_load_lds_dwordx4 v[242:243], off
	s_waitcnt vmcnt(8)
	s_waitcnt lgkmcnt(0)
	s_barrier
	s_waitcnt lgkmcnt(0)
	v_mfma_f32_16x16x32_bf16 v[124:127], v[128:131], v[160:163], v[124:127]
	v_mfma_f32_16x16x32_bf16 v[120:123], v[136:139], v[160:163], v[120:123]
	v_mfma_f32_16x16x32_bf16 v[108:111], v[128:131], v[168:171], v[108:111]
	v_mfma_f32_16x16x32_bf16 v[104:107], v[136:139], v[168:171], v[104:107]
	v_mfma_f32_16x16x32_bf16 v[92:95], v[128:131], v[176:179], v[92:95]
	v_mfma_f32_16x16x32_bf16 v[88:91], v[136:139], v[176:179], v[88:91]
	v_mfma_f32_16x16x32_bf16 v[76:79], v[128:131], v[230:233], v[76:79]
	v_mfma_f32_16x16x32_bf16 v[72:75], v[136:139], v[230:233], v[72:75]
	v_mfma_f32_16x16x32_bf16 v[124:127], v[132:135], v[164:167], v[124:127]
	v_mfma_f32_16x16x32_bf16 v[120:123], v[140:143], v[164:167], v[120:123]
	v_mfma_f32_16x16x32_bf16 v[108:111], v[132:135], v[172:175], v[108:111]
	v_mfma_f32_16x16x32_bf16 v[104:107], v[140:143], v[172:175], v[104:107]
	v_mfma_f32_16x16x32_bf16 v[92:95], v[132:135], v[180:183], v[92:95]
	v_mfma_f32_16x16x32_bf16 v[88:91], v[140:143], v[180:183], v[88:91]
	v_mfma_f32_16x16x32_bf16 v[76:79], v[132:135], v[234:237], v[76:79]
	v_mfma_f32_16x16x32_bf16 v[72:75], v[140:143], v[234:237], v[72:75]
	v_mfma_f32_16x16x32_bf16 v[116:119], v[144:147], v[160:163], v[116:119]
	v_mfma_f32_16x16x32_bf16 v[112:115], v[152:155], v[160:163], v[112:115]
	v_mfma_f32_16x16x32_bf16 v[100:103], v[144:147], v[168:171], v[100:103]
	v_mfma_f32_16x16x32_bf16 v[96:99], v[152:155], v[168:171], v[96:99]
	v_mfma_f32_16x16x32_bf16 v[84:87], v[144:147], v[176:179], v[84:87]
	v_mfma_f32_16x16x32_bf16 v[80:83], v[152:155], v[176:179], v[80:83]
	v_mfma_f32_16x16x32_bf16 v[68:71], v[144:147], v[230:233], v[68:71]
	v_mfma_f32_16x16x32_bf16 v[64:67], v[152:155], v[230:233], v[64:67]
	v_mfma_f32_16x16x32_bf16 v[116:119], v[148:151], v[164:167], v[116:119]
	v_mfma_f32_16x16x32_bf16 v[112:115], v[156:159], v[164:167], v[112:115]
	v_mfma_f32_16x16x32_bf16 v[100:103], v[148:151], v[172:175], v[100:103]
	v_mfma_f32_16x16x32_bf16 v[96:99], v[156:159], v[172:175], v[96:99]
	v_mfma_f32_16x16x32_bf16 v[84:87], v[148:151], v[180:183], v[84:87]
	v_mfma_f32_16x16x32_bf16 v[80:83], v[156:159], v[180:183], v[80:83]
	v_mfma_f32_16x16x32_bf16 v[68:71], v[148:151], v[234:237], v[68:71]
	v_mfma_f32_16x16x32_bf16 v[64:67], v[156:159], v[234:237], v[64:67]
	s_barrier
; #define PG8_STAGE(bufoff, gbase, voff) do { _Pragma("unroll") for (int _i = 0; _i < 2; ++_i) \
;         __builtin_amdgcn_global_load_lds((const unsigned*)((const char*)(gbase) + (voff)[_i]), (PG8_LAS unsigned*)(lds + (bufoff) + ldsw + _i * 8192), 16, 0, 0); } while (0)
; #define PG8_LDA(dst, b, h) do { _Pragma("unroll") for (int m = 0; m < 4; ++m) _Pragma("unroll") for (int k = 0; k < 2; ++k) dst[m][k] = *(const PG8_LAS bf16x8*)(lds + PG8_SA(b, h) + aoff + m * 2048 + k * 1024); } while (0)
; #define PG8_LDB(dst, b, h) do { _Pragma("unroll") for (int n = 0; n < 2; ++n) _Pragma("unroll") for (int k = 0; k < 2; ++k) dst[n][k] = *(const PG8_LAS bf16x8*)(lds + PG8_SB(b, h) + boff + n * 2048 + k * 1024); } while (0)
; #define PG8_MMA(ai, bj, At, Bt) do { __builtin_amdgcn_s_setprio(1); _Pragma("unroll") for (int m = 0; m < 4; ++m) _Pragma("unroll") for (int n = 0; n < 2; ++n) _Pragma("unroll") for (int k = 0; k < 2; ++k) \
;         acc[ai][bj][m][n] = __builtin_amdgcn_mfma_f32_16x16x32_bf16(Bt[n][k], At[m][k], acc[ai][bj][m][n], 0, 0, 0); __builtin_amdgcn_s_setprio(0); } while (0)
; #define PG8_WAIT_V(n) asm volatile("s_waitcnt vmcnt(" #n ")" ::: "memory")
; template <class Epi, class Sched, bool ALIGN_EPI = false, bool SP2 = false>
; __device__ __forceinline__ void gemm_phase(PG8_LAS unsigned char* lds, const Gemm g, const Sched& S, const Epi& E) {
;     ...
;             PG8_LDB(B0, 0, 0); PG8_LDB(B1, 0, 1); PG8_SCHED; PG8_LDA(At, 0, 0); PG8_STAGE(PG8_SA(1, 1), a1 + hstepA, voffA);
;             PG8_WAIT_V(8); PG8_WAIT_L(0); PG8_BAR; PG8_MMA(0, 0, At, B0); PG8_MMA(0, 1, At, B1); PG8_BAR; PG8_SCHED;
;             PG8_LDA(At, 0, 1); PG8_STAGE(PG8_SB(0, 0), b2, voffB); PG8_STAGE(PG8_SB(0, 1), b2 + hstepB, voffB); PG8_STAGE(PG8_SA(0, 0), a2, voffA);
;             PG8_WAIT_V(8); PG8_WAIT_L(0); PG8_BAR; PG8_MMA(1, 0, At, B0); PG8_MMA(1, 1, At, B1); PG8_BAR; PG8_SCHED;
;             PG8_LDB(B0, 1, 0); PG8_LDB(B1, 1, 1); PG8_SCHED; PG8_LDA(At, 1, 0); PG8_STAGE(PG8_SA(0, 1), a2 + hstepA, voffA);
;             PG8_WAIT_V(8); PG8_WAIT_L(0); PG8_BAR; PG8_MMA(0, 0, At, B0); PG8_MMA(0, 1, At, B1); PG8_BAR; PG8_SCHED;
;             PG8_LDA(At, 1, 1); PG8_STAGE(PG8_SB(1, 0), b3, voffB); PG8_STAGE(PG8_SB(1, 1), b3 + hstepB, voffB); PG8_STAGE(PG8_SA(1, 0), a3, voffA);
;             PG8_WAIT_V(8); PG8_WAIT_L(0); PG8_BAR; PG8_MMA(1, 0, At, B0); PG8_MMA(1, 1, At, B1); PG8_BAR; PG8_SCHED;
	s_add_i32 s33, s88, s14
	v_lshl_add_u64 v[242:243], v[238:239], 0, s[46:47]
	s_mov_b32 m0, s33
	ds_read_b128 v[160:163], v222 offset:49152
	ds_read_b128 v[164:167], v222 offset:50176
	ds_read_b128 v[168:171], v222 offset:51200
	ds_read_b128 v[172:175], v222 offset:52224
	ds_read_b128 v[176:179], v222 offset:53248
	ds_read_b128 v[180:183], v222 offset:54272
	ds_read_b128 v[230:233], v222 offset:55296
	ds_read_b128 v[234:237], v222 offset:56320
	global_load_lds_dwordx4 v[242:243], off
	v_lshl_add_u64 v[242:243], v[238:239], 0, s[48:49]
	s_add_i32 m0, s33, 0x2000
	s_add_i32 s33, s89, s14
	global_load_lds_dwordx4 v[242:243], off
	v_lshl_add_u64 v[242:243], v[238:239], 0, s[52:53]
	s_mov_b32 m0, s33
	v_lshl_add_u64 v[238:239], v[238:239], 0, s[54:55]
	global_load_lds_dwordx4 v[242:243], off
	s_add_i32 m0, s33, 0x2000
	s_nop 0
	global_load_lds_dwordx4 v[238:239], off
	v_lshl_add_u64 v[238:239], v[240:241], 0, s[46:47]
	s_mov_b32 m0, s80
	s_nop 0
	global_load_lds_dwordx4 v[238:239], off
	v_lshl_add_u64 v[238:239], v[240:241], 0, s[48:49]
	s_mov_b32 m0, s81
	s_nop 0
	global_load_lds_dwordx4 v[238:239], off
	s_waitcnt vmcnt(8)
	s_waitcnt lgkmcnt(0)
	s_barrier
	s_waitcnt lgkmcnt(0)
	v_mfma_f32_16x16x32_bf16 v[60:63], v[128:131], v[160:163], v[60:63]
	v_mfma_f32_16x16x32_bf16 v[56:59], v[136:139], v[160:163], v[56:59]
	v_mfma_f32_16x16x32_bf16 v[44:47], v[128:131], v[168:171], v[44:47]
	v_mfma_f32_16x16x32_bf16 v[40:43], v[136:139], v[168:171], v[40:43]
	v_mfma_f32_16x16x32_bf16 v[28:31], v[128:131], v[176:179], v[28:31]
	v_mfma_f32_16x16x32_bf16 v[24:27], v[136:139], v[176:179], v[24:27]
	v_mfma_f32_16x16x32_bf16 v[12:15], v[128:131], v[230:233], v[12:15]
	v_mfma_f32_16x16x32_bf16 v[8:11], v[136:139], v[230:233], v[8:11]
	v_mfma_f32_16x16x32_bf16 v[60:63], v[132:135], v[164:167], v[60:63]
	v_mfma_f32_16x16x32_bf16 v[56:59], v[140:143], v[164:167], v[56:59]
	v_mfma_f32_16x16x32_bf16 v[44:47], v[132:135], v[172:175], v[44:47]
	v_mfma_f32_16x16x32_bf16 v[40:43], v[140:143], v[172:175], v[40:43]
	v_mfma_f32_16x16x32_bf16 v[28:31], v[132:135], v[180:183], v[28:31]
	v_mfma_f32_16x16x32_bf16 v[24:27], v[140:143], v[180:183], v[24:27]
	v_mfma_f32_16x16x32_bf16 v[12:15], v[132:135], v[234:237], v[12:15]
	v_mfma_f32_16x16x32_bf16 v[8:11], v[140:143], v[234:237], v[8:11]
	v_mfma_f32_16x16x32_bf16 v[52:55], v[144:147], v[160:163], v[52:55]
	v_mfma_f32_16x16x32_bf16 v[48:51], v[152:155], v[160:163], v[48:51]
	v_mfma_f32_16x16x32_bf16 v[36:39], v[144:147], v[168:171], v[36:39]
	v_mfma_f32_16x16x32_bf16 v[32:35], v[152:155], v[168:171], v[32:35]
	v_mfma_f32_16x16x32_bf16 v[20:23], v[144:147], v[176:179], v[20:23]
	v_mfma_f32_16x16x32_bf16 v[16:19], v[152:155], v[176:179], v[16:19]
	v_mfma_f32_16x16x32_bf16 v[4:7], v[144:147], v[230:233], v[4:7]
	v_mfma_f32_16x16x32_bf16 v[0:3], v[152:155], v[230:233], v[0:3]
	v_mfma_f32_16x16x32_bf16 v[52:55], v[148:151], v[164:167], v[52:55]
	v_mfma_f32_16x16x32_bf16 v[48:51], v[156:159], v[164:167], v[48:51]
	v_mfma_f32_16x16x32_bf16 v[36:39], v[148:151], v[172:175], v[36:39]
	v_mfma_f32_16x16x32_bf16 v[32:35], v[156:159], v[172:175], v[32:35]
	v_mfma_f32_16x16x32_bf16 v[20:23], v[148:151], v[180:183], v[20:23]
	v_mfma_f32_16x16x32_bf16 v[16:19], v[156:159], v[180:183], v[16:19]
	v_mfma_f32_16x16x32_bf16 v[4:7], v[148:151], v[234:237], v[4:7]
	v_mfma_f32_16x16x32_bf16 v[0:3], v[156:159], v[234:237], v[0:3]
	s_barrier
	s_add_i32 s73, s73, 2
	s_add_u32 s70, s70, 0x10000
	s_addc_u32 s71, s71, 0
	s_add_u32 s69, s69, 0x10000
	s_addc_u32 s72, s72, 0
	s_cmp_gt_u32 s73, 41
.LBB0_1004:
	ds_read_b128 v[128:131], v220
	ds_read_b128 v[132:135], v220 offset:1024
	ds_read_b128 v[136:139], v220 offset:2048
	ds_read_b128 v[140:143], v220 offset:3072
	ds_read_b128 v[144:147], v221
	ds_read_b128 v[148:151], v221 offset:1024
	ds_read_b128 v[152:155], v221 offset:2048
	ds_read_b128 v[156:159], v221 offset:3072
	s_cmp_eq_u32 s73, 40
	s_cselect_b32 s75, s1, s71
	s_cselect_b32 s74, s0, s70
	s_cselect_b32 s77, s67, s72
	s_cselect_b32 s76, s66, s69
	v_lshl_add_u64 v[238:239], s[70:71], 0, v[190:191]
	v_lshl_add_u64 v[240:241], v[238:239], 0, s[62:63]
	s_add_i32 m0, s15, 0xc000
	ds_read_b128 v[160:163], v222
	ds_read_b128 v[164:167], v222 offset:1024
	ds_read_b128 v[168:171], v222 offset:2048
	ds_read_b128 v[172:175], v222 offset:3072
	ds_read_b128 v[176:179], v222 offset:4096
	ds_read_b128 v[180:183], v222 offset:5120
	ds_read_b128 v[230:233], v222 offset:6144
	ds_read_b128 v[234:237], v222 offset:7168
	global_load_lds_dwordx4 v[240:241], off
	v_lshl_add_u64 v[238:239], v[238:239], 0, s[64:65]
	s_add_i32 m0, s15, 0xe000
	s_nop 0
	global_load_lds_dwordx4 v[238:239], off
	s_waitcnt vmcnt(8)
	s_waitcnt lgkmcnt(0)
	s_barrier
; #define PG8_STAGE(bufoff, gbase, voff) do { _Pragma("unroll") for (int _i = 0; _i < 2; ++_i) \
;         __builtin_amdgcn_global_load_lds((const unsigned*)((const char*)(gbase) + (voff)[_i]), (PG8_LAS unsigned*)(lds + (bufoff) + ldsw + _i * 8192), 16, 0, 0); } while (0)
; #define PG8_LDA(dst, b, h) do { _Pragma("unroll") for (int m = 0; m < 4; ++m) _Pragma("unroll") for (int k = 0; k < 2; ++k) dst[m][k] = *(const PG8_LAS bf16x8*)(lds + PG8_SA(b, h) + aoff + m * 2048 + k * 1024); } while (0)
; #define PG8_MMA(ai, bj, At, Bt) do { __builtin_amdgcn_s_setprio(1); _Pragma("unroll") for (int m = 0; m < 4; ++m) _Pragma("unroll") for (int n = 0; n < 2; ++n) _Pragma("unroll") for (int k = 0; k < 2; ++k) \
;         acc[ai][bj][m][n] = __builtin_amdgcn_mfma_f32_16x16x32_bf16(Bt[n][k], At[m][k], acc[ai][bj][m][n], 0, 0, 0); __builtin_amdgcn_s_setprio(0); } while (0)
; #define PG8_WAIT_V(n) asm volatile("s_waitcnt vmcnt(" #n ")" ::: "memory")
; #define PG8_WAIT_L(n) asm volatile("s_waitcnt lgkmcnt(" #n ")" ::: "memory")
; #define PG8_BAR __builtin_amdgcn_s_barrier()
; #define PG8_SCHED __builtin_amdgcn_sched_barrier(0)
; template <class Epi, class Sched, bool ALIGN_EPI = false, bool SP2 = false>
; __device__ __forceinline__ void gemm_phase(PG8_LAS unsigned char* lds, const Gemm g, const Sched& S, const Epi& E) {
;     ...
;             PG8_WAIT_V(8); PG8_WAIT_L(0); PG8_BAR; PG8_MMA(0, 0, At, B0); PG8_MMA(0, 1, At, B1); PG8_BAR; PG8_SCHED;
;             PG8_LDA(At, 0, 1); PG8_STAGE(PG8_SB(0, 0), b2, voffB); PG8_STAGE(PG8_SB(0, 1), b2 + hstepB, voffB); PG8_STAGE(PG8_SA(0, 0), a2, voffA);
;             PG8_WAIT_V(8); PG8_WAIT_L(0); PG8_BAR; PG8_MMA(1, 0, At, B0); PG8_MMA(1, 1, At, B1); PG8_BAR; PG8_SCHED;
	s_waitcnt lgkmcnt(0)
	v_mfma_f32_16x16x32_bf16 v[124:127], v[128:131], v[160:163], v[124:127]
	v_mfma_f32_16x16x32_bf16 v[120:123], v[136:139], v[160:163], v[120:123]
	v_mfma_f32_16x16x32_bf16 v[108:111], v[128:131], v[168:171], v[108:111]
	v_mfma_f32_16x16x32_bf16 v[104:107], v[136:139], v[168:171], v[104:107]
	v_mfma_f32_16x16x32_bf16 v[92:95], v[128:131], v[176:179], v[92:95]
	v_mfma_f32_16x16x32_bf16 v[88:91], v[136:139], v[176:179], v[88:91]
	v_mfma_f32_16x16x32_bf16 v[76:79], v[128:131], v[230:233], v[76:79]
	v_mfma_f32_16x16x32_bf16 v[72:75], v[136:139], v[230:233], v[72:75]
	v_mfma_f32_16x16x32_bf16 v[124:127], v[132:135], v[164:167], v[124:127]
	v_mfma_f32_16x16x32_bf16 v[120:123], v[140:143], v[164:167], v[120:123]
	v_mfma_f32_16x16x32_bf16 v[108:111], v[132:135], v[172:175], v[108:111]
	v_mfma_f32_16x16x32_bf16 v[104:107], v[140:143], v[172:175], v[104:107]
	v_mfma_f32_16x16x32_bf16 v[92:95], v[132:135], v[180:183], v[92:95]
	v_mfma_f32_16x16x32_bf16 v[88:91], v[140:143], v[180:183], v[88:91]
	v_mfma_f32_16x16x32_bf16 v[76:79], v[132:135], v[234:237], v[76:79]
	v_mfma_f32_16x16x32_bf16 v[72:75], v[140:143], v[234:237], v[72:75]
	v_mfma_f32_16x16x32_bf16 v[116:119], v[144:147], v[160:163], v[116:119]
	v_mfma_f32_16x16x32_bf16 v[112:115], v[152:155], v[160:163], v[112:115]
	v_mfma_f32_16x16x32_bf16 v[100:103], v[144:147], v[168:171], v[100:103]
	v_mfma_f32_16x16x32_bf16 v[96:99], v[152:155], v[168:171], v[96:99]
	v_mfma_f32_16x16x32_bf16 v[84:87], v[144:147], v[176:179], v[84:87]
	v_mfma_f32_16x16x32_bf16 v[80:83], v[152:155], v[176:179], v[80:83]
	v_mfma_f32_16x16x32_bf16 v[68:71], v[144:147], v[230:233], v[68:71]
	v_mfma_f32_16x16x32_bf16 v[64:67], v[152:155], v[230:233], v[64:67]
	v_mfma_f32_16x16x32_bf16 v[116:119], v[148:151], v[164:167], v[116:119]
	v_mfma_f32_16x16x32_bf16 v[112:115], v[156:159], v[164:167], v[112:115]
	v_mfma_f32_16x16x32_bf16 v[100:103], v[148:151], v[172:175], v[100:103]
	v_mfma_f32_16x16x32_bf16 v[96:99], v[156:159], v[172:175], v[96:99]
	v_mfma_f32_16x16x32_bf16 v[84:87], v[148:151], v[180:183], v[84:87]
	v_mfma_f32_16x16x32_bf16 v[80:83], v[156:159], v[180:183], v[80:83]
	v_mfma_f32_16x16x32_bf16 v[68:71], v[148:151], v[234:237], v[68:71]
	v_mfma_f32_16x16x32_bf16 v[64:67], v[156:159], v[234:237], v[64:67]
	s_barrier
	s_add_i32 s33, s86, s14
	v_lshl_add_u64 v[238:239], s[76:77], 0, v[190:191]
	s_mov_b32 m0, s33
	ds_read_b128 v[160:163], v222 offset:16384
	ds_read_b128 v[164:167], v222 offset:17408
	ds_read_b128 v[168:171], v222 offset:18432
	ds_read_b128 v[172:175], v222 offset:19456
	ds_read_b128 v[176:179], v222 offset:20480
	ds_read_b128 v[180:183], v222 offset:21504
	ds_read_b128 v[230:233], v222 offset:22528
	ds_read_b128 v[234:237], v222 offset:23552
	global_load_lds_dwordx4 v[238:239], off
	v_lshl_add_u64 v[240:241], v[238:239], 0, s[40:41]
	s_add_i32 m0, s33, 0x2000
	s_add_i32 s33, s87, s14
	global_load_lds_dwordx4 v[240:241], off
	v_lshl_add_u64 v[240:241], v[238:239], 0, s[42:43]
	s_mov_b32 m0, s33
	s_nop 0
	global_load_lds_dwordx4 v[240:241], off
	v_lshl_add_u64 v[240:241], v[238:239], 0, s[44:45]
	s_add_i32 m0, s33, 0x2000
	s_nop 0
	global_load_lds_dwordx4 v[240:241], off
	v_lshl_add_u64 v[240:241], s[74:75], 0, v[190:191]
	s_mov_b32 m0, s15
	v_lshl_add_u64 v[242:243], v[240:241], 0, s[40:41]
	global_load_lds_dwordx4 v[240:241], off
	s_mov_b32 m0, s17
	s_nop 0
	global_load_lds_dwordx4 v[242:243], off
	s_waitcnt vmcnt(8)
	s_waitcnt lgkmcnt(0)
	s_barrier
	s_waitcnt lgkmcnt(0)
	v_mfma_f32_16x16x32_bf16 v[60:63], v[128:131], v[160:163], v[60:63]
	v_mfma_f32_16x16x32_bf16 v[56:59], v[136:139], v[160:163], v[56:59]
	v_mfma_f32_16x16x32_bf16 v[44:47], v[128:131], v[168:171], v[44:47]
	v_mfma_f32_16x16x32_bf16 v[40:43], v[136:139], v[168:171], v[40:43]
	v_mfma_f32_16x16x32_bf16 v[28:31], v[128:131], v[176:179], v[28:31]
	v_mfma_f32_16x16x32_bf16 v[24:27], v[136:139], v[176:179], v[24:27]
	v_mfma_f32_16x16x32_bf16 v[12:15], v[128:131], v[230:233], v[12:15]
	v_mfma_f32_16x16x32_bf16 v[8:11], v[136:139], v[230:233], v[8:11]
	v_mfma_f32_16x16x32_bf16 v[60:63], v[132:135], v[164:167], v[60:63]
	v_mfma_f32_16x16x32_bf16 v[56:59], v[140:143], v[164:167], v[56:59]
	v_mfma_f32_16x16x32_bf16 v[44:47], v[132:135], v[172:175], v[44:47]
	v_mfma_f32_16x16x32_bf16 v[40:43], v[140:143], v[172:175], v[40:43]
	v_mfma_f32_16x16x32_bf16 v[28:31], v[132:135], v[180:183], v[28:31]
	v_mfma_f32_16x16x32_bf16 v[24:27], v[140:143], v[180:183], v[24:27]
	v_mfma_f32_16x16x32_bf16 v[12:15], v[132:135], v[234:237], v[12:15]
	v_mfma_f32_16x16x32_bf16 v[8:11], v[140:143], v[234:237], v[8:11]
	v_mfma_f32_16x16x32_bf16 v[52:55], v[144:147], v[160:163], v[52:55]
	v_mfma_f32_16x16x32_bf16 v[48:51], v[152:155], v[160:163], v[48:51]
	v_mfma_f32_16x16x32_bf16 v[36:39], v[144:147], v[168:171], v[36:39]
	v_mfma_f32_16x16x32_bf16 v[32:35], v[152:155], v[168:171], v[32:35]
	v_mfma_f32_16x16x32_bf16 v[20:23], v[144:147], v[176:179], v[20:23]
	v_mfma_f32_16x16x32_bf16 v[16:19], v[152:155], v[176:179], v[16:19]
	v_mfma_f32_16x16x32_bf16 v[4:7], v[144:147], v[230:233], v[4:7]
	v_mfma_f32_16x16x32_bf16 v[0:3], v[152:155], v[230:233], v[0:3]
	v_mfma_f32_16x16x32_bf16 v[52:55], v[148:151], v[164:167], v[52:55]
	v_mfma_f32_16x16x32_bf16 v[48:51], v[156:159], v[164:167], v[48:51]
	v_mfma_f32_16x16x32_bf16 v[36:39], v[148:151], v[172:175], v[36:39]
	v_mfma_f32_16x16x32_bf16 v[32:35], v[156:159], v[172:175], v[32:35]
	v_mfma_f32_16x16x32_bf16 v[20:23], v[148:151], v[180:183], v[20:23]
	v_mfma_f32_16x16x32_bf16 v[16:19], v[156:159], v[180:183], v[16:19]
	v_mfma_f32_16x16x32_bf16 v[4:7], v[148:151], v[234:237], v[4:7]
	v_mfma_f32_16x16x32_bf16 v[0:3], v[156:159], v[234:237], v[0:3]
	s_barrier
; #define PG8_STAGE(bufoff, gbase, voff) do { _Pragma("unroll") for (int _i = 0; _i < 2; ++_i) \
;         __builtin_amdgcn_global_load_lds((const unsigned*)((const char*)(gbase) + (voff)[_i]), (PG8_LAS unsigned*)(lds + (bufoff) + ldsw + _i * 8192), 16, 0, 0); } while (0)
; #define PG8_LDA(dst, b, h) do { _Pragma("unroll") for (int m = 0; m < 4; ++m) _Pragma("unroll") for (int k = 0; k < 2; ++k) dst[m][k] = *(const PG8_LAS bf16x8*)(lds + PG8_SA(b, h) + aoff + m * 2048 + k * 1024); } while (0)
; #define PG8_LDB(dst, b, h) do { _Pragma("unroll") for (int n = 0; n < 2; ++n) _Pragma("unroll") for (int k = 0; k < 2; ++k) dst[n][k] = *(const PG8_LAS bf16x8*)(lds + PG8_SB(b, h) + boff + n * 2048 + k * 1024); } while (0)
; #define PG8_MMA(ai, bj, At, Bt) do { __builtin_amdgcn_s_setprio(1); _Pragma("unroll") for (int m = 0; m < 4; ++m) _Pragma("unroll") for (int n = 0; n < 2; ++n) _Pragma("unroll") for (int k = 0; k < 2; ++k) \
;         acc[ai][bj][m][n] = __builtin_amdgcn_mfma_f32_16x16x32_bf16(Bt[n][k], At[m][k], acc[ai][bj][m][n], 0, 0, 0); __builtin_amdgcn_s_setprio(0); } while (0)
; #define PG8_WAIT_V(n) asm volatile("s_waitcnt vmcnt(" #n ")" ::: "memory")
; #define PG8_WAIT_L(n) asm volatile("s_waitcnt lgkmcnt(" #n ")" ::: "memory")
; #define PG8_BAR __builtin_amdgcn_s_barrier()
; #define PG8_SCHED __builtin_amdgcn_sched_barrier(0)
; template <class Epi, class Sched, bool ALIGN_EPI = false, bool SP2 = false>
; __device__ __forceinline__ void gemm_phase(PG8_LAS unsigned char* lds, const Gemm g, const Sched& S, const Epi& E) {
;     ...
;             PG8_LDB(B0, 1, 0); PG8_LDB(B1, 1, 1); PG8_SCHED; PG8_LDA(At, 1, 0); PG8_STAGE(PG8_SA(0, 1), a2 + hstepA, voffA);
;             PG8_WAIT_V(8); PG8_WAIT_L(0); PG8_BAR; PG8_MMA(0, 0, At, B0); PG8_MMA(0, 1, At, B1); PG8_BAR; PG8_SCHED;
;             PG8_LDA(At, 1, 1); PG8_STAGE(PG8_SB(1, 0), b3, voffB); PG8_STAGE(PG8_SB(1, 1), b3 + hstepB, voffB); PG8_STAGE(PG8_SA(1, 0), a3, voffA);
;             PG8_WAIT_V(8); PG8_WAIT_L(0); PG8_BAR; PG8_MMA(1, 0, At, B0); PG8_MMA(1, 1, At, B1); PG8_BAR; PG8_SCHED;
;     ...
;         if constexpr (ALIGN_EPI) { if (wr == 0) PG8_BAR; }
	ds_read_b128 v[128:131], v223
	ds_read_b128 v[132:135], v223 offset:1024
	ds_read_b128 v[136:139], v223 offset:2048
	ds_read_b128 v[140:143], v223 offset:3072
	ds_read_b128 v[144:147], v224
	ds_read_b128 v[148:151], v224 offset:1024
	ds_read_b128 v[152:155], v224 offset:2048
	ds_read_b128 v[156:159], v224 offset:3072
	s_mov_b32 m0, s18
	v_lshl_add_u64 v[242:243], v[240:241], 0, s[42:43]
	ds_read_b128 v[160:163], v222 offset:32768
	ds_read_b128 v[164:167], v222 offset:33792
	ds_read_b128 v[168:171], v222 offset:34816
	ds_read_b128 v[172:175], v222 offset:35840
	ds_read_b128 v[176:179], v222 offset:36864
	ds_read_b128 v[180:183], v222 offset:37888
	ds_read_b128 v[230:233], v222 offset:38912
	ds_read_b128 v[234:237], v222 offset:39936
	global_load_lds_dwordx4 v[242:243], off
	v_lshl_add_u64 v[242:243], v[240:241], 0, s[44:45]
	s_mov_b32 m0, s19
	s_nop 0
	global_load_lds_dwordx4 v[242:243], off
	s_waitcnt vmcnt(8)
	s_waitcnt lgkmcnt(0)
	s_barrier
	s_waitcnt lgkmcnt(0)
	v_mfma_f32_16x16x32_bf16 v[124:127], v[128:131], v[160:163], v[124:127]
	v_mfma_f32_16x16x32_bf16 v[120:123], v[136:139], v[160:163], v[120:123]
	v_mfma_f32_16x16x32_bf16 v[108:111], v[128:131], v[168:171], v[108:111]
	v_mfma_f32_16x16x32_bf16 v[104:107], v[136:139], v[168:171], v[104:107]
	v_mfma_f32_16x16x32_bf16 v[92:95], v[128:131], v[176:179], v[92:95]
	v_mfma_f32_16x16x32_bf16 v[88:91], v[136:139], v[176:179], v[88:91]
	v_mfma_f32_16x16x32_bf16 v[76:79], v[128:131], v[230:233], v[76:79]
	v_mfma_f32_16x16x32_bf16 v[72:75], v[136:139], v[230:233], v[72:75]
	v_mfma_f32_16x16x32_bf16 v[124:127], v[132:135], v[164:167], v[124:127]
	v_mfma_f32_16x16x32_bf16 v[120:123], v[140:143], v[164:167], v[120:123]
	v_mfma_f32_16x16x32_bf16 v[108:111], v[132:135], v[172:175], v[108:111]
	v_mfma_f32_16x16x32_bf16 v[104:107], v[140:143], v[172:175], v[104:107]
	v_mfma_f32_16x16x32_bf16 v[92:95], v[132:135], v[180:183], v[92:95]
	v_mfma_f32_16x16x32_bf16 v[88:91], v[140:143], v[180:183], v[88:91]
	v_mfma_f32_16x16x32_bf16 v[76:79], v[132:135], v[234:237], v[76:79]
	v_mfma_f32_16x16x32_bf16 v[72:75], v[140:143], v[234:237], v[72:75]
	v_mfma_f32_16x16x32_bf16 v[116:119], v[144:147], v[160:163], v[116:119]
	v_mfma_f32_16x16x32_bf16 v[112:115], v[152:155], v[160:163], v[112:115]
	v_mfma_f32_16x16x32_bf16 v[100:103], v[144:147], v[168:171], v[100:103]
	v_mfma_f32_16x16x32_bf16 v[96:99], v[152:155], v[168:171], v[96:99]
	v_mfma_f32_16x16x32_bf16 v[84:87], v[144:147], v[176:179], v[84:87]
	v_mfma_f32_16x16x32_bf16 v[80:83], v[152:155], v[176:179], v[80:83]
	v_mfma_f32_16x16x32_bf16 v[68:71], v[144:147], v[230:233], v[68:71]
	v_mfma_f32_16x16x32_bf16 v[64:67], v[152:155], v[230:233], v[64:67]
	v_mfma_f32_16x16x32_bf16 v[116:119], v[148:151], v[164:167], v[116:119]
	v_mfma_f32_16x16x32_bf16 v[112:115], v[156:159], v[164:167], v[112:115]
	v_mfma_f32_16x16x32_bf16 v[100:103], v[148:151], v[172:175], v[100:103]
	v_mfma_f32_16x16x32_bf16 v[96:99], v[156:159], v[172:175], v[96:99]
	v_mfma_f32_16x16x32_bf16 v[84:87], v[148:151], v[180:183], v[84:87]
	v_mfma_f32_16x16x32_bf16 v[80:83], v[156:159], v[180:183], v[80:83]
	v_mfma_f32_16x16x32_bf16 v[68:71], v[148:151], v[234:237], v[68:71]
	v_mfma_f32_16x16x32_bf16 v[64:67], v[156:159], v[234:237], v[64:67]
	s_barrier
	s_add_i32 s33, s88, s14
	v_lshl_add_u64 v[242:243], v[238:239], 0, s[46:47]
	s_mov_b32 m0, s33
	ds_read_b128 v[160:163], v222 offset:49152
	ds_read_b128 v[164:167], v222 offset:50176
	ds_read_b128 v[168:171], v222 offset:51200
	ds_read_b128 v[172:175], v222 offset:52224
	ds_read_b128 v[176:179], v222 offset:53248
	ds_read_b128 v[180:183], v222 offset:54272
	ds_read_b128 v[230:233], v222 offset:55296
	ds_read_b128 v[234:237], v222 offset:56320
	global_load_lds_dwordx4 v[242:243], off
	v_lshl_add_u64 v[242:243], v[238:239], 0, s[48:49]
	s_add_i32 m0, s33, 0x2000
	s_add_i32 s33, s89, s14
	global_load_lds_dwordx4 v[242:243], off
	v_lshl_add_u64 v[242:243], v[238:239], 0, s[52:53]
	s_mov_b32 m0, s33
	v_lshl_add_u64 v[238:239], v[238:239], 0, s[54:55]
	global_load_lds_dwordx4 v[242:243], off
	s_add_i32 m0, s33, 0x2000
	s_nop 0
	global_load_lds_dwordx4 v[238:239], off
	v_lshl_add_u64 v[238:239], v[240:241], 0, s[46:47]
	s_mov_b32 m0, s80
	s_nop 0
	global_load_lds_dwordx4 v[238:239], off
	v_lshl_add_u64 v[238:239], v[240:241], 0, s[48:49]
	s_mov_b32 m0, s81
	s_nop 0
	global_load_lds_dwordx4 v[238:239], off
	s_waitcnt vmcnt(8)
	s_waitcnt lgkmcnt(0)
	s_barrier
	s_waitcnt lgkmcnt(0)
	v_mfma_f32_16x16x32_bf16 v[60:63], v[128:131], v[160:163], v[60:63]
	v_mfma_f32_16x16x32_bf16 v[56:59], v[136:139], v[160:163], v[56:59]
	v_mfma_f32_16x16x32_bf16 v[44:47], v[128:131], v[168:171], v[44:47]
	v_mfma_f32_16x16x32_bf16 v[40:43], v[136:139], v[168:171], v[40:43]
	v_mfma_f32_16x16x32_bf16 v[28:31], v[128:131], v[176:179], v[28:31]
	v_mfma_f32_16x16x32_bf16 v[24:27], v[136:139], v[176:179], v[24:27]
	v_mfma_f32_16x16x32_bf16 v[12:15], v[128:131], v[230:233], v[12:15]
	v_mfma_f32_16x16x32_bf16 v[8:11], v[136:139], v[230:233], v[8:11]
	v_mfma_f32_16x16x32_bf16 v[60:63], v[132:135], v[164:167], v[60:63]
	v_mfma_f32_16x16x32_bf16 v[56:59], v[140:143], v[164:167], v[56:59]
	v_mfma_f32_16x16x32_bf16 v[44:47], v[132:135], v[172:175], v[44:47]
	v_mfma_f32_16x16x32_bf16 v[40:43], v[140:143], v[172:175], v[40:43]
	v_mfma_f32_16x16x32_bf16 v[28:31], v[132:135], v[180:183], v[28:31]
	v_mfma_f32_16x16x32_bf16 v[24:27], v[140:143], v[180:183], v[24:27]
	v_mfma_f32_16x16x32_bf16 v[12:15], v[132:135], v[234:237], v[12:15]
	v_mfma_f32_16x16x32_bf16 v[8:11], v[140:143], v[234:237], v[8:11]
	v_mfma_f32_16x16x32_bf16 v[52:55], v[144:147], v[160:163], v[52:55]
	v_mfma_f32_16x16x32_bf16 v[48:51], v[152:155], v[160:163], v[48:51]
	v_mfma_f32_16x16x32_bf16 v[36:39], v[144:147], v[168:171], v[36:39]
	v_mfma_f32_16x16x32_bf16 v[32:35], v[152:155], v[168:171], v[32:35]
	v_mfma_f32_16x16x32_bf16 v[20:23], v[144:147], v[176:179], v[20:23]
	v_mfma_f32_16x16x32_bf16 v[16:19], v[152:155], v[176:179], v[16:19]
	v_mfma_f32_16x16x32_bf16 v[4:7], v[144:147], v[230:233], v[4:7]
	v_mfma_f32_16x16x32_bf16 v[0:3], v[152:155], v[230:233], v[0:3]
	v_mfma_f32_16x16x32_bf16 v[52:55], v[148:151], v[164:167], v[52:55]
	v_mfma_f32_16x16x32_bf16 v[48:51], v[156:159], v[164:167], v[48:51]
	v_mfma_f32_16x16x32_bf16 v[36:39], v[148:151], v[172:175], v[36:39]
	v_mfma_f32_16x16x32_bf16 v[32:35], v[156:159], v[172:175], v[32:35]
	v_mfma_f32_16x16x32_bf16 v[20:23], v[148:151], v[180:183], v[20:23]
	v_mfma_f32_16x16x32_bf16 v[16:19], v[156:159], v[180:183], v[16:19]
	v_mfma_f32_16x16x32_bf16 v[4:7], v[148:151], v[234:237], v[4:7]
	v_mfma_f32_16x16x32_bf16 v[0:3], v[156:159], v[234:237], v[0:3]
	s_barrier
	s_add_i32 s73, s73, 2
	s_add_u32 s70, s70, 0x10000
	s_addc_u32 s71, s71, 0
	s_add_u32 s69, s69, 0x10000
	s_addc_u32 s72, s72, 0
	s_cmp_gt_u32 s73, 41
	s_cbranch_scc0 .LBB0_1004
	s_and_b64 vcc, exec, s[60:61]
	s_cbranch_vccz .LBB0_1007
	s_barrier
